# v62 + result-store ladder de-serialisation: stage_store_tile in the 4 outproj and 3 gate tile loops reads 8 row chunks up front and keeps 8 LDS reads in flight while storing (constant address steps)
# baseline (speedup 1.0000x reference)
; DI int otid() { int t = threadIdx.x; asm volatile("" : "+v"(t)); return t; }
; DI void stg16_nt(void* p, u32x4 v) { __builtin_nontemporal_store(v, (u32x4*)p); }
; DI void stage_store_tile(const bf16_t* stg, bf16_t* tilebase) {
;   const int tid = otid();
;   const int r0 = tid >> 5, c = tid & 31;
;   const unsigned o0 = (unsigned)(r0 * 1024 + c * 8);
; #pragma unroll
;   for (int it = 0; it < 16; ++it) stg16_nt(tilebase + (o0 + (unsigned)(it * 16 * 1024)), stage_read16(stg, r0 + 16 * it, c));
; }
.LBB0_406:
	s_or_b64 exec, exec, s[40:41]
	v_mov_b32_e32 v0, v192
	s_waitcnt lgkmcnt(0)
	s_barrier
	s_mov_b64 s[100:101], 0x8000
	s_lshl_b64 s[36:37], s[36:37], 18
	s_lshl_b64 s[36:37], s[36:37], 1
	s_add_u32 s36, s76, s36
	s_addc_u32 s37, s77, s37
	s_add_u32 s36, s36, s52
	s_addc_u32 s37, s37, 0
	s_add_i32 s44, s44, s69
	s_andn2_b64 vcc, exec, s[38:39]
	s_add_i32 s45, s45, s42
	v_ashrrev_i32_e32 v190, 5, v192
	v_and_b32_e32 v191, 31, v192
	v_mul_lo_u32 v252, v190, s48
	v_lshl_add_u32 v252, v191, 4, v252
	v_lshlrev_b32_e32 v191, 3, v191
	v_lshl_or_b32 v254, v190, 10, v191
	v_mov_b32_e32 v255, v161
	ds_read2_b64 v[218:221], v252 offset1:1
	v_add_u32_e32 v253, 0x2080, v252
	ds_read2_b64 v[222:225], v253 offset1:1
	v_add_u32_e32 v253, 0x4100, v252
	ds_read2_b64 v[226:229], v253 offset1:1
	v_add_u32_e32 v253, 0x6180, v252
	ds_read2_b64 v[230:233], v253 offset1:1
	v_add_u32_e32 v253, 0x8200, v252
	ds_read2_b64 v[234:237], v253 offset1:1
	v_add_u32_e32 v253, 0xa280, v252
	ds_read2_b64 v[238:241], v253 offset1:1
	v_add_u32_e32 v253, 0xc300, v252
	ds_read2_b64 v[242:245], v253 offset1:1
	v_add_u32_e32 v253, 0xe380, v252
	ds_read2_b64 v[248:251], v253 offset1:1
	v_lshl_add_u64 v[254:255], v[254:255], 1, s[36:37]
	s_waitcnt lgkmcnt(7)
	global_store_dwordx4 v[254:255], v[218:221], off nt
	v_add_u32_e32 v253, 0x10400, v252
	ds_read2_b64 v[218:221], v253 offset1:1
	v_lshl_add_u64 v[254:255], v[254:255], 0, s[100:101]
	s_waitcnt lgkmcnt(7)
	global_store_dwordx4 v[254:255], v[222:225], off nt
	v_add_u32_e32 v253, 0x12480, v252
	ds_read2_b64 v[222:225], v253 offset1:1
	v_lshl_add_u64 v[254:255], v[254:255], 0, s[100:101]
	s_waitcnt lgkmcnt(7)
	global_store_dwordx4 v[254:255], v[226:229], off nt
	v_add_u32_e32 v253, 0x14500, v252
	ds_read2_b64 v[226:229], v253 offset1:1
	v_lshl_add_u64 v[254:255], v[254:255], 0, s[100:101]
	s_waitcnt lgkmcnt(7)
	global_store_dwordx4 v[254:255], v[230:233], off nt
	v_add_u32_e32 v253, 0x16580, v252
	ds_read2_b64 v[230:233], v253 offset1:1
	v_lshl_add_u64 v[254:255], v[254:255], 0, s[100:101]
	s_waitcnt lgkmcnt(7)
	global_store_dwordx4 v[254:255], v[234:237], off nt
	v_add_u32_e32 v253, 0x18600, v252
	ds_read2_b64 v[234:237], v253 offset1:1
	v_lshl_add_u64 v[254:255], v[254:255], 0, s[100:101]
	s_waitcnt lgkmcnt(7)
	global_store_dwordx4 v[254:255], v[238:241], off nt
	v_add_u32_e32 v253, 0x1a680, v252
	ds_read2_b64 v[238:241], v253 offset1:1
	v_lshl_add_u64 v[254:255], v[254:255], 0, s[100:101]
	s_waitcnt lgkmcnt(7)
	global_store_dwordx4 v[254:255], v[242:245], off nt
	v_add_u32_e32 v253, 0x1c700, v252
	ds_read2_b64 v[242:245], v253 offset1:1
	v_lshl_add_u64 v[254:255], v[254:255], 0, s[100:101]
	s_waitcnt lgkmcnt(7)
	global_store_dwordx4 v[254:255], v[248:251], off nt
	v_add_u32_e32 v253, 0x1e780, v252
	ds_read2_b64 v[248:251], v253 offset1:1
	v_lshl_add_u64 v[254:255], v[254:255], 0, s[100:101]
	s_waitcnt lgkmcnt(7)
	global_store_dwordx4 v[254:255], v[218:221], off nt
	v_lshl_add_u64 v[254:255], v[254:255], 0, s[100:101]
	s_waitcnt lgkmcnt(6)
	global_store_dwordx4 v[254:255], v[222:225], off nt
	v_lshl_add_u64 v[254:255], v[254:255], 0, s[100:101]
	s_waitcnt lgkmcnt(5)
	global_store_dwordx4 v[254:255], v[226:229], off nt
	v_lshl_add_u64 v[254:255], v[254:255], 0, s[100:101]
	s_waitcnt lgkmcnt(4)
	global_store_dwordx4 v[254:255], v[230:233], off nt
	v_lshl_add_u64 v[254:255], v[254:255], 0, s[100:101]
	s_waitcnt lgkmcnt(3)
	global_store_dwordx4 v[254:255], v[234:237], off nt
	v_lshl_add_u64 v[254:255], v[254:255], 0, s[100:101]
	s_waitcnt lgkmcnt(2)
	global_store_dwordx4 v[254:255], v[238:241], off nt
	v_lshl_add_u64 v[254:255], v[254:255], 0, s[100:101]
	s_waitcnt lgkmcnt(1)
	global_store_dwordx4 v[254:255], v[242:245], off nt
	v_lshl_add_u64 v[254:255], v[254:255], 0, s[100:101]
	s_waitcnt lgkmcnt(0)
	global_store_dwordx4 v[254:255], v[248:251], off nt
	s_barrier
	s_cbranch_vccz .LBB0_417

; DI unsigned pack2(float a, float b) { f32x2_t v = {a, b}; bf16x2_t r = __builtin_convertvector(v, bf16x2_t); return __builtin_bit_cast(unsigned, r); }
; DI float sigmoidf_(float x) { return __builtin_amdgcn_rcpf(1.f + __expf(-x)); }
; template <bool LAST>
; DI void phase_gate(const Params& P, int layer, unsigned char* smem, int L, int G) {
;     ...
;     unsigned gq[4][2][8];
; #pragma unroll
;     for (int i = 0; i < 4; ++i)
; #pragma unroll
;       for (int q4 = 0; q4 < 4; ++q4) {
;         const int fl = wm * 128 + i * 32 + 8 * q4 + 4 * h;
;         const f32x4 c1v = *(const f32x4*)(vecL + fl), c2v = *(const f32x4*)(vecL + 256 + fl);
;         const float c1a[4] = {c1v.x, c1v.y, c1v.z, c1v.w}, c2a[4] = {c2v.x, c2v.y, c2v.z, c2v.w};
; #pragma unroll
;         for (int j = 0; j < 2; ++j) {
;           const int lrow = wn * 64 + j * 32 + r;
;           const float mu = rowA[lrow], rstd = rowB[lrow];
;           float sg4[4];
; #pragma unroll
;           for (int e = 0; e < 4; ++e) sg4[e] = sigmoidf_(rstd * (accu[i][j][4 * q4 + e] - mu * c1a[e]) + c2a[e]);
;           gq[i][j][2 * q4] = pack2(sg4[0], sg4[1]); gq[i][j][2 * q4 + 1] = pack2(sg4[2], sg4[3]);
;         }
;         __builtin_amdgcn_sched_barrier(0);
;       }
;     stage_load_tile<true>(stg, PPb + (size_t)mt * 256 * 1024 + nt * 256);
.LBB0_479:
	s_ashr_i32 s25, s24, 31
	s_lshl_b64 s[24:25], s[24:25], 19
	s_add_u32 s30, s66, s24
	s_addc_u32 s31, s67, s25
	v_and_b32_e32 v188, 31, v192
	v_ashrrev_i32_e32 v189, 5, v192
	v_lshlrev_b32_e32 v188, 3, v188
	v_lshl_or_b32 v188, v189, 10, v188
	v_add_u32_e32 v188, v188, v162
	v_lshlrev_b32_e32 v188, 1, v188
	global_load_dwordx4 v[180:183], v188, s[30:31] nt
	s_add_u32 s100, s30, 0x8000
	s_addc_u32 s101, s31, 0
	global_load_dwordx4 v[184:187], v188, s[100:101] nt
	s_add_u32 s100, s30, 0x10000
	s_addc_u32 s101, s31, 0
	global_load_dwordx4 v[194:197], v188, s[100:101] nt
	s_add_u32 s100, s30, 0x18000
	s_addc_u32 s101, s31, 0
	global_load_dwordx4 v[198:201], v188, s[100:101] nt
	s_add_u32 s100, s30, 0x20000
	s_addc_u32 s101, s31, 0
	global_load_dwordx4 v[202:205], v188, s[100:101] nt
	s_add_u32 s100, s30, 0x28000
	s_addc_u32 s101, s31, 0
	global_load_dwordx4 v[206:209], v188, s[100:101] nt
	s_add_u32 s100, s30, 0x30000
	s_addc_u32 s101, s31, 0
	global_load_dwordx4 v[210:213], v188, s[100:101] nt
	s_add_u32 s100, s30, 0x38000
	s_addc_u32 s101, s31, 0
	global_load_dwordx4 v[214:217], v188, s[100:101] nt
	s_add_u32 s100, s30, 0x40000
	s_addc_u32 s101, s31, 0
	global_load_dwordx4 v[218:221], v188, s[100:101] nt
	s_add_u32 s100, s30, 0x48000
	s_addc_u32 s101, s31, 0
	global_load_dwordx4 v[222:225], v188, s[100:101] nt
	s_add_u32 s100, s30, 0x50000
	s_addc_u32 s101, s31, 0
	global_load_dwordx4 v[226:229], v188, s[100:101] nt
	s_add_u32 s100, s30, 0x58000
	s_addc_u32 s101, s31, 0
	global_load_dwordx4 v[230:233], v188, s[100:101] nt
	s_add_u32 s100, s30, 0x60000
	s_addc_u32 s101, s31, 0
	global_load_dwordx4 v[234:237], v188, s[100:101] nt
	s_add_u32 s100, s30, 0x68000
	s_addc_u32 s101, s31, 0
	global_load_dwordx4 v[238:241], v188, s[100:101] nt
	s_add_u32 s100, s30, 0x70000
	s_addc_u32 s101, s31, 0
	global_load_dwordx4 v[242:245], v188, s[100:101] nt
	s_add_u32 s100, s30, 0x78000
	s_addc_u32 s101, s31, 0
	global_load_dwordx4 v[248:251], v188, s[100:101] nt
	v_lshrrev_b32_e32 v160, 1, v163
	v_lshrrev_b32_e32 v163, 3, v163
	v_and_b32_e32 v163, 4, v163
	v_and_or_b32 v160, v160, s43, v163
	v_lshlrev_b32_e32 v160, 2, v160
	v_add_u32_e32 v163, 0x24800, v160
	v_add_u32_e32 v164, 0x24c00, v160
	v_and_b32_e32 v167, 0x37c, v168
	ds_read_b128 v[170:173], v163
	ds_read_b128 v[174:177], v164
	v_or_b32_e32 v164, 0x24000, v167
	v_or_b32_e32 v166, 0x24080, v167
	v_or_b32_e32 v165, 0x24400, v167
	ds_read_b32 v168, v164
	ds_read_b32 v169, v165
	v_or_b32_e32 v167, 0x24480, v167
	ds_read_b32 v178, v166
	ds_read_b32 v179, v167
	s_waitcnt lgkmcnt(3)
	v_fma_f32 v112, -v170, v168, v112
	v_fma_f32 v113, -v171, v168, v113
	s_waitcnt lgkmcnt(1)
	v_fma_f32 v98, -v172, v178, v98
	v_fma_f32 v114, -v172, v168, v114
	v_fma_f32 v115, -v173, v168, v115
	v_fma_f32 v96, -v170, v178, v96
	v_fma_f32 v97, -v171, v178, v97
	s_waitcnt lgkmcnt(0)
	v_fma_f32 v98, v179, v98, v176
	v_fma_f32 v99, -v173, v178, v99
	v_fma_f32 v112, v169, v112, v174
	v_fma_f32 v113, v169, v113, v175
	v_fma_f32 v114, v169, v114, v176
	v_fma_f32 v115, v169, v115, v177
	v_fma_f32 v96, v179, v96, v174
	v_fma_f32 v97, v179, v97, v175
	v_mul_f32_e32 v98, 0xbfb8aa3b, v98
	v_fmac_f32_e32 v177, v179, v99
	v_mul_f32_e32 v112, 0xbfb8aa3b, v112
	v_mul_f32_e32 v113, 0xbfb8aa3b, v113
	v_mul_f32_e32 v114, 0xbfb8aa3b, v114
	v_mul_f32_e32 v115, 0xbfb8aa3b, v115
	v_mul_f32_e32 v96, 0xbfb8aa3b, v96
	v_mul_f32_e32 v97, 0xbfb8aa3b, v97
	v_exp_f32_e32 v98, v98
	v_mul_f32_e32 v99, 0xbfb8aa3b, v177
	v_exp_f32_e32 v112, v112
	v_exp_f32_e32 v113, v113
	v_exp_f32_e32 v114, v114
	v_exp_f32_e32 v115, v115
	v_exp_f32_e32 v96, v96
	v_exp_f32_e32 v97, v97
	v_exp_f32_e32 v99, v99
	v_add_f32_e32 v98, 1.0, v98
	v_add_f32_e32 v112, 1.0, v112
	v_add_f32_e32 v113, 1.0, v113
	v_add_f32_e32 v114, 1.0, v114
	v_add_f32_e32 v115, 1.0, v115
	v_add_f32_e32 v96, 1.0, v96
	v_add_f32_e32 v97, 1.0, v97
	v_rcp_f32_e32 v168, v98
	v_add_f32_e32 v98, 1.0, v99
	v_rcp_f32_e32 v112, v112
	v_rcp_f32_e32 v113, v113
	v_rcp_f32_e32 v114, v114
	v_rcp_f32_e32 v115, v115
	v_rcp_f32_e32 v96, v96
	v_rcp_f32_e32 v97, v97
	v_rcp_f32_e32 v169, v98
	v_cvt_pk_bf16_f32 v99, v112, v113
	v_cvt_pk_bf16_f32 v98, v114, v115
	v_cvt_pk_bf16_f32 v97, v96, v97
	v_cvt_pk_bf16_f32 v96, v168, v169
	v_add_u32_e32 v112, 0x24820, v160
	v_add_u32_e32 v168, 0x24c20, v160
	ds_read_b128 v[112:115], v112
	ds_read_b128 v[168:171], v168
	ds_read_b32 v172, v164
	ds_read_b32 v173, v165
	ds_read_b32 v174, v166
	ds_read_b32 v175, v167
	s_waitcnt lgkmcnt(3)
	v_fma_f32 v116, -v112, v172, v116
	v_fma_f32 v117, -v113, v172, v117
	s_waitcnt lgkmcnt(1)
	v_fma_f32 v102, -v114, v174, v102
	v_fma_f32 v118, -v114, v172, v118
	v_fma_f32 v119, -v115, v172, v119
	v_fma_f32 v100, -v112, v174, v100
	v_fma_f32 v101, -v113, v174, v101
	s_waitcnt lgkmcnt(0)
	v_fma_f32 v102, v175, v102, v170
	v_fma_f32 v103, -v115, v174, v103
	v_fma_f32 v116, v173, v116, v168
	v_fma_f32 v117, v173, v117, v169
	v_fma_f32 v118, v173, v118, v170
	v_fma_f32 v119, v173, v119, v171
	v_fma_f32 v100, v175, v100, v168
	v_fma_f32 v101, v175, v101, v169
	v_mul_f32_e32 v102, 0xbfb8aa3b, v102
	v_fmac_f32_e32 v171, v175, v103
	v_mul_f32_e32 v116, 0xbfb8aa3b, v116
	v_mul_f32_e32 v117, 0xbfb8aa3b, v117
	v_mul_f32_e32 v118, 0xbfb8aa3b, v118
	v_mul_f32_e32 v119, 0xbfb8aa3b, v119
	v_mul_f32_e32 v100, 0xbfb8aa3b, v100
	v_mul_f32_e32 v101, 0xbfb8aa3b, v101
	v_exp_f32_e32 v102, v102
	v_mul_f32_e32 v103, 0xbfb8aa3b, v171
	v_exp_f32_e32 v116, v116
	v_exp_f32_e32 v117, v117
	v_exp_f32_e32 v118, v118
	v_exp_f32_e32 v119, v119
	v_exp_f32_e32 v100, v100
	v_exp_f32_e32 v101, v101
	v_exp_f32_e32 v103, v103
	v_add_f32_e32 v102, 1.0, v102
	v_add_f32_e32 v116, 1.0, v116
	v_add_f32_e32 v117, 1.0, v117
	v_add_f32_e32 v118, 1.0, v118
	v_add_f32_e32 v119, 1.0, v119
	v_add_f32_e32 v100, 1.0, v100
	v_add_f32_e32 v101, 1.0, v101
	v_rcp_f32_e32 v113, v102
	v_add_f32_e32 v102, 1.0, v103
	v_rcp_f32_e32 v116, v116
	v_rcp_f32_e32 v117, v117
	v_rcp_f32_e32 v118, v118
	v_rcp_f32_e32 v112, v119
	v_rcp_f32_e32 v100, v100
	v_rcp_f32_e32 v101, v101
	v_rcp_f32_e32 v114, v102
	v_cvt_pk_bf16_f32 v103, v116, v117
	v_cvt_pk_bf16_f32 v102, v118, v112
	v_cvt_pk_bf16_f32 v101, v100, v101
	v_cvt_pk_bf16_f32 v100, v113, v114
	v_add_u32_e32 v112, 0x24840, v160
	v_add_u32_e32 v116, 0x24c40, v160
	ds_read_b128 v[112:115], v112
	ds_read_b128 v[116:119], v116
	ds_read_b32 v168, v164
	ds_read_b32 v169, v165
	ds_read_b32 v170, v166
	ds_read_b32 v171, v167
	s_waitcnt lgkmcnt(3)
; DI unsigned pack2(float a, float b) { f32x2_t v = {a, b}; bf16x2_t r = __builtin_convertvector(v, bf16x2_t); return __builtin_bit_cast(unsigned, r); }
; DI float sigmoidf_(float x) { return __builtin_amdgcn_rcpf(1.f + __expf(-x)); }
; template <bool LAST>
; DI void phase_gate(const Params& P, int layer, unsigned char* smem, int L, int G) {
;     ...
;     unsigned gq[4][2][8];
; #pragma unroll
;     for (int i = 0; i < 4; ++i)
; #pragma unroll
;       for (int q4 = 0; q4 < 4; ++q4) {
;         const int fl = wm * 128 + i * 32 + 8 * q4 + 4 * h;
;         const f32x4 c1v = *(const f32x4*)(vecL + fl), c2v = *(const f32x4*)(vecL + 256 + fl);
;         const float c1a[4] = {c1v.x, c1v.y, c1v.z, c1v.w}, c2a[4] = {c2v.x, c2v.y, c2v.z, c2v.w};
; #pragma unroll
;         for (int j = 0; j < 2; ++j) {
;           const int lrow = wn * 64 + j * 32 + r;
;           const float mu = rowA[lrow], rstd = rowB[lrow];
;           float sg4[4];
; #pragma unroll
;           for (int e = 0; e < 4; ++e) sg4[e] = sigmoidf_(rstd * (accu[i][j][4 * q4 + e] - mu * c1a[e]) + c2a[e]);
;           gq[i][j][2 * q4] = pack2(sg4[0], sg4[1]); gq[i][j][2 * q4 + 1] = pack2(sg4[2], sg4[3]);
;         }
;         __builtin_amdgcn_sched_barrier(0);
;       }
	v_fma_f32 v120, -v112, v168, v120
	v_fma_f32 v121, -v113, v168, v121
	s_waitcnt lgkmcnt(1)
	v_fma_f32 v106, -v114, v170, v106
	v_fma_f32 v122, -v114, v168, v122
	v_fma_f32 v123, -v115, v168, v123
	v_fma_f32 v104, -v112, v170, v104
	v_fma_f32 v105, -v113, v170, v105
	s_waitcnt lgkmcnt(0)
	v_fma_f32 v106, v171, v106, v118
	v_fma_f32 v107, -v115, v170, v107
	v_fma_f32 v120, v169, v120, v116
	v_fma_f32 v121, v169, v121, v117
	v_fma_f32 v122, v169, v122, v118
	v_fma_f32 v123, v169, v123, v119
	v_fma_f32 v104, v171, v104, v116
	v_fma_f32 v105, v171, v105, v117
	v_mul_f32_e32 v106, 0xbfb8aa3b, v106
	v_fmac_f32_e32 v119, v171, v107
	v_mul_f32_e32 v120, 0xbfb8aa3b, v120
	v_mul_f32_e32 v121, 0xbfb8aa3b, v121
	v_mul_f32_e32 v122, 0xbfb8aa3b, v122
	v_mul_f32_e32 v123, 0xbfb8aa3b, v123
	v_mul_f32_e32 v104, 0xbfb8aa3b, v104
	v_mul_f32_e32 v105, 0xbfb8aa3b, v105
	v_exp_f32_e32 v106, v106
	v_mul_f32_e32 v107, 0xbfb8aa3b, v119
	v_exp_f32_e32 v120, v120
	v_exp_f32_e32 v121, v121
	v_exp_f32_e32 v122, v122
	v_exp_f32_e32 v123, v123
	v_exp_f32_e32 v104, v104
	v_exp_f32_e32 v105, v105
	v_exp_f32_e32 v107, v107
	v_add_f32_e32 v106, 1.0, v106
	v_add_f32_e32 v120, 1.0, v120
	v_add_f32_e32 v121, 1.0, v121
	v_add_f32_e32 v122, 1.0, v122
	v_add_f32_e32 v123, 1.0, v123
	v_add_f32_e32 v104, 1.0, v104
	v_add_f32_e32 v105, 1.0, v105
	v_rcp_f32_e32 v113, v106
	v_add_f32_e32 v106, 1.0, v107
	v_rcp_f32_e32 v120, v120
	v_rcp_f32_e32 v121, v121
	v_rcp_f32_e32 v122, v122
	v_rcp_f32_e32 v112, v123
	v_rcp_f32_e32 v104, v104
	v_rcp_f32_e32 v105, v105
	v_rcp_f32_e32 v114, v106
	v_cvt_pk_bf16_f32 v107, v120, v121
	v_cvt_pk_bf16_f32 v106, v122, v112
	v_cvt_pk_bf16_f32 v105, v104, v105
	v_cvt_pk_bf16_f32 v104, v113, v114
	v_add_u32_e32 v112, 0x24860, v160
	v_add_u32_e32 v116, 0x24c60, v160
	ds_read_b128 v[112:115], v112
	ds_read_b128 v[116:119], v116
	ds_read_b32 v120, v164
	ds_read_b32 v121, v165
	ds_read_b32 v122, v166
	ds_read_b32 v123, v167
	s_waitcnt lgkmcnt(3)
	v_fma_f32 v125, -v113, v120, v125
	v_fma_f32 v124, -v112, v120, v124
	s_waitcnt lgkmcnt(1)
	v_fma_f32 v110, -v114, v122, v110
	v_fma_f32 v125, v121, v125, v117
	v_fma_f32 v126, -v114, v120, v126
	v_fma_f32 v120, -v115, v120, v127
	v_fma_f32 v108, -v112, v122, v108
	v_fma_f32 v109, -v113, v122, v109
	s_waitcnt lgkmcnt(0)
	v_fma_f32 v110, v123, v110, v118
	v_fma_f32 v111, -v115, v122, v111
	v_fma_f32 v124, v121, v124, v116
	v_mul_f32_e32 v125, 0xbfb8aa3b, v125
	v_fma_f32 v126, v121, v126, v118
	v_fma_f32 v120, v121, v120, v119
	v_fma_f32 v108, v123, v108, v116
	v_fma_f32 v109, v123, v109, v117
	v_mul_f32_e32 v110, 0xbfb8aa3b, v110
	v_fmac_f32_e32 v119, v123, v111
	v_mul_f32_e32 v124, 0xbfb8aa3b, v124
	v_exp_f32_e32 v125, v125
	v_mul_f32_e32 v126, 0xbfb8aa3b, v126
	v_mul_f32_e32 v120, 0xbfb8aa3b, v120
	v_mul_f32_e32 v108, 0xbfb8aa3b, v108
	v_mul_f32_e32 v109, 0xbfb8aa3b, v109
	v_exp_f32_e32 v110, v110
	v_mul_f32_e32 v111, 0xbfb8aa3b, v119
	v_exp_f32_e32 v124, v124
	v_exp_f32_e32 v126, v126
	v_exp_f32_e32 v120, v120
	v_exp_f32_e32 v108, v108
	v_exp_f32_e32 v109, v109
	v_exp_f32_e32 v111, v111
	v_add_f32_e32 v125, 1.0, v125
	v_add_f32_e32 v110, 1.0, v110
	v_add_f32_e32 v124, 1.0, v124
	v_rcp_f32_e32 v121, v125
	v_add_f32_e32 v125, 1.0, v126
	v_add_f32_e32 v120, 1.0, v120
	v_add_f32_e32 v108, 1.0, v108
	v_add_f32_e32 v109, 1.0, v109
	v_rcp_f32_e32 v113, v110
	v_add_f32_e32 v110, 1.0, v111
	v_rcp_f32_e32 v124, v124
	v_rcp_f32_e32 v125, v125
	v_rcp_f32_e32 v112, v120
	v_rcp_f32_e32 v108, v108
	v_rcp_f32_e32 v109, v109
	v_rcp_f32_e32 v114, v110
	v_cvt_pk_bf16_f32 v111, v124, v121
	v_cvt_pk_bf16_f32 v110, v125, v112
	v_cvt_pk_bf16_f32 v109, v108, v109
	v_cvt_pk_bf16_f32 v108, v113, v114
	v_add_u32_e32 v112, 0x24880, v160
	v_add_u32_e32 v116, 0x24c80, v160
	ds_read_b128 v[112:115], v112
	ds_read_b128 v[116:119], v116
	ds_read_b32 v120, v164
	ds_read_b32 v121, v165
	ds_read_b32 v122, v166
	ds_read_b32 v123, v167
	s_waitcnt lgkmcnt(3)
	v_fma_f32 v80, -v112, v120, v80
	v_fma_f32 v81, -v113, v120, v81
	s_waitcnt lgkmcnt(1)
	v_fma_f32 v66, -v114, v122, v66
	v_fma_f32 v82, -v114, v120, v82
	v_fma_f32 v83, -v115, v120, v83
	v_fma_f32 v64, -v112, v122, v64
	v_fma_f32 v65, -v113, v122, v65
	s_waitcnt lgkmcnt(0)
	v_fma_f32 v66, v123, v66, v118
	v_fma_f32 v67, -v115, v122, v67
	v_fma_f32 v80, v121, v80, v116
	v_fma_f32 v81, v121, v81, v117
	v_fma_f32 v82, v121, v82, v118
	v_fma_f32 v83, v121, v83, v119
	v_fma_f32 v64, v123, v64, v116
	v_fma_f32 v65, v123, v65, v117
	v_mul_f32_e32 v66, 0xbfb8aa3b, v66
	v_fmac_f32_e32 v119, v123, v67
	v_mul_f32_e32 v80, 0xbfb8aa3b, v80
	v_mul_f32_e32 v81, 0xbfb8aa3b, v81
	v_mul_f32_e32 v82, 0xbfb8aa3b, v82
	v_mul_f32_e32 v83, 0xbfb8aa3b, v83
	v_mul_f32_e32 v64, 0xbfb8aa3b, v64
	v_mul_f32_e32 v65, 0xbfb8aa3b, v65
	v_exp_f32_e32 v66, v66
	v_mul_f32_e32 v67, 0xbfb8aa3b, v119
	v_exp_f32_e32 v80, v80
	v_exp_f32_e32 v81, v81
	v_exp_f32_e32 v82, v82
	v_exp_f32_e32 v83, v83
	v_exp_f32_e32 v64, v64
	v_exp_f32_e32 v65, v65
	v_exp_f32_e32 v67, v67
	v_add_f32_e32 v66, 1.0, v66
	v_add_f32_e32 v80, 1.0, v80
	v_add_f32_e32 v81, 1.0, v81
	v_add_f32_e32 v82, 1.0, v82
	v_add_f32_e32 v83, 1.0, v83
	v_add_f32_e32 v64, 1.0, v64
	v_add_f32_e32 v65, 1.0, v65
	v_rcp_f32_e32 v112, v66
	v_add_f32_e32 v66, 1.0, v67
	v_rcp_f32_e32 v80, v80
	v_rcp_f32_e32 v81, v81
	v_rcp_f32_e32 v82, v82
	v_rcp_f32_e32 v83, v83
	v_rcp_f32_e32 v64, v64
	v_rcp_f32_e32 v65, v65
	v_rcp_f32_e32 v113, v66
	v_cvt_pk_bf16_f32 v67, v80, v81
	v_cvt_pk_bf16_f32 v66, v82, v83
	v_cvt_pk_bf16_f32 v65, v64, v65
	v_cvt_pk_bf16_f32 v64, v112, v113
	v_add_u32_e32 v80, 0x248a0, v160
	v_add_u32_e32 v112, 0x24ca0, v160
	ds_read_b128 v[80:83], v80
	ds_read_b128 v[112:115], v112
	ds_read_b32 v116, v164
	ds_read_b32 v117, v165
	ds_read_b32 v118, v166
	ds_read_b32 v119, v167
	s_waitcnt lgkmcnt(3)
; DI unsigned pack2(float a, float b) { f32x2_t v = {a, b}; bf16x2_t r = __builtin_convertvector(v, bf16x2_t); return __builtin_bit_cast(unsigned, r); }
; DI float sigmoidf_(float x) { return __builtin_amdgcn_rcpf(1.f + __expf(-x)); }
; template <bool LAST>
; DI void phase_gate(const Params& P, int layer, unsigned char* smem, int L, int G) {
;     ...
;     unsigned gq[4][2][8];
; #pragma unroll
;     for (int i = 0; i < 4; ++i)
; #pragma unroll
;       for (int q4 = 0; q4 < 4; ++q4) {
;         const int fl = wm * 128 + i * 32 + 8 * q4 + 4 * h;
;         const f32x4 c1v = *(const f32x4*)(vecL + fl), c2v = *(const f32x4*)(vecL + 256 + fl);
;         const float c1a[4] = {c1v.x, c1v.y, c1v.z, c1v.w}, c2a[4] = {c2v.x, c2v.y, c2v.z, c2v.w};
; #pragma unroll
;         for (int j = 0; j < 2; ++j) {
;           const int lrow = wn * 64 + j * 32 + r;
;           const float mu = rowA[lrow], rstd = rowB[lrow];
;           float sg4[4];
; #pragma unroll
;           for (int e = 0; e < 4; ++e) sg4[e] = sigmoidf_(rstd * (accu[i][j][4 * q4 + e] - mu * c1a[e]) + c2a[e]);
;           gq[i][j][2 * q4] = pack2(sg4[0], sg4[1]); gq[i][j][2 * q4 + 1] = pack2(sg4[2], sg4[3]);
;         }
;         __builtin_amdgcn_sched_barrier(0);
;       }
	v_fma_f32 v84, -v80, v116, v84
	v_fma_f32 v85, -v81, v116, v85
	s_waitcnt lgkmcnt(1)
	v_fma_f32 v70, -v82, v118, v70
	v_fma_f32 v86, -v82, v116, v86
	v_fma_f32 v87, -v83, v116, v87
	v_fma_f32 v68, -v80, v118, v68
	v_fma_f32 v69, -v81, v118, v69
	s_waitcnt lgkmcnt(0)
	v_fma_f32 v70, v119, v70, v114
	v_fma_f32 v71, -v83, v118, v71
	v_fma_f32 v84, v117, v84, v112
	v_fma_f32 v85, v117, v85, v113
	v_fma_f32 v86, v117, v86, v114
	v_fma_f32 v87, v117, v87, v115
	v_fma_f32 v68, v119, v68, v112
	v_fma_f32 v69, v119, v69, v113
	v_mul_f32_e32 v70, 0xbfb8aa3b, v70
	v_fmac_f32_e32 v115, v119, v71
	v_mul_f32_e32 v84, 0xbfb8aa3b, v84
	v_mul_f32_e32 v85, 0xbfb8aa3b, v85
	v_mul_f32_e32 v86, 0xbfb8aa3b, v86
	v_mul_f32_e32 v87, 0xbfb8aa3b, v87
	v_mul_f32_e32 v68, 0xbfb8aa3b, v68
	v_mul_f32_e32 v69, 0xbfb8aa3b, v69
	v_exp_f32_e32 v70, v70
	v_mul_f32_e32 v71, 0xbfb8aa3b, v115
	v_exp_f32_e32 v84, v84
	v_exp_f32_e32 v85, v85
	v_exp_f32_e32 v86, v86
	v_exp_f32_e32 v87, v87
	v_exp_f32_e32 v68, v68
	v_exp_f32_e32 v69, v69
	v_exp_f32_e32 v71, v71
	v_add_f32_e32 v70, 1.0, v70
	v_add_f32_e32 v84, 1.0, v84
	v_add_f32_e32 v85, 1.0, v85
	v_add_f32_e32 v86, 1.0, v86
	v_add_f32_e32 v87, 1.0, v87
	v_add_f32_e32 v68, 1.0, v68
	v_add_f32_e32 v69, 1.0, v69
	v_rcp_f32_e32 v81, v70
	v_add_f32_e32 v70, 1.0, v71
	v_rcp_f32_e32 v84, v84
	v_rcp_f32_e32 v85, v85
	v_rcp_f32_e32 v86, v86
	v_rcp_f32_e32 v80, v87
	v_rcp_f32_e32 v68, v68
	v_rcp_f32_e32 v69, v69
	v_rcp_f32_e32 v82, v70
	v_cvt_pk_bf16_f32 v71, v84, v85
	v_cvt_pk_bf16_f32 v70, v86, v80
	v_cvt_pk_bf16_f32 v69, v68, v69
	v_cvt_pk_bf16_f32 v68, v81, v82
	v_add_u32_e32 v80, 0x248c0, v160
	v_add_u32_e32 v84, 0x24cc0, v160
	ds_read_b128 v[80:83], v80
	ds_read_b128 v[84:87], v84
	ds_read_b32 v112, v164
	ds_read_b32 v113, v165
	ds_read_b32 v114, v166
	ds_read_b32 v115, v167
	s_waitcnt lgkmcnt(3)
	v_fma_f32 v88, -v80, v112, v88
	v_fma_f32 v89, -v81, v112, v89
	s_waitcnt lgkmcnt(1)
	v_fma_f32 v74, -v82, v114, v74
	v_fma_f32 v90, -v82, v112, v90
	v_fma_f32 v91, -v83, v112, v91
	v_fma_f32 v72, -v80, v114, v72
	v_fma_f32 v73, -v81, v114, v73
	s_waitcnt lgkmcnt(0)
	v_fma_f32 v74, v115, v74, v86
	v_fma_f32 v75, -v83, v114, v75
	v_fma_f32 v88, v113, v88, v84
	v_fma_f32 v89, v113, v89, v85
	v_fma_f32 v90, v113, v90, v86
	v_fma_f32 v91, v113, v91, v87
	v_fma_f32 v72, v115, v72, v84
	v_fma_f32 v73, v115, v73, v85
	v_mul_f32_e32 v74, 0xbfb8aa3b, v74
	v_fmac_f32_e32 v87, v115, v75
	v_mul_f32_e32 v88, 0xbfb8aa3b, v88
	v_mul_f32_e32 v89, 0xbfb8aa3b, v89
	v_mul_f32_e32 v90, 0xbfb8aa3b, v90
	v_mul_f32_e32 v91, 0xbfb8aa3b, v91
	v_mul_f32_e32 v72, 0xbfb8aa3b, v72
	v_mul_f32_e32 v73, 0xbfb8aa3b, v73
	v_exp_f32_e32 v74, v74
	v_mul_f32_e32 v75, 0xbfb8aa3b, v87
	v_exp_f32_e32 v88, v88
	v_exp_f32_e32 v89, v89
	v_exp_f32_e32 v90, v90
	v_exp_f32_e32 v91, v91
	v_exp_f32_e32 v72, v72
	v_exp_f32_e32 v73, v73
	v_exp_f32_e32 v75, v75
	v_add_f32_e32 v74, 1.0, v74
	v_add_f32_e32 v88, 1.0, v88
	v_add_f32_e32 v89, 1.0, v89
	v_add_f32_e32 v90, 1.0, v90
	v_add_f32_e32 v91, 1.0, v91
	v_add_f32_e32 v72, 1.0, v72
	v_add_f32_e32 v73, 1.0, v73
	v_rcp_f32_e32 v81, v74
	v_add_f32_e32 v74, 1.0, v75
	v_rcp_f32_e32 v88, v88
	v_rcp_f32_e32 v89, v89
	v_rcp_f32_e32 v90, v90
	v_rcp_f32_e32 v80, v91
	v_rcp_f32_e32 v72, v72
	v_rcp_f32_e32 v73, v73
	v_rcp_f32_e32 v82, v74
	v_cvt_pk_bf16_f32 v75, v88, v89
	v_cvt_pk_bf16_f32 v74, v90, v80
	v_cvt_pk_bf16_f32 v73, v72, v73
	v_cvt_pk_bf16_f32 v72, v81, v82
	v_add_u32_e32 v80, 0x248e0, v160
	v_add_u32_e32 v84, 0x24ce0, v160
	ds_read_b128 v[80:83], v80
	ds_read_b128 v[84:87], v84
	ds_read_b32 v88, v164
	ds_read_b32 v89, v165
	ds_read_b32 v90, v166
	ds_read_b32 v91, v167
	s_waitcnt lgkmcnt(3)
	v_fma_f32 v93, -v81, v88, v93
	v_fma_f32 v92, -v80, v88, v92
	s_waitcnt lgkmcnt(1)
	v_fma_f32 v78, -v82, v90, v78
	v_fma_f32 v93, v89, v93, v85
	v_fma_f32 v94, -v82, v88, v94
	v_fma_f32 v88, -v83, v88, v95
	v_fma_f32 v76, -v80, v90, v76
	v_fma_f32 v77, -v81, v90, v77
	s_waitcnt lgkmcnt(0)
	v_fma_f32 v78, v91, v78, v86
	v_fma_f32 v79, -v83, v90, v79
	v_fma_f32 v92, v89, v92, v84
	v_mul_f32_e32 v93, 0xbfb8aa3b, v93
	v_fma_f32 v94, v89, v94, v86
	v_fma_f32 v88, v89, v88, v87
	v_fma_f32 v76, v91, v76, v84
	v_fma_f32 v77, v91, v77, v85
	v_mul_f32_e32 v78, 0xbfb8aa3b, v78
	v_fmac_f32_e32 v87, v91, v79
	v_mul_f32_e32 v92, 0xbfb8aa3b, v92
	v_exp_f32_e32 v93, v93
	v_mul_f32_e32 v94, 0xbfb8aa3b, v94
	v_mul_f32_e32 v88, 0xbfb8aa3b, v88
	v_mul_f32_e32 v76, 0xbfb8aa3b, v76
	v_mul_f32_e32 v77, 0xbfb8aa3b, v77
	v_exp_f32_e32 v78, v78
	v_mul_f32_e32 v79, 0xbfb8aa3b, v87
	v_exp_f32_e32 v92, v92
	v_exp_f32_e32 v94, v94
	v_exp_f32_e32 v88, v88
	v_exp_f32_e32 v76, v76
	v_exp_f32_e32 v77, v77
	v_exp_f32_e32 v79, v79
	v_add_f32_e32 v93, 1.0, v93
	v_add_f32_e32 v78, 1.0, v78
	v_add_f32_e32 v92, 1.0, v92
	v_rcp_f32_e32 v89, v93
	v_add_f32_e32 v93, 1.0, v94
	v_add_f32_e32 v88, 1.0, v88
	v_add_f32_e32 v76, 1.0, v76
	v_add_f32_e32 v77, 1.0, v77
	v_rcp_f32_e32 v81, v78
	v_add_f32_e32 v78, 1.0, v79
	v_rcp_f32_e32 v92, v92
	v_rcp_f32_e32 v93, v93
	v_rcp_f32_e32 v80, v88
	v_rcp_f32_e32 v76, v76
	v_rcp_f32_e32 v77, v77
	v_rcp_f32_e32 v82, v78
	v_cvt_pk_bf16_f32 v79, v92, v89
	v_cvt_pk_bf16_f32 v78, v93, v80
	v_cvt_pk_bf16_f32 v77, v76, v77
	v_cvt_pk_bf16_f32 v76, v81, v82
	v_add_u32_e32 v80, 0x24900, v160
	v_add_u32_e32 v84, 0x24d00, v160
	ds_read_b128 v[80:83], v80
	ds_read_b128 v[84:87], v84
	ds_read_b32 v88, v164
	ds_read_b32 v89, v165
	ds_read_b32 v90, v166
	ds_read_b32 v91, v167
	s_waitcnt lgkmcnt(3)
	v_fma_f32 v48, -v80, v88, v48
	v_fma_f32 v49, -v81, v88, v49
	s_waitcnt lgkmcnt(1)
	v_fma_f32 v34, -v82, v90, v34
	v_fma_f32 v50, -v82, v88, v50
	v_fma_f32 v51, -v83, v88, v51
	v_fma_f32 v32, -v80, v90, v32
	v_fma_f32 v33, -v81, v90, v33
	s_waitcnt lgkmcnt(0)
; DI unsigned pack2(float a, float b) { f32x2_t v = {a, b}; bf16x2_t r = __builtin_convertvector(v, bf16x2_t); return __builtin_bit_cast(unsigned, r); }
; DI float sigmoidf_(float x) { return __builtin_amdgcn_rcpf(1.f + __expf(-x)); }
; template <bool LAST>
; DI void phase_gate(const Params& P, int layer, unsigned char* smem, int L, int G) {
;     ...
;     unsigned gq[4][2][8];
; #pragma unroll
;     for (int i = 0; i < 4; ++i)
; #pragma unroll
;       for (int q4 = 0; q4 < 4; ++q4) {
;         const int fl = wm * 128 + i * 32 + 8 * q4 + 4 * h;
;         const f32x4 c1v = *(const f32x4*)(vecL + fl), c2v = *(const f32x4*)(vecL + 256 + fl);
;         const float c1a[4] = {c1v.x, c1v.y, c1v.z, c1v.w}, c2a[4] = {c2v.x, c2v.y, c2v.z, c2v.w};
; #pragma unroll
;         for (int j = 0; j < 2; ++j) {
;           const int lrow = wn * 64 + j * 32 + r;
;           const float mu = rowA[lrow], rstd = rowB[lrow];
;           float sg4[4];
; #pragma unroll
;           for (int e = 0; e < 4; ++e) sg4[e] = sigmoidf_(rstd * (accu[i][j][4 * q4 + e] - mu * c1a[e]) + c2a[e]);
;           gq[i][j][2 * q4] = pack2(sg4[0], sg4[1]); gq[i][j][2 * q4 + 1] = pack2(sg4[2], sg4[3]);
;         }
;         __builtin_amdgcn_sched_barrier(0);
;       }
	v_fma_f32 v34, v91, v34, v86
	v_fma_f32 v35, -v83, v90, v35
	v_fma_f32 v48, v89, v48, v84
	v_fma_f32 v49, v89, v49, v85
	v_fma_f32 v50, v89, v50, v86
	v_fma_f32 v51, v89, v51, v87
	v_fma_f32 v32, v91, v32, v84
	v_fma_f32 v33, v91, v33, v85
	v_mul_f32_e32 v34, 0xbfb8aa3b, v34
	v_fmac_f32_e32 v87, v91, v35
	v_mul_f32_e32 v48, 0xbfb8aa3b, v48
	v_mul_f32_e32 v49, 0xbfb8aa3b, v49
	v_mul_f32_e32 v50, 0xbfb8aa3b, v50
	v_mul_f32_e32 v51, 0xbfb8aa3b, v51
	v_mul_f32_e32 v32, 0xbfb8aa3b, v32
	v_mul_f32_e32 v33, 0xbfb8aa3b, v33
	v_exp_f32_e32 v34, v34
	v_mul_f32_e32 v35, 0xbfb8aa3b, v87
	v_exp_f32_e32 v48, v48
	v_exp_f32_e32 v49, v49
	v_exp_f32_e32 v50, v50
	v_exp_f32_e32 v51, v51
	v_exp_f32_e32 v32, v32
	v_exp_f32_e32 v33, v33
	v_exp_f32_e32 v35, v35
	v_add_f32_e32 v34, 1.0, v34
	v_add_f32_e32 v48, 1.0, v48
	v_add_f32_e32 v49, 1.0, v49
	v_add_f32_e32 v50, 1.0, v50
	v_add_f32_e32 v51, 1.0, v51
	v_add_f32_e32 v32, 1.0, v32
	v_add_f32_e32 v33, 1.0, v33
	v_rcp_f32_e32 v80, v34
	v_add_f32_e32 v34, 1.0, v35
	v_rcp_f32_e32 v48, v48
	v_rcp_f32_e32 v49, v49
	v_rcp_f32_e32 v50, v50
	v_rcp_f32_e32 v51, v51
	v_rcp_f32_e32 v32, v32
	v_rcp_f32_e32 v33, v33
	v_rcp_f32_e32 v81, v34
	v_cvt_pk_bf16_f32 v35, v48, v49
	v_cvt_pk_bf16_f32 v34, v50, v51
	v_cvt_pk_bf16_f32 v33, v32, v33
	v_cvt_pk_bf16_f32 v32, v80, v81
	v_add_u32_e32 v48, 0x24920, v160
	v_add_u32_e32 v80, 0x24d20, v160
	ds_read_b128 v[48:51], v48
	ds_read_b128 v[80:83], v80
	ds_read_b32 v84, v164
	ds_read_b32 v85, v165
	ds_read_b32 v86, v166
	ds_read_b32 v87, v167
	s_waitcnt lgkmcnt(3)
	v_fma_f32 v53, -v49, v84, v53
	v_fma_f32 v52, -v48, v84, v52
	s_waitcnt lgkmcnt(1)
	v_fma_f32 v36, -v48, v86, v36
	s_waitcnt lgkmcnt(0)
	v_fma_f32 v36, v87, v36, v80
	v_fma_f32 v37, -v49, v86, v37
	v_mul_f32_e32 v36, 0xbfb8aa3b, v36
	v_fma_f32 v37, v87, v37, v81
	v_exp_f32_e32 v36, v36
	v_mul_f32_e32 v37, 0xbfb8aa3b, v37
	v_exp_f32_e32 v37, v37
	v_fma_f32 v54, -v50, v84, v54
	v_add_f32_e32 v36, 1.0, v36
	v_rcp_f32_e32 v49, v36
	v_add_f32_e32 v36, 1.0, v37
	v_fma_f32 v37, -v50, v86, v38
	v_fma_f32 v55, -v51, v84, v55
	v_fma_f32 v37, v87, v37, v82
	v_fma_f32 v38, -v51, v86, v39
	v_fma_f32 v52, v85, v52, v80
	v_fma_f32 v53, v85, v53, v81
	v_fma_f32 v54, v85, v54, v82
	v_fma_f32 v55, v85, v55, v83
	v_mul_f32_e32 v37, 0xbfb8aa3b, v37
	v_fmac_f32_e32 v83, v87, v38
	v_mul_f32_e32 v52, 0xbfb8aa3b, v52
	v_mul_f32_e32 v53, 0xbfb8aa3b, v53
	v_mul_f32_e32 v54, 0xbfb8aa3b, v54
	v_mul_f32_e32 v55, 0xbfb8aa3b, v55
	v_exp_f32_e32 v37, v37
	v_mul_f32_e32 v38, 0xbfb8aa3b, v83
	v_exp_f32_e32 v52, v52
	v_exp_f32_e32 v53, v53
	v_exp_f32_e32 v54, v54
	v_exp_f32_e32 v55, v55
	v_exp_f32_e32 v38, v38
	v_rcp_f32_e32 v39, v36
	v_add_f32_e32 v36, 1.0, v37
	v_add_f32_e32 v52, 1.0, v52
	v_add_f32_e32 v53, 1.0, v53
	v_add_f32_e32 v54, 1.0, v54
	v_add_f32_e32 v55, 1.0, v55
	v_rcp_f32_e32 v37, v36
	v_add_f32_e32 v36, 1.0, v38
	v_rcp_f32_e32 v52, v52
	v_rcp_f32_e32 v53, v53
	v_rcp_f32_e32 v54, v54
	v_rcp_f32_e32 v48, v55
	v_rcp_f32_e32 v38, v36
	v_cvt_pk_bf16_f32 v80, v52, v53
	v_cvt_pk_bf16_f32 v55, v49, v39
	v_cvt_pk_bf16_f32 v36, v54, v48
	v_cvt_pk_bf16_f32 v53, v37, v38
	v_add_u32_e32 v37, 0x24940, v160
	v_add_u32_e32 v38, 0x24d40, v160
	ds_read_b128 v[48:51], v37
	ds_read_b128 v[82:85], v38
	ds_read_b32 v37, v164
	ds_read_b32 v38, v165
	ds_read_b32 v39, v166
	ds_read_b32 v52, v167
	s_waitcnt lgkmcnt(3)
	v_fma_f32 v54, -v48, v37, v56
	v_fma_f32 v56, -v49, v37, v57
	s_waitcnt lgkmcnt(2)
	v_fma_f32 v56, v38, v56, v83
	v_fma_f32 v57, -v50, v37, v58
	v_fma_f32 v37, -v51, v37, v59
	s_waitcnt lgkmcnt(1)
	v_fma_f32 v40, -v48, v39, v40
	v_fma_f32 v41, -v49, v39, v41
	v_fma_f32 v42, -v50, v39, v42
	v_fma_f32 v39, -v51, v39, v43
	v_fma_f32 v54, v38, v54, v82
	v_mul_f32_e32 v56, 0xbfb8aa3b, v56
	v_fma_f32 v57, v38, v57, v84
	v_fma_f32 v37, v38, v37, v85
	s_waitcnt lgkmcnt(0)
	v_fma_f32 v40, v52, v40, v82
	v_fma_f32 v41, v52, v41, v83
	v_fma_f32 v42, v52, v42, v84
	v_fmac_f32_e32 v85, v52, v39
	v_mul_f32_e32 v54, 0xbfb8aa3b, v54
	v_exp_f32_e32 v56, v56
	v_mul_f32_e32 v57, 0xbfb8aa3b, v57
	v_mul_f32_e32 v37, 0xbfb8aa3b, v37
	v_mul_f32_e32 v40, 0xbfb8aa3b, v40
	v_mul_f32_e32 v41, 0xbfb8aa3b, v41
	v_mul_f32_e32 v42, 0xbfb8aa3b, v42
	v_mul_f32_e32 v39, 0xbfb8aa3b, v85
	v_exp_f32_e32 v54, v54
	v_exp_f32_e32 v57, v57
	v_exp_f32_e32 v37, v37
	v_exp_f32_e32 v40, v40
	v_exp_f32_e32 v41, v41
	v_exp_f32_e32 v42, v42
	v_exp_f32_e32 v39, v39
	v_add_f32_e32 v56, 1.0, v56
	v_add_f32_e32 v54, 1.0, v54
	v_rcp_f32_e32 v38, v56
	v_add_f32_e32 v56, 1.0, v57
	v_add_f32_e32 v37, 1.0, v37
	v_add_f32_e32 v40, 1.0, v40
	v_add_f32_e32 v41, 1.0, v41
	v_add_f32_e32 v42, 1.0, v42
	v_add_f32_e32 v39, 1.0, v39
	v_rcp_f32_e32 v54, v54
	v_rcp_f32_e32 v56, v56
	v_rcp_f32_e32 v37, v37
	v_rcp_f32_e32 v40, v40
	v_rcp_f32_e32 v41, v41
	v_rcp_f32_e32 v42, v42
	v_rcp_f32_e32 v39, v39
	v_cvt_pk_bf16_f32 v83, v54, v38
	v_cvt_pk_bf16_f32 v82, v56, v37
	v_cvt_pk_bf16_f32 v81, v40, v41
	v_cvt_pk_bf16_f32 v59, v42, v39
	v_add_u32_e32 v37, 0x24960, v160
	v_add_u32_e32 v42, 0x24d60, v160
	ds_read_b128 v[38:41], v37
	ds_read_b128 v[48:51], v42
	ds_read_b32 v37, v164
	ds_read_b32 v42, v165
	ds_read_b32 v43, v166
	ds_read_b32 v52, v167
	s_waitcnt lgkmcnt(3)
	v_fma_f32 v56, -v39, v37, v61
	v_fma_f32 v54, -v38, v37, v60
	s_waitcnt lgkmcnt(2)
	v_fma_f32 v56, v42, v56, v49
	v_fma_f32 v57, -v40, v37, v62
	v_fma_f32 v37, -v41, v37, v63
	s_waitcnt lgkmcnt(1)
	v_fma_f32 v38, -v38, v43, v44
	v_fma_f32 v39, -v39, v43, v45
	v_fma_f32 v40, -v40, v43, v46
	v_fma_f32 v41, -v41, v43, v47
	v_fma_f32 v54, v42, v54, v48
	v_mul_f32_e32 v56, 0xbfb8aa3b, v56
	v_fma_f32 v57, v42, v57, v50
	v_fma_f32 v37, v42, v37, v51
	s_waitcnt lgkmcnt(0)
; DI unsigned pack2(float a, float b) { f32x2_t v = {a, b}; bf16x2_t r = __builtin_convertvector(v, bf16x2_t); return __builtin_bit_cast(unsigned, r); }
; DI float sigmoidf_(float x) { return __builtin_amdgcn_rcpf(1.f + __expf(-x)); }
; template <bool LAST>
; DI void phase_gate(const Params& P, int layer, unsigned char* smem, int L, int G) {
;     ...
;     unsigned gq[4][2][8];
; #pragma unroll
;     for (int i = 0; i < 4; ++i)
; #pragma unroll
;       for (int q4 = 0; q4 < 4; ++q4) {
;         const int fl = wm * 128 + i * 32 + 8 * q4 + 4 * h;
;         const f32x4 c1v = *(const f32x4*)(vecL + fl), c2v = *(const f32x4*)(vecL + 256 + fl);
;         const float c1a[4] = {c1v.x, c1v.y, c1v.z, c1v.w}, c2a[4] = {c2v.x, c2v.y, c2v.z, c2v.w};
; #pragma unroll
;         for (int j = 0; j < 2; ++j) {
;           const int lrow = wn * 64 + j * 32 + r;
;           const float mu = rowA[lrow], rstd = rowB[lrow];
;           float sg4[4];
; #pragma unroll
;           for (int e = 0; e < 4; ++e) sg4[e] = sigmoidf_(rstd * (accu[i][j][4 * q4 + e] - mu * c1a[e]) + c2a[e]);
;           gq[i][j][2 * q4] = pack2(sg4[0], sg4[1]); gq[i][j][2 * q4 + 1] = pack2(sg4[2], sg4[3]);
;         }
;         __builtin_amdgcn_sched_barrier(0);
;       }
	v_fma_f32 v38, v52, v38, v48
	v_fma_f32 v39, v52, v39, v49
	v_fma_f32 v40, v52, v40, v50
	v_fmac_f32_e32 v51, v52, v41
	v_mul_f32_e32 v54, 0xbfb8aa3b, v54
	v_exp_f32_e32 v56, v56
	v_mul_f32_e32 v57, 0xbfb8aa3b, v57
	v_mul_f32_e32 v37, 0xbfb8aa3b, v37
	v_mul_f32_e32 v38, 0xbfb8aa3b, v38
	v_mul_f32_e32 v39, 0xbfb8aa3b, v39
	v_mul_f32_e32 v40, 0xbfb8aa3b, v40
	v_mul_f32_e32 v41, 0xbfb8aa3b, v51
	v_exp_f32_e32 v54, v54
	v_exp_f32_e32 v57, v57
	v_exp_f32_e32 v37, v37
	v_exp_f32_e32 v38, v38
	v_exp_f32_e32 v39, v39
	v_exp_f32_e32 v40, v40
	v_exp_f32_e32 v41, v41
	v_add_f32_e32 v56, 1.0, v56
	v_add_f32_e32 v54, 1.0, v54
	v_rcp_f32_e32 v42, v56
	v_add_f32_e32 v56, 1.0, v57
	v_add_f32_e32 v37, 1.0, v37
	v_add_f32_e32 v38, 1.0, v38
	v_add_f32_e32 v39, 1.0, v39
	v_add_f32_e32 v40, 1.0, v40
	v_add_f32_e32 v41, 1.0, v41
	v_rcp_f32_e32 v54, v54
	v_rcp_f32_e32 v56, v56
	v_rcp_f32_e32 v37, v37
	v_rcp_f32_e32 v38, v38
	v_rcp_f32_e32 v39, v39
	v_rcp_f32_e32 v40, v40
	v_rcp_f32_e32 v41, v41
	v_cvt_pk_bf16_f32 v91, v54, v42
	v_cvt_pk_bf16_f32 v86, v56, v37
	v_cvt_pk_bf16_f32 v85, v38, v39
	v_cvt_pk_bf16_f32 v84, v40, v41
	v_add_u32_e32 v37, 0x24980, v160
	v_add_u32_e32 v42, 0x24d80, v160
	ds_read_b128 v[38:41], v37
	ds_read_b128 v[42:45], v42
	ds_read_b32 v37, v164
	ds_read_b32 v46, v165
	ds_read_b32 v47, v166
	ds_read_b32 v48, v167
	s_waitcnt lgkmcnt(3)
	v_fma_f32 v16, -v38, v37, v16
	v_fma_f32 v17, -v39, v37, v17
	v_fma_f32 v18, -v40, v37, v18
	v_fma_f32 v19, -v41, v37, v19
	s_waitcnt lgkmcnt(1)
	v_fma_f32 v0, -v38, v47, v0
	v_fma_f32 v1, -v39, v47, v1
	v_fma_f32 v2, -v40, v47, v2
	v_fma_f32 v3, -v41, v47, v3
	v_fma_f32 v16, v46, v16, v42
	v_fma_f32 v17, v46, v17, v43
	v_fma_f32 v18, v46, v18, v44
	v_fma_f32 v19, v46, v19, v45
	s_waitcnt lgkmcnt(0)
	v_fma_f32 v0, v48, v0, v42
	v_fma_f32 v1, v48, v1, v43
	v_fma_f32 v2, v48, v2, v44
	v_fmac_f32_e32 v45, v48, v3
	v_mul_f32_e32 v16, 0xbfb8aa3b, v16
	v_mul_f32_e32 v17, 0xbfb8aa3b, v17
	v_mul_f32_e32 v18, 0xbfb8aa3b, v18
	v_mul_f32_e32 v19, 0xbfb8aa3b, v19
	v_mul_f32_e32 v0, 0xbfb8aa3b, v0
	v_mul_f32_e32 v1, 0xbfb8aa3b, v1
	v_mul_f32_e32 v2, 0xbfb8aa3b, v2
	v_mul_f32_e32 v3, 0xbfb8aa3b, v45
	v_exp_f32_e32 v16, v16
	v_exp_f32_e32 v17, v17
	v_exp_f32_e32 v18, v18
	v_exp_f32_e32 v19, v19
	v_exp_f32_e32 v0, v0
	v_exp_f32_e32 v1, v1
	v_exp_f32_e32 v2, v2
	v_exp_f32_e32 v3, v3
	v_add_f32_e32 v16, 1.0, v16
	v_add_f32_e32 v17, 1.0, v17
	v_add_f32_e32 v18, 1.0, v18
	v_add_f32_e32 v19, 1.0, v19
	v_add_f32_e32 v0, 1.0, v0
	v_add_f32_e32 v1, 1.0, v1
	v_add_f32_e32 v2, 1.0, v2
	v_add_f32_e32 v3, 1.0, v3
	v_rcp_f32_e32 v16, v16
	v_rcp_f32_e32 v17, v17
	v_rcp_f32_e32 v18, v18
	v_rcp_f32_e32 v19, v19
	v_rcp_f32_e32 v0, v0
	v_rcp_f32_e32 v1, v1
	v_rcp_f32_e32 v2, v2
	v_rcp_f32_e32 v37, v3
	v_cvt_pk_bf16_f32 v17, v16, v17
	v_cvt_pk_bf16_f32 v16, v18, v19
	v_cvt_pk_bf16_f32 v3, v0, v1
	v_cvt_pk_bf16_f32 v2, v2, v37
	v_add_u32_e32 v0, 0x249a0, v160
	v_add_u32_e32 v1, 0x24da0, v160
	ds_read_b128 v[38:41], v0
	ds_read_b128 v[42:45], v1
	ds_read_b32 v0, v164
	ds_read_b32 v1, v165
	ds_read_b32 v18, v166
	ds_read_b32 v19, v167
	s_waitcnt lgkmcnt(3)
	v_fma_f32 v21, -v39, v0, v21
	v_fma_f32 v20, -v38, v0, v20
	s_waitcnt lgkmcnt(1)
	v_fma_f32 v6, -v40, v18, v6
	v_fma_f32 v21, v1, v21, v43
	v_fma_f32 v22, -v40, v0, v22
	v_fma_f32 v0, -v41, v0, v23
	v_fma_f32 v4, -v38, v18, v4
	v_fma_f32 v5, -v39, v18, v5
	s_waitcnt lgkmcnt(0)
	v_fma_f32 v6, v19, v6, v44
	v_fma_f32 v7, -v41, v18, v7
	v_fma_f32 v20, v1, v20, v42
	v_mul_f32_e32 v21, 0xbfb8aa3b, v21
	v_fma_f32 v22, v1, v22, v44
	v_fma_f32 v0, v1, v0, v45
	v_fma_f32 v4, v19, v4, v42
	v_fma_f32 v5, v19, v5, v43
	v_mul_f32_e32 v6, 0xbfb8aa3b, v6
	v_fmac_f32_e32 v45, v19, v7
	v_mul_f32_e32 v20, 0xbfb8aa3b, v20
	v_exp_f32_e32 v21, v21
	v_mul_f32_e32 v22, 0xbfb8aa3b, v22
	v_mul_f32_e32 v0, 0xbfb8aa3b, v0
	v_mul_f32_e32 v4, 0xbfb8aa3b, v4
	v_mul_f32_e32 v5, 0xbfb8aa3b, v5
	v_exp_f32_e32 v6, v6
	v_mul_f32_e32 v7, 0xbfb8aa3b, v45
	v_exp_f32_e32 v20, v20
	v_exp_f32_e32 v22, v22
	v_exp_f32_e32 v0, v0
	v_exp_f32_e32 v4, v4
	v_exp_f32_e32 v5, v5
	v_exp_f32_e32 v7, v7
	v_add_f32_e32 v21, 1.0, v21
	v_add_f32_e32 v6, 1.0, v6
	v_add_f32_e32 v20, 1.0, v20
	v_rcp_f32_e32 v1, v21
	v_add_f32_e32 v21, 1.0, v22
	v_add_f32_e32 v0, 1.0, v0
	v_add_f32_e32 v4, 1.0, v4
	v_add_f32_e32 v5, 1.0, v5
	v_rcp_f32_e32 v18, v6
	v_add_f32_e32 v6, 1.0, v7
	v_rcp_f32_e32 v20, v20
	v_rcp_f32_e32 v21, v21
	v_rcp_f32_e32 v0, v0
	v_rcp_f32_e32 v4, v4
	v_rcp_f32_e32 v5, v5
	v_rcp_f32_e32 v19, v6
	v_cvt_pk_bf16_f32 v7, v20, v1
	v_cvt_pk_bf16_f32 v6, v21, v0
	v_cvt_pk_bf16_f32 v5, v4, v5
	v_cvt_pk_bf16_f32 v4, v18, v19
	v_add_u32_e32 v0, 0x249c0, v160
	v_add_u32_e32 v1, 0x24dc0, v160
	ds_read_b128 v[18:21], v0
	ds_read_b128 v[38:41], v1
	ds_read_b32 v0, v164
	ds_read_b32 v1, v165
	ds_read_b32 v22, v166
	ds_read_b32 v23, v167
	s_waitcnt lgkmcnt(3)
	v_fma_f32 v25, -v19, v0, v25
	v_fma_f32 v24, -v18, v0, v24
	s_waitcnt lgkmcnt(1)
	v_fma_f32 v9, -v19, v22, v9
	s_waitcnt lgkmcnt(0)
; DI unsigned pack2(float a, float b) { f32x2_t v = {a, b}; bf16x2_t r = __builtin_convertvector(v, bf16x2_t); return __builtin_bit_cast(unsigned, r); }
; DI float sigmoidf_(float x) { return __builtin_amdgcn_rcpf(1.f + __expf(-x)); }
; DI int otid() { int t = threadIdx.x; asm volatile("" : "+v"(t)); return t; }
; template <bool NT>
; DI void stage_load_tile(bf16_t* stg, const bf16_t* tilebase) {
;   const int tid = otid();
;   const int r0 = tid >> 5, c = tid & 31;
;   const unsigned o0 = (unsigned)(r0 * 1024 + c * 8);
;   __builtin_amdgcn_sched_barrier(0);
; #pragma unroll
;   for (int hf = 0; hf < 2; ++hf) {
; #pragma unroll
;     for (int it = 8 * hf; it < 8 * hf + 8; ++it) {
;       const u32x4* gp = (const u32x4*)(tilebase + (o0 + (unsigned)(it * 16 * 1024)));
;       stage_write16(stg, r0 + 16 * it, c, NT ? __builtin_nontemporal_load(gp) : *gp);
;     }
;     __builtin_amdgcn_sched_barrier(0);
;   }
; }
; template <bool LAST>
; DI void phase_gate(const Params& P, int layer, unsigned char* smem, int L, int G) {
;     ...
;     unsigned gq[4][2][8];
; #pragma unroll
;     for (int i = 0; i < 4; ++i)
; #pragma unroll
;       for (int q4 = 0; q4 < 4; ++q4) {
;         const int fl = wm * 128 + i * 32 + 8 * q4 + 4 * h;
;         const f32x4 c1v = *(const f32x4*)(vecL + fl), c2v = *(const f32x4*)(vecL + 256 + fl);
;         const float c1a[4] = {c1v.x, c1v.y, c1v.z, c1v.w}, c2a[4] = {c2v.x, c2v.y, c2v.z, c2v.w};
; #pragma unroll
;         for (int j = 0; j < 2; ++j) {
;           const int lrow = wn * 64 + j * 32 + r;
;           const float mu = rowA[lrow], rstd = rowB[lrow];
;           float sg4[4];
; #pragma unroll
;           for (int e = 0; e < 4; ++e) sg4[e] = sigmoidf_(rstd * (accu[i][j][4 * q4 + e] - mu * c1a[e]) + c2a[e]);
;           gq[i][j][2 * q4] = pack2(sg4[0], sg4[1]); gq[i][j][2 * q4 + 1] = pack2(sg4[2], sg4[3]);
;         }
;         __builtin_amdgcn_sched_barrier(0);
;       }
;     stage_load_tile<true>(stg, PPb + (size_t)mt * 256 * 1024 + nt * 256);
;     __syncthreads();
	v_fma_f32 v9, v23, v9, v39
	v_fma_f32 v10, -v20, v22, v10
	v_fma_f32 v25, v1, v25, v39
	v_fma_f32 v26, -v20, v0, v26
	v_fma_f32 v0, -v21, v0, v27
	v_fma_f32 v8, -v18, v22, v8
	v_mul_f32_e32 v9, 0xbfb8aa3b, v9
	v_fma_f32 v10, v23, v10, v40
	v_fma_f32 v11, -v21, v22, v11
	v_fma_f32 v24, v1, v24, v38
	v_mul_f32_e32 v25, 0xbfb8aa3b, v25
	v_fma_f32 v26, v1, v26, v40
	v_fma_f32 v0, v1, v0, v41
	v_fma_f32 v8, v23, v8, v38
	v_exp_f32_e32 v9, v9
	v_mul_f32_e32 v10, 0xbfb8aa3b, v10
	v_fmac_f32_e32 v41, v23, v11
	v_mul_f32_e32 v24, 0xbfb8aa3b, v24
	v_exp_f32_e32 v25, v25
	v_mul_f32_e32 v26, 0xbfb8aa3b, v26
	v_mul_f32_e32 v0, 0xbfb8aa3b, v0
	v_mul_f32_e32 v8, 0xbfb8aa3b, v8
	v_exp_f32_e32 v10, v10
	v_mul_f32_e32 v11, 0xbfb8aa3b, v41
	v_exp_f32_e32 v24, v24
	v_exp_f32_e32 v26, v26
	v_exp_f32_e32 v0, v0
	v_exp_f32_e32 v8, v8
	v_exp_f32_e32 v11, v11
	v_add_f32_e32 v9, 1.0, v9
	v_add_f32_e32 v25, 1.0, v25
	v_rcp_f32_e32 v18, v9
	v_add_f32_e32 v9, 1.0, v10
	v_add_f32_e32 v24, 1.0, v24
	v_rcp_f32_e32 v1, v25
	v_add_f32_e32 v25, 1.0, v26
	v_add_f32_e32 v0, 1.0, v0
	v_add_f32_e32 v8, 1.0, v8
	v_rcp_f32_e32 v10, v9
	v_add_f32_e32 v9, 1.0, v11
	v_rcp_f32_e32 v24, v24
	v_rcp_f32_e32 v25, v25
	v_rcp_f32_e32 v0, v0
	v_rcp_f32_e32 v8, v8
	v_rcp_f32_e32 v11, v9
	v_cvt_pk_bf16_f32 v27, v24, v1
	v_cvt_pk_bf16_f32 v9, v25, v0
	v_cvt_pk_bf16_f32 v19, v8, v18
	v_cvt_pk_bf16_f32 v8, v10, v11
	v_add_u32_e32 v0, 0x24de0, v160
	ds_read_b128 v[20:23], v163 offset:480
	ds_read_b32 v1, v164
	ds_read_b128 v[38:41], v0
	ds_read_b32 v0, v165
	ds_read_b32 v10, v166
	ds_read_b32 v18, v167
	s_waitcnt lgkmcnt(4)
	v_fma_f32 v24, -v21, v1, v29
	v_fma_f32 v11, -v20, v1, v28
	s_waitcnt lgkmcnt(2)
	v_fma_f32 v24, v0, v24, v39
	v_fma_f32 v25, -v22, v1, v30
	v_fma_f32 v1, -v23, v1, v31
	s_waitcnt lgkmcnt(1)
	v_fma_f32 v12, -v20, v10, v12
	v_fma_f32 v13, -v21, v10, v13
	v_fma_f32 v14, -v22, v10, v14
	v_fma_f32 v10, -v23, v10, v15
	v_fma_f32 v11, v0, v11, v38
	v_mul_f32_e32 v24, 0xbfb8aa3b, v24
	v_fma_f32 v25, v0, v25, v40
	v_fma_f32 v0, v0, v1, v41
	s_waitcnt lgkmcnt(0)
	v_fma_f32 v12, v18, v12, v38
	v_fma_f32 v13, v18, v13, v39
	v_fma_f32 v14, v18, v14, v40
	v_fmac_f32_e32 v41, v18, v10
	v_mul_f32_e32 v11, 0xbfb8aa3b, v11
	v_exp_f32_e32 v24, v24
	v_mul_f32_e32 v25, 0xbfb8aa3b, v25
	v_mul_f32_e32 v0, 0xbfb8aa3b, v0
	v_mul_f32_e32 v12, 0xbfb8aa3b, v12
	v_mul_f32_e32 v13, 0xbfb8aa3b, v13
	v_mul_f32_e32 v14, 0xbfb8aa3b, v14
	v_mul_f32_e32 v10, 0xbfb8aa3b, v41
	v_exp_f32_e32 v11, v11
	v_exp_f32_e32 v25, v25
	v_exp_f32_e32 v0, v0
	v_exp_f32_e32 v12, v12
	v_exp_f32_e32 v13, v13
	v_exp_f32_e32 v14, v14
	v_exp_f32_e32 v10, v10
	v_add_f32_e32 v24, 1.0, v24
	v_add_f32_e32 v11, 1.0, v11
	v_rcp_f32_e32 v1, v24
	v_add_f32_e32 v24, 1.0, v25
	v_add_f32_e32 v0, 1.0, v0
	v_add_f32_e32 v12, 1.0, v12
	v_add_f32_e32 v13, 1.0, v13
	v_add_f32_e32 v14, 1.0, v14
	v_add_f32_e32 v10, 1.0, v10
	v_rcp_f32_e32 v11, v11
	v_rcp_f32_e32 v24, v24
	v_rcp_f32_e32 v0, v0
	v_rcp_f32_e32 v12, v12
	v_rcp_f32_e32 v13, v13
	v_rcp_f32_e32 v14, v14
	v_rcp_f32_e32 v10, v10
	v_cvt_pk_bf16_f32 v112, v11, v1
	v_cvt_pk_bf16_f32 v30, v24, v0
	v_cvt_pk_bf16_f32 v29, v12, v13
	v_cvt_pk_bf16_f32 v28, v14, v10
	v_mov_b32_e32 v163, v161
	v_lshlrev_b64 v[0:1], 1, v[162:163]
	v_and_b32_e32 v26, 31, v192
	v_ashrrev_i32_e32 v18, 5, v192
	v_mul_lo_u32 v18, v18, s44
	v_lshl_add_u32 v18, v26, 4, v18
	v_add_u32_e32 v24, 0x2080, v18
	v_add_u32_e32 v25, 0x4100, v18
	v_add_u32_e32 v26, 0x6180, v18
	v_add_u32_e32 v31, 0x8200, v18
	v_add_u32_e32 v37, 0xa280, v18
	v_add_u32_e32 v50, 0xc300, v18
	v_add_u32_e32 v51, 0xe380, v18
	s_waitcnt vmcnt(15)
	ds_write2_b64 v18, v[180:181], v[182:183] offset1:1
	s_waitcnt vmcnt(14)
	ds_write2_b64 v24, v[184:185], v[186:187] offset1:1
	s_waitcnt vmcnt(13)
	ds_write2_b64 v25, v[194:195], v[196:197] offset1:1
	s_waitcnt vmcnt(12)
	ds_write2_b64 v26, v[198:199], v[200:201] offset1:1
	s_waitcnt vmcnt(11)
	ds_write2_b64 v31, v[202:203], v[204:205] offset1:1
	s_waitcnt vmcnt(10)
	ds_write2_b64 v37, v[206:207], v[208:209] offset1:1
	s_waitcnt vmcnt(9)
	ds_write2_b64 v50, v[210:211], v[212:213] offset1:1
	s_waitcnt vmcnt(8)
	ds_write2_b64 v51, v[214:215], v[216:217] offset1:1
	v_add_u32_e32 v14, 0x10400, v18
	v_add_u32_e32 v15, 0x12480, v18
	v_add_u32_e32 v24, 0x14500, v18
	v_add_u32_e32 v25, 0x16580, v18
	v_add_u32_e32 v26, 0x18600, v18
	v_add_u32_e32 v31, 0x1a680, v18
	v_add_u32_e32 v37, 0x1c700, v18
	v_add_u32_e32 v18, 0x1e780, v18
	s_waitcnt vmcnt(7)
	ds_write2_b64 v14, v[218:219], v[220:221] offset1:1
	s_waitcnt vmcnt(6)
	ds_write2_b64 v15, v[222:223], v[224:225] offset1:1
	s_waitcnt vmcnt(5)
	ds_write2_b64 v24, v[226:227], v[228:229] offset1:1
	s_waitcnt vmcnt(4)
	ds_write2_b64 v25, v[230:231], v[232:233] offset1:1
	s_waitcnt vmcnt(3)
	ds_write2_b64 v26, v[234:235], v[236:237] offset1:1
	s_waitcnt vmcnt(2)
	ds_write2_b64 v31, v[238:239], v[240:241] offset1:1
	s_waitcnt vmcnt(1)
	ds_write2_b64 v37, v[242:243], v[244:245] offset1:1
	s_waitcnt vmcnt(0)
	ds_write2_b64 v18, v[248:249], v[250:251] offset1:1
	v_mov_b32_e32 v10, v192
	s_waitcnt lgkmcnt(0)
	s_barrier
; DI unsigned pack2(float a, float b) { f32x2_t v = {a, b}; bf16x2_t r = __builtin_convertvector(v, bf16x2_t); return __builtin_bit_cast(unsigned, r); }
; DI float bflo(unsigned u) { return __uint_as_float(u << 16); }
; DI float bfhi(unsigned u) { return __uint_as_float(u & 0xffff0000u); }
; DI int otid() { int t = threadIdx.x; asm volatile("" : "+v"(t)); return t; }
; template <bool LAST>
; DI void phase_gate(const Params& P, int layer, unsigned char* smem, int L, int G) {
;     ...
;     {
;       const int tid1 = otid();
;       const int lane1 = tid1 & 63, w1 = tid1 >> 6, r1 = lane1 & 31, h1 = lane1 >> 5, wm1 = w1 >> 2, wn1 = w1 & 3;
; #pragma unroll
;       for (int i = 0; i < 4; ++i)
; #pragma unroll
;         for (int q4 = 0; q4 < 4; ++q4) {
; #pragma unroll
;           for (int j = 0; j < 2; ++j) {
;             const uint2 pv = *(const uint2*)(stg + (wn1 * 64 + j * 32 + r1) * STG + wm1 * 128 + i * 32 + 8 * q4 + 4 * h1);
;             const unsigned g0 = gq[i][j][2 * q4], g1 = gq[i][j][2 * q4 + 1];
;             gq[i][j][2 * q4] = pack2(bflo(g0) * bflo(pv.x), bfhi(g0) * bfhi(pv.x));
;             gq[i][j][2 * q4 + 1] = pack2(bflo(g1) * bflo(pv.y), bfhi(g1) * bfhi(pv.y));
;           }
;           __builtin_amdgcn_sched_barrier(0);
;         }
;     }
	v_and_b32_e32 v13, 0xffff0000, v99
	v_lshrrev_b32_e32 v12, 2, v10
	v_and_b32_e32 v12, 8, v12
	v_and_b32_e32 v11, 0xdf, v10
	v_and_or_b32 v10, v10, s42, v12
	v_mad_u32_u24 v113, v11, s44, v10
	ds_read_b64 v[10:11], v113
	ds_read_b64 v[14:15], v113 offset:16640
	v_lshlrev_b32_e32 v12, 16, v99
	s_waitcnt lgkmcnt(1)
	v_lshlrev_b32_e32 v20, 16, v10
	v_and_b32_e32 v21, 0xffff0000, v10
	v_pk_mul_f32 v[12:13], v[12:13], v[20:21]
	v_lshlrev_b32_e32 v10, 16, v11
	v_cvt_pk_bf16_f32 v31, v12, v13
	v_lshlrev_b32_e32 v12, 16, v98
	v_and_b32_e32 v13, 0xffff0000, v98
	v_and_b32_e32 v11, 0xffff0000, v11
	v_pk_mul_f32 v[10:11], v[12:13], v[10:11]
	s_waitcnt lgkmcnt(0)
	v_lshlrev_b32_e32 v12, 16, v14
	v_cvt_pk_bf16_f32 v98, v10, v11
	v_lshlrev_b32_e32 v10, 16, v97
	v_and_b32_e32 v11, 0xffff0000, v97
	v_and_b32_e32 v13, 0xffff0000, v14
	v_pk_mul_f32 v[10:11], v[10:11], v[12:13]
	v_lshlrev_b32_e32 v12, 16, v15
	v_cvt_pk_bf16_f32 v97, v10, v11
	v_lshlrev_b32_e32 v10, 16, v96
	v_and_b32_e32 v11, 0xffff0000, v96
	v_and_b32_e32 v13, 0xffff0000, v15
	v_pk_mul_f32 v[10:11], v[10:11], v[12:13]
	s_nop 0
	v_cvt_pk_bf16_f32 v96, v10, v11
	ds_read_b64 v[10:11], v113 offset:16
	ds_read_b64 v[14:15], v113 offset:16656
	v_lshlrev_b32_e32 v12, 16, v103
	v_and_b32_e32 v13, 0xffff0000, v103
	s_waitcnt lgkmcnt(1)
	v_lshlrev_b32_e32 v20, 16, v10
	v_and_b32_e32 v21, 0xffff0000, v10
	v_pk_mul_f32 v[12:13], v[12:13], v[20:21]
	v_lshlrev_b32_e32 v10, 16, v11
	v_cvt_pk_bf16_f32 v93, v12, v13
	v_lshlrev_b32_e32 v12, 16, v102
	v_and_b32_e32 v13, 0xffff0000, v102
	v_and_b32_e32 v11, 0xffff0000, v11
	v_pk_mul_f32 v[10:11], v[12:13], v[10:11]
	s_waitcnt lgkmcnt(0)
	v_lshlrev_b32_e32 v12, 16, v14
	v_cvt_pk_bf16_f32 v95, v10, v11
	v_lshlrev_b32_e32 v10, 16, v101
	v_and_b32_e32 v11, 0xffff0000, v101
	v_and_b32_e32 v13, 0xffff0000, v14
	v_pk_mul_f32 v[10:11], v[10:11], v[12:13]
	v_lshlrev_b32_e32 v12, 16, v15
	v_cvt_pk_bf16_f32 v92, v10, v11
	v_lshlrev_b32_e32 v10, 16, v100
	v_and_b32_e32 v11, 0xffff0000, v100
	v_and_b32_e32 v13, 0xffff0000, v15
	v_pk_mul_f32 v[10:11], v[10:11], v[12:13]
	s_nop 0
	v_cvt_pk_bf16_f32 v94, v10, v11
	ds_read_b64 v[10:11], v113 offset:32
	ds_read_b64 v[14:15], v113 offset:16672
	v_lshlrev_b32_e32 v12, 16, v107
	v_and_b32_e32 v13, 0xffff0000, v107
	s_waitcnt lgkmcnt(1)
	v_lshlrev_b32_e32 v20, 16, v10
	v_and_b32_e32 v21, 0xffff0000, v10
	v_pk_mul_f32 v[12:13], v[12:13], v[20:21]
	v_lshlrev_b32_e32 v10, 16, v11
	v_cvt_pk_bf16_f32 v88, v12, v13
	v_lshlrev_b32_e32 v12, 16, v106
	v_and_b32_e32 v13, 0xffff0000, v106
	v_and_b32_e32 v11, 0xffff0000, v11
	v_pk_mul_f32 v[10:11], v[12:13], v[10:11]
	s_waitcnt lgkmcnt(0)
	v_lshlrev_b32_e32 v12, 16, v14
	v_cvt_pk_bf16_f32 v90, v10, v11
	v_lshlrev_b32_e32 v10, 16, v105
	v_and_b32_e32 v11, 0xffff0000, v105
	v_and_b32_e32 v13, 0xffff0000, v14
	v_pk_mul_f32 v[10:11], v[10:11], v[12:13]
	v_lshlrev_b32_e32 v12, 16, v15
	v_cvt_pk_bf16_f32 v87, v10, v11
	v_lshlrev_b32_e32 v10, 16, v104
	v_and_b32_e32 v11, 0xffff0000, v104
	v_and_b32_e32 v13, 0xffff0000, v15
	v_pk_mul_f32 v[10:11], v[10:11], v[12:13]
	s_nop 0
	v_cvt_pk_bf16_f32 v89, v10, v11
	ds_read_b64 v[10:11], v113 offset:48
	ds_read_b64 v[14:15], v113 offset:16688
	v_lshlrev_b32_e32 v12, 16, v111
	v_and_b32_e32 v13, 0xffff0000, v111
	s_waitcnt lgkmcnt(1)
	v_lshlrev_b32_e32 v20, 16, v10
	v_and_b32_e32 v21, 0xffff0000, v10
	v_pk_mul_f32 v[12:13], v[12:13], v[20:21]
	v_lshlrev_b32_e32 v10, 16, v11
	v_cvt_pk_bf16_f32 v61, v12, v13
	v_lshlrev_b32_e32 v12, 16, v110
	v_and_b32_e32 v13, 0xffff0000, v110
	v_and_b32_e32 v11, 0xffff0000, v11
	v_pk_mul_f32 v[10:11], v[12:13], v[10:11]
	s_waitcnt lgkmcnt(0)
	v_lshlrev_b32_e32 v12, 16, v14
	v_cvt_pk_bf16_f32 v63, v10, v11
	v_lshlrev_b32_e32 v10, 16, v109
	v_and_b32_e32 v11, 0xffff0000, v109
	v_and_b32_e32 v13, 0xffff0000, v14
	v_pk_mul_f32 v[10:11], v[10:11], v[12:13]
	v_lshlrev_b32_e32 v12, 16, v15
	v_cvt_pk_bf16_f32 v60, v10, v11
	v_lshlrev_b32_e32 v10, 16, v108
	v_and_b32_e32 v11, 0xffff0000, v108
	v_and_b32_e32 v13, 0xffff0000, v15
	v_pk_mul_f32 v[10:11], v[10:11], v[12:13]
	s_nop 0
	v_cvt_pk_bf16_f32 v62, v10, v11
	ds_read_b64 v[10:11], v113 offset:64
	ds_read_b64 v[14:15], v113 offset:16704
	v_lshlrev_b32_e32 v12, 16, v67
	v_and_b32_e32 v13, 0xffff0000, v67
	s_waitcnt lgkmcnt(1)
	v_lshlrev_b32_e32 v20, 16, v10
	v_and_b32_e32 v21, 0xffff0000, v10
	v_pk_mul_f32 v[12:13], v[12:13], v[20:21]
	v_lshlrev_b32_e32 v10, 16, v11
	v_cvt_pk_bf16_f32 v56, v12, v13
	v_lshlrev_b32_e32 v12, 16, v66
	v_and_b32_e32 v13, 0xffff0000, v66
	v_and_b32_e32 v11, 0xffff0000, v11
	v_pk_mul_f32 v[10:11], v[12:13], v[10:11]
	s_waitcnt lgkmcnt(0)
	v_lshlrev_b32_e32 v12, 16, v14
	v_cvt_pk_bf16_f32 v58, v10, v11
	v_lshlrev_b32_e32 v10, 16, v65
	v_and_b32_e32 v11, 0xffff0000, v65
	v_and_b32_e32 v13, 0xffff0000, v14
	v_pk_mul_f32 v[10:11], v[10:11], v[12:13]
	v_lshlrev_b32_e32 v12, 16, v15
	v_cvt_pk_bf16_f32 v54, v10, v11
	v_lshlrev_b32_e32 v10, 16, v64
	v_and_b32_e32 v11, 0xffff0000, v64
	v_and_b32_e32 v13, 0xffff0000, v15
	v_pk_mul_f32 v[10:11], v[10:11], v[12:13]
	s_nop 0
	v_cvt_pk_bf16_f32 v57, v10, v11
	ds_read_b64 v[10:11], v113 offset:80
	ds_read_b64 v[14:15], v113 offset:16720
	v_lshlrev_b32_e32 v12, 16, v71
	v_and_b32_e32 v13, 0xffff0000, v71
	s_waitcnt lgkmcnt(1)
	v_lshlrev_b32_e32 v20, 16, v10
	v_and_b32_e32 v21, 0xffff0000, v10
	v_pk_mul_f32 v[12:13], v[12:13], v[20:21]
	v_lshlrev_b32_e32 v10, 16, v11
	v_cvt_pk_bf16_f32 v50, v12, v13
	v_lshlrev_b32_e32 v12, 16, v70
	v_and_b32_e32 v13, 0xffff0000, v70
	v_and_b32_e32 v11, 0xffff0000, v11
	v_pk_mul_f32 v[10:11], v[12:13], v[10:11]
	s_waitcnt lgkmcnt(0)
; DI unsigned pack2(float a, float b) { f32x2_t v = {a, b}; bf16x2_t r = __builtin_convertvector(v, bf16x2_t); return __builtin_bit_cast(unsigned, r); }
; DI float bflo(unsigned u) { return __uint_as_float(u << 16); }
; DI float bfhi(unsigned u) { return __uint_as_float(u & 0xffff0000u); }
; DI int otid() { int t = threadIdx.x; asm volatile("" : "+v"(t)); return t; }
; template <bool LAST>
; DI void phase_gate(const Params& P, int layer, unsigned char* smem, int L, int G) {
;     ...
;     {
;       const int tid1 = otid();
;       const int lane1 = tid1 & 63, w1 = tid1 >> 6, r1 = lane1 & 31, h1 = lane1 >> 5, wm1 = w1 >> 2, wn1 = w1 & 3;
; #pragma unroll
;       for (int i = 0; i < 4; ++i)
; #pragma unroll
;         for (int q4 = 0; q4 < 4; ++q4) {
; #pragma unroll
;           for (int j = 0; j < 2; ++j) {
;             const uint2 pv = *(const uint2*)(stg + (wn1 * 64 + j * 32 + r1) * STG + wm1 * 128 + i * 32 + 8 * q4 + 4 * h1);
;             const unsigned g0 = gq[i][j][2 * q4], g1 = gq[i][j][2 * q4 + 1];
;             gq[i][j][2 * q4] = pack2(bflo(g0) * bflo(pv.x), bfhi(g0) * bfhi(pv.x));
;             gq[i][j][2 * q4 + 1] = pack2(bflo(g1) * bflo(pv.y), bfhi(g1) * bfhi(pv.y));
;           }
;           __builtin_amdgcn_sched_barrier(0);
;         }
;     }
	v_lshlrev_b32_e32 v12, 16, v14
	v_cvt_pk_bf16_f32 v52, v10, v11
	v_lshlrev_b32_e32 v10, 16, v69
	v_and_b32_e32 v11, 0xffff0000, v69
	v_and_b32_e32 v13, 0xffff0000, v14
	v_pk_mul_f32 v[10:11], v[10:11], v[12:13]
	v_lshlrev_b32_e32 v12, 16, v15
	v_cvt_pk_bf16_f32 v49, v10, v11
	v_lshlrev_b32_e32 v10, 16, v68
	v_and_b32_e32 v11, 0xffff0000, v68
	v_and_b32_e32 v13, 0xffff0000, v15
	v_pk_mul_f32 v[10:11], v[10:11], v[12:13]
	s_nop 0
	v_cvt_pk_bf16_f32 v51, v10, v11
	ds_read_b64 v[10:11], v113 offset:96
	ds_read_b64 v[14:15], v113 offset:16736
	v_lshlrev_b32_e32 v12, 16, v75
	v_and_b32_e32 v13, 0xffff0000, v75
	s_waitcnt lgkmcnt(1)
	v_lshlrev_b32_e32 v20, 16, v10
	v_and_b32_e32 v21, 0xffff0000, v10
	v_pk_mul_f32 v[12:13], v[12:13], v[20:21]
	v_lshlrev_b32_e32 v10, 16, v11
	v_cvt_pk_bf16_f32 v46, v12, v13
	v_lshlrev_b32_e32 v12, 16, v74
	v_and_b32_e32 v13, 0xffff0000, v74
	v_and_b32_e32 v11, 0xffff0000, v11
	v_pk_mul_f32 v[10:11], v[12:13], v[10:11]
	s_waitcnt lgkmcnt(0)
	v_lshlrev_b32_e32 v12, 16, v14
	v_cvt_pk_bf16_f32 v48, v10, v11
	v_lshlrev_b32_e32 v10, 16, v73
	v_and_b32_e32 v11, 0xffff0000, v73
	v_and_b32_e32 v13, 0xffff0000, v14
	v_pk_mul_f32 v[10:11], v[10:11], v[12:13]
	v_lshlrev_b32_e32 v12, 16, v15
	v_cvt_pk_bf16_f32 v45, v10, v11
	v_lshlrev_b32_e32 v10, 16, v72
	v_and_b32_e32 v11, 0xffff0000, v72
	v_and_b32_e32 v13, 0xffff0000, v15
	v_pk_mul_f32 v[10:11], v[10:11], v[12:13]
	s_nop 0
	v_cvt_pk_bf16_f32 v47, v10, v11
	ds_read_b64 v[10:11], v113 offset:112
	ds_read_b64 v[14:15], v113 offset:16752
	v_lshlrev_b32_e32 v12, 16, v79
	v_and_b32_e32 v13, 0xffff0000, v79
	s_waitcnt lgkmcnt(1)
	v_lshlrev_b32_e32 v20, 16, v10
	v_and_b32_e32 v21, 0xffff0000, v10
	v_pk_mul_f32 v[12:13], v[12:13], v[20:21]
	v_lshlrev_b32_e32 v10, 16, v11
	v_cvt_pk_bf16_f32 v42, v12, v13
	v_lshlrev_b32_e32 v12, 16, v78
	v_and_b32_e32 v13, 0xffff0000, v78
	v_and_b32_e32 v11, 0xffff0000, v11
	v_pk_mul_f32 v[10:11], v[12:13], v[10:11]
	s_waitcnt lgkmcnt(0)
	v_lshlrev_b32_e32 v12, 16, v14
	v_cvt_pk_bf16_f32 v44, v10, v11
	v_lshlrev_b32_e32 v10, 16, v77
	v_and_b32_e32 v11, 0xffff0000, v77
	v_and_b32_e32 v13, 0xffff0000, v14
	v_pk_mul_f32 v[10:11], v[10:11], v[12:13]
	v_lshlrev_b32_e32 v12, 16, v15
	v_cvt_pk_bf16_f32 v41, v10, v11
	v_lshlrev_b32_e32 v10, 16, v76
	v_and_b32_e32 v11, 0xffff0000, v76
	v_and_b32_e32 v13, 0xffff0000, v15
	v_pk_mul_f32 v[10:11], v[10:11], v[12:13]
	s_nop 0
	v_cvt_pk_bf16_f32 v43, v10, v11
	ds_read_b64 v[10:11], v113 offset:128
	ds_read_b64 v[14:15], v113 offset:16768
	v_lshlrev_b32_e32 v12, 16, v35
	v_and_b32_e32 v13, 0xffff0000, v35
	s_waitcnt lgkmcnt(1)
	v_lshlrev_b32_e32 v20, 16, v10
	v_and_b32_e32 v21, 0xffff0000, v10
	v_pk_mul_f32 v[12:13], v[12:13], v[20:21]
	v_lshlrev_b32_e32 v10, 16, v11
	v_cvt_pk_bf16_f32 v38, v12, v13
	v_lshlrev_b32_e32 v12, 16, v34
	v_and_b32_e32 v13, 0xffff0000, v34
	v_and_b32_e32 v11, 0xffff0000, v11
	v_pk_mul_f32 v[10:11], v[12:13], v[10:11]
	s_waitcnt lgkmcnt(0)
	v_lshlrev_b32_e32 v12, 16, v14
	v_cvt_pk_bf16_f32 v40, v10, v11
	v_lshlrev_b32_e32 v10, 16, v33
	v_and_b32_e32 v11, 0xffff0000, v33
	v_and_b32_e32 v13, 0xffff0000, v14
	v_pk_mul_f32 v[10:11], v[10:11], v[12:13]
	v_lshlrev_b32_e32 v12, 16, v15
	v_cvt_pk_bf16_f32 v37, v10, v11
	v_lshlrev_b32_e32 v10, 16, v32
	v_and_b32_e32 v11, 0xffff0000, v32
	v_and_b32_e32 v13, 0xffff0000, v15
	v_pk_mul_f32 v[10:11], v[10:11], v[12:13]
	s_nop 0
	v_cvt_pk_bf16_f32 v39, v10, v11
	ds_read_b64 v[10:11], v113 offset:144
	ds_read_b64 v[14:15], v113 offset:16784
	v_lshlrev_b32_e32 v12, 16, v80
	v_and_b32_e32 v13, 0xffff0000, v80
	s_waitcnt lgkmcnt(1)
	v_lshlrev_b32_e32 v20, 16, v10
	v_and_b32_e32 v21, 0xffff0000, v10
	v_pk_mul_f32 v[12:13], v[12:13], v[20:21]
	v_lshlrev_b32_e32 v10, 16, v11
	v_cvt_pk_bf16_f32 v34, v12, v13
	v_lshlrev_b32_e32 v12, 16, v36
	v_and_b32_e32 v13, 0xffff0000, v36
	v_and_b32_e32 v11, 0xffff0000, v11
	v_pk_mul_f32 v[10:11], v[12:13], v[10:11]
	s_waitcnt lgkmcnt(0)
	v_lshlrev_b32_e32 v12, 16, v14
	v_cvt_pk_bf16_f32 v36, v10, v11
	v_lshlrev_b32_e32 v10, 16, v55
	v_and_b32_e32 v11, 0xffff0000, v55
	v_and_b32_e32 v13, 0xffff0000, v14
	v_pk_mul_f32 v[10:11], v[10:11], v[12:13]
	v_lshlrev_b32_e32 v12, 16, v15
	v_cvt_pk_bf16_f32 v32, v10, v11
	v_lshlrev_b32_e32 v10, 16, v53
	v_and_b32_e32 v11, 0xffff0000, v53
	v_and_b32_e32 v13, 0xffff0000, v15
	v_pk_mul_f32 v[10:11], v[10:11], v[12:13]
	s_nop 0
	v_cvt_pk_bf16_f32 v35, v10, v11
	ds_read_b64 v[10:11], v113 offset:160
	ds_read_b64 v[14:15], v113 offset:16800
	v_lshlrev_b32_e32 v12, 16, v83
	v_and_b32_e32 v13, 0xffff0000, v83
	s_waitcnt lgkmcnt(1)
	v_lshlrev_b32_e32 v20, 16, v10
	v_and_b32_e32 v21, 0xffff0000, v10
	v_pk_mul_f32 v[12:13], v[12:13], v[20:21]
	v_lshlrev_b32_e32 v10, 16, v11
	v_cvt_pk_bf16_f32 v24, v12, v13
	v_lshlrev_b32_e32 v12, 16, v82
	v_and_b32_e32 v13, 0xffff0000, v82
	v_and_b32_e32 v11, 0xffff0000, v11
	v_pk_mul_f32 v[10:11], v[12:13], v[10:11]
	s_waitcnt lgkmcnt(0)
	v_lshlrev_b32_e32 v12, 16, v14
	v_cvt_pk_bf16_f32 v26, v10, v11
	v_lshlrev_b32_e32 v10, 16, v81
	v_and_b32_e32 v11, 0xffff0000, v81
	v_and_b32_e32 v13, 0xffff0000, v14
	v_pk_mul_f32 v[10:11], v[10:11], v[12:13]
	v_lshlrev_b32_e32 v12, 16, v15
	v_cvt_pk_bf16_f32 v23, v10, v11
	v_lshlrev_b32_e32 v10, 16, v59
	v_and_b32_e32 v11, 0xffff0000, v59
	v_and_b32_e32 v13, 0xffff0000, v15
	v_pk_mul_f32 v[10:11], v[10:11], v[12:13]
	s_nop 0
	v_cvt_pk_bf16_f32 v25, v10, v11
	ds_read_b64 v[10:11], v113 offset:176
	ds_read_b64 v[14:15], v113 offset:16816
	v_lshlrev_b32_e32 v12, 16, v91
	v_and_b32_e32 v13, 0xffff0000, v91
	s_waitcnt lgkmcnt(1)
; DI unsigned pack2(float a, float b) { f32x2_t v = {a, b}; bf16x2_t r = __builtin_convertvector(v, bf16x2_t); return __builtin_bit_cast(unsigned, r); }
; DI float bflo(unsigned u) { return __uint_as_float(u << 16); }
; DI float bfhi(unsigned u) { return __uint_as_float(u & 0xffff0000u); }
; DI int otid() { int t = threadIdx.x; asm volatile("" : "+v"(t)); return t; }
; template <bool LAST>
; DI void phase_gate(const Params& P, int layer, unsigned char* smem, int L, int G) {
;     ...
;     {
;       const int tid1 = otid();
;       const int lane1 = tid1 & 63, w1 = tid1 >> 6, r1 = lane1 & 31, h1 = lane1 >> 5, wm1 = w1 >> 2, wn1 = w1 & 3;
; #pragma unroll
;       for (int i = 0; i < 4; ++i)
; #pragma unroll
;         for (int q4 = 0; q4 < 4; ++q4) {
; #pragma unroll
;           for (int j = 0; j < 2; ++j) {
;             const uint2 pv = *(const uint2*)(stg + (wn1 * 64 + j * 32 + r1) * STG + wm1 * 128 + i * 32 + 8 * q4 + 4 * h1);
;             const unsigned g0 = gq[i][j][2 * q4], g1 = gq[i][j][2 * q4 + 1];
;             gq[i][j][2 * q4] = pack2(bflo(g0) * bflo(pv.x), bfhi(g0) * bfhi(pv.x));
;             gq[i][j][2 * q4 + 1] = pack2(bflo(g1) * bflo(pv.y), bfhi(g1) * bfhi(pv.y));
;           }
;           __builtin_amdgcn_sched_barrier(0);
;         }
;     }
;     __syncthreads();
	v_lshlrev_b32_e32 v20, 16, v10
	v_and_b32_e32 v21, 0xffff0000, v10
	v_pk_mul_f32 v[12:13], v[12:13], v[20:21]
	v_lshlrev_b32_e32 v10, 16, v11
	v_cvt_pk_bf16_f32 v20, v12, v13
	v_lshlrev_b32_e32 v12, 16, v86
	v_and_b32_e32 v13, 0xffff0000, v86
	v_and_b32_e32 v11, 0xffff0000, v11
	v_pk_mul_f32 v[10:11], v[12:13], v[10:11]
	s_waitcnt lgkmcnt(0)
	v_lshlrev_b32_e32 v12, 16, v14
	v_cvt_pk_bf16_f32 v22, v10, v11
	v_lshlrev_b32_e32 v10, 16, v85
	v_and_b32_e32 v11, 0xffff0000, v85
	v_and_b32_e32 v13, 0xffff0000, v14
	v_pk_mul_f32 v[10:11], v[10:11], v[12:13]
	v_lshlrev_b32_e32 v12, 16, v15
	v_cvt_pk_bf16_f32 v18, v10, v11
	v_lshlrev_b32_e32 v10, 16, v84
	v_and_b32_e32 v11, 0xffff0000, v84
	v_and_b32_e32 v13, 0xffff0000, v15
	v_pk_mul_f32 v[10:11], v[10:11], v[12:13]
	s_nop 0
	v_cvt_pk_bf16_f32 v21, v10, v11
	ds_read_b64 v[10:11], v113 offset:192
	ds_read_b64 v[64:65], v113 offset:16832
	v_lshlrev_b32_e32 v12, 16, v17
	v_and_b32_e32 v13, 0xffff0000, v17
	s_waitcnt lgkmcnt(1)
	v_lshlrev_b32_e32 v14, 16, v10
	v_and_b32_e32 v15, 0xffff0000, v10
	v_pk_mul_f32 v[12:13], v[12:13], v[14:15]
	v_lshlrev_b32_e32 v10, 16, v11
	v_cvt_pk_bf16_f32 v15, v12, v13
	v_lshlrev_b32_e32 v12, 16, v16
	v_and_b32_e32 v13, 0xffff0000, v16
	v_and_b32_e32 v11, 0xffff0000, v11
	v_pk_mul_f32 v[10:11], v[12:13], v[10:11]
	s_waitcnt lgkmcnt(0)
	v_lshlrev_b32_e32 v12, 16, v64
	v_cvt_pk_bf16_f32 v17, v10, v11
	v_lshlrev_b32_e32 v10, 16, v3
	v_and_b32_e32 v11, 0xffff0000, v3
	v_and_b32_e32 v13, 0xffff0000, v64
	v_pk_mul_f32 v[10:11], v[10:11], v[12:13]
	v_lshlrev_b32_e32 v12, 16, v65
	v_cvt_pk_bf16_f32 v14, v10, v11
	v_lshlrev_b32_e32 v10, 16, v2
	v_and_b32_e32 v11, 0xffff0000, v2
	v_and_b32_e32 v13, 0xffff0000, v65
	v_pk_mul_f32 v[2:3], v[10:11], v[12:13]
	s_nop 0
	v_cvt_pk_bf16_f32 v16, v2, v3
	ds_read_b64 v[2:3], v113 offset:208
	ds_read_b64 v[64:65], v113 offset:16848
	v_lshlrev_b32_e32 v10, 16, v7
	v_and_b32_e32 v11, 0xffff0000, v7
	s_waitcnt lgkmcnt(1)
	v_lshlrev_b32_e32 v12, 16, v2
	v_and_b32_e32 v13, 0xffff0000, v2
	v_pk_mul_f32 v[10:11], v[10:11], v[12:13]
	v_lshlrev_b32_e32 v12, 16, v6
	v_lshlrev_b32_e32 v2, 16, v3
	v_and_b32_e32 v13, 0xffff0000, v6
	v_and_b32_e32 v3, 0xffff0000, v3
	v_pk_mul_f32 v[2:3], v[12:13], v[2:3]
	s_waitcnt lgkmcnt(0)
	v_lshlrev_b32_e32 v6, 16, v64
	v_cvt_pk_bf16_f32 v13, v2, v3
	v_lshlrev_b32_e32 v2, 16, v5
	v_and_b32_e32 v3, 0xffff0000, v5
	v_and_b32_e32 v7, 0xffff0000, v64
	v_pk_mul_f32 v[2:3], v[2:3], v[6:7]
	v_cvt_pk_bf16_f32 v11, v10, v11
	v_cvt_pk_bf16_f32 v10, v2, v3
	v_lshlrev_b32_e32 v2, 16, v4
	v_lshlrev_b32_e32 v6, 16, v65
	v_and_b32_e32 v3, 0xffff0000, v4
	v_and_b32_e32 v7, 0xffff0000, v65
	v_pk_mul_f32 v[2:3], v[2:3], v[6:7]
	s_nop 0
	v_cvt_pk_bf16_f32 v12, v2, v3
	ds_read_b64 v[2:3], v113 offset:224
	ds_read_b64 v[64:65], v113 offset:16864
	v_lshlrev_b32_e32 v4, 16, v27
	v_and_b32_e32 v5, 0xffff0000, v27
	s_waitcnt lgkmcnt(1)
	v_lshlrev_b32_e32 v6, 16, v2
	v_and_b32_e32 v7, 0xffff0000, v2
	v_pk_mul_f32 v[4:5], v[4:5], v[6:7]
	v_lshlrev_b32_e32 v2, 16, v3
	v_cvt_pk_bf16_f32 v7, v4, v5
	v_lshlrev_b32_e32 v4, 16, v9
	v_and_b32_e32 v5, 0xffff0000, v9
	v_and_b32_e32 v3, 0xffff0000, v3
	v_pk_mul_f32 v[2:3], v[4:5], v[2:3]
	s_waitcnt lgkmcnt(0)
	v_lshlrev_b32_e32 v4, 16, v64
	v_cvt_pk_bf16_f32 v9, v2, v3
	v_lshlrev_b32_e32 v2, 16, v19
	v_and_b32_e32 v3, 0xffff0000, v19
	v_and_b32_e32 v5, 0xffff0000, v64
	v_pk_mul_f32 v[2:3], v[2:3], v[4:5]
	v_lshlrev_b32_e32 v4, 16, v65
	v_cvt_pk_bf16_f32 v6, v2, v3
	v_lshlrev_b32_e32 v2, 16, v8
	v_and_b32_e32 v3, 0xffff0000, v8
	v_and_b32_e32 v5, 0xffff0000, v65
	v_pk_mul_f32 v[2:3], v[2:3], v[4:5]
	s_nop 0
	v_cvt_pk_bf16_f32 v8, v2, v3
	ds_read_b64 v[2:3], v113 offset:240
	ds_read_b64 v[64:65], v113 offset:16880
	v_lshlrev_b32_e32 v4, 16, v112
	v_and_b32_e32 v5, 0xffff0000, v112
	s_waitcnt lgkmcnt(1)
	v_lshlrev_b32_e32 v66, 16, v2
	v_and_b32_e32 v67, 0xffff0000, v2
	v_pk_mul_f32 v[4:5], v[4:5], v[66:67]
	v_lshlrev_b32_e32 v66, 16, v30
	v_lshlrev_b32_e32 v2, 16, v3
	v_and_b32_e32 v67, 0xffff0000, v30
	v_and_b32_e32 v3, 0xffff0000, v3
	v_pk_mul_f32 v[2:3], v[66:67], v[2:3]
	v_cvt_pk_bf16_f32 v4, v4, v5
	v_cvt_pk_bf16_f32 v5, v2, v3
	v_lshlrev_b32_e32 v2, 16, v29
	s_waitcnt lgkmcnt(0)
	v_lshlrev_b32_e32 v66, 16, v64
	v_and_b32_e32 v3, 0xffff0000, v29
	v_and_b32_e32 v67, 0xffff0000, v64
	v_pk_mul_f32 v[2:3], v[2:3], v[66:67]
	v_lshlrev_b32_e32 v66, 16, v28
	v_lshlrev_b32_e32 v64, 16, v65
	v_and_b32_e32 v67, 0xffff0000, v28
	v_and_b32_e32 v65, 0xffff0000, v65
	v_pk_mul_f32 v[28:29], v[66:67], v[64:65]
	v_cvt_pk_bf16_f32 v2, v2, v3
	v_cvt_pk_bf16_f32 v3, v28, v29
	v_mov_b32_e32 v19, v192
	s_barrier
; DI int otid() { int t = threadIdx.x; asm volatile("" : "+v"(t)); return t; }
; template <bool NT>
; DI void stage_load_tile(bf16_t* stg, const bf16_t* tilebase) {
;   const int tid = otid();
;   const int r0 = tid >> 5, c = tid & 31;
;   const unsigned o0 = (unsigned)(r0 * 1024 + c * 8);
;   __builtin_amdgcn_sched_barrier(0);
; #pragma unroll
;   for (int hf = 0; hf < 2; ++hf) {
; #pragma unroll
;     for (int it = 8 * hf; it < 8 * hf + 8; ++it) {
;       const u32x4* gp = (const u32x4*)(tilebase + (o0 + (unsigned)(it * 16 * 1024)));
;       stage_write16(stg, r0 + 16 * it, c, NT ? __builtin_nontemporal_load(gp) : *gp);
;     }
;     __builtin_amdgcn_sched_barrier(0);
;   }
; }
; template <bool LAST>
; DI void phase_gate(const Params& P, int layer, unsigned char* smem, int L, int G) {
;     ...
;     stage_load_tile<false>(stg, Sb + (size_t)mt * 256 * 1024 + nt * 256);
;     __syncthreads();
	s_add_u32 s30, s76, s24
	v_ashrrev_i32_e32 v27, 5, v19
	v_and_b32_e32 v19, 31, v19
	s_addc_u32 s31, s77, s25
	v_lshlrev_b32_e32 v30, 3, v19
	v_lshl_add_u64 v[28:29], s[30:31], 0, v[0:1]
	v_lshl_or_b32 v160, v27, 10, v30
	v_add_u32_e32 v66, 0x4000, v160
	v_mov_b32_e32 v67, v161
	v_add_u32_e32 v72, 0x8000, v160
	v_mov_b32_e32 v73, v161
	v_add_u32_e32 v74, 0xc000, v160
	v_mov_b32_e32 v75, v161
	v_add_u32_e32 v80, 0x10000, v160
	v_mov_b32_e32 v81, v161
	v_add_u32_e32 v82, 0x14000, v160
	v_mov_b32_e32 v83, v161
	v_lshl_add_u64 v[64:65], v[160:161], 1, v[28:29]
	v_lshl_add_u64 v[68:69], v[66:67], 1, v[28:29]
	v_lshl_add_u64 v[72:73], v[72:73], 1, v[28:29]
	v_lshl_add_u64 v[76:77], v[74:75], 1, v[28:29]
	v_lshl_add_u64 v[80:81], v[80:81], 1, v[28:29]
	v_lshl_add_u64 v[84:85], v[82:83], 1, v[28:29]
	global_load_dwordx4 v[64:67], v[64:65], off
	s_nop 0
	global_load_dwordx4 v[68:71], v[68:69], off
	s_nop 0
	global_load_dwordx4 v[72:75], v[72:73], off
	s_nop 0
	global_load_dwordx4 v[76:79], v[76:77], off
	s_nop 0
	global_load_dwordx4 v[80:83], v[80:81], off
	s_nop 0
	global_load_dwordx4 v[100:103], v[84:85], off
	v_add_u32_e32 v84, 0x18000, v160
	v_mov_b32_e32 v85, v161
	v_add_u32_e32 v104, 0x1c000, v160
	v_mov_b32_e32 v105, v161
	v_lshl_add_u64 v[84:85], v[84:85], 1, v[28:29]
	v_lshl_add_u64 v[108:109], v[104:105], 1, v[28:29]
	global_load_dwordx4 v[104:107], v[84:85], off
	s_nop 0
	global_load_dwordx4 v[108:111], v[108:109], off
	v_add_u32_e32 v218, 0x20000, v160
	v_mov_b32_e32 v219, v161
	v_add_u32_e32 v220, 0x24000, v160
	v_mov_b32_e32 v221, v161
	v_add_u32_e32 v226, 0x28000, v160
	v_mov_b32_e32 v227, v161
	v_add_u32_e32 v228, 0x2c000, v160
	v_mov_b32_e32 v229, v161
	v_add_u32_e32 v234, 0x30000, v160
	v_mov_b32_e32 v235, v161
	v_add_u32_e32 v236, 0x34000, v160
	v_mov_b32_e32 v237, v161
	v_lshl_add_u64 v[218:219], v[218:219], 1, v[28:29]
	v_lshl_add_u64 v[222:223], v[220:221], 1, v[28:29]
	v_lshl_add_u64 v[226:227], v[226:227], 1, v[28:29]
	v_lshl_add_u64 v[230:231], v[228:229], 1, v[28:29]
	v_lshl_add_u64 v[234:235], v[234:235], 1, v[28:29]
	v_lshl_add_u64 v[252:253], v[236:237], 1, v[28:29]
	global_load_dwordx4 v[218:221], v[218:219], off
	s_nop 0
	global_load_dwordx4 v[222:225], v[222:223], off
	s_nop 0
	global_load_dwordx4 v[226:229], v[226:227], off
	s_nop 0
	global_load_dwordx4 v[230:233], v[230:231], off
	s_nop 0
	global_load_dwordx4 v[234:237], v[234:235], off
	s_nop 0
	global_load_dwordx4 v[238:241], v[252:253], off
	v_add_u32_e32 v252, 0x38000, v160
	v_mov_b32_e32 v253, v161
	v_lshl_add_u64 v[252:253], v[252:253], 1, v[28:29]
	v_add_u32_e32 v160, 0x3c000, v160
	v_lshl_add_u64 v[190:191], v[160:161], 1, v[28:29]
	global_load_dwordx4 v[242:245], v[252:253], off
	global_load_dwordx4 v[248:251], v[190:191], off
	v_mul_lo_u32 v27, v27, s44
	v_lshl_add_u32 v19, v19, 4, v27
	v_add_u32_e32 v27, 0x2080, v19
	v_add_u32_e32 v30, 0x4100, v19
	v_add_u32_e32 v33, 0x6180, v19
	v_add_u32_e32 v53, 0x8200, v19
	v_add_u32_e32 v55, 0xa280, v19
	v_add_u32_e32 v59, 0xc300, v19
	v_add_u32_e32 v84, 0xe380, v19
	s_waitcnt vmcnt(15)
	ds_write2_b64 v19, v[64:65], v[66:67] offset1:1
	s_waitcnt vmcnt(14)
	ds_write2_b64 v27, v[68:69], v[70:71] offset1:1
	s_waitcnt vmcnt(13)
	ds_write2_b64 v30, v[72:73], v[74:75] offset1:1
	s_waitcnt vmcnt(12)
	ds_write2_b64 v33, v[76:77], v[78:79] offset1:1
	s_waitcnt vmcnt(11)
	ds_write2_b64 v53, v[80:81], v[82:83] offset1:1
	s_waitcnt vmcnt(10)
	ds_write2_b64 v55, v[100:101], v[102:103] offset1:1
	s_waitcnt vmcnt(9)
	ds_write2_b64 v59, v[104:105], v[106:107] offset1:1
	s_waitcnt vmcnt(8)
	ds_write2_b64 v84, v[108:109], v[110:111] offset1:1
	v_add_u32_e32 v27, 0x10400, v19
	v_add_u32_e32 v28, 0x12480, v19
	v_add_u32_e32 v29, 0x14500, v19
	v_add_u32_e32 v30, 0x16580, v19
	v_add_u32_e32 v33, 0x18600, v19
	v_add_u32_e32 v53, 0x1a680, v19
	v_add_u32_e32 v55, 0x1c700, v19
	v_add_u32_e32 v19, 0x1e780, v19
	s_waitcnt vmcnt(7)
	ds_write2_b64 v27, v[218:219], v[220:221] offset1:1
	s_waitcnt vmcnt(6)
	ds_write2_b64 v28, v[222:223], v[224:225] offset1:1
	s_waitcnt vmcnt(5)
	ds_write2_b64 v29, v[226:227], v[228:229] offset1:1
	s_waitcnt vmcnt(4)
	ds_write2_b64 v30, v[230:231], v[232:233] offset1:1
	s_waitcnt vmcnt(3)
	ds_write2_b64 v33, v[234:235], v[236:237] offset1:1
	s_waitcnt vmcnt(2)
	ds_write2_b64 v53, v[238:239], v[240:241] offset1:1
	s_waitcnt vmcnt(1)
	ds_write2_b64 v55, v[242:243], v[244:245] offset1:1
	s_waitcnt vmcnt(0)
	ds_write2_b64 v19, v[248:249], v[250:251] offset1:1
	v_mov_b32_e32 v19, v192
	s_waitcnt lgkmcnt(0)
	s_barrier
; DI unsigned pack2(float a, float b) { f32x2_t v = {a, b}; bf16x2_t r = __builtin_convertvector(v, bf16x2_t); return __builtin_bit_cast(unsigned, r); }
; DI float bflo(unsigned u) { return __uint_as_float(u << 16); }
; DI float bfhi(unsigned u) { return __uint_as_float(u & 0xffff0000u); }
; DI int otid() { int t = threadIdx.x; asm volatile("" : "+v"(t)); return t; }
; template <bool LAST>
; DI void phase_gate(const Params& P, int layer, unsigned char* smem, int L, int G) {
;     ...
;     const int tid2 = otid();
;     const int lane2 = tid2 & 63, w2 = tid2 >> 6, r2 = lane2 & 31, h2 = lane2 >> 5, wm2 = w2 >> 2, wn2 = w2 & 3;
; #pragma unroll
;     for (int i = 0; i < 4; ++i)
; #pragma unroll
;       for (int q4 = 0; q4 < 4; ++q4) {
;         const int fl = wm2 * 128 + i * 32 + 8 * q4 + 4 * h2;
;         const int f0 = nt * 256 + fl;
;         const f32x4 gv = *(const f32x4*)(vecL + 512 + fl), bv = *(const f32x4*)(vecL + 768 + fl);
;         const float ga[4] = {gv.x, gv.y, gv.z, gv.w}, ba[4] = {bv.x, bv.y, bv.z, bv.w};
; #pragma unroll
;         for (int j = 0; j < 2; ++j) {
;           const int lrow = wn2 * 64 + j * 32 + r2;
;           const float mu = rowA[lrow], rstd = rowB[lrow];
;           uint2* sp = (uint2*)(stg + lrow * STG + fl);
;           const uint2 sv = *sp;
;           const float sa[4] = {bflo(sv.x), bfhi(sv.x), bflo(sv.y), bfhi(sv.y)};
;           float y[4];
;           const float gg[4] = {bflo(gq[i][j][2 * q4]), bfhi(gq[i][j][2 * q4]), bflo(gq[i][j][2 * q4 + 1]), bfhi(gq[i][j][2 * q4 + 1])};
; #pragma unroll
;           for (int e = 0; e < 4; ++e) y[e] = (sa[e] - mu) * rstd * ga[e] + ba[e] + gg[e];
;           if (LAST) { f32x4 o = {y[0], y[1], y[2], y[3]}; *(f32x4*)(P.out + (size_t)(mt * 256 + lrow) * 1024 + f0) = o; }
;           else { uint2 pk; pk.x = pack2(y[0], y[1]); pk.y = pack2(y[2], y[3]); *sp = pk; }
;         }
;         __builtin_amdgcn_sched_barrier(0);
	v_lshlrev_b32_e32 v82, 16, v31
	v_lshrrev_b32_e32 v28, 3, v19
	v_ashrrev_i32_e32 v27, 1, v19
	v_and_b32_e32 v28, 4, v28
	v_and_or_b32 v30, v27, s45, v28
	v_and_b32_e32 v19, 0xdf, v19
	v_lshlrev_b32_e32 v27, 2, v30
	v_lshlrev_b32_e32 v33, 2, v19
	v_mul_u32_u24_e32 v19, 0x208, v19
	v_add_u32_e32 v28, 0x25000, v27
	v_lshl_add_u32 v19, v30, 1, v19
	v_add_u32_e32 v29, 0x25400, v27
	ds_read_b128 v[64:67], v28
	ds_read_b128 v[68:71], v29
	ds_read_b64 v[72:73], v19
	v_or_b32_e32 v29, 0x24000, v33
	v_or_b32_e32 v30, 0x24400, v33
	ds_read_b32 v74, v29
	ds_read_b32 v76, v30
	ds_read_b64 v[78:79], v19 offset:16640
	v_and_b32_e32 v83, 0xffff0000, v31
	s_waitcnt lgkmcnt(3)
	v_lshlrev_b32_e32 v80, 16, v72
	v_and_b32_e32 v81, 0xffff0000, v72
	v_lshlrev_b32_e32 v72, 16, v73
	v_and_b32_e32 v73, 0xffff0000, v73
	s_waitcnt lgkmcnt(2)
	v_pk_add_f32 v[80:81], v[80:81], v[74:75] op_sel_hi:[1,0] neg_lo:[0,1] neg_hi:[0,1]
	v_pk_add_f32 v[72:73], v[72:73], v[74:75] op_sel_hi:[1,0] neg_lo:[0,1] neg_hi:[0,1]
	s_waitcnt lgkmcnt(1)
	v_pk_mul_f32 v[80:81], v[76:77], v[80:81] op_sel_hi:[0,1]
	v_pk_mul_f32 v[72:73], v[76:77], v[72:73] op_sel_hi:[0,1]
	v_lshlrev_b32_e32 v84, 16, v98
	v_and_b32_e32 v85, 0xffff0000, v98
	v_pk_fma_f32 v[80:81], v[64:65], v[80:81], v[68:69]
	v_pk_fma_f32 v[72:73], v[66:67], v[72:73], v[70:71]
	v_pk_add_f32 v[80:81], v[80:81], v[82:83]
	v_pk_add_f32 v[72:73], v[72:73], v[84:85]
	v_cvt_pk_bf16_f32 v74, v80, v81
	v_cvt_pk_bf16_f32 v75, v72, v73
	ds_write_b64 v19, v[74:75]
	v_or_b32_e32 v31, 0x24080, v33
	v_or_b32_e32 v33, 0x24480, v33
	ds_read_b32 v72, v31
	ds_read_b32 v74, v33
	s_waitcnt lgkmcnt(3)
	v_lshlrev_b32_e32 v76, 16, v78
	v_and_b32_e32 v77, 0xffff0000, v78
	v_lshlrev_b32_e32 v78, 16, v79
	s_waitcnt lgkmcnt(1)
	v_pk_add_f32 v[76:77], v[76:77], v[72:73] op_sel_hi:[1,0] neg_lo:[0,1] neg_hi:[0,1]
	v_and_b32_e32 v79, 0xffff0000, v79
	s_waitcnt lgkmcnt(0)
	v_pk_mul_f32 v[76:77], v[74:75], v[76:77] op_sel_hi:[0,1]
	v_pk_fma_f32 v[64:65], v[64:65], v[76:77], v[68:69]
	v_pk_add_f32 v[68:69], v[78:79], v[72:73] op_sel_hi:[1,0] neg_lo:[0,1] neg_hi:[0,1]
	v_lshlrev_b32_e32 v80, 16, v97
	v_pk_mul_f32 v[68:69], v[74:75], v[68:69] op_sel_hi:[0,1]
	v_and_b32_e32 v81, 0xffff0000, v97
	v_lshlrev_b32_e32 v82, 16, v96
	v_and_b32_e32 v83, 0xffff0000, v96
	v_pk_fma_f32 v[66:67], v[66:67], v[68:69], v[70:71]
	v_pk_add_f32 v[64:65], v[64:65], v[80:81]
	v_pk_add_f32 v[66:67], v[66:67], v[82:83]
	v_cvt_pk_bf16_f32 v64, v64, v65
	v_cvt_pk_bf16_f32 v65, v66, v67
	ds_write_b64 v19, v[64:65] offset:16640
	v_add_u32_e32 v53, 0x25020, v27
	v_add_u32_e32 v55, 0x25420, v27
	ds_read_b64 v[72:73], v19 offset:16
	ds_read_b128 v[64:67], v53
	ds_read_b128 v[68:71], v55
	ds_read_b32 v74, v29
	ds_read_b32 v76, v30
	ds_read_b64 v[78:79], v19 offset:16656
	s_waitcnt lgkmcnt(5)
	v_lshlrev_b32_e32 v80, 16, v72
	v_and_b32_e32 v81, 0xffff0000, v72
	v_lshlrev_b32_e32 v72, 16, v73
	v_and_b32_e32 v73, 0xffff0000, v73
	s_waitcnt lgkmcnt(2)
	v_pk_add_f32 v[80:81], v[80:81], v[74:75] op_sel_hi:[1,0] neg_lo:[0,1] neg_hi:[0,1]
	v_pk_add_f32 v[72:73], v[72:73], v[74:75] op_sel_hi:[1,0] neg_lo:[0,1] neg_hi:[0,1]
	s_waitcnt lgkmcnt(1)
	v_pk_mul_f32 v[80:81], v[76:77], v[80:81] op_sel_hi:[0,1]
	v_pk_mul_f32 v[72:73], v[76:77], v[72:73] op_sel_hi:[0,1]
	v_lshlrev_b32_e32 v82, 16, v93
	v_and_b32_e32 v83, 0xffff0000, v93
	v_lshlrev_b32_e32 v84, 16, v95
	v_and_b32_e32 v85, 0xffff0000, v95
	v_pk_fma_f32 v[80:81], v[64:65], v[80:81], v[68:69]
	v_pk_fma_f32 v[72:73], v[66:67], v[72:73], v[70:71]
	v_pk_add_f32 v[80:81], v[80:81], v[82:83]
	v_pk_add_f32 v[72:73], v[72:73], v[84:85]
	v_cvt_pk_bf16_f32 v74, v80, v81
	v_cvt_pk_bf16_f32 v75, v72, v73
	ds_write_b64 v19, v[74:75] offset:16
	ds_read_b32 v72, v31
	ds_read_b32 v74, v33
	s_waitcnt lgkmcnt(3)
	v_lshlrev_b32_e32 v76, 16, v78
	v_and_b32_e32 v77, 0xffff0000, v78
	v_lshlrev_b32_e32 v78, 16, v79
	s_waitcnt lgkmcnt(1)
	v_pk_add_f32 v[76:77], v[76:77], v[72:73] op_sel_hi:[1,0] neg_lo:[0,1] neg_hi:[0,1]
	v_and_b32_e32 v79, 0xffff0000, v79
	s_waitcnt lgkmcnt(0)
	v_pk_mul_f32 v[76:77], v[74:75], v[76:77] op_sel_hi:[0,1]
	v_pk_fma_f32 v[64:65], v[64:65], v[76:77], v[68:69]
	v_pk_add_f32 v[68:69], v[78:79], v[72:73] op_sel_hi:[1,0] neg_lo:[0,1] neg_hi:[0,1]
	v_lshlrev_b32_e32 v80, 16, v92
	v_pk_mul_f32 v[68:69], v[74:75], v[68:69] op_sel_hi:[0,1]
	v_and_b32_e32 v81, 0xffff0000, v92
	v_lshlrev_b32_e32 v82, 16, v94
	v_and_b32_e32 v83, 0xffff0000, v94
	v_pk_fma_f32 v[66:67], v[66:67], v[68:69], v[70:71]
	v_pk_add_f32 v[64:65], v[64:65], v[80:81]
	v_pk_add_f32 v[66:67], v[66:67], v[82:83]
	v_cvt_pk_bf16_f32 v64, v64, v65
	v_cvt_pk_bf16_f32 v65, v66, v67
	ds_write_b64 v19, v[64:65] offset:16656
	v_add_u32_e32 v53, 0x25040, v27
	v_add_u32_e32 v55, 0x25440, v27
	ds_read_b64 v[72:73], v19 offset:32
	ds_read_b128 v[64:67], v53
	ds_read_b128 v[68:71], v55
	ds_read_b32 v74, v29
	ds_read_b32 v76, v30
	ds_read_b64 v[78:79], v19 offset:16672
	s_waitcnt lgkmcnt(5)
	v_lshlrev_b32_e32 v80, 16, v72
	v_and_b32_e32 v81, 0xffff0000, v72
	v_lshlrev_b32_e32 v72, 16, v73
	v_and_b32_e32 v73, 0xffff0000, v73
	s_waitcnt lgkmcnt(2)
	v_pk_add_f32 v[80:81], v[80:81], v[74:75] op_sel_hi:[1,0] neg_lo:[0,1] neg_hi:[0,1]
	v_pk_add_f32 v[72:73], v[72:73], v[74:75] op_sel_hi:[1,0] neg_lo:[0,1] neg_hi:[0,1]
	s_waitcnt lgkmcnt(1)
	v_pk_mul_f32 v[80:81], v[76:77], v[80:81] op_sel_hi:[0,1]
	v_pk_mul_f32 v[72:73], v[76:77], v[72:73] op_sel_hi:[0,1]
	v_lshlrev_b32_e32 v82, 16, v88
	v_and_b32_e32 v83, 0xffff0000, v88
	v_lshlrev_b32_e32 v84, 16, v90
	v_and_b32_e32 v85, 0xffff0000, v90
	v_pk_fma_f32 v[80:81], v[64:65], v[80:81], v[68:69]
	v_pk_fma_f32 v[72:73], v[66:67], v[72:73], v[70:71]
	v_pk_add_f32 v[80:81], v[80:81], v[82:83]
	v_pk_add_f32 v[72:73], v[72:73], v[84:85]
	v_cvt_pk_bf16_f32 v74, v80, v81
	v_cvt_pk_bf16_f32 v75, v72, v73
	ds_write_b64 v19, v[74:75] offset:32
	ds_read_b32 v72, v31
	ds_read_b32 v74, v33
	s_waitcnt lgkmcnt(3)
; DI unsigned pack2(float a, float b) { f32x2_t v = {a, b}; bf16x2_t r = __builtin_convertvector(v, bf16x2_t); return __builtin_bit_cast(unsigned, r); }
; DI float bflo(unsigned u) { return __uint_as_float(u << 16); }
; DI float bfhi(unsigned u) { return __uint_as_float(u & 0xffff0000u); }
; DI int otid() { int t = threadIdx.x; asm volatile("" : "+v"(t)); return t; }
; template <bool LAST>
; DI void phase_gate(const Params& P, int layer, unsigned char* smem, int L, int G) {
;     ...
;     const int tid2 = otid();
;     const int lane2 = tid2 & 63, w2 = tid2 >> 6, r2 = lane2 & 31, h2 = lane2 >> 5, wm2 = w2 >> 2, wn2 = w2 & 3;
; #pragma unroll
;     for (int i = 0; i < 4; ++i)
; #pragma unroll
;       for (int q4 = 0; q4 < 4; ++q4) {
;         const int fl = wm2 * 128 + i * 32 + 8 * q4 + 4 * h2;
;         const int f0 = nt * 256 + fl;
;         const f32x4 gv = *(const f32x4*)(vecL + 512 + fl), bv = *(const f32x4*)(vecL + 768 + fl);
;         const float ga[4] = {gv.x, gv.y, gv.z, gv.w}, ba[4] = {bv.x, bv.y, bv.z, bv.w};
; #pragma unroll
;         for (int j = 0; j < 2; ++j) {
;           const int lrow = wn2 * 64 + j * 32 + r2;
;           const float mu = rowA[lrow], rstd = rowB[lrow];
;           uint2* sp = (uint2*)(stg + lrow * STG + fl);
;           const uint2 sv = *sp;
;           const float sa[4] = {bflo(sv.x), bfhi(sv.x), bflo(sv.y), bfhi(sv.y)};
;           float y[4];
;           const float gg[4] = {bflo(gq[i][j][2 * q4]), bfhi(gq[i][j][2 * q4]), bflo(gq[i][j][2 * q4 + 1]), bfhi(gq[i][j][2 * q4 + 1])};
; #pragma unroll
;           for (int e = 0; e < 4; ++e) y[e] = (sa[e] - mu) * rstd * ga[e] + ba[e] + gg[e];
;           if (LAST) { f32x4 o = {y[0], y[1], y[2], y[3]}; *(f32x4*)(P.out + (size_t)(mt * 256 + lrow) * 1024 + f0) = o; }
;           else { uint2 pk; pk.x = pack2(y[0], y[1]); pk.y = pack2(y[2], y[3]); *sp = pk; }
;         }
;         __builtin_amdgcn_sched_barrier(0);
	v_lshlrev_b32_e32 v76, 16, v78
	v_and_b32_e32 v77, 0xffff0000, v78
	v_lshlrev_b32_e32 v78, 16, v79
	s_waitcnt lgkmcnt(1)
	v_pk_add_f32 v[76:77], v[76:77], v[72:73] op_sel_hi:[1,0] neg_lo:[0,1] neg_hi:[0,1]
	v_and_b32_e32 v79, 0xffff0000, v79
	s_waitcnt lgkmcnt(0)
	v_pk_mul_f32 v[76:77], v[74:75], v[76:77] op_sel_hi:[0,1]
	v_pk_fma_f32 v[64:65], v[64:65], v[76:77], v[68:69]
	v_pk_add_f32 v[68:69], v[78:79], v[72:73] op_sel_hi:[1,0] neg_lo:[0,1] neg_hi:[0,1]
	v_lshlrev_b32_e32 v80, 16, v87
	v_pk_mul_f32 v[68:69], v[74:75], v[68:69] op_sel_hi:[0,1]
	v_and_b32_e32 v81, 0xffff0000, v87
	v_lshlrev_b32_e32 v82, 16, v89
	v_and_b32_e32 v83, 0xffff0000, v89
	v_pk_fma_f32 v[66:67], v[66:67], v[68:69], v[70:71]
	v_pk_add_f32 v[64:65], v[64:65], v[80:81]
	v_pk_add_f32 v[66:67], v[66:67], v[82:83]
	v_cvt_pk_bf16_f32 v64, v64, v65
	v_cvt_pk_bf16_f32 v65, v66, v67
	ds_write_b64 v19, v[64:65] offset:16672
	v_add_u32_e32 v53, 0x25060, v27
	v_add_u32_e32 v55, 0x25460, v27
	ds_read_b64 v[72:73], v19 offset:48
	ds_read_b128 v[64:67], v53
	ds_read_b128 v[68:71], v55
	ds_read_b32 v74, v29
	ds_read_b32 v76, v30
	ds_read_b64 v[78:79], v19 offset:16688
	s_waitcnt lgkmcnt(5)
	v_lshlrev_b32_e32 v80, 16, v72
	v_and_b32_e32 v81, 0xffff0000, v72
	v_lshlrev_b32_e32 v72, 16, v73
	v_and_b32_e32 v73, 0xffff0000, v73
	s_waitcnt lgkmcnt(2)
	v_pk_add_f32 v[80:81], v[80:81], v[74:75] op_sel_hi:[1,0] neg_lo:[0,1] neg_hi:[0,1]
	v_pk_add_f32 v[72:73], v[72:73], v[74:75] op_sel_hi:[1,0] neg_lo:[0,1] neg_hi:[0,1]
	s_waitcnt lgkmcnt(1)
	v_pk_mul_f32 v[80:81], v[76:77], v[80:81] op_sel_hi:[0,1]
	v_pk_mul_f32 v[72:73], v[76:77], v[72:73] op_sel_hi:[0,1]
	v_lshlrev_b32_e32 v82, 16, v61
	v_and_b32_e32 v83, 0xffff0000, v61
	v_lshlrev_b32_e32 v84, 16, v63
	v_and_b32_e32 v85, 0xffff0000, v63
	v_pk_fma_f32 v[80:81], v[64:65], v[80:81], v[68:69]
	v_pk_fma_f32 v[72:73], v[66:67], v[72:73], v[70:71]
	v_pk_add_f32 v[80:81], v[80:81], v[82:83]
	v_pk_add_f32 v[72:73], v[72:73], v[84:85]
	v_cvt_pk_bf16_f32 v74, v80, v81
	v_cvt_pk_bf16_f32 v75, v72, v73
	ds_write_b64 v19, v[74:75] offset:48
	ds_read_b32 v72, v31
	ds_read_b32 v74, v33
	s_waitcnt lgkmcnt(3)
	v_lshlrev_b32_e32 v76, 16, v78
	v_and_b32_e32 v77, 0xffff0000, v78
	v_lshlrev_b32_e32 v80, 16, v60
	v_and_b32_e32 v81, 0xffff0000, v60
	v_lshlrev_b32_e32 v60, 16, v62
	v_and_b32_e32 v61, 0xffff0000, v62
	s_waitcnt lgkmcnt(1)
	v_pk_add_f32 v[62:63], v[76:77], v[72:73] op_sel_hi:[1,0] neg_lo:[0,1] neg_hi:[0,1]
	v_lshlrev_b32_e32 v78, 16, v79
	v_and_b32_e32 v79, 0xffff0000, v79
	s_waitcnt lgkmcnt(0)
	v_pk_mul_f32 v[62:63], v[74:75], v[62:63] op_sel_hi:[0,1]
	v_pk_fma_f32 v[62:63], v[64:65], v[62:63], v[68:69]
	v_pk_add_f32 v[64:65], v[78:79], v[72:73] op_sel_hi:[1,0] neg_lo:[0,1] neg_hi:[0,1]
	v_pk_add_f32 v[62:63], v[62:63], v[80:81]
	v_pk_mul_f32 v[64:65], v[74:75], v[64:65] op_sel_hi:[0,1]
	v_pk_fma_f32 v[64:65], v[66:67], v[64:65], v[70:71]
	v_cvt_pk_bf16_f32 v62, v62, v63
	v_pk_add_f32 v[60:61], v[64:65], v[60:61]
	s_nop 0
	v_cvt_pk_bf16_f32 v63, v60, v61
	ds_write_b64 v19, v[62:63] offset:16688
	v_add_u32_e32 v53, 0x25080, v27
	v_add_u32_e32 v55, 0x25480, v27
	ds_read_b64 v[68:69], v19 offset:64
	ds_read_b128 v[60:63], v53
	ds_read_b128 v[64:67], v55
	ds_read_b32 v70, v29
	ds_read_b32 v72, v30
	ds_read_b64 v[74:75], v19 offset:16704
	s_waitcnt lgkmcnt(5)
	v_lshlrev_b32_e32 v76, 16, v68
	v_and_b32_e32 v77, 0xffff0000, v68
	v_lshlrev_b32_e32 v68, 16, v69
	v_and_b32_e32 v69, 0xffff0000, v69
	v_lshlrev_b32_e32 v80, 16, v58
	v_and_b32_e32 v81, 0xffff0000, v58
	s_waitcnt lgkmcnt(2)
	v_pk_add_f32 v[58:59], v[76:77], v[70:71] op_sel_hi:[1,0] neg_lo:[0,1] neg_hi:[0,1]
	v_pk_add_f32 v[68:69], v[68:69], v[70:71] op_sel_hi:[1,0] neg_lo:[0,1] neg_hi:[0,1]
	s_waitcnt lgkmcnt(1)
	v_pk_mul_f32 v[58:59], v[72:73], v[58:59] op_sel_hi:[0,1]
	v_pk_mul_f32 v[68:69], v[72:73], v[68:69] op_sel_hi:[0,1]
	v_lshlrev_b32_e32 v78, 16, v56
	v_and_b32_e32 v79, 0xffff0000, v56
	v_pk_fma_f32 v[58:59], v[60:61], v[58:59], v[64:65]
	v_pk_fma_f32 v[68:69], v[62:63], v[68:69], v[66:67]
	v_pk_add_f32 v[58:59], v[58:59], v[78:79]
	v_pk_add_f32 v[68:69], v[68:69], v[80:81]
	v_cvt_pk_bf16_f32 v58, v58, v59
	v_cvt_pk_bf16_f32 v59, v68, v69
	ds_write_b64 v19, v[58:59] offset:64
	ds_read_b32 v56, v31
	ds_read_b32 v58, v33
	s_waitcnt lgkmcnt(3)
	v_lshlrev_b32_e32 v68, 16, v74
	v_and_b32_e32 v69, 0xffff0000, v74
	v_lshlrev_b32_e32 v70, 16, v75
	v_and_b32_e32 v71, 0xffff0000, v75
	v_lshlrev_b32_e32 v72, 16, v54
	v_and_b32_e32 v73, 0xffff0000, v54
	v_lshlrev_b32_e32 v54, 16, v57
	v_and_b32_e32 v55, 0xffff0000, v57
	s_waitcnt lgkmcnt(1)
	v_pk_add_f32 v[68:69], v[68:69], v[56:57] op_sel_hi:[1,0] neg_lo:[0,1] neg_hi:[0,1]
	v_pk_add_f32 v[56:57], v[70:71], v[56:57] op_sel_hi:[1,0] neg_lo:[0,1] neg_hi:[0,1]
	s_waitcnt lgkmcnt(0)
	v_pk_mul_f32 v[68:69], v[58:59], v[68:69] op_sel_hi:[0,1]
	v_pk_mul_f32 v[56:57], v[58:59], v[56:57] op_sel_hi:[0,1]
	v_pk_fma_f32 v[60:61], v[60:61], v[68:69], v[64:65]
	v_pk_fma_f32 v[56:57], v[62:63], v[56:57], v[66:67]
	v_pk_add_f32 v[60:61], v[60:61], v[72:73]
	v_pk_add_f32 v[54:55], v[56:57], v[54:55]
	v_cvt_pk_bf16_f32 v56, v60, v61
	v_cvt_pk_bf16_f32 v57, v54, v55
	ds_write_b64 v19, v[56:57] offset:16704
	v_add_u32_e32 v58, 0x254a0, v27
	v_add_u32_e32 v53, 0x250a0, v27
	ds_read_b64 v[62:63], v19 offset:80
	ds_read_b128 v[54:57], v53
	ds_read_b128 v[58:61], v58
	ds_read_b32 v64, v29
	ds_read_b32 v66, v30
	ds_read_b64 v[68:69], v19 offset:16720
	s_waitcnt lgkmcnt(5)
	v_lshlrev_b32_e32 v70, 16, v62
	v_and_b32_e32 v71, 0xffff0000, v62
	v_lshlrev_b32_e32 v62, 16, v63
	v_and_b32_e32 v63, 0xffff0000, v63
	v_lshlrev_b32_e32 v74, 16, v52
	v_and_b32_e32 v75, 0xffff0000, v52
	s_waitcnt lgkmcnt(2)
; DI unsigned pack2(float a, float b) { f32x2_t v = {a, b}; bf16x2_t r = __builtin_convertvector(v, bf16x2_t); return __builtin_bit_cast(unsigned, r); }
; DI float bflo(unsigned u) { return __uint_as_float(u << 16); }
; DI float bfhi(unsigned u) { return __uint_as_float(u & 0xffff0000u); }
; template <bool LAST>
; DI void phase_gate(const Params& P, int layer, unsigned char* smem, int L, int G) {
;     ...
; #pragma unroll
;     for (int i = 0; i < 4; ++i)
; #pragma unroll
;       for (int q4 = 0; q4 < 4; ++q4) {
;         const int fl = wm2 * 128 + i * 32 + 8 * q4 + 4 * h2;
;         const int f0 = nt * 256 + fl;
;         const f32x4 gv = *(const f32x4*)(vecL + 512 + fl), bv = *(const f32x4*)(vecL + 768 + fl);
;         const float ga[4] = {gv.x, gv.y, gv.z, gv.w}, ba[4] = {bv.x, bv.y, bv.z, bv.w};
; #pragma unroll
;         for (int j = 0; j < 2; ++j) {
;           const int lrow = wn2 * 64 + j * 32 + r2;
;           const float mu = rowA[lrow], rstd = rowB[lrow];
;           uint2* sp = (uint2*)(stg + lrow * STG + fl);
;           const uint2 sv = *sp;
;           const float sa[4] = {bflo(sv.x), bfhi(sv.x), bflo(sv.y), bfhi(sv.y)};
;           float y[4];
;           const float gg[4] = {bflo(gq[i][j][2 * q4]), bfhi(gq[i][j][2 * q4]), bflo(gq[i][j][2 * q4 + 1]), bfhi(gq[i][j][2 * q4 + 1])};
; #pragma unroll
;           for (int e = 0; e < 4; ++e) y[e] = (sa[e] - mu) * rstd * ga[e] + ba[e] + gg[e];
;           if (LAST) { f32x4 o = {y[0], y[1], y[2], y[3]}; *(f32x4*)(P.out + (size_t)(mt * 256 + lrow) * 1024 + f0) = o; }
;           else { uint2 pk; pk.x = pack2(y[0], y[1]); pk.y = pack2(y[2], y[3]); *sp = pk; }
;         }
;         __builtin_amdgcn_sched_barrier(0);
;       }
	v_pk_add_f32 v[52:53], v[70:71], v[64:65] op_sel_hi:[1,0] neg_lo:[0,1] neg_hi:[0,1]
	v_pk_add_f32 v[62:63], v[62:63], v[64:65] op_sel_hi:[1,0] neg_lo:[0,1] neg_hi:[0,1]
	s_waitcnt lgkmcnt(1)
	v_pk_mul_f32 v[52:53], v[66:67], v[52:53] op_sel_hi:[0,1]
	v_pk_mul_f32 v[62:63], v[66:67], v[62:63] op_sel_hi:[0,1]
	v_lshlrev_b32_e32 v72, 16, v50
	v_and_b32_e32 v73, 0xffff0000, v50
	v_pk_fma_f32 v[52:53], v[54:55], v[52:53], v[58:59]
	v_pk_fma_f32 v[62:63], v[56:57], v[62:63], v[60:61]
	v_pk_add_f32 v[52:53], v[52:53], v[72:73]
	v_pk_add_f32 v[62:63], v[62:63], v[74:75]
	v_cvt_pk_bf16_f32 v52, v52, v53
	v_cvt_pk_bf16_f32 v53, v62, v63
	ds_write_b64 v19, v[52:53] offset:80
	ds_read_b32 v50, v31
	ds_read_b32 v52, v33
	s_waitcnt lgkmcnt(3)
	v_lshlrev_b32_e32 v62, 16, v68
	v_and_b32_e32 v63, 0xffff0000, v68
	v_lshlrev_b32_e32 v64, 16, v69
	v_and_b32_e32 v65, 0xffff0000, v69
	v_lshlrev_b32_e32 v68, 16, v51
	v_and_b32_e32 v69, 0xffff0000, v51
	s_waitcnt lgkmcnt(1)
	v_pk_add_f32 v[62:63], v[62:63], v[50:51] op_sel_hi:[1,0] neg_lo:[0,1] neg_hi:[0,1]
	v_pk_add_f32 v[50:51], v[64:65], v[50:51] op_sel_hi:[1,0] neg_lo:[0,1] neg_hi:[0,1]
	s_waitcnt lgkmcnt(0)
	v_pk_mul_f32 v[62:63], v[52:53], v[62:63] op_sel_hi:[0,1]
	v_pk_mul_f32 v[50:51], v[52:53], v[50:51] op_sel_hi:[0,1]
	v_lshlrev_b32_e32 v66, 16, v49
	v_and_b32_e32 v67, 0xffff0000, v49
	v_pk_fma_f32 v[54:55], v[54:55], v[62:63], v[58:59]
	v_pk_fma_f32 v[50:51], v[56:57], v[50:51], v[60:61]
	v_pk_add_f32 v[54:55], v[54:55], v[66:67]
	v_pk_add_f32 v[50:51], v[50:51], v[68:69]
	v_cvt_pk_bf16_f32 v52, v54, v55
	v_cvt_pk_bf16_f32 v53, v50, v51
	ds_write_b64 v19, v[52:53] offset:16720
	v_add_u32_e32 v54, 0x254c0, v27
	v_add_u32_e32 v49, 0x250c0, v27
	ds_read_b64 v[58:59], v19 offset:96
	ds_read_b128 v[50:53], v49
	ds_read_b128 v[54:57], v54
	ds_read_b32 v60, v29
	ds_read_b32 v62, v30
	ds_read_b64 v[64:65], v19 offset:16736
	s_waitcnt lgkmcnt(5)
	v_lshlrev_b32_e32 v66, 16, v58
	v_and_b32_e32 v67, 0xffff0000, v58
	v_lshlrev_b32_e32 v58, 16, v59
	v_and_b32_e32 v59, 0xffff0000, v59
	v_lshlrev_b32_e32 v70, 16, v48
	v_and_b32_e32 v71, 0xffff0000, v48
	s_waitcnt lgkmcnt(2)
	v_pk_add_f32 v[48:49], v[66:67], v[60:61] op_sel_hi:[1,0] neg_lo:[0,1] neg_hi:[0,1]
	v_pk_add_f32 v[58:59], v[58:59], v[60:61] op_sel_hi:[1,0] neg_lo:[0,1] neg_hi:[0,1]
	s_waitcnt lgkmcnt(1)
	v_pk_mul_f32 v[48:49], v[62:63], v[48:49] op_sel_hi:[0,1]
	v_pk_mul_f32 v[58:59], v[62:63], v[58:59] op_sel_hi:[0,1]
	v_lshlrev_b32_e32 v68, 16, v46
	v_and_b32_e32 v69, 0xffff0000, v46
	v_pk_fma_f32 v[48:49], v[50:51], v[48:49], v[54:55]
	v_pk_fma_f32 v[58:59], v[52:53], v[58:59], v[56:57]
	v_pk_add_f32 v[48:49], v[48:49], v[68:69]
	v_pk_add_f32 v[58:59], v[58:59], v[70:71]
	v_cvt_pk_bf16_f32 v48, v48, v49
	v_cvt_pk_bf16_f32 v49, v58, v59
	ds_write_b64 v19, v[48:49] offset:96
	ds_read_b32 v46, v31
	ds_read_b32 v48, v33
	s_waitcnt lgkmcnt(3)
	v_lshlrev_b32_e32 v58, 16, v64
	v_and_b32_e32 v59, 0xffff0000, v64
	v_lshlrev_b32_e32 v60, 16, v65
	v_and_b32_e32 v61, 0xffff0000, v65
	v_lshlrev_b32_e32 v64, 16, v47
	v_and_b32_e32 v65, 0xffff0000, v47
	s_waitcnt lgkmcnt(1)
	v_pk_add_f32 v[58:59], v[58:59], v[46:47] op_sel_hi:[1,0] neg_lo:[0,1] neg_hi:[0,1]
	v_pk_add_f32 v[46:47], v[60:61], v[46:47] op_sel_hi:[1,0] neg_lo:[0,1] neg_hi:[0,1]
	s_waitcnt lgkmcnt(0)
	v_pk_mul_f32 v[58:59], v[48:49], v[58:59] op_sel_hi:[0,1]
	v_pk_mul_f32 v[46:47], v[48:49], v[46:47] op_sel_hi:[0,1]
	v_lshlrev_b32_e32 v62, 16, v45
	v_and_b32_e32 v63, 0xffff0000, v45
	v_pk_fma_f32 v[50:51], v[50:51], v[58:59], v[54:55]
	v_pk_fma_f32 v[46:47], v[52:53], v[46:47], v[56:57]
	v_pk_add_f32 v[50:51], v[50:51], v[62:63]
	v_pk_add_f32 v[46:47], v[46:47], v[64:65]
	v_cvt_pk_bf16_f32 v48, v50, v51
	v_cvt_pk_bf16_f32 v49, v46, v47
	ds_write_b64 v19, v[48:49] offset:16736
	v_add_u32_e32 v50, 0x254e0, v27
	v_add_u32_e32 v45, 0x250e0, v27
	ds_read_b64 v[54:55], v19 offset:112
	ds_read_b128 v[46:49], v45
	ds_read_b128 v[50:53], v50
	ds_read_b32 v56, v29
	ds_read_b32 v58, v30
	ds_read_b64 v[60:61], v19 offset:16752
	s_waitcnt lgkmcnt(5)
	v_lshlrev_b32_e32 v62, 16, v54
	v_and_b32_e32 v63, 0xffff0000, v54
	v_lshlrev_b32_e32 v54, 16, v55
	v_and_b32_e32 v55, 0xffff0000, v55
	v_lshlrev_b32_e32 v66, 16, v44
	v_and_b32_e32 v67, 0xffff0000, v44
	s_waitcnt lgkmcnt(2)
	v_pk_add_f32 v[44:45], v[62:63], v[56:57] op_sel_hi:[1,0] neg_lo:[0,1] neg_hi:[0,1]
	v_pk_add_f32 v[54:55], v[54:55], v[56:57] op_sel_hi:[1,0] neg_lo:[0,1] neg_hi:[0,1]
	s_waitcnt lgkmcnt(1)
	v_pk_mul_f32 v[44:45], v[58:59], v[44:45] op_sel_hi:[0,1]
	v_pk_mul_f32 v[54:55], v[58:59], v[54:55] op_sel_hi:[0,1]
	v_lshlrev_b32_e32 v64, 16, v42
	v_and_b32_e32 v65, 0xffff0000, v42
	v_pk_fma_f32 v[44:45], v[46:47], v[44:45], v[50:51]
	v_pk_fma_f32 v[54:55], v[48:49], v[54:55], v[52:53]
	v_pk_add_f32 v[44:45], v[44:45], v[64:65]
	v_pk_add_f32 v[54:55], v[54:55], v[66:67]
	v_cvt_pk_bf16_f32 v44, v44, v45
	v_cvt_pk_bf16_f32 v45, v54, v55
	ds_write_b64 v19, v[44:45] offset:112
	ds_read_b32 v42, v31
	ds_read_b32 v44, v33
	s_waitcnt lgkmcnt(3)
	v_lshlrev_b32_e32 v54, 16, v60
	v_and_b32_e32 v55, 0xffff0000, v60
	v_lshlrev_b32_e32 v56, 16, v61
	v_and_b32_e32 v57, 0xffff0000, v61
	v_lshlrev_b32_e32 v60, 16, v43
	v_and_b32_e32 v61, 0xffff0000, v43
	s_waitcnt lgkmcnt(1)
	v_pk_add_f32 v[54:55], v[54:55], v[42:43] op_sel_hi:[1,0] neg_lo:[0,1] neg_hi:[0,1]
	v_pk_add_f32 v[42:43], v[56:57], v[42:43] op_sel_hi:[1,0] neg_lo:[0,1] neg_hi:[0,1]
	s_waitcnt lgkmcnt(0)
; DI unsigned pack2(float a, float b) { f32x2_t v = {a, b}; bf16x2_t r = __builtin_convertvector(v, bf16x2_t); return __builtin_bit_cast(unsigned, r); }
; DI float bflo(unsigned u) { return __uint_as_float(u << 16); }
; DI float bfhi(unsigned u) { return __uint_as_float(u & 0xffff0000u); }
; template <bool LAST>
; DI void phase_gate(const Params& P, int layer, unsigned char* smem, int L, int G) {
;     ...
; #pragma unroll
;     for (int i = 0; i < 4; ++i)
; #pragma unroll
;       for (int q4 = 0; q4 < 4; ++q4) {
;         const int fl = wm2 * 128 + i * 32 + 8 * q4 + 4 * h2;
;         const int f0 = nt * 256 + fl;
;         const f32x4 gv = *(const f32x4*)(vecL + 512 + fl), bv = *(const f32x4*)(vecL + 768 + fl);
;         const float ga[4] = {gv.x, gv.y, gv.z, gv.w}, ba[4] = {bv.x, bv.y, bv.z, bv.w};
; #pragma unroll
;         for (int j = 0; j < 2; ++j) {
;           const int lrow = wn2 * 64 + j * 32 + r2;
;           const float mu = rowA[lrow], rstd = rowB[lrow];
;           uint2* sp = (uint2*)(stg + lrow * STG + fl);
;           const uint2 sv = *sp;
;           const float sa[4] = {bflo(sv.x), bfhi(sv.x), bflo(sv.y), bfhi(sv.y)};
;           float y[4];
;           const float gg[4] = {bflo(gq[i][j][2 * q4]), bfhi(gq[i][j][2 * q4]), bflo(gq[i][j][2 * q4 + 1]), bfhi(gq[i][j][2 * q4 + 1])};
; #pragma unroll
;           for (int e = 0; e < 4; ++e) y[e] = (sa[e] - mu) * rstd * ga[e] + ba[e] + gg[e];
;           if (LAST) { f32x4 o = {y[0], y[1], y[2], y[3]}; *(f32x4*)(P.out + (size_t)(mt * 256 + lrow) * 1024 + f0) = o; }
;           else { uint2 pk; pk.x = pack2(y[0], y[1]); pk.y = pack2(y[2], y[3]); *sp = pk; }
;         }
;         __builtin_amdgcn_sched_barrier(0);
;       }
	v_pk_mul_f32 v[54:55], v[44:45], v[54:55] op_sel_hi:[0,1]
	v_pk_mul_f32 v[42:43], v[44:45], v[42:43] op_sel_hi:[0,1]
	v_lshlrev_b32_e32 v58, 16, v41
	v_and_b32_e32 v59, 0xffff0000, v41
	v_pk_fma_f32 v[46:47], v[46:47], v[54:55], v[50:51]
	v_pk_fma_f32 v[42:43], v[48:49], v[42:43], v[52:53]
	v_pk_add_f32 v[46:47], v[46:47], v[58:59]
	v_pk_add_f32 v[42:43], v[42:43], v[60:61]
	v_cvt_pk_bf16_f32 v44, v46, v47
	v_cvt_pk_bf16_f32 v45, v42, v43
	ds_write_b64 v19, v[44:45] offset:16752
	v_add_u32_e32 v46, 0x25500, v27
	v_add_u32_e32 v41, 0x25100, v27
	ds_read_b64 v[50:51], v19 offset:128
	ds_read_b128 v[42:45], v41
	ds_read_b128 v[46:49], v46
	ds_read_b32 v52, v29
	ds_read_b32 v54, v30
	ds_read_b64 v[56:57], v19 offset:16768
	s_waitcnt lgkmcnt(5)
	v_lshlrev_b32_e32 v58, 16, v50
	v_and_b32_e32 v59, 0xffff0000, v50
	v_lshlrev_b32_e32 v50, 16, v51
	v_and_b32_e32 v51, 0xffff0000, v51
	v_lshlrev_b32_e32 v62, 16, v40
	v_and_b32_e32 v63, 0xffff0000, v40
	s_waitcnt lgkmcnt(2)
	v_pk_add_f32 v[40:41], v[58:59], v[52:53] op_sel_hi:[1,0] neg_lo:[0,1] neg_hi:[0,1]
	v_pk_add_f32 v[50:51], v[50:51], v[52:53] op_sel_hi:[1,0] neg_lo:[0,1] neg_hi:[0,1]
	s_waitcnt lgkmcnt(1)
	v_pk_mul_f32 v[40:41], v[54:55], v[40:41] op_sel_hi:[0,1]
	v_pk_mul_f32 v[50:51], v[54:55], v[50:51] op_sel_hi:[0,1]
	v_lshlrev_b32_e32 v60, 16, v38
	v_and_b32_e32 v61, 0xffff0000, v38
	v_pk_fma_f32 v[40:41], v[42:43], v[40:41], v[46:47]
	v_pk_fma_f32 v[50:51], v[44:45], v[50:51], v[48:49]
	v_pk_add_f32 v[40:41], v[40:41], v[60:61]
	v_pk_add_f32 v[50:51], v[50:51], v[62:63]
	v_cvt_pk_bf16_f32 v40, v40, v41
	v_cvt_pk_bf16_f32 v41, v50, v51
	ds_write_b64 v19, v[40:41] offset:128
	ds_read_b32 v38, v31
	ds_read_b32 v40, v33
	s_waitcnt lgkmcnt(3)
	v_lshlrev_b32_e32 v50, 16, v56
	v_and_b32_e32 v51, 0xffff0000, v56
	v_lshlrev_b32_e32 v52, 16, v57
	v_and_b32_e32 v53, 0xffff0000, v57
	v_lshlrev_b32_e32 v56, 16, v39
	v_and_b32_e32 v57, 0xffff0000, v39
	s_waitcnt lgkmcnt(1)
	v_pk_add_f32 v[50:51], v[50:51], v[38:39] op_sel_hi:[1,0] neg_lo:[0,1] neg_hi:[0,1]
	v_pk_add_f32 v[38:39], v[52:53], v[38:39] op_sel_hi:[1,0] neg_lo:[0,1] neg_hi:[0,1]
	s_waitcnt lgkmcnt(0)
	v_pk_mul_f32 v[50:51], v[40:41], v[50:51] op_sel_hi:[0,1]
	v_pk_mul_f32 v[38:39], v[40:41], v[38:39] op_sel_hi:[0,1]
	v_lshlrev_b32_e32 v54, 16, v37
	v_and_b32_e32 v55, 0xffff0000, v37
	v_pk_fma_f32 v[42:43], v[42:43], v[50:51], v[46:47]
	v_pk_fma_f32 v[38:39], v[44:45], v[38:39], v[48:49]
	v_pk_add_f32 v[42:43], v[42:43], v[54:55]
	v_pk_add_f32 v[38:39], v[38:39], v[56:57]
	v_cvt_pk_bf16_f32 v40, v42, v43
	v_cvt_pk_bf16_f32 v41, v38, v39
	ds_write_b64 v19, v[40:41] offset:16768
	v_add_u32_e32 v42, 0x25520, v27
	v_add_u32_e32 v37, 0x25120, v27
	ds_read_b64 v[46:47], v19 offset:144
	ds_read_b128 v[38:41], v37
	ds_read_b128 v[42:45], v42
	ds_read_b32 v48, v29
	ds_read_b32 v50, v30
	ds_read_b64 v[52:53], v19 offset:16784
	s_waitcnt lgkmcnt(5)
	v_lshlrev_b32_e32 v54, 16, v46
	v_and_b32_e32 v55, 0xffff0000, v46
	v_lshlrev_b32_e32 v46, 16, v47
	v_and_b32_e32 v47, 0xffff0000, v47
	v_lshlrev_b32_e32 v58, 16, v36
	v_and_b32_e32 v59, 0xffff0000, v36
	s_waitcnt lgkmcnt(2)
	v_pk_add_f32 v[36:37], v[54:55], v[48:49] op_sel_hi:[1,0] neg_lo:[0,1] neg_hi:[0,1]
	v_pk_add_f32 v[46:47], v[46:47], v[48:49] op_sel_hi:[1,0] neg_lo:[0,1] neg_hi:[0,1]
	s_waitcnt lgkmcnt(1)
	v_pk_mul_f32 v[36:37], v[50:51], v[36:37] op_sel_hi:[0,1]
	v_pk_mul_f32 v[46:47], v[50:51], v[46:47] op_sel_hi:[0,1]
	v_lshlrev_b32_e32 v56, 16, v34
	v_and_b32_e32 v57, 0xffff0000, v34
	v_pk_fma_f32 v[36:37], v[38:39], v[36:37], v[42:43]
	v_pk_fma_f32 v[46:47], v[40:41], v[46:47], v[44:45]
	v_pk_add_f32 v[36:37], v[36:37], v[56:57]
	v_pk_add_f32 v[46:47], v[46:47], v[58:59]
	v_cvt_pk_bf16_f32 v36, v36, v37
	v_cvt_pk_bf16_f32 v37, v46, v47
	ds_write_b64 v19, v[36:37] offset:144
	ds_read_b32 v34, v31
	ds_read_b32 v36, v33
	s_waitcnt lgkmcnt(3)
	v_lshlrev_b32_e32 v46, 16, v52
	v_and_b32_e32 v47, 0xffff0000, v52
	v_lshlrev_b32_e32 v48, 16, v53
	v_and_b32_e32 v49, 0xffff0000, v53
	v_lshlrev_b32_e32 v52, 16, v35
	v_and_b32_e32 v53, 0xffff0000, v35
	s_waitcnt lgkmcnt(1)
	v_pk_add_f32 v[46:47], v[46:47], v[34:35] op_sel_hi:[1,0] neg_lo:[0,1] neg_hi:[0,1]
	v_pk_add_f32 v[34:35], v[48:49], v[34:35] op_sel_hi:[1,0] neg_lo:[0,1] neg_hi:[0,1]
	s_waitcnt lgkmcnt(0)
	v_pk_mul_f32 v[46:47], v[36:37], v[46:47] op_sel_hi:[0,1]
	v_pk_mul_f32 v[34:35], v[36:37], v[34:35] op_sel_hi:[0,1]
	v_lshlrev_b32_e32 v50, 16, v32
	v_and_b32_e32 v51, 0xffff0000, v32
	v_pk_fma_f32 v[38:39], v[38:39], v[46:47], v[42:43]
	v_pk_fma_f32 v[34:35], v[40:41], v[34:35], v[44:45]
	v_pk_add_f32 v[38:39], v[38:39], v[50:51]
	v_pk_add_f32 v[34:35], v[34:35], v[52:53]
	v_cvt_pk_bf16_f32 v36, v38, v39
	v_cvt_pk_bf16_f32 v37, v34, v35
	ds_write_b64 v19, v[36:37] offset:16784
	v_add_u32_e32 v32, 0x25140, v27
	v_add_u32_e32 v38, 0x25540, v27
	ds_read_b64 v[42:43], v19 offset:160
	ds_read_b128 v[34:37], v32
	ds_read_b128 v[38:41], v38
	ds_read_b32 v32, v29
	ds_read_b32 v44, v30
	ds_read_b64 v[46:47], v19 offset:16800
	s_waitcnt lgkmcnt(5)
	v_lshlrev_b32_e32 v48, 16, v42
	v_and_b32_e32 v49, 0xffff0000, v42
	v_lshlrev_b32_e32 v42, 16, v43
	v_and_b32_e32 v43, 0xffff0000, v43
	s_waitcnt lgkmcnt(2)
	v_pk_add_f32 v[48:49], v[48:49], v[32:33] op_sel_hi:[1,0] neg_lo:[0,1] neg_hi:[0,1]
	v_pk_add_f32 v[42:43], v[42:43], v[32:33] op_sel_hi:[1,0] neg_lo:[0,1] neg_hi:[0,1]
	s_waitcnt lgkmcnt(1)
; DI unsigned pack2(float a, float b) { f32x2_t v = {a, b}; bf16x2_t r = __builtin_convertvector(v, bf16x2_t); return __builtin_bit_cast(unsigned, r); }
; DI float bflo(unsigned u) { return __uint_as_float(u << 16); }
; DI float bfhi(unsigned u) { return __uint_as_float(u & 0xffff0000u); }
; template <bool LAST>
; DI void phase_gate(const Params& P, int layer, unsigned char* smem, int L, int G) {
;     ...
; #pragma unroll
;     for (int i = 0; i < 4; ++i)
; #pragma unroll
;       for (int q4 = 0; q4 < 4; ++q4) {
;         const int fl = wm2 * 128 + i * 32 + 8 * q4 + 4 * h2;
;         const int f0 = nt * 256 + fl;
;         const f32x4 gv = *(const f32x4*)(vecL + 512 + fl), bv = *(const f32x4*)(vecL + 768 + fl);
;         const float ga[4] = {gv.x, gv.y, gv.z, gv.w}, ba[4] = {bv.x, bv.y, bv.z, bv.w};
; #pragma unroll
;         for (int j = 0; j < 2; ++j) {
;           const int lrow = wn2 * 64 + j * 32 + r2;
;           const float mu = rowA[lrow], rstd = rowB[lrow];
;           uint2* sp = (uint2*)(stg + lrow * STG + fl);
;           const uint2 sv = *sp;
;           const float sa[4] = {bflo(sv.x), bfhi(sv.x), bflo(sv.y), bfhi(sv.y)};
;           float y[4];
;           const float gg[4] = {bflo(gq[i][j][2 * q4]), bfhi(gq[i][j][2 * q4]), bflo(gq[i][j][2 * q4 + 1]), bfhi(gq[i][j][2 * q4 + 1])};
; #pragma unroll
;           for (int e = 0; e < 4; ++e) y[e] = (sa[e] - mu) * rstd * ga[e] + ba[e] + gg[e];
;           if (LAST) { f32x4 o = {y[0], y[1], y[2], y[3]}; *(f32x4*)(P.out + (size_t)(mt * 256 + lrow) * 1024 + f0) = o; }
;           else { uint2 pk; pk.x = pack2(y[0], y[1]); pk.y = pack2(y[2], y[3]); *sp = pk; }
;         }
;         __builtin_amdgcn_sched_barrier(0);
;       }
	v_pk_mul_f32 v[48:49], v[44:45], v[48:49] op_sel_hi:[0,1]
	v_pk_mul_f32 v[42:43], v[44:45], v[42:43] op_sel_hi:[0,1]
	v_lshlrev_b32_e32 v50, 16, v24
	v_and_b32_e32 v51, 0xffff0000, v24
	v_lshlrev_b32_e32 v52, 16, v26
	v_and_b32_e32 v53, 0xffff0000, v26
	v_pk_fma_f32 v[48:49], v[34:35], v[48:49], v[38:39]
	v_pk_fma_f32 v[42:43], v[36:37], v[42:43], v[40:41]
	v_pk_add_f32 v[48:49], v[48:49], v[50:51]
	v_pk_add_f32 v[42:43], v[42:43], v[52:53]
	v_cvt_pk_bf16_f32 v44, v48, v49
	v_cvt_pk_bf16_f32 v45, v42, v43
	ds_write_b64 v19, v[44:45] offset:160
	ds_read_b32 v24, v31
	ds_read_b32 v26, v33
	s_waitcnt lgkmcnt(3)
	v_lshlrev_b32_e32 v42, 16, v46
	v_and_b32_e32 v43, 0xffff0000, v46
	v_lshlrev_b32_e32 v44, 16, v47
	v_and_b32_e32 v45, 0xffff0000, v47
	v_lshlrev_b32_e32 v48, 16, v25
	v_and_b32_e32 v49, 0xffff0000, v25
	s_waitcnt lgkmcnt(1)
	v_pk_add_f32 v[42:43], v[42:43], v[24:25] op_sel_hi:[1,0] neg_lo:[0,1] neg_hi:[0,1]
	v_pk_add_f32 v[24:25], v[44:45], v[24:25] op_sel_hi:[1,0] neg_lo:[0,1] neg_hi:[0,1]
	s_waitcnt lgkmcnt(0)
	v_pk_mul_f32 v[42:43], v[26:27], v[42:43] op_sel_hi:[0,1]
	v_pk_mul_f32 v[24:25], v[26:27], v[24:25] op_sel_hi:[0,1]
	v_lshlrev_b32_e32 v46, 16, v23
	v_and_b32_e32 v47, 0xffff0000, v23
	v_pk_fma_f32 v[34:35], v[34:35], v[42:43], v[38:39]
	v_pk_fma_f32 v[24:25], v[36:37], v[24:25], v[40:41]
	v_pk_add_f32 v[34:35], v[34:35], v[46:47]
	v_pk_add_f32 v[24:25], v[24:25], v[48:49]
	v_cvt_pk_bf16_f32 v34, v34, v35
	v_cvt_pk_bf16_f32 v35, v24, v25
	ds_write_b64 v19, v[34:35] offset:16800
	v_add_u32_e32 v26, 0x25560, v27
	v_add_u32_e32 v23, 0x25160, v27
	ds_read_b64 v[24:25], v19 offset:176
	ds_read_b128 v[34:37], v23
	ds_read_b128 v[38:41], v26
	ds_read_b32 v26, v29
	ds_read_b32 v32, v30
	ds_read_b64 v[42:43], v19 offset:16816
	s_waitcnt lgkmcnt(5)
	v_lshlrev_b32_e32 v44, 16, v24
	v_and_b32_e32 v45, 0xffff0000, v24
	v_lshlrev_b32_e32 v24, 16, v25
	v_and_b32_e32 v25, 0xffff0000, v25
	v_lshlrev_b32_e32 v48, 16, v22
	v_and_b32_e32 v49, 0xffff0000, v22
	s_waitcnt lgkmcnt(2)
	v_pk_add_f32 v[22:23], v[44:45], v[26:27] op_sel_hi:[1,0] neg_lo:[0,1] neg_hi:[0,1]
	v_pk_add_f32 v[24:25], v[24:25], v[26:27] op_sel_hi:[1,0] neg_lo:[0,1] neg_hi:[0,1]
	s_waitcnt lgkmcnt(1)
	v_pk_mul_f32 v[22:23], v[32:33], v[22:23] op_sel_hi:[0,1]
	v_pk_mul_f32 v[24:25], v[32:33], v[24:25] op_sel_hi:[0,1]
	v_lshlrev_b32_e32 v46, 16, v20
	v_and_b32_e32 v47, 0xffff0000, v20
	v_pk_fma_f32 v[22:23], v[34:35], v[22:23], v[38:39]
	v_pk_fma_f32 v[24:25], v[36:37], v[24:25], v[40:41]
	v_pk_add_f32 v[22:23], v[22:23], v[46:47]
	v_pk_add_f32 v[24:25], v[24:25], v[48:49]
	v_cvt_pk_bf16_f32 v22, v22, v23
	v_cvt_pk_bf16_f32 v23, v24, v25
	ds_write_b64 v19, v[22:23] offset:176
	ds_read_b32 v20, v31
	ds_read_b32 v22, v33
	s_waitcnt lgkmcnt(3)
	v_lshlrev_b32_e32 v24, 16, v42
	v_and_b32_e32 v25, 0xffff0000, v42
	v_lshlrev_b32_e32 v42, 16, v43
	v_and_b32_e32 v43, 0xffff0000, v43
	v_lshlrev_b32_e32 v46, 16, v21
	v_and_b32_e32 v47, 0xffff0000, v21
	s_waitcnt lgkmcnt(1)
	v_pk_add_f32 v[24:25], v[24:25], v[20:21] op_sel_hi:[1,0] neg_lo:[0,1] neg_hi:[0,1]
	v_pk_add_f32 v[20:21], v[42:43], v[20:21] op_sel_hi:[1,0] neg_lo:[0,1] neg_hi:[0,1]
	s_waitcnt lgkmcnt(0)
	v_pk_mul_f32 v[24:25], v[22:23], v[24:25] op_sel_hi:[0,1]
	v_pk_mul_f32 v[20:21], v[22:23], v[20:21] op_sel_hi:[0,1]
	v_lshlrev_b32_e32 v44, 16, v18
	v_and_b32_e32 v45, 0xffff0000, v18
	v_pk_fma_f32 v[24:25], v[34:35], v[24:25], v[38:39]
	v_pk_fma_f32 v[20:21], v[36:37], v[20:21], v[40:41]
	v_pk_add_f32 v[24:25], v[24:25], v[44:45]
	v_pk_add_f32 v[20:21], v[20:21], v[46:47]
	v_cvt_pk_bf16_f32 v22, v24, v25
	v_cvt_pk_bf16_f32 v23, v20, v21
	ds_write_b64 v19, v[22:23] offset:16816
	v_add_u32_e32 v18, 0x25180, v27
	v_add_u32_e32 v26, 0x25580, v27
	ds_read_b64 v[24:25], v19 offset:192
	ds_read_b128 v[20:23], v18
	ds_read_b128 v[34:37], v26
	ds_read_b32 v18, v29
	ds_read_b32 v26, v30
	ds_read_b64 v[38:39], v19 offset:16832
	s_waitcnt lgkmcnt(5)
	v_lshlrev_b32_e32 v40, 16, v24
	v_and_b32_e32 v41, 0xffff0000, v24
	v_lshlrev_b32_e32 v24, 16, v25
	v_and_b32_e32 v25, 0xffff0000, v25
	s_waitcnt lgkmcnt(2)
	v_pk_add_f32 v[40:41], v[40:41], v[18:19] op_sel_hi:[1,0] neg_lo:[0,1] neg_hi:[0,1]
	v_pk_add_f32 v[24:25], v[24:25], v[18:19] op_sel_hi:[1,0] neg_lo:[0,1] neg_hi:[0,1]
	s_waitcnt lgkmcnt(1)
	v_pk_mul_f32 v[40:41], v[26:27], v[40:41] op_sel_hi:[0,1]
	v_pk_mul_f32 v[24:25], v[26:27], v[24:25] op_sel_hi:[0,1]
	v_lshlrev_b32_e32 v42, 16, v15
	v_and_b32_e32 v43, 0xffff0000, v15
	v_lshlrev_b32_e32 v44, 16, v17
	v_and_b32_e32 v45, 0xffff0000, v17
	v_pk_fma_f32 v[40:41], v[20:21], v[40:41], v[34:35]
	v_pk_fma_f32 v[24:25], v[22:23], v[24:25], v[36:37]
	v_pk_add_f32 v[40:41], v[40:41], v[42:43]
	v_pk_add_f32 v[24:25], v[24:25], v[44:45]
	v_cvt_pk_bf16_f32 v40, v40, v41
	v_cvt_pk_bf16_f32 v41, v24, v25
	ds_write_b64 v19, v[40:41] offset:192
	ds_read_b32 v18, v31
	ds_read_b32 v24, v33
	s_waitcnt lgkmcnt(3)
	v_lshlrev_b32_e32 v40, 16, v38
	v_and_b32_e32 v41, 0xffff0000, v38
	v_lshlrev_b32_e32 v42, 16, v14
	v_and_b32_e32 v43, 0xffff0000, v14
	v_lshlrev_b32_e32 v14, 16, v16
	v_and_b32_e32 v15, 0xffff0000, v16
	s_waitcnt lgkmcnt(1)
	v_pk_add_f32 v[16:17], v[40:41], v[18:19] op_sel_hi:[1,0] neg_lo:[0,1] neg_hi:[0,1]
	v_lshlrev_b32_e32 v38, 16, v39
	v_and_b32_e32 v39, 0xffff0000, v39
	s_waitcnt lgkmcnt(0)
; DI unsigned pack2(float a, float b) { f32x2_t v = {a, b}; bf16x2_t r = __builtin_convertvector(v, bf16x2_t); return __builtin_bit_cast(unsigned, r); }
; DI float bflo(unsigned u) { return __uint_as_float(u << 16); }
; DI float bfhi(unsigned u) { return __uint_as_float(u & 0xffff0000u); }
; template <bool LAST>
; DI void phase_gate(const Params& P, int layer, unsigned char* smem, int L, int G) {
;     ...
; #pragma unroll
;     for (int i = 0; i < 4; ++i)
; #pragma unroll
;       for (int q4 = 0; q4 < 4; ++q4) {
;         const int fl = wm2 * 128 + i * 32 + 8 * q4 + 4 * h2;
;         const int f0 = nt * 256 + fl;
;         const f32x4 gv = *(const f32x4*)(vecL + 512 + fl), bv = *(const f32x4*)(vecL + 768 + fl);
;         const float ga[4] = {gv.x, gv.y, gv.z, gv.w}, ba[4] = {bv.x, bv.y, bv.z, bv.w};
; #pragma unroll
;         for (int j = 0; j < 2; ++j) {
;           const int lrow = wn2 * 64 + j * 32 + r2;
;           const float mu = rowA[lrow], rstd = rowB[lrow];
;           uint2* sp = (uint2*)(stg + lrow * STG + fl);
;           const uint2 sv = *sp;
;           const float sa[4] = {bflo(sv.x), bfhi(sv.x), bflo(sv.y), bfhi(sv.y)};
;           float y[4];
;           const float gg[4] = {bflo(gq[i][j][2 * q4]), bfhi(gq[i][j][2 * q4]), bflo(gq[i][j][2 * q4 + 1]), bfhi(gq[i][j][2 * q4 + 1])};
; #pragma unroll
;           for (int e = 0; e < 4; ++e) y[e] = (sa[e] - mu) * rstd * ga[e] + ba[e] + gg[e];
;           if (LAST) { f32x4 o = {y[0], y[1], y[2], y[3]}; *(f32x4*)(P.out + (size_t)(mt * 256 + lrow) * 1024 + f0) = o; }
;           else { uint2 pk; pk.x = pack2(y[0], y[1]); pk.y = pack2(y[2], y[3]); *sp = pk; }
;         }
;         __builtin_amdgcn_sched_barrier(0);
;       }
;     __syncthreads();
	v_pk_mul_f32 v[16:17], v[24:25], v[16:17] op_sel_hi:[0,1]
	v_pk_fma_f32 v[16:17], v[20:21], v[16:17], v[34:35]
	v_pk_add_f32 v[20:21], v[38:39], v[18:19] op_sel_hi:[1,0] neg_lo:[0,1] neg_hi:[0,1]
	v_pk_add_f32 v[16:17], v[16:17], v[42:43]
	v_pk_mul_f32 v[20:21], v[24:25], v[20:21] op_sel_hi:[0,1]
	v_pk_fma_f32 v[20:21], v[22:23], v[20:21], v[36:37]
	v_cvt_pk_bf16_f32 v16, v16, v17
	v_pk_add_f32 v[14:15], v[20:21], v[14:15]
	s_nop 0
	v_cvt_pk_bf16_f32 v17, v14, v15
	ds_write_b64 v19, v[16:17] offset:16832
	v_add_u32_e32 v14, 0x251a0, v27
	v_add_u32_e32 v18, 0x255a0, v27
	ds_read_b64 v[24:25], v19 offset:208
	ds_read_b128 v[14:17], v14
	ds_read_b128 v[20:23], v18
	ds_read_b32 v18, v29
	ds_read_b32 v26, v30
	ds_read_b64 v[34:35], v19 offset:16848
	s_waitcnt lgkmcnt(5)
	v_lshlrev_b32_e32 v36, 16, v24
	v_and_b32_e32 v37, 0xffff0000, v24
	v_lshlrev_b32_e32 v24, 16, v25
	v_and_b32_e32 v25, 0xffff0000, v25
	s_waitcnt lgkmcnt(2)
	v_pk_add_f32 v[36:37], v[36:37], v[18:19] op_sel_hi:[1,0] neg_lo:[0,1] neg_hi:[0,1]
	v_pk_add_f32 v[24:25], v[24:25], v[18:19] op_sel_hi:[1,0] neg_lo:[0,1] neg_hi:[0,1]
	s_waitcnt lgkmcnt(1)
	v_pk_mul_f32 v[36:37], v[26:27], v[36:37] op_sel_hi:[0,1]
	v_pk_mul_f32 v[24:25], v[26:27], v[24:25] op_sel_hi:[0,1]
	v_lshlrev_b32_e32 v38, 16, v11
	v_and_b32_e32 v39, 0xffff0000, v11
	v_lshlrev_b32_e32 v40, 16, v13
	v_and_b32_e32 v41, 0xffff0000, v13
	v_pk_fma_f32 v[36:37], v[14:15], v[36:37], v[20:21]
	v_pk_fma_f32 v[24:25], v[16:17], v[24:25], v[22:23]
	v_pk_add_f32 v[36:37], v[36:37], v[38:39]
	v_pk_add_f32 v[24:25], v[24:25], v[40:41]
	v_cvt_pk_bf16_f32 v36, v36, v37
	v_cvt_pk_bf16_f32 v37, v24, v25
	ds_write_b64 v19, v[36:37] offset:208
	ds_read_b32 v18, v31
	ds_read_b32 v24, v33
	s_waitcnt lgkmcnt(3)
	v_lshlrev_b32_e32 v36, 16, v34
	v_and_b32_e32 v37, 0xffff0000, v34
	v_lshlrev_b32_e32 v38, 16, v10
	v_and_b32_e32 v39, 0xffff0000, v10
	v_lshlrev_b32_e32 v10, 16, v12
	v_and_b32_e32 v11, 0xffff0000, v12
	s_waitcnt lgkmcnt(1)
	v_pk_add_f32 v[12:13], v[36:37], v[18:19] op_sel_hi:[1,0] neg_lo:[0,1] neg_hi:[0,1]
	v_lshlrev_b32_e32 v34, 16, v35
	v_and_b32_e32 v35, 0xffff0000, v35
	s_waitcnt lgkmcnt(0)
	v_pk_mul_f32 v[12:13], v[24:25], v[12:13] op_sel_hi:[0,1]
	v_pk_fma_f32 v[12:13], v[14:15], v[12:13], v[20:21]
	v_pk_add_f32 v[14:15], v[34:35], v[18:19] op_sel_hi:[1,0] neg_lo:[0,1] neg_hi:[0,1]
	v_pk_add_f32 v[12:13], v[12:13], v[38:39]
	v_pk_mul_f32 v[14:15], v[24:25], v[14:15] op_sel_hi:[0,1]
	v_pk_fma_f32 v[14:15], v[16:17], v[14:15], v[22:23]
	v_cvt_pk_bf16_f32 v12, v12, v13
	v_pk_add_f32 v[10:11], v[14:15], v[10:11]
	s_nop 0
	v_cvt_pk_bf16_f32 v13, v10, v11
	ds_write_b64 v19, v[12:13] offset:16848
	v_add_u32_e32 v10, 0x251c0, v27
	v_add_u32_e32 v14, 0x255c0, v27
	ds_read_b64 v[20:21], v19 offset:224
	ds_read_b128 v[10:13], v10
	ds_read_b128 v[14:17], v14
	ds_read_b32 v18, v29
	ds_read_b32 v22, v30
	ds_read_b64 v[24:25], v19 offset:16864
	s_waitcnt lgkmcnt(5)
	v_lshlrev_b32_e32 v34, 16, v20
	v_and_b32_e32 v35, 0xffff0000, v20
	v_lshlrev_b32_e32 v20, 16, v21
	v_and_b32_e32 v21, 0xffff0000, v21
	s_waitcnt lgkmcnt(2)
	v_pk_add_f32 v[34:35], v[34:35], v[18:19] op_sel_hi:[1,0] neg_lo:[0,1] neg_hi:[0,1]
	v_pk_add_f32 v[20:21], v[20:21], v[18:19] op_sel_hi:[1,0] neg_lo:[0,1] neg_hi:[0,1]
	s_waitcnt lgkmcnt(1)
	v_pk_mul_f32 v[34:35], v[22:23], v[34:35] op_sel_hi:[0,1]
	v_pk_mul_f32 v[20:21], v[22:23], v[20:21] op_sel_hi:[0,1]
	v_lshlrev_b32_e32 v36, 16, v7
	v_and_b32_e32 v37, 0xffff0000, v7
	v_lshlrev_b32_e32 v38, 16, v9
	v_and_b32_e32 v39, 0xffff0000, v9
	v_pk_fma_f32 v[34:35], v[10:11], v[34:35], v[14:15]
	v_pk_fma_f32 v[20:21], v[12:13], v[20:21], v[16:17]
	v_pk_add_f32 v[34:35], v[34:35], v[36:37]
	v_pk_add_f32 v[20:21], v[20:21], v[38:39]
	v_cvt_pk_bf16_f32 v22, v34, v35
	v_cvt_pk_bf16_f32 v23, v20, v21
	ds_write_b64 v19, v[22:23] offset:224
	ds_read_b32 v18, v31
	ds_read_b32 v20, v33
	s_waitcnt lgkmcnt(3)
	v_lshlrev_b32_e32 v22, 16, v24
	v_and_b32_e32 v23, 0xffff0000, v24
	v_lshlrev_b32_e32 v34, 16, v6
	v_and_b32_e32 v35, 0xffff0000, v6
	v_lshlrev_b32_e32 v6, 16, v8
	v_and_b32_e32 v7, 0xffff0000, v8
	s_waitcnt lgkmcnt(1)
	v_pk_add_f32 v[8:9], v[22:23], v[18:19] op_sel_hi:[1,0] neg_lo:[0,1] neg_hi:[0,1]
	v_lshlrev_b32_e32 v24, 16, v25
	v_and_b32_e32 v25, 0xffff0000, v25
	s_waitcnt lgkmcnt(0)
	v_pk_mul_f32 v[8:9], v[20:21], v[8:9] op_sel_hi:[0,1]
	v_pk_fma_f32 v[8:9], v[10:11], v[8:9], v[14:15]
	v_pk_add_f32 v[10:11], v[24:25], v[18:19] op_sel_hi:[1,0] neg_lo:[0,1] neg_hi:[0,1]
	v_pk_add_f32 v[8:9], v[8:9], v[34:35]
	v_pk_mul_f32 v[10:11], v[20:21], v[10:11] op_sel_hi:[0,1]
	v_pk_fma_f32 v[10:11], v[12:13], v[10:11], v[16:17]
	v_cvt_pk_bf16_f32 v8, v8, v9
	v_pk_add_f32 v[6:7], v[10:11], v[6:7]
	s_nop 0
	v_cvt_pk_bf16_f32 v9, v6, v7
	ds_write_b64 v19, v[8:9] offset:16864
	ds_read_b128 v[6:9], v28 offset:480
	ds_read_b64 v[14:15], v19 offset:240
	ds_read_b32 v16, v29
	ds_read_b32 v18, v30
	v_add_u32_e32 v10, 0x255e0, v27
	ds_read_b128 v[10:13], v10
	s_waitcnt lgkmcnt(3)
	v_lshlrev_b32_e32 v20, 16, v14
	v_and_b32_e32 v21, 0xffff0000, v14
	v_lshlrev_b32_e32 v14, 16, v15
	v_and_b32_e32 v15, 0xffff0000, v15
	s_waitcnt lgkmcnt(2)
	v_pk_add_f32 v[20:21], v[20:21], v[16:17] op_sel_hi:[1,0] neg_lo:[0,1] neg_hi:[0,1]
	v_pk_add_f32 v[14:15], v[14:15], v[16:17] op_sel_hi:[1,0] neg_lo:[0,1] neg_hi:[0,1]
	s_waitcnt lgkmcnt(1)
	v_pk_mul_f32 v[20:21], v[18:19], v[20:21] op_sel_hi:[0,1]
	v_pk_mul_f32 v[14:15], v[18:19], v[14:15] op_sel_hi:[0,1]
	v_lshlrev_b32_e32 v22, 16, v4
	v_and_b32_e32 v23, 0xffff0000, v4
	v_lshlrev_b32_e32 v4, 16, v5
	v_and_b32_e32 v5, 0xffff0000, v5
	s_waitcnt lgkmcnt(0)
	v_pk_fma_f32 v[20:21], v[6:7], v[20:21], v[10:11]
	v_pk_fma_f32 v[14:15], v[8:9], v[14:15], v[12:13]
	v_pk_add_f32 v[20:21], v[20:21], v[22:23]
	v_pk_add_f32 v[4:5], v[14:15], v[4:5]
	v_cvt_pk_bf16_f32 v14, v20, v21
	v_cvt_pk_bf16_f32 v15, v4, v5
	ds_write_b64 v19, v[14:15] offset:240
	ds_read_b32 v4, v33
	ds_read_b64 v[14:15], v19 offset:16880
	ds_read_b32 v16, v31
	v_lshlrev_b32_e32 v22, 16, v2
	v_and_b32_e32 v23, 0xffff0000, v2
	v_lshlrev_b32_e32 v2, 16, v3
	s_waitcnt lgkmcnt(1)
	v_lshlrev_b32_e32 v20, 16, v14
	v_and_b32_e32 v21, 0xffff0000, v14
	s_waitcnt lgkmcnt(0)
	v_pk_add_f32 v[20:21], v[20:21], v[16:17] op_sel_hi:[1,0] neg_lo:[0,1] neg_hi:[0,1]
	v_lshlrev_b32_e32 v14, 16, v15
	v_and_b32_e32 v15, 0xffff0000, v15
	v_pk_mul_f32 v[20:21], v[4:5], v[20:21] op_sel_hi:[0,1]
	v_pk_fma_f32 v[6:7], v[6:7], v[20:21], v[10:11]
	v_pk_add_f32 v[10:11], v[14:15], v[16:17] op_sel_hi:[1,0] neg_lo:[0,1] neg_hi:[0,1]
	v_and_b32_e32 v3, 0xffff0000, v3
	v_pk_mul_f32 v[4:5], v[4:5], v[10:11] op_sel_hi:[0,1]
	v_pk_fma_f32 v[4:5], v[8:9], v[4:5], v[12:13]
	v_pk_add_f32 v[6:7], v[6:7], v[22:23]
	v_pk_add_f32 v[2:3], v[4:5], v[2:3]
	v_cvt_pk_bf16_f32 v4, v6, v7
	v_cvt_pk_bf16_f32 v5, v2, v3
	ds_write_b64 v19, v[4:5] offset:16880
	s_add_u32 s24, s80, s24
	s_addc_u32 s25, s81, s25
	v_lshl_add_u64 v[8:9], s[24:25], 0, v[0:1]
	v_mov_b32_e32 v0, v192
	s_waitcnt lgkmcnt(0)
	s_barrier
; DI int otid() { int t = threadIdx.x; asm volatile("" : "+v"(t)); return t; }
; DI void stg16_nt(void* p, u32x4 v) { __builtin_nontemporal_store(v, (u32x4*)p); }
; DI void stage_store_tile(const bf16_t* stg, bf16_t* tilebase) {
;   const int tid = otid();
;   const int r0 = tid >> 5, c = tid & 31;
;   const unsigned o0 = (unsigned)(r0 * 1024 + c * 8);
; #pragma unroll
;   for (int it = 0; it < 16; ++it) stg16_nt(tilebase + (o0 + (unsigned)(it * 16 * 1024)), stage_read16(stg, r0 + 16 * it, c));
; }
; template <bool LAST>
; DI void phase_gate(const Params& P, int layer, unsigned char* smem, int L, int G) {
;     ...
;     if (!LAST) stage_store_tile(stg, xb + (size_t)mt * 256 * 1024 + nt * 256);
	s_mov_b64 s[100:101], 0x8000
	s_add_i32 s36, s36, s74
	s_add_i32 s33, s33, s69
	s_add_i32 s34, s34, s35
	s_add_i32 s24, s70, s36
	s_cmpk_lt_i32 s24, 0x400
	v_ashrrev_i32_e32 v190, 5, v192
	v_and_b32_e32 v191, 31, v192
	v_mul_lo_u32 v252, v190, s44
	v_lshl_add_u32 v252, v191, 4, v252
	v_lshlrev_b32_e32 v191, 3, v191
	v_lshl_or_b32 v254, v190, 10, v191
	v_mov_b32_e32 v255, v161
	ds_read2_b64 v[218:221], v252 offset1:1
	v_add_u32_e32 v253, 0x2080, v252
	ds_read2_b64 v[222:225], v253 offset1:1
	v_add_u32_e32 v253, 0x4100, v252
	ds_read2_b64 v[226:229], v253 offset1:1
	v_add_u32_e32 v253, 0x6180, v252
	ds_read2_b64 v[230:233], v253 offset1:1
	v_add_u32_e32 v253, 0x8200, v252
	ds_read2_b64 v[234:237], v253 offset1:1
	v_add_u32_e32 v253, 0xa280, v252
	ds_read2_b64 v[238:241], v253 offset1:1
	v_add_u32_e32 v253, 0xc300, v252
	ds_read2_b64 v[242:245], v253 offset1:1
	v_add_u32_e32 v253, 0xe380, v252
	ds_read2_b64 v[248:251], v253 offset1:1
	v_lshl_add_u64 v[254:255], v[254:255], 1, v[8:9]
	s_waitcnt lgkmcnt(7)
	global_store_dwordx4 v[254:255], v[218:221], off nt
	v_add_u32_e32 v253, 0x10400, v252
	ds_read2_b64 v[218:221], v253 offset1:1
	v_lshl_add_u64 v[254:255], v[254:255], 0, s[100:101]
	s_waitcnt lgkmcnt(7)
	global_store_dwordx4 v[254:255], v[222:225], off nt
	v_add_u32_e32 v253, 0x12480, v252
	ds_read2_b64 v[222:225], v253 offset1:1
	v_lshl_add_u64 v[254:255], v[254:255], 0, s[100:101]
	s_waitcnt lgkmcnt(7)
	global_store_dwordx4 v[254:255], v[226:229], off nt
	v_add_u32_e32 v253, 0x14500, v252
	ds_read2_b64 v[226:229], v253 offset1:1
	v_lshl_add_u64 v[254:255], v[254:255], 0, s[100:101]
	s_waitcnt lgkmcnt(7)
	global_store_dwordx4 v[254:255], v[230:233], off nt
	v_add_u32_e32 v253, 0x16580, v252
	ds_read2_b64 v[230:233], v253 offset1:1
	v_lshl_add_u64 v[254:255], v[254:255], 0, s[100:101]
	s_waitcnt lgkmcnt(7)
	global_store_dwordx4 v[254:255], v[234:237], off nt
	v_add_u32_e32 v253, 0x18600, v252
	ds_read2_b64 v[234:237], v253 offset1:1
	v_lshl_add_u64 v[254:255], v[254:255], 0, s[100:101]
	s_waitcnt lgkmcnt(7)
	global_store_dwordx4 v[254:255], v[238:241], off nt
	v_add_u32_e32 v253, 0x1a680, v252
	ds_read2_b64 v[238:241], v253 offset1:1
	v_lshl_add_u64 v[254:255], v[254:255], 0, s[100:101]
	s_waitcnt lgkmcnt(7)
	global_store_dwordx4 v[254:255], v[242:245], off nt
	v_add_u32_e32 v253, 0x1c700, v252
	ds_read2_b64 v[242:245], v253 offset1:1
	v_lshl_add_u64 v[254:255], v[254:255], 0, s[100:101]
	s_waitcnt lgkmcnt(7)
	global_store_dwordx4 v[254:255], v[248:251], off nt
	v_add_u32_e32 v253, 0x1e780, v252
	ds_read2_b64 v[248:251], v253 offset1:1
	v_lshl_add_u64 v[254:255], v[254:255], 0, s[100:101]
	s_waitcnt lgkmcnt(7)
	global_store_dwordx4 v[254:255], v[218:221], off nt
	v_lshl_add_u64 v[254:255], v[254:255], 0, s[100:101]
	s_waitcnt lgkmcnt(6)
	global_store_dwordx4 v[254:255], v[222:225], off nt
	v_lshl_add_u64 v[254:255], v[254:255], 0, s[100:101]
	s_waitcnt lgkmcnt(5)
	global_store_dwordx4 v[254:255], v[226:229], off nt
	v_lshl_add_u64 v[254:255], v[254:255], 0, s[100:101]
	s_waitcnt lgkmcnt(4)
	global_store_dwordx4 v[254:255], v[230:233], off nt
	v_lshl_add_u64 v[254:255], v[254:255], 0, s[100:101]
	s_waitcnt lgkmcnt(3)
	global_store_dwordx4 v[254:255], v[234:237], off nt
	v_lshl_add_u64 v[254:255], v[254:255], 0, s[100:101]
	s_waitcnt lgkmcnt(2)
	global_store_dwordx4 v[254:255], v[238:241], off nt
	v_lshl_add_u64 v[254:255], v[254:255], 0, s[100:101]
	s_waitcnt lgkmcnt(1)
	global_store_dwordx4 v[254:255], v[242:245], off nt
	v_lshl_add_u64 v[254:255], v[254:255], 0, s[100:101]
	s_waitcnt lgkmcnt(0)
	global_store_dwordx4 v[254:255], v[248:251], off nt
	s_barrier
	s_cbranch_scc0 .LBB0_488

; DI int otid() { int t = threadIdx.x; asm volatile("" : "+v"(t)); return t; }
; DI void stg16_nt(void* p, u32x4 v) { __builtin_nontemporal_store(v, (u32x4*)p); }
; DI void stage_store_tile(const bf16_t* stg, bf16_t* tilebase) {
;   const int tid = otid();
;   const int r0 = tid >> 5, c = tid & 31;
;   const unsigned o0 = (unsigned)(r0 * 1024 + c * 8);
; #pragma unroll
;   for (int it = 0; it < 16; ++it) stg16_nt(tilebase + (o0 + (unsigned)(it * 16 * 1024)), stage_read16(stg, r0 + 16 * it, c));
; }
; template <bool XF32>
; DI void phase_outproj(const Params& P, int layer, const void* xres, const bf16_t* og, unsigned char* smem, int L, int G) {
;     ...
;     __syncthreads();
;     stage_store_tile(stg, Sb + (size_t)mt * 256 * 1024 + nt * 256);
;     __syncthreads();
.LBB0_847:
	s_or_b64 exec, exec, s[20:21]
	v_mov_b32_e32 v0, v192
	s_waitcnt lgkmcnt(0)
	s_barrier
	s_mov_b64 s[100:101], 0x8000
	s_lshl_b64 s[14:15], s[14:15], 18
	s_lshl_b64 s[14:15], s[14:15], 1
	s_add_u32 s14, s76, s14
	s_addc_u32 s15, s77, s15
	s_add_u32 s14, s14, s34
	s_addc_u32 s15, s15, 0
	s_add_i32 s25, s25, s69
	s_andn2_b64 vcc, exec, s[18:19]
	s_add_i32 s26, s26, s23
	v_ashrrev_i32_e32 v190, 5, v192
	v_and_b32_e32 v191, 31, v192
	v_mul_lo_u32 v252, v190, s29
	v_lshl_add_u32 v252, v191, 4, v252
	v_lshlrev_b32_e32 v191, 3, v191
	v_lshl_or_b32 v254, v190, 10, v191
	v_mov_b32_e32 v255, v161
	ds_read2_b64 v[218:221], v252 offset1:1
	v_add_u32_e32 v253, 0x2080, v252
	ds_read2_b64 v[222:225], v253 offset1:1
	v_add_u32_e32 v253, 0x4100, v252
	ds_read2_b64 v[226:229], v253 offset1:1
	v_add_u32_e32 v253, 0x6180, v252
	ds_read2_b64 v[230:233], v253 offset1:1
	v_add_u32_e32 v253, 0x8200, v252
	ds_read2_b64 v[234:237], v253 offset1:1
	v_add_u32_e32 v253, 0xa280, v252
	ds_read2_b64 v[238:241], v253 offset1:1
	v_add_u32_e32 v253, 0xc300, v252
	ds_read2_b64 v[242:245], v253 offset1:1
	v_add_u32_e32 v253, 0xe380, v252
	ds_read2_b64 v[248:251], v253 offset1:1
	v_lshl_add_u64 v[254:255], v[254:255], 1, s[14:15]
	s_waitcnt lgkmcnt(7)
	global_store_dwordx4 v[254:255], v[218:221], off nt
	v_add_u32_e32 v253, 0x10400, v252
	ds_read2_b64 v[218:221], v253 offset1:1
	v_lshl_add_u64 v[254:255], v[254:255], 0, s[100:101]
	s_waitcnt lgkmcnt(7)
	global_store_dwordx4 v[254:255], v[222:225], off nt
	v_add_u32_e32 v253, 0x12480, v252
	ds_read2_b64 v[222:225], v253 offset1:1
	v_lshl_add_u64 v[254:255], v[254:255], 0, s[100:101]
	s_waitcnt lgkmcnt(7)
	global_store_dwordx4 v[254:255], v[226:229], off nt
	v_add_u32_e32 v253, 0x14500, v252
	ds_read2_b64 v[226:229], v253 offset1:1
	v_lshl_add_u64 v[254:255], v[254:255], 0, s[100:101]
	s_waitcnt lgkmcnt(7)
	global_store_dwordx4 v[254:255], v[230:233], off nt
	v_add_u32_e32 v253, 0x16580, v252
	ds_read2_b64 v[230:233], v253 offset1:1
	v_lshl_add_u64 v[254:255], v[254:255], 0, s[100:101]
	s_waitcnt lgkmcnt(7)
	global_store_dwordx4 v[254:255], v[234:237], off nt
	v_add_u32_e32 v253, 0x18600, v252
	ds_read2_b64 v[234:237], v253 offset1:1
	v_lshl_add_u64 v[254:255], v[254:255], 0, s[100:101]
	s_waitcnt lgkmcnt(7)
	global_store_dwordx4 v[254:255], v[238:241], off nt
	v_add_u32_e32 v253, 0x1a680, v252
	ds_read2_b64 v[238:241], v253 offset1:1
	v_lshl_add_u64 v[254:255], v[254:255], 0, s[100:101]
	s_waitcnt lgkmcnt(7)
	global_store_dwordx4 v[254:255], v[242:245], off nt
	v_add_u32_e32 v253, 0x1c700, v252
	ds_read2_b64 v[242:245], v253 offset1:1
	v_lshl_add_u64 v[254:255], v[254:255], 0, s[100:101]
	s_waitcnt lgkmcnt(7)
	global_store_dwordx4 v[254:255], v[248:251], off nt
	v_add_u32_e32 v253, 0x1e780, v252
	ds_read2_b64 v[248:251], v253 offset1:1
	v_lshl_add_u64 v[254:255], v[254:255], 0, s[100:101]
	s_waitcnt lgkmcnt(7)
	global_store_dwordx4 v[254:255], v[218:221], off nt
	v_lshl_add_u64 v[254:255], v[254:255], 0, s[100:101]
	s_waitcnt lgkmcnt(6)
	global_store_dwordx4 v[254:255], v[222:225], off nt
	v_lshl_add_u64 v[254:255], v[254:255], 0, s[100:101]
	s_waitcnt lgkmcnt(5)
	global_store_dwordx4 v[254:255], v[226:229], off nt
	v_lshl_add_u64 v[254:255], v[254:255], 0, s[100:101]
	s_waitcnt lgkmcnt(4)
	global_store_dwordx4 v[254:255], v[230:233], off nt
	v_lshl_add_u64 v[254:255], v[254:255], 0, s[100:101]
	s_waitcnt lgkmcnt(3)
	global_store_dwordx4 v[254:255], v[234:237], off nt
	v_lshl_add_u64 v[254:255], v[254:255], 0, s[100:101]
	s_waitcnt lgkmcnt(2)
	global_store_dwordx4 v[254:255], v[238:241], off nt
	v_lshl_add_u64 v[254:255], v[254:255], 0, s[100:101]
	s_waitcnt lgkmcnt(1)
	global_store_dwordx4 v[254:255], v[242:245], off nt
	v_lshl_add_u64 v[254:255], v[254:255], 0, s[100:101]
	s_waitcnt lgkmcnt(0)
	global_store_dwordx4 v[254:255], v[248:251], off nt
	s_barrier
	s_cbranch_vccz .LBB0_858

; DI unsigned pack2(float a, float b) { f32x2_t v = {a, b}; bf16x2_t r = __builtin_convertvector(v, bf16x2_t); return __builtin_bit_cast(unsigned, r); }
; DI float sigmoidf_(float x) { return __builtin_amdgcn_rcpf(1.f + __expf(-x)); }
; DI int otid() { int t = threadIdx.x; asm volatile("" : "+v"(t)); return t; }
; template <bool NT>
; DI void stage_load_tile(bf16_t* stg, const bf16_t* tilebase) {
;   const int tid = otid();
;   const int r0 = tid >> 5, c = tid & 31;
;   const unsigned o0 = (unsigned)(r0 * 1024 + c * 8);
;   __builtin_amdgcn_sched_barrier(0);
; #pragma unroll
;   for (int hf = 0; hf < 2; ++hf) {
; #pragma unroll
;     for (int it = 8 * hf; it < 8 * hf + 8; ++it) {
;       const u32x4* gp = (const u32x4*)(tilebase + (o0 + (unsigned)(it * 16 * 1024)));
;       stage_write16(stg, r0 + 16 * it, c, NT ? __builtin_nontemporal_load(gp) : *gp);
;     }
;     __builtin_amdgcn_sched_barrier(0);
;   }
; }
; template <bool LAST>
; DI void phase_gate(const Params& P, int layer, unsigned char* smem, int L, int G) {
;     ...
;     unsigned gq[4][2][8];
; #pragma unroll
;     for (int i = 0; i < 4; ++i)
; #pragma unroll
;       for (int q4 = 0; q4 < 4; ++q4) {
;         const int fl = wm * 128 + i * 32 + 8 * q4 + 4 * h;
;         const f32x4 c1v = *(const f32x4*)(vecL + fl), c2v = *(const f32x4*)(vecL + 256 + fl);
;         const float c1a[4] = {c1v.x, c1v.y, c1v.z, c1v.w}, c2a[4] = {c2v.x, c2v.y, c2v.z, c2v.w};
; #pragma unroll
;         for (int j = 0; j < 2; ++j) {
;           const int lrow = wn * 64 + j * 32 + r;
;           const float mu = rowA[lrow], rstd = rowB[lrow];
;           float sg4[4];
; #pragma unroll
;           for (int e = 0; e < 4; ++e) sg4[e] = sigmoidf_(rstd * (accu[i][j][4 * q4 + e] - mu * c1a[e]) + c2a[e]);
;           gq[i][j][2 * q4] = pack2(sg4[0], sg4[1]); gq[i][j][2 * q4 + 1] = pack2(sg4[2], sg4[3]);
;         }
;         __builtin_amdgcn_sched_barrier(0);
;       }
;     stage_load_tile<true>(stg, PPb + (size_t)mt * 256 * 1024 + nt * 256);
.LBB0_920:
	s_ashr_i32 s25, s24, 31
	s_lshl_b64 s[24:25], s[24:25], 19
	s_add_u32 s26, s66, s24
	s_addc_u32 s27, s67, s25
	v_and_b32_e32 v188, 31, v192
	v_ashrrev_i32_e32 v189, 5, v192
	v_lshlrev_b32_e32 v188, 3, v188
	v_lshl_or_b32 v188, v189, 10, v188
	v_add_u32_e32 v188, v188, v162
	v_lshlrev_b32_e32 v188, 1, v188
	global_load_dwordx4 v[180:183], v188, s[26:27] nt
	s_add_u32 s100, s26, 0x8000
	s_addc_u32 s101, s27, 0
	global_load_dwordx4 v[184:187], v188, s[100:101] nt
	s_add_u32 s100, s26, 0x10000
	s_addc_u32 s101, s27, 0
	global_load_dwordx4 v[194:197], v188, s[100:101] nt
	s_add_u32 s100, s26, 0x18000
	s_addc_u32 s101, s27, 0
	global_load_dwordx4 v[198:201], v188, s[100:101] nt
	s_add_u32 s100, s26, 0x20000
	s_addc_u32 s101, s27, 0
	global_load_dwordx4 v[202:205], v188, s[100:101] nt
	s_add_u32 s100, s26, 0x28000
	s_addc_u32 s101, s27, 0
	global_load_dwordx4 v[206:209], v188, s[100:101] nt
	s_add_u32 s100, s26, 0x30000
	s_addc_u32 s101, s27, 0
	global_load_dwordx4 v[210:213], v188, s[100:101] nt
	s_add_u32 s100, s26, 0x38000
	s_addc_u32 s101, s27, 0
	global_load_dwordx4 v[214:217], v188, s[100:101] nt
	s_add_u32 s100, s26, 0x40000
	s_addc_u32 s101, s27, 0
	global_load_dwordx4 v[218:221], v188, s[100:101] nt
	s_add_u32 s100, s26, 0x48000
	s_addc_u32 s101, s27, 0
	global_load_dwordx4 v[222:225], v188, s[100:101] nt
	s_add_u32 s100, s26, 0x50000
	s_addc_u32 s101, s27, 0
	global_load_dwordx4 v[226:229], v188, s[100:101] nt
	s_add_u32 s100, s26, 0x58000
	s_addc_u32 s101, s27, 0
	global_load_dwordx4 v[230:233], v188, s[100:101] nt
	s_add_u32 s100, s26, 0x60000
	s_addc_u32 s101, s27, 0
	global_load_dwordx4 v[234:237], v188, s[100:101] nt
	s_add_u32 s100, s26, 0x68000
	s_addc_u32 s101, s27, 0
	global_load_dwordx4 v[238:241], v188, s[100:101] nt
	s_add_u32 s100, s26, 0x70000
	s_addc_u32 s101, s27, 0
	global_load_dwordx4 v[242:245], v188, s[100:101] nt
	s_add_u32 s100, s26, 0x78000
	s_addc_u32 s101, s27, 0
	global_load_dwordx4 v[248:251], v188, s[100:101] nt
	v_lshrrev_b32_e32 v160, 1, v163
	v_lshrrev_b32_e32 v163, 3, v163
	v_and_b32_e32 v163, 4, v163
	v_and_or_b32 v160, v160, s39, v163
	v_lshlrev_b32_e32 v160, 2, v160
	v_add_u32_e32 v163, 0x24800, v160
	v_add_u32_e32 v164, 0x24c00, v160
	v_and_b32_e32 v167, 0x37c, v168
	ds_read_b128 v[170:173], v163
	ds_read_b128 v[174:177], v164
	v_or_b32_e32 v164, 0x24000, v167
	v_or_b32_e32 v166, 0x24080, v167
	v_or_b32_e32 v165, 0x24400, v167
	ds_read_b32 v168, v164
	ds_read_b32 v169, v165
	v_or_b32_e32 v167, 0x24480, v167
	ds_read_b32 v178, v166
	ds_read_b32 v179, v167
	s_waitcnt lgkmcnt(3)
	v_fma_f32 v112, -v170, v168, v112
	v_fma_f32 v113, -v171, v168, v113
	s_waitcnt lgkmcnt(1)
	v_fma_f32 v98, -v172, v178, v98
	v_fma_f32 v114, -v172, v168, v114
	v_fma_f32 v115, -v173, v168, v115
	v_fma_f32 v96, -v170, v178, v96
	v_fma_f32 v97, -v171, v178, v97
	s_waitcnt lgkmcnt(0)
	v_fma_f32 v98, v179, v98, v176
	v_fma_f32 v99, -v173, v178, v99
	v_fma_f32 v112, v169, v112, v174
	v_fma_f32 v113, v169, v113, v175
	v_fma_f32 v114, v169, v114, v176
	v_fma_f32 v115, v169, v115, v177
	v_fma_f32 v96, v179, v96, v174
	v_fma_f32 v97, v179, v97, v175
	v_mul_f32_e32 v98, 0xbfb8aa3b, v98
	v_fmac_f32_e32 v177, v179, v99
	v_mul_f32_e32 v112, 0xbfb8aa3b, v112
	v_mul_f32_e32 v113, 0xbfb8aa3b, v113
	v_mul_f32_e32 v114, 0xbfb8aa3b, v114
	v_mul_f32_e32 v115, 0xbfb8aa3b, v115
	v_mul_f32_e32 v96, 0xbfb8aa3b, v96
	v_mul_f32_e32 v97, 0xbfb8aa3b, v97
	v_exp_f32_e32 v98, v98
	v_mul_f32_e32 v99, 0xbfb8aa3b, v177
	v_exp_f32_e32 v112, v112
	v_exp_f32_e32 v113, v113
	v_exp_f32_e32 v114, v114
	v_exp_f32_e32 v115, v115
	v_exp_f32_e32 v96, v96
	v_exp_f32_e32 v97, v97
	v_exp_f32_e32 v99, v99
	v_add_f32_e32 v98, 1.0, v98
	v_add_f32_e32 v112, 1.0, v112
	v_add_f32_e32 v113, 1.0, v113
	v_add_f32_e32 v114, 1.0, v114
	v_add_f32_e32 v115, 1.0, v115
	v_add_f32_e32 v96, 1.0, v96
	v_add_f32_e32 v97, 1.0, v97
	v_rcp_f32_e32 v168, v98
	v_add_f32_e32 v98, 1.0, v99
	v_rcp_f32_e32 v112, v112
	v_rcp_f32_e32 v113, v113
	v_rcp_f32_e32 v114, v114
	v_rcp_f32_e32 v115, v115
	v_rcp_f32_e32 v96, v96
	v_rcp_f32_e32 v97, v97
	v_rcp_f32_e32 v169, v98
	v_cvt_pk_bf16_f32 v99, v112, v113
	v_cvt_pk_bf16_f32 v98, v114, v115
	v_cvt_pk_bf16_f32 v97, v96, v97
	v_cvt_pk_bf16_f32 v96, v168, v169
	v_add_u32_e32 v112, 0x24820, v160
	v_add_u32_e32 v168, 0x24c20, v160
	ds_read_b128 v[112:115], v112
	ds_read_b128 v[168:171], v168
	ds_read_b32 v172, v164
	ds_read_b32 v173, v165
	ds_read_b32 v174, v166
	ds_read_b32 v175, v167
	s_waitcnt lgkmcnt(3)
	v_fma_f32 v116, -v112, v172, v116
	v_fma_f32 v117, -v113, v172, v117
	s_waitcnt lgkmcnt(1)
	v_fma_f32 v102, -v114, v174, v102
	v_fma_f32 v118, -v114, v172, v118
	v_fma_f32 v119, -v115, v172, v119
	v_fma_f32 v100, -v112, v174, v100
	v_fma_f32 v101, -v113, v174, v101
	s_waitcnt lgkmcnt(0)
	v_fma_f32 v102, v175, v102, v170
	v_fma_f32 v103, -v115, v174, v103
	v_fma_f32 v116, v173, v116, v168
	v_fma_f32 v117, v173, v117, v169
	v_fma_f32 v118, v173, v118, v170
	v_fma_f32 v119, v173, v119, v171
	v_fma_f32 v100, v175, v100, v168
	v_fma_f32 v101, v175, v101, v169
	v_mul_f32_e32 v102, 0xbfb8aa3b, v102
	v_fmac_f32_e32 v171, v175, v103
	v_mul_f32_e32 v116, 0xbfb8aa3b, v116
	v_mul_f32_e32 v117, 0xbfb8aa3b, v117
	v_mul_f32_e32 v118, 0xbfb8aa3b, v118
	v_mul_f32_e32 v119, 0xbfb8aa3b, v119
	v_mul_f32_e32 v100, 0xbfb8aa3b, v100
	v_mul_f32_e32 v101, 0xbfb8aa3b, v101
	v_exp_f32_e32 v102, v102
	v_mul_f32_e32 v103, 0xbfb8aa3b, v171
	v_exp_f32_e32 v116, v116
	v_exp_f32_e32 v117, v117
	v_exp_f32_e32 v118, v118
	v_exp_f32_e32 v119, v119
	v_exp_f32_e32 v100, v100
	v_exp_f32_e32 v101, v101
	v_exp_f32_e32 v103, v103
	v_add_f32_e32 v102, 1.0, v102
	v_add_f32_e32 v116, 1.0, v116
	v_add_f32_e32 v117, 1.0, v117
	v_add_f32_e32 v118, 1.0, v118
	v_add_f32_e32 v119, 1.0, v119
	v_add_f32_e32 v100, 1.0, v100
	v_add_f32_e32 v101, 1.0, v101
	v_rcp_f32_e32 v113, v102
	v_add_f32_e32 v102, 1.0, v103
	v_rcp_f32_e32 v116, v116
	v_rcp_f32_e32 v117, v117
	v_rcp_f32_e32 v118, v118
	v_rcp_f32_e32 v112, v119
	v_rcp_f32_e32 v100, v100
	v_rcp_f32_e32 v101, v101
	v_rcp_f32_e32 v114, v102
	v_cvt_pk_bf16_f32 v103, v116, v117
	v_cvt_pk_bf16_f32 v102, v118, v112
	v_cvt_pk_bf16_f32 v101, v100, v101
	v_cvt_pk_bf16_f32 v100, v113, v114
	v_add_u32_e32 v112, 0x24840, v160
	v_add_u32_e32 v116, 0x24c40, v160
	ds_read_b128 v[112:115], v112
	ds_read_b128 v[116:119], v116
	ds_read_b32 v168, v164
	ds_read_b32 v169, v165
	ds_read_b32 v170, v166
	ds_read_b32 v171, v167
	s_waitcnt lgkmcnt(3)
; DI unsigned pack2(float a, float b) { f32x2_t v = {a, b}; bf16x2_t r = __builtin_convertvector(v, bf16x2_t); return __builtin_bit_cast(unsigned, r); }
; DI float sigmoidf_(float x) { return __builtin_amdgcn_rcpf(1.f + __expf(-x)); }
; template <bool LAST>
; DI void phase_gate(const Params& P, int layer, unsigned char* smem, int L, int G) {
;     ...
;     unsigned gq[4][2][8];
; #pragma unroll
;     for (int i = 0; i < 4; ++i)
; #pragma unroll
;       for (int q4 = 0; q4 < 4; ++q4) {
;         const int fl = wm * 128 + i * 32 + 8 * q4 + 4 * h;
;         const f32x4 c1v = *(const f32x4*)(vecL + fl), c2v = *(const f32x4*)(vecL + 256 + fl);
;         const float c1a[4] = {c1v.x, c1v.y, c1v.z, c1v.w}, c2a[4] = {c2v.x, c2v.y, c2v.z, c2v.w};
; #pragma unroll
;         for (int j = 0; j < 2; ++j) {
;           const int lrow = wn * 64 + j * 32 + r;
;           const float mu = rowA[lrow], rstd = rowB[lrow];
;           float sg4[4];
; #pragma unroll
;           for (int e = 0; e < 4; ++e) sg4[e] = sigmoidf_(rstd * (accu[i][j][4 * q4 + e] - mu * c1a[e]) + c2a[e]);
;           gq[i][j][2 * q4] = pack2(sg4[0], sg4[1]); gq[i][j][2 * q4 + 1] = pack2(sg4[2], sg4[3]);
;         }
;         __builtin_amdgcn_sched_barrier(0);
;       }
	v_fma_f32 v120, -v112, v168, v120
	v_fma_f32 v121, -v113, v168, v121
	s_waitcnt lgkmcnt(1)
	v_fma_f32 v106, -v114, v170, v106
	v_fma_f32 v122, -v114, v168, v122
	v_fma_f32 v123, -v115, v168, v123
	v_fma_f32 v104, -v112, v170, v104
	v_fma_f32 v105, -v113, v170, v105
	s_waitcnt lgkmcnt(0)
	v_fma_f32 v106, v171, v106, v118
	v_fma_f32 v107, -v115, v170, v107
	v_fma_f32 v120, v169, v120, v116
	v_fma_f32 v121, v169, v121, v117
	v_fma_f32 v122, v169, v122, v118
	v_fma_f32 v123, v169, v123, v119
	v_fma_f32 v104, v171, v104, v116
	v_fma_f32 v105, v171, v105, v117
	v_mul_f32_e32 v106, 0xbfb8aa3b, v106
	v_fmac_f32_e32 v119, v171, v107
	v_mul_f32_e32 v120, 0xbfb8aa3b, v120
	v_mul_f32_e32 v121, 0xbfb8aa3b, v121
	v_mul_f32_e32 v122, 0xbfb8aa3b, v122
	v_mul_f32_e32 v123, 0xbfb8aa3b, v123
	v_mul_f32_e32 v104, 0xbfb8aa3b, v104
	v_mul_f32_e32 v105, 0xbfb8aa3b, v105
	v_exp_f32_e32 v106, v106
	v_mul_f32_e32 v107, 0xbfb8aa3b, v119
	v_exp_f32_e32 v120, v120
	v_exp_f32_e32 v121, v121
	v_exp_f32_e32 v122, v122
	v_exp_f32_e32 v123, v123
	v_exp_f32_e32 v104, v104
	v_exp_f32_e32 v105, v105
	v_exp_f32_e32 v107, v107
	v_add_f32_e32 v106, 1.0, v106
	v_add_f32_e32 v120, 1.0, v120
	v_add_f32_e32 v121, 1.0, v121
	v_add_f32_e32 v122, 1.0, v122
	v_add_f32_e32 v123, 1.0, v123
	v_add_f32_e32 v104, 1.0, v104
	v_add_f32_e32 v105, 1.0, v105
	v_rcp_f32_e32 v113, v106
	v_add_f32_e32 v106, 1.0, v107
	v_rcp_f32_e32 v120, v120
	v_rcp_f32_e32 v121, v121
	v_rcp_f32_e32 v122, v122
	v_rcp_f32_e32 v112, v123
	v_rcp_f32_e32 v104, v104
	v_rcp_f32_e32 v105, v105
	v_rcp_f32_e32 v114, v106
	v_cvt_pk_bf16_f32 v107, v120, v121
	v_cvt_pk_bf16_f32 v106, v122, v112
	v_cvt_pk_bf16_f32 v105, v104, v105
	v_cvt_pk_bf16_f32 v104, v113, v114
	v_add_u32_e32 v112, 0x24860, v160
	v_add_u32_e32 v116, 0x24c60, v160
	ds_read_b128 v[112:115], v112
	ds_read_b128 v[116:119], v116
	ds_read_b32 v120, v164
	ds_read_b32 v121, v165
	ds_read_b32 v122, v166
	ds_read_b32 v123, v167
	s_waitcnt lgkmcnt(3)
	v_fma_f32 v125, -v113, v120, v125
	v_fma_f32 v124, -v112, v120, v124
	s_waitcnt lgkmcnt(1)
	v_fma_f32 v110, -v114, v122, v110
	v_fma_f32 v125, v121, v125, v117
	v_fma_f32 v126, -v114, v120, v126
	v_fma_f32 v120, -v115, v120, v127
	v_fma_f32 v108, -v112, v122, v108
	v_fma_f32 v109, -v113, v122, v109
	s_waitcnt lgkmcnt(0)
	v_fma_f32 v110, v123, v110, v118
	v_fma_f32 v111, -v115, v122, v111
	v_fma_f32 v124, v121, v124, v116
	v_mul_f32_e32 v125, 0xbfb8aa3b, v125
	v_fma_f32 v126, v121, v126, v118
	v_fma_f32 v120, v121, v120, v119
	v_fma_f32 v108, v123, v108, v116
	v_fma_f32 v109, v123, v109, v117
	v_mul_f32_e32 v110, 0xbfb8aa3b, v110
	v_fmac_f32_e32 v119, v123, v111
	v_mul_f32_e32 v124, 0xbfb8aa3b, v124
	v_exp_f32_e32 v125, v125
	v_mul_f32_e32 v126, 0xbfb8aa3b, v126
	v_mul_f32_e32 v120, 0xbfb8aa3b, v120
	v_mul_f32_e32 v108, 0xbfb8aa3b, v108
	v_mul_f32_e32 v109, 0xbfb8aa3b, v109
	v_exp_f32_e32 v110, v110
	v_mul_f32_e32 v111, 0xbfb8aa3b, v119
	v_exp_f32_e32 v124, v124
	v_exp_f32_e32 v126, v126
	v_exp_f32_e32 v120, v120
	v_exp_f32_e32 v108, v108
	v_exp_f32_e32 v109, v109
	v_exp_f32_e32 v111, v111
	v_add_f32_e32 v125, 1.0, v125
	v_add_f32_e32 v110, 1.0, v110
	v_add_f32_e32 v124, 1.0, v124
	v_rcp_f32_e32 v121, v125
	v_add_f32_e32 v125, 1.0, v126
	v_add_f32_e32 v120, 1.0, v120
	v_add_f32_e32 v108, 1.0, v108
	v_add_f32_e32 v109, 1.0, v109
	v_rcp_f32_e32 v113, v110
	v_add_f32_e32 v110, 1.0, v111
	v_rcp_f32_e32 v124, v124
	v_rcp_f32_e32 v125, v125
	v_rcp_f32_e32 v112, v120
	v_rcp_f32_e32 v108, v108
	v_rcp_f32_e32 v109, v109
	v_rcp_f32_e32 v114, v110
	v_cvt_pk_bf16_f32 v111, v124, v121
	v_cvt_pk_bf16_f32 v110, v125, v112
	v_cvt_pk_bf16_f32 v109, v108, v109
	v_cvt_pk_bf16_f32 v108, v113, v114
	v_add_u32_e32 v112, 0x24880, v160
	v_add_u32_e32 v116, 0x24c80, v160
	ds_read_b128 v[112:115], v112
	ds_read_b128 v[116:119], v116
	ds_read_b32 v120, v164
	ds_read_b32 v121, v165
	ds_read_b32 v122, v166
	ds_read_b32 v123, v167
	s_waitcnt lgkmcnt(3)
	v_fma_f32 v80, -v112, v120, v80
	v_fma_f32 v81, -v113, v120, v81
	s_waitcnt lgkmcnt(1)
	v_fma_f32 v66, -v114, v122, v66
	v_fma_f32 v82, -v114, v120, v82
	v_fma_f32 v83, -v115, v120, v83
	v_fma_f32 v64, -v112, v122, v64
	v_fma_f32 v65, -v113, v122, v65
	s_waitcnt lgkmcnt(0)
	v_fma_f32 v66, v123, v66, v118
	v_fma_f32 v67, -v115, v122, v67
	v_fma_f32 v80, v121, v80, v116
	v_fma_f32 v81, v121, v81, v117
	v_fma_f32 v82, v121, v82, v118
	v_fma_f32 v83, v121, v83, v119
	v_fma_f32 v64, v123, v64, v116
	v_fma_f32 v65, v123, v65, v117
	v_mul_f32_e32 v66, 0xbfb8aa3b, v66
	v_fmac_f32_e32 v119, v123, v67
	v_mul_f32_e32 v80, 0xbfb8aa3b, v80
	v_mul_f32_e32 v81, 0xbfb8aa3b, v81
	v_mul_f32_e32 v82, 0xbfb8aa3b, v82
	v_mul_f32_e32 v83, 0xbfb8aa3b, v83
	v_mul_f32_e32 v64, 0xbfb8aa3b, v64
	v_mul_f32_e32 v65, 0xbfb8aa3b, v65
	v_exp_f32_e32 v66, v66
	v_mul_f32_e32 v67, 0xbfb8aa3b, v119
	v_exp_f32_e32 v80, v80
	v_exp_f32_e32 v81, v81
	v_exp_f32_e32 v82, v82
	v_exp_f32_e32 v83, v83
	v_exp_f32_e32 v64, v64
	v_exp_f32_e32 v65, v65
	v_exp_f32_e32 v67, v67
	v_add_f32_e32 v66, 1.0, v66
	v_add_f32_e32 v80, 1.0, v80
	v_add_f32_e32 v81, 1.0, v81
	v_add_f32_e32 v82, 1.0, v82
	v_add_f32_e32 v83, 1.0, v83
	v_add_f32_e32 v64, 1.0, v64
	v_add_f32_e32 v65, 1.0, v65
	v_rcp_f32_e32 v112, v66
	v_add_f32_e32 v66, 1.0, v67
	v_rcp_f32_e32 v80, v80
	v_rcp_f32_e32 v81, v81
	v_rcp_f32_e32 v82, v82
	v_rcp_f32_e32 v83, v83
	v_rcp_f32_e32 v64, v64
	v_rcp_f32_e32 v65, v65
	v_rcp_f32_e32 v113, v66
	v_cvt_pk_bf16_f32 v67, v80, v81
	v_cvt_pk_bf16_f32 v66, v82, v83
	v_cvt_pk_bf16_f32 v65, v64, v65
	v_cvt_pk_bf16_f32 v64, v112, v113
	v_add_u32_e32 v80, 0x248a0, v160
	v_add_u32_e32 v112, 0x24ca0, v160
	ds_read_b128 v[80:83], v80
	ds_read_b128 v[112:115], v112
	ds_read_b32 v116, v164
	ds_read_b32 v117, v165
	ds_read_b32 v118, v166
	ds_read_b32 v119, v167
	s_waitcnt lgkmcnt(3)
; DI unsigned pack2(float a, float b) { f32x2_t v = {a, b}; bf16x2_t r = __builtin_convertvector(v, bf16x2_t); return __builtin_bit_cast(unsigned, r); }
; DI float sigmoidf_(float x) { return __builtin_amdgcn_rcpf(1.f + __expf(-x)); }
; template <bool LAST>
; DI void phase_gate(const Params& P, int layer, unsigned char* smem, int L, int G) {
;     ...
;     unsigned gq[4][2][8];
; #pragma unroll
;     for (int i = 0; i < 4; ++i)
; #pragma unroll
;       for (int q4 = 0; q4 < 4; ++q4) {
;         const int fl = wm * 128 + i * 32 + 8 * q4 + 4 * h;
;         const f32x4 c1v = *(const f32x4*)(vecL + fl), c2v = *(const f32x4*)(vecL + 256 + fl);
;         const float c1a[4] = {c1v.x, c1v.y, c1v.z, c1v.w}, c2a[4] = {c2v.x, c2v.y, c2v.z, c2v.w};
; #pragma unroll
;         for (int j = 0; j < 2; ++j) {
;           const int lrow = wn * 64 + j * 32 + r;
;           const float mu = rowA[lrow], rstd = rowB[lrow];
;           float sg4[4];
; #pragma unroll
;           for (int e = 0; e < 4; ++e) sg4[e] = sigmoidf_(rstd * (accu[i][j][4 * q4 + e] - mu * c1a[e]) + c2a[e]);
;           gq[i][j][2 * q4] = pack2(sg4[0], sg4[1]); gq[i][j][2 * q4 + 1] = pack2(sg4[2], sg4[3]);
;         }
;         __builtin_amdgcn_sched_barrier(0);
;       }
	v_fma_f32 v84, -v80, v116, v84
	v_fma_f32 v85, -v81, v116, v85
	s_waitcnt lgkmcnt(1)
	v_fma_f32 v70, -v82, v118, v70
	v_fma_f32 v86, -v82, v116, v86
	v_fma_f32 v87, -v83, v116, v87
	v_fma_f32 v68, -v80, v118, v68
	v_fma_f32 v69, -v81, v118, v69
	s_waitcnt lgkmcnt(0)
	v_fma_f32 v70, v119, v70, v114
	v_fma_f32 v71, -v83, v118, v71
	v_fma_f32 v84, v117, v84, v112
	v_fma_f32 v85, v117, v85, v113
	v_fma_f32 v86, v117, v86, v114
	v_fma_f32 v87, v117, v87, v115
	v_fma_f32 v68, v119, v68, v112
	v_fma_f32 v69, v119, v69, v113
	v_mul_f32_e32 v70, 0xbfb8aa3b, v70
	v_fmac_f32_e32 v115, v119, v71
	v_mul_f32_e32 v84, 0xbfb8aa3b, v84
	v_mul_f32_e32 v85, 0xbfb8aa3b, v85
	v_mul_f32_e32 v86, 0xbfb8aa3b, v86
	v_mul_f32_e32 v87, 0xbfb8aa3b, v87
	v_mul_f32_e32 v68, 0xbfb8aa3b, v68
	v_mul_f32_e32 v69, 0xbfb8aa3b, v69
	v_exp_f32_e32 v70, v70
	v_mul_f32_e32 v71, 0xbfb8aa3b, v115
	v_exp_f32_e32 v84, v84
	v_exp_f32_e32 v85, v85
	v_exp_f32_e32 v86, v86
	v_exp_f32_e32 v87, v87
	v_exp_f32_e32 v68, v68
	v_exp_f32_e32 v69, v69
	v_exp_f32_e32 v71, v71
	v_add_f32_e32 v70, 1.0, v70
	v_add_f32_e32 v84, 1.0, v84
	v_add_f32_e32 v85, 1.0, v85
	v_add_f32_e32 v86, 1.0, v86
	v_add_f32_e32 v87, 1.0, v87
	v_add_f32_e32 v68, 1.0, v68
	v_add_f32_e32 v69, 1.0, v69
	v_rcp_f32_e32 v81, v70
	v_add_f32_e32 v70, 1.0, v71
	v_rcp_f32_e32 v84, v84
	v_rcp_f32_e32 v85, v85
	v_rcp_f32_e32 v86, v86
	v_rcp_f32_e32 v80, v87
	v_rcp_f32_e32 v68, v68
	v_rcp_f32_e32 v69, v69
	v_rcp_f32_e32 v82, v70
	v_cvt_pk_bf16_f32 v71, v84, v85
	v_cvt_pk_bf16_f32 v70, v86, v80
	v_cvt_pk_bf16_f32 v69, v68, v69
	v_cvt_pk_bf16_f32 v68, v81, v82
	v_add_u32_e32 v80, 0x248c0, v160
	v_add_u32_e32 v84, 0x24cc0, v160
	ds_read_b128 v[80:83], v80
	ds_read_b128 v[84:87], v84
	ds_read_b32 v112, v164
	ds_read_b32 v113, v165
	ds_read_b32 v114, v166
	ds_read_b32 v115, v167
	s_waitcnt lgkmcnt(3)
	v_fma_f32 v88, -v80, v112, v88
	v_fma_f32 v89, -v81, v112, v89
	s_waitcnt lgkmcnt(1)
	v_fma_f32 v74, -v82, v114, v74
	v_fma_f32 v90, -v82, v112, v90
	v_fma_f32 v91, -v83, v112, v91
	v_fma_f32 v72, -v80, v114, v72
	v_fma_f32 v73, -v81, v114, v73
	s_waitcnt lgkmcnt(0)
	v_fma_f32 v74, v115, v74, v86
	v_fma_f32 v75, -v83, v114, v75
	v_fma_f32 v88, v113, v88, v84
	v_fma_f32 v89, v113, v89, v85
	v_fma_f32 v90, v113, v90, v86
	v_fma_f32 v91, v113, v91, v87
	v_fma_f32 v72, v115, v72, v84
	v_fma_f32 v73, v115, v73, v85
	v_mul_f32_e32 v74, 0xbfb8aa3b, v74
	v_fmac_f32_e32 v87, v115, v75
	v_mul_f32_e32 v88, 0xbfb8aa3b, v88
	v_mul_f32_e32 v89, 0xbfb8aa3b, v89
	v_mul_f32_e32 v90, 0xbfb8aa3b, v90
	v_mul_f32_e32 v91, 0xbfb8aa3b, v91
	v_mul_f32_e32 v72, 0xbfb8aa3b, v72
	v_mul_f32_e32 v73, 0xbfb8aa3b, v73
	v_exp_f32_e32 v74, v74
	v_mul_f32_e32 v75, 0xbfb8aa3b, v87
	v_exp_f32_e32 v88, v88
	v_exp_f32_e32 v89, v89
	v_exp_f32_e32 v90, v90
	v_exp_f32_e32 v91, v91
	v_exp_f32_e32 v72, v72
	v_exp_f32_e32 v73, v73
	v_exp_f32_e32 v75, v75
	v_add_f32_e32 v74, 1.0, v74
	v_add_f32_e32 v88, 1.0, v88
	v_add_f32_e32 v89, 1.0, v89
	v_add_f32_e32 v90, 1.0, v90
	v_add_f32_e32 v91, 1.0, v91
	v_add_f32_e32 v72, 1.0, v72
	v_add_f32_e32 v73, 1.0, v73
	v_rcp_f32_e32 v81, v74
	v_add_f32_e32 v74, 1.0, v75
	v_rcp_f32_e32 v88, v88
	v_rcp_f32_e32 v89, v89
	v_rcp_f32_e32 v90, v90
	v_rcp_f32_e32 v80, v91
	v_rcp_f32_e32 v72, v72
	v_rcp_f32_e32 v73, v73
	v_rcp_f32_e32 v82, v74
	v_cvt_pk_bf16_f32 v75, v88, v89
	v_cvt_pk_bf16_f32 v74, v90, v80
	v_cvt_pk_bf16_f32 v73, v72, v73
	v_cvt_pk_bf16_f32 v72, v81, v82
	v_add_u32_e32 v80, 0x248e0, v160
	v_add_u32_e32 v84, 0x24ce0, v160
	ds_read_b128 v[80:83], v80
	ds_read_b128 v[84:87], v84
	ds_read_b32 v88, v164
	ds_read_b32 v89, v165
	ds_read_b32 v90, v166
	ds_read_b32 v91, v167
	s_waitcnt lgkmcnt(3)
	v_fma_f32 v93, -v81, v88, v93
	v_fma_f32 v92, -v80, v88, v92
	s_waitcnt lgkmcnt(1)
	v_fma_f32 v78, -v82, v90, v78
	v_fma_f32 v93, v89, v93, v85
	v_fma_f32 v94, -v82, v88, v94
	v_fma_f32 v88, -v83, v88, v95
	v_fma_f32 v76, -v80, v90, v76
	v_fma_f32 v77, -v81, v90, v77
	s_waitcnt lgkmcnt(0)
	v_fma_f32 v78, v91, v78, v86
	v_fma_f32 v79, -v83, v90, v79
	v_fma_f32 v92, v89, v92, v84
	v_mul_f32_e32 v93, 0xbfb8aa3b, v93
	v_fma_f32 v94, v89, v94, v86
	v_fma_f32 v88, v89, v88, v87
	v_fma_f32 v76, v91, v76, v84
	v_fma_f32 v77, v91, v77, v85
	v_mul_f32_e32 v78, 0xbfb8aa3b, v78
	v_fmac_f32_e32 v87, v91, v79
	v_mul_f32_e32 v92, 0xbfb8aa3b, v92
	v_exp_f32_e32 v93, v93
	v_mul_f32_e32 v94, 0xbfb8aa3b, v94
	v_mul_f32_e32 v88, 0xbfb8aa3b, v88
	v_mul_f32_e32 v76, 0xbfb8aa3b, v76
	v_mul_f32_e32 v77, 0xbfb8aa3b, v77
	v_exp_f32_e32 v78, v78
	v_mul_f32_e32 v79, 0xbfb8aa3b, v87
	v_exp_f32_e32 v92, v92
	v_exp_f32_e32 v94, v94
	v_exp_f32_e32 v88, v88
	v_exp_f32_e32 v76, v76
	v_exp_f32_e32 v77, v77
	v_exp_f32_e32 v79, v79
	v_add_f32_e32 v93, 1.0, v93
	v_add_f32_e32 v78, 1.0, v78
	v_add_f32_e32 v92, 1.0, v92
	v_rcp_f32_e32 v89, v93
	v_add_f32_e32 v93, 1.0, v94
	v_add_f32_e32 v88, 1.0, v88
	v_add_f32_e32 v76, 1.0, v76
	v_add_f32_e32 v77, 1.0, v77
	v_rcp_f32_e32 v81, v78
	v_add_f32_e32 v78, 1.0, v79
	v_rcp_f32_e32 v92, v92
	v_rcp_f32_e32 v93, v93
	v_rcp_f32_e32 v80, v88
	v_rcp_f32_e32 v76, v76
	v_rcp_f32_e32 v77, v77
	v_rcp_f32_e32 v82, v78
	v_cvt_pk_bf16_f32 v79, v92, v89
	v_cvt_pk_bf16_f32 v78, v93, v80
	v_cvt_pk_bf16_f32 v77, v76, v77
	v_cvt_pk_bf16_f32 v76, v81, v82
	v_add_u32_e32 v80, 0x24900, v160
	v_add_u32_e32 v84, 0x24d00, v160
	ds_read_b128 v[80:83], v80
	ds_read_b128 v[84:87], v84
	ds_read_b32 v88, v164
	ds_read_b32 v89, v165
	ds_read_b32 v90, v166
	ds_read_b32 v91, v167
	s_waitcnt lgkmcnt(3)
	v_fma_f32 v48, -v80, v88, v48
	v_fma_f32 v49, -v81, v88, v49
	s_waitcnt lgkmcnt(1)
	v_fma_f32 v34, -v82, v90, v34
	v_fma_f32 v50, -v82, v88, v50
	v_fma_f32 v51, -v83, v88, v51
	v_fma_f32 v32, -v80, v90, v32
	v_fma_f32 v33, -v81, v90, v33
	s_waitcnt lgkmcnt(0)
; DI unsigned pack2(float a, float b) { f32x2_t v = {a, b}; bf16x2_t r = __builtin_convertvector(v, bf16x2_t); return __builtin_bit_cast(unsigned, r); }
; DI float sigmoidf_(float x) { return __builtin_amdgcn_rcpf(1.f + __expf(-x)); }
; template <bool LAST>
; DI void phase_gate(const Params& P, int layer, unsigned char* smem, int L, int G) {
;     ...
;     unsigned gq[4][2][8];
; #pragma unroll
;     for (int i = 0; i < 4; ++i)
; #pragma unroll
;       for (int q4 = 0; q4 < 4; ++q4) {
;         const int fl = wm * 128 + i * 32 + 8 * q4 + 4 * h;
;         const f32x4 c1v = *(const f32x4*)(vecL + fl), c2v = *(const f32x4*)(vecL + 256 + fl);
;         const float c1a[4] = {c1v.x, c1v.y, c1v.z, c1v.w}, c2a[4] = {c2v.x, c2v.y, c2v.z, c2v.w};
; #pragma unroll
;         for (int j = 0; j < 2; ++j) {
;           const int lrow = wn * 64 + j * 32 + r;
;           const float mu = rowA[lrow], rstd = rowB[lrow];
;           float sg4[4];
; #pragma unroll
;           for (int e = 0; e < 4; ++e) sg4[e] = sigmoidf_(rstd * (accu[i][j][4 * q4 + e] - mu * c1a[e]) + c2a[e]);
;           gq[i][j][2 * q4] = pack2(sg4[0], sg4[1]); gq[i][j][2 * q4 + 1] = pack2(sg4[2], sg4[3]);
;         }
;         __builtin_amdgcn_sched_barrier(0);
;       }
	v_fma_f32 v34, v91, v34, v86
	v_fma_f32 v35, -v83, v90, v35
	v_fma_f32 v48, v89, v48, v84
	v_fma_f32 v49, v89, v49, v85
	v_fma_f32 v50, v89, v50, v86
	v_fma_f32 v51, v89, v51, v87
	v_fma_f32 v32, v91, v32, v84
	v_fma_f32 v33, v91, v33, v85
	v_mul_f32_e32 v34, 0xbfb8aa3b, v34
	v_fmac_f32_e32 v87, v91, v35
	v_mul_f32_e32 v48, 0xbfb8aa3b, v48
	v_mul_f32_e32 v49, 0xbfb8aa3b, v49
	v_mul_f32_e32 v50, 0xbfb8aa3b, v50
	v_mul_f32_e32 v51, 0xbfb8aa3b, v51
	v_mul_f32_e32 v32, 0xbfb8aa3b, v32
	v_mul_f32_e32 v33, 0xbfb8aa3b, v33
	v_exp_f32_e32 v34, v34
	v_mul_f32_e32 v35, 0xbfb8aa3b, v87
	v_exp_f32_e32 v48, v48
	v_exp_f32_e32 v49, v49
	v_exp_f32_e32 v50, v50
	v_exp_f32_e32 v51, v51
	v_exp_f32_e32 v32, v32
	v_exp_f32_e32 v33, v33
	v_exp_f32_e32 v35, v35
	v_add_f32_e32 v34, 1.0, v34
	v_add_f32_e32 v48, 1.0, v48
	v_add_f32_e32 v49, 1.0, v49
	v_add_f32_e32 v50, 1.0, v50
	v_add_f32_e32 v51, 1.0, v51
	v_add_f32_e32 v32, 1.0, v32
	v_add_f32_e32 v33, 1.0, v33
	v_rcp_f32_e32 v80, v34
	v_add_f32_e32 v34, 1.0, v35
	v_rcp_f32_e32 v48, v48
	v_rcp_f32_e32 v49, v49
	v_rcp_f32_e32 v50, v50
	v_rcp_f32_e32 v51, v51
	v_rcp_f32_e32 v32, v32
	v_rcp_f32_e32 v33, v33
	v_rcp_f32_e32 v81, v34
	v_cvt_pk_bf16_f32 v35, v48, v49
	v_cvt_pk_bf16_f32 v34, v50, v51
	v_cvt_pk_bf16_f32 v33, v32, v33
	v_cvt_pk_bf16_f32 v32, v80, v81
	v_add_u32_e32 v48, 0x24920, v160
	v_add_u32_e32 v80, 0x24d20, v160
	ds_read_b128 v[48:51], v48
	ds_read_b128 v[80:83], v80
	ds_read_b32 v84, v164
	ds_read_b32 v85, v165
	ds_read_b32 v86, v166
	ds_read_b32 v87, v167
	s_waitcnt lgkmcnt(3)
	v_fma_f32 v53, -v49, v84, v53
	v_fma_f32 v52, -v48, v84, v52
	s_waitcnt lgkmcnt(1)
	v_fma_f32 v36, -v48, v86, v36
	s_waitcnt lgkmcnt(0)
	v_fma_f32 v36, v87, v36, v80
	v_fma_f32 v37, -v49, v86, v37
	v_mul_f32_e32 v36, 0xbfb8aa3b, v36
	v_fma_f32 v37, v87, v37, v81
	v_exp_f32_e32 v36, v36
	v_mul_f32_e32 v37, 0xbfb8aa3b, v37
	v_exp_f32_e32 v37, v37
	v_fma_f32 v54, -v50, v84, v54
	v_add_f32_e32 v36, 1.0, v36
	v_rcp_f32_e32 v49, v36
	v_add_f32_e32 v36, 1.0, v37
	v_fma_f32 v37, -v50, v86, v38
	v_fma_f32 v55, -v51, v84, v55
	v_fma_f32 v37, v87, v37, v82
	v_fma_f32 v38, -v51, v86, v39
	v_fma_f32 v52, v85, v52, v80
	v_fma_f32 v53, v85, v53, v81
	v_fma_f32 v54, v85, v54, v82
	v_fma_f32 v55, v85, v55, v83
	v_mul_f32_e32 v37, 0xbfb8aa3b, v37
	v_fmac_f32_e32 v83, v87, v38
	v_mul_f32_e32 v52, 0xbfb8aa3b, v52
	v_mul_f32_e32 v53, 0xbfb8aa3b, v53
	v_mul_f32_e32 v54, 0xbfb8aa3b, v54
	v_mul_f32_e32 v55, 0xbfb8aa3b, v55
	v_exp_f32_e32 v37, v37
	v_mul_f32_e32 v38, 0xbfb8aa3b, v83
	v_exp_f32_e32 v52, v52
	v_exp_f32_e32 v53, v53
	v_exp_f32_e32 v54, v54
	v_exp_f32_e32 v55, v55
	v_exp_f32_e32 v38, v38
	v_rcp_f32_e32 v39, v36
	v_add_f32_e32 v36, 1.0, v37
	v_add_f32_e32 v52, 1.0, v52
	v_add_f32_e32 v53, 1.0, v53
	v_add_f32_e32 v54, 1.0, v54
	v_add_f32_e32 v55, 1.0, v55
	v_rcp_f32_e32 v37, v36
	v_add_f32_e32 v36, 1.0, v38
	v_rcp_f32_e32 v52, v52
	v_rcp_f32_e32 v53, v53
	v_rcp_f32_e32 v54, v54
	v_rcp_f32_e32 v48, v55
	v_rcp_f32_e32 v38, v36
	v_cvt_pk_bf16_f32 v80, v52, v53
	v_cvt_pk_bf16_f32 v55, v49, v39
	v_cvt_pk_bf16_f32 v36, v54, v48
	v_cvt_pk_bf16_f32 v53, v37, v38
	v_add_u32_e32 v37, 0x24940, v160
	v_add_u32_e32 v38, 0x24d40, v160
	ds_read_b128 v[48:51], v37
	ds_read_b128 v[82:85], v38
	ds_read_b32 v37, v164
	ds_read_b32 v38, v165
	ds_read_b32 v39, v166
	ds_read_b32 v52, v167
	s_waitcnt lgkmcnt(3)
	v_fma_f32 v54, -v48, v37, v56
	v_fma_f32 v56, -v49, v37, v57
	s_waitcnt lgkmcnt(2)
	v_fma_f32 v56, v38, v56, v83
	v_fma_f32 v57, -v50, v37, v58
	v_fma_f32 v37, -v51, v37, v59
	s_waitcnt lgkmcnt(1)
	v_fma_f32 v40, -v48, v39, v40
	v_fma_f32 v41, -v49, v39, v41
	v_fma_f32 v42, -v50, v39, v42
	v_fma_f32 v39, -v51, v39, v43
	v_fma_f32 v54, v38, v54, v82
	v_mul_f32_e32 v56, 0xbfb8aa3b, v56
	v_fma_f32 v57, v38, v57, v84
	v_fma_f32 v37, v38, v37, v85
	s_waitcnt lgkmcnt(0)
	v_fma_f32 v40, v52, v40, v82
	v_fma_f32 v41, v52, v41, v83
	v_fma_f32 v42, v52, v42, v84
	v_fmac_f32_e32 v85, v52, v39
	v_mul_f32_e32 v54, 0xbfb8aa3b, v54
	v_exp_f32_e32 v56, v56
	v_mul_f32_e32 v57, 0xbfb8aa3b, v57
	v_mul_f32_e32 v37, 0xbfb8aa3b, v37
	v_mul_f32_e32 v40, 0xbfb8aa3b, v40
	v_mul_f32_e32 v41, 0xbfb8aa3b, v41
	v_mul_f32_e32 v42, 0xbfb8aa3b, v42
	v_mul_f32_e32 v39, 0xbfb8aa3b, v85
	v_exp_f32_e32 v54, v54
	v_exp_f32_e32 v57, v57
	v_exp_f32_e32 v37, v37
	v_exp_f32_e32 v40, v40
	v_exp_f32_e32 v41, v41
	v_exp_f32_e32 v42, v42
	v_exp_f32_e32 v39, v39
	v_add_f32_e32 v56, 1.0, v56
	v_add_f32_e32 v54, 1.0, v54
	v_rcp_f32_e32 v38, v56
	v_add_f32_e32 v56, 1.0, v57
	v_add_f32_e32 v37, 1.0, v37
	v_add_f32_e32 v40, 1.0, v40
	v_add_f32_e32 v41, 1.0, v41
	v_add_f32_e32 v42, 1.0, v42
	v_add_f32_e32 v39, 1.0, v39
	v_rcp_f32_e32 v54, v54
	v_rcp_f32_e32 v56, v56
	v_rcp_f32_e32 v37, v37
	v_rcp_f32_e32 v40, v40
	v_rcp_f32_e32 v41, v41
	v_rcp_f32_e32 v42, v42
	v_rcp_f32_e32 v39, v39
	v_cvt_pk_bf16_f32 v83, v54, v38
	v_cvt_pk_bf16_f32 v82, v56, v37
	v_cvt_pk_bf16_f32 v81, v40, v41
	v_cvt_pk_bf16_f32 v59, v42, v39
	v_add_u32_e32 v37, 0x24960, v160
	v_add_u32_e32 v42, 0x24d60, v160
	ds_read_b128 v[38:41], v37
	ds_read_b128 v[48:51], v42
	ds_read_b32 v37, v164
	ds_read_b32 v42, v165
	ds_read_b32 v43, v166
	ds_read_b32 v52, v167
	s_waitcnt lgkmcnt(3)
	v_fma_f32 v56, -v39, v37, v61
	v_fma_f32 v54, -v38, v37, v60
	s_waitcnt lgkmcnt(2)
	v_fma_f32 v56, v42, v56, v49
	v_fma_f32 v57, -v40, v37, v62
	v_fma_f32 v37, -v41, v37, v63
	s_waitcnt lgkmcnt(1)
	v_fma_f32 v38, -v38, v43, v44
	v_fma_f32 v39, -v39, v43, v45
	v_fma_f32 v40, -v40, v43, v46
	v_fma_f32 v41, -v41, v43, v47
	v_fma_f32 v54, v42, v54, v48
	v_mul_f32_e32 v56, 0xbfb8aa3b, v56
	v_fma_f32 v57, v42, v57, v50
	v_fma_f32 v37, v42, v37, v51
	s_waitcnt lgkmcnt(0)
; DI unsigned pack2(float a, float b) { f32x2_t v = {a, b}; bf16x2_t r = __builtin_convertvector(v, bf16x2_t); return __builtin_bit_cast(unsigned, r); }
; DI float sigmoidf_(float x) { return __builtin_amdgcn_rcpf(1.f + __expf(-x)); }
; template <bool LAST>
; DI void phase_gate(const Params& P, int layer, unsigned char* smem, int L, int G) {
;     ...
;     unsigned gq[4][2][8];
; #pragma unroll
;     for (int i = 0; i < 4; ++i)
; #pragma unroll
;       for (int q4 = 0; q4 < 4; ++q4) {
;         const int fl = wm * 128 + i * 32 + 8 * q4 + 4 * h;
;         const f32x4 c1v = *(const f32x4*)(vecL + fl), c2v = *(const f32x4*)(vecL + 256 + fl);
;         const float c1a[4] = {c1v.x, c1v.y, c1v.z, c1v.w}, c2a[4] = {c2v.x, c2v.y, c2v.z, c2v.w};
; #pragma unroll
;         for (int j = 0; j < 2; ++j) {
;           const int lrow = wn * 64 + j * 32 + r;
;           const float mu = rowA[lrow], rstd = rowB[lrow];
;           float sg4[4];
; #pragma unroll
;           for (int e = 0; e < 4; ++e) sg4[e] = sigmoidf_(rstd * (accu[i][j][4 * q4 + e] - mu * c1a[e]) + c2a[e]);
;           gq[i][j][2 * q4] = pack2(sg4[0], sg4[1]); gq[i][j][2 * q4 + 1] = pack2(sg4[2], sg4[3]);
;         }
;         __builtin_amdgcn_sched_barrier(0);
;       }
	v_fma_f32 v38, v52, v38, v48
	v_fma_f32 v39, v52, v39, v49
	v_fma_f32 v40, v52, v40, v50
	v_fmac_f32_e32 v51, v52, v41
	v_mul_f32_e32 v54, 0xbfb8aa3b, v54
	v_exp_f32_e32 v56, v56
	v_mul_f32_e32 v57, 0xbfb8aa3b, v57
	v_mul_f32_e32 v37, 0xbfb8aa3b, v37
	v_mul_f32_e32 v38, 0xbfb8aa3b, v38
	v_mul_f32_e32 v39, 0xbfb8aa3b, v39
	v_mul_f32_e32 v40, 0xbfb8aa3b, v40
	v_mul_f32_e32 v41, 0xbfb8aa3b, v51
	v_exp_f32_e32 v54, v54
	v_exp_f32_e32 v57, v57
	v_exp_f32_e32 v37, v37
	v_exp_f32_e32 v38, v38
	v_exp_f32_e32 v39, v39
	v_exp_f32_e32 v40, v40
	v_exp_f32_e32 v41, v41
	v_add_f32_e32 v56, 1.0, v56
	v_add_f32_e32 v54, 1.0, v54
	v_rcp_f32_e32 v42, v56
	v_add_f32_e32 v56, 1.0, v57
	v_add_f32_e32 v37, 1.0, v37
	v_add_f32_e32 v38, 1.0, v38
	v_add_f32_e32 v39, 1.0, v39
	v_add_f32_e32 v40, 1.0, v40
	v_add_f32_e32 v41, 1.0, v41
	v_rcp_f32_e32 v54, v54
	v_rcp_f32_e32 v56, v56
	v_rcp_f32_e32 v37, v37
	v_rcp_f32_e32 v38, v38
	v_rcp_f32_e32 v39, v39
	v_rcp_f32_e32 v40, v40
	v_rcp_f32_e32 v41, v41
	v_cvt_pk_bf16_f32 v91, v54, v42
	v_cvt_pk_bf16_f32 v86, v56, v37
	v_cvt_pk_bf16_f32 v85, v38, v39
	v_cvt_pk_bf16_f32 v84, v40, v41
	v_add_u32_e32 v37, 0x24980, v160
	v_add_u32_e32 v42, 0x24d80, v160
	ds_read_b128 v[38:41], v37
	ds_read_b128 v[42:45], v42
	ds_read_b32 v37, v164
	ds_read_b32 v46, v165
	ds_read_b32 v47, v166
	ds_read_b32 v48, v167
	s_waitcnt lgkmcnt(3)
	v_fma_f32 v16, -v38, v37, v16
	v_fma_f32 v17, -v39, v37, v17
	v_fma_f32 v18, -v40, v37, v18
	v_fma_f32 v19, -v41, v37, v19
	s_waitcnt lgkmcnt(1)
	v_fma_f32 v0, -v38, v47, v0
	v_fma_f32 v1, -v39, v47, v1
	v_fma_f32 v2, -v40, v47, v2
	v_fma_f32 v3, -v41, v47, v3
	v_fma_f32 v16, v46, v16, v42
	v_fma_f32 v17, v46, v17, v43
	v_fma_f32 v18, v46, v18, v44
	v_fma_f32 v19, v46, v19, v45
	s_waitcnt lgkmcnt(0)
	v_fma_f32 v0, v48, v0, v42
	v_fma_f32 v1, v48, v1, v43
	v_fma_f32 v2, v48, v2, v44
	v_fmac_f32_e32 v45, v48, v3
	v_mul_f32_e32 v16, 0xbfb8aa3b, v16
	v_mul_f32_e32 v17, 0xbfb8aa3b, v17
	v_mul_f32_e32 v18, 0xbfb8aa3b, v18
	v_mul_f32_e32 v19, 0xbfb8aa3b, v19
	v_mul_f32_e32 v0, 0xbfb8aa3b, v0
	v_mul_f32_e32 v1, 0xbfb8aa3b, v1
	v_mul_f32_e32 v2, 0xbfb8aa3b, v2
	v_mul_f32_e32 v3, 0xbfb8aa3b, v45
	v_exp_f32_e32 v16, v16
	v_exp_f32_e32 v17, v17
	v_exp_f32_e32 v18, v18
	v_exp_f32_e32 v19, v19
	v_exp_f32_e32 v0, v0
	v_exp_f32_e32 v1, v1
	v_exp_f32_e32 v2, v2
	v_exp_f32_e32 v3, v3
	v_add_f32_e32 v16, 1.0, v16
	v_add_f32_e32 v17, 1.0, v17
	v_add_f32_e32 v18, 1.0, v18
	v_add_f32_e32 v19, 1.0, v19
	v_add_f32_e32 v0, 1.0, v0
	v_add_f32_e32 v1, 1.0, v1
	v_add_f32_e32 v2, 1.0, v2
	v_add_f32_e32 v3, 1.0, v3
	v_rcp_f32_e32 v16, v16
	v_rcp_f32_e32 v17, v17
	v_rcp_f32_e32 v18, v18
	v_rcp_f32_e32 v19, v19
	v_rcp_f32_e32 v0, v0
	v_rcp_f32_e32 v1, v1
	v_rcp_f32_e32 v2, v2
	v_rcp_f32_e32 v37, v3
	v_cvt_pk_bf16_f32 v17, v16, v17
	v_cvt_pk_bf16_f32 v16, v18, v19
	v_cvt_pk_bf16_f32 v3, v0, v1
	v_cvt_pk_bf16_f32 v2, v2, v37
	v_add_u32_e32 v0, 0x249a0, v160
	v_add_u32_e32 v1, 0x24da0, v160
	ds_read_b128 v[38:41], v0
	ds_read_b128 v[42:45], v1
	ds_read_b32 v0, v164
	ds_read_b32 v1, v165
	ds_read_b32 v18, v166
	ds_read_b32 v19, v167
	s_waitcnt lgkmcnt(3)
	v_fma_f32 v21, -v39, v0, v21
	v_fma_f32 v20, -v38, v0, v20
	s_waitcnt lgkmcnt(1)
	v_fma_f32 v6, -v40, v18, v6
	v_fma_f32 v21, v1, v21, v43
	v_fma_f32 v22, -v40, v0, v22
	v_fma_f32 v0, -v41, v0, v23
	v_fma_f32 v4, -v38, v18, v4
	v_fma_f32 v5, -v39, v18, v5
	s_waitcnt lgkmcnt(0)
	v_fma_f32 v6, v19, v6, v44
	v_fma_f32 v7, -v41, v18, v7
	v_fma_f32 v20, v1, v20, v42
	v_mul_f32_e32 v21, 0xbfb8aa3b, v21
	v_fma_f32 v22, v1, v22, v44
	v_fma_f32 v0, v1, v0, v45
	v_fma_f32 v4, v19, v4, v42
	v_fma_f32 v5, v19, v5, v43
	v_mul_f32_e32 v6, 0xbfb8aa3b, v6
	v_fmac_f32_e32 v45, v19, v7
	v_mul_f32_e32 v20, 0xbfb8aa3b, v20
	v_exp_f32_e32 v21, v21
	v_mul_f32_e32 v22, 0xbfb8aa3b, v22
	v_mul_f32_e32 v0, 0xbfb8aa3b, v0
	v_mul_f32_e32 v4, 0xbfb8aa3b, v4
	v_mul_f32_e32 v5, 0xbfb8aa3b, v5
	v_exp_f32_e32 v6, v6
	v_mul_f32_e32 v7, 0xbfb8aa3b, v45
	v_exp_f32_e32 v20, v20
	v_exp_f32_e32 v22, v22
	v_exp_f32_e32 v0, v0
	v_exp_f32_e32 v4, v4
	v_exp_f32_e32 v5, v5
	v_exp_f32_e32 v7, v7
	v_add_f32_e32 v21, 1.0, v21
	v_add_f32_e32 v6, 1.0, v6
	v_add_f32_e32 v20, 1.0, v20
	v_rcp_f32_e32 v1, v21
	v_add_f32_e32 v21, 1.0, v22
	v_add_f32_e32 v0, 1.0, v0
	v_add_f32_e32 v4, 1.0, v4
	v_add_f32_e32 v5, 1.0, v5
	v_rcp_f32_e32 v18, v6
	v_add_f32_e32 v6, 1.0, v7
	v_rcp_f32_e32 v20, v20
	v_rcp_f32_e32 v21, v21
	v_rcp_f32_e32 v0, v0
	v_rcp_f32_e32 v4, v4
	v_rcp_f32_e32 v5, v5
	v_rcp_f32_e32 v19, v6
	v_cvt_pk_bf16_f32 v7, v20, v1
	v_cvt_pk_bf16_f32 v6, v21, v0
	v_cvt_pk_bf16_f32 v5, v4, v5
	v_cvt_pk_bf16_f32 v4, v18, v19
	v_add_u32_e32 v0, 0x249c0, v160
	v_add_u32_e32 v1, 0x24dc0, v160
	ds_read_b128 v[18:21], v0
	ds_read_b128 v[38:41], v1
	ds_read_b32 v0, v164
	ds_read_b32 v1, v165
	ds_read_b32 v22, v166
	ds_read_b32 v23, v167
	s_waitcnt lgkmcnt(3)
	v_fma_f32 v25, -v19, v0, v25
	v_fma_f32 v24, -v18, v0, v24
	s_waitcnt lgkmcnt(1)
	v_fma_f32 v9, -v19, v22, v9
	s_waitcnt lgkmcnt(0)
; DI unsigned pack2(float a, float b) { f32x2_t v = {a, b}; bf16x2_t r = __builtin_convertvector(v, bf16x2_t); return __builtin_bit_cast(unsigned, r); }
; DI float sigmoidf_(float x) { return __builtin_amdgcn_rcpf(1.f + __expf(-x)); }
; DI int otid() { int t = threadIdx.x; asm volatile("" : "+v"(t)); return t; }
; template <bool NT>
; DI void stage_load_tile(bf16_t* stg, const bf16_t* tilebase) {
;   const int tid = otid();
;   const int r0 = tid >> 5, c = tid & 31;
;   const unsigned o0 = (unsigned)(r0 * 1024 + c * 8);
;   __builtin_amdgcn_sched_barrier(0);
; #pragma unroll
;   for (int hf = 0; hf < 2; ++hf) {
; #pragma unroll
;     for (int it = 8 * hf; it < 8 * hf + 8; ++it) {
;       const u32x4* gp = (const u32x4*)(tilebase + (o0 + (unsigned)(it * 16 * 1024)));
;       stage_write16(stg, r0 + 16 * it, c, NT ? __builtin_nontemporal_load(gp) : *gp);
;     }
;     __builtin_amdgcn_sched_barrier(0);
;   }
; }
; template <bool LAST>
; DI void phase_gate(const Params& P, int layer, unsigned char* smem, int L, int G) {
;     ...
;     unsigned gq[4][2][8];
; #pragma unroll
;     for (int i = 0; i < 4; ++i)
; #pragma unroll
;       for (int q4 = 0; q4 < 4; ++q4) {
;         const int fl = wm * 128 + i * 32 + 8 * q4 + 4 * h;
;         const f32x4 c1v = *(const f32x4*)(vecL + fl), c2v = *(const f32x4*)(vecL + 256 + fl);
;         const float c1a[4] = {c1v.x, c1v.y, c1v.z, c1v.w}, c2a[4] = {c2v.x, c2v.y, c2v.z, c2v.w};
; #pragma unroll
;         for (int j = 0; j < 2; ++j) {
;           const int lrow = wn * 64 + j * 32 + r;
;           const float mu = rowA[lrow], rstd = rowB[lrow];
;           float sg4[4];
; #pragma unroll
;           for (int e = 0; e < 4; ++e) sg4[e] = sigmoidf_(rstd * (accu[i][j][4 * q4 + e] - mu * c1a[e]) + c2a[e]);
;           gq[i][j][2 * q4] = pack2(sg4[0], sg4[1]); gq[i][j][2 * q4 + 1] = pack2(sg4[2], sg4[3]);
;         }
;         __builtin_amdgcn_sched_barrier(0);
;       }
;     stage_load_tile<true>(stg, PPb + (size_t)mt * 256 * 1024 + nt * 256);
;     __syncthreads();
	v_fma_f32 v9, v23, v9, v39
	v_fma_f32 v10, -v20, v22, v10
	v_fma_f32 v25, v1, v25, v39
	v_fma_f32 v26, -v20, v0, v26
	v_fma_f32 v0, -v21, v0, v27
	v_fma_f32 v8, -v18, v22, v8
	v_mul_f32_e32 v9, 0xbfb8aa3b, v9
	v_fma_f32 v10, v23, v10, v40
	v_fma_f32 v11, -v21, v22, v11
	v_fma_f32 v24, v1, v24, v38
	v_mul_f32_e32 v25, 0xbfb8aa3b, v25
	v_fma_f32 v26, v1, v26, v40
	v_fma_f32 v0, v1, v0, v41
	v_fma_f32 v8, v23, v8, v38
	v_exp_f32_e32 v9, v9
	v_mul_f32_e32 v10, 0xbfb8aa3b, v10
	v_fmac_f32_e32 v41, v23, v11
	v_mul_f32_e32 v24, 0xbfb8aa3b, v24
	v_exp_f32_e32 v25, v25
	v_mul_f32_e32 v26, 0xbfb8aa3b, v26
	v_mul_f32_e32 v0, 0xbfb8aa3b, v0
	v_mul_f32_e32 v8, 0xbfb8aa3b, v8
	v_exp_f32_e32 v10, v10
	v_mul_f32_e32 v11, 0xbfb8aa3b, v41
	v_exp_f32_e32 v24, v24
	v_exp_f32_e32 v26, v26
	v_exp_f32_e32 v0, v0
	v_exp_f32_e32 v8, v8
	v_exp_f32_e32 v11, v11
	v_add_f32_e32 v9, 1.0, v9
	v_add_f32_e32 v25, 1.0, v25
	v_rcp_f32_e32 v18, v9
	v_add_f32_e32 v9, 1.0, v10
	v_add_f32_e32 v24, 1.0, v24
	v_rcp_f32_e32 v1, v25
	v_add_f32_e32 v25, 1.0, v26
	v_add_f32_e32 v0, 1.0, v0
	v_add_f32_e32 v8, 1.0, v8
	v_rcp_f32_e32 v10, v9
	v_add_f32_e32 v9, 1.0, v11
	v_rcp_f32_e32 v24, v24
	v_rcp_f32_e32 v25, v25
	v_rcp_f32_e32 v0, v0
	v_rcp_f32_e32 v8, v8
	v_rcp_f32_e32 v11, v9
	v_cvt_pk_bf16_f32 v27, v24, v1
	v_cvt_pk_bf16_f32 v9, v25, v0
	v_cvt_pk_bf16_f32 v19, v8, v18
	v_cvt_pk_bf16_f32 v8, v10, v11
	v_add_u32_e32 v0, 0x24de0, v160
	ds_read_b128 v[20:23], v163 offset:480
	ds_read_b32 v1, v164
	ds_read_b128 v[38:41], v0
	ds_read_b32 v0, v165
	ds_read_b32 v10, v166
	ds_read_b32 v18, v167
	s_waitcnt lgkmcnt(4)
	v_fma_f32 v24, -v21, v1, v29
	v_fma_f32 v11, -v20, v1, v28
	s_waitcnt lgkmcnt(2)
	v_fma_f32 v24, v0, v24, v39
	v_fma_f32 v25, -v22, v1, v30
	v_fma_f32 v1, -v23, v1, v31
	s_waitcnt lgkmcnt(1)
	v_fma_f32 v12, -v20, v10, v12
	v_fma_f32 v13, -v21, v10, v13
	v_fma_f32 v14, -v22, v10, v14
	v_fma_f32 v10, -v23, v10, v15
	v_fma_f32 v11, v0, v11, v38
	v_mul_f32_e32 v24, 0xbfb8aa3b, v24
	v_fma_f32 v25, v0, v25, v40
	v_fma_f32 v0, v0, v1, v41
	s_waitcnt lgkmcnt(0)
	v_fma_f32 v12, v18, v12, v38
	v_fma_f32 v13, v18, v13, v39
	v_fma_f32 v14, v18, v14, v40
	v_fmac_f32_e32 v41, v18, v10
	v_mul_f32_e32 v11, 0xbfb8aa3b, v11
	v_exp_f32_e32 v24, v24
	v_mul_f32_e32 v25, 0xbfb8aa3b, v25
	v_mul_f32_e32 v0, 0xbfb8aa3b, v0
	v_mul_f32_e32 v12, 0xbfb8aa3b, v12
	v_mul_f32_e32 v13, 0xbfb8aa3b, v13
	v_mul_f32_e32 v14, 0xbfb8aa3b, v14
	v_mul_f32_e32 v10, 0xbfb8aa3b, v41
	v_exp_f32_e32 v11, v11
	v_exp_f32_e32 v25, v25
	v_exp_f32_e32 v0, v0
	v_exp_f32_e32 v12, v12
	v_exp_f32_e32 v13, v13
	v_exp_f32_e32 v14, v14
	v_exp_f32_e32 v10, v10
	v_add_f32_e32 v24, 1.0, v24
	v_add_f32_e32 v11, 1.0, v11
	v_rcp_f32_e32 v1, v24
	v_add_f32_e32 v24, 1.0, v25
	v_add_f32_e32 v0, 1.0, v0
	v_add_f32_e32 v12, 1.0, v12
	v_add_f32_e32 v13, 1.0, v13
	v_add_f32_e32 v14, 1.0, v14
	v_add_f32_e32 v10, 1.0, v10
	v_rcp_f32_e32 v11, v11
	v_rcp_f32_e32 v24, v24
	v_rcp_f32_e32 v0, v0
	v_rcp_f32_e32 v12, v12
	v_rcp_f32_e32 v13, v13
	v_rcp_f32_e32 v14, v14
	v_rcp_f32_e32 v10, v10
	v_cvt_pk_bf16_f32 v112, v11, v1
	v_cvt_pk_bf16_f32 v30, v24, v0
	v_cvt_pk_bf16_f32 v29, v12, v13
	v_cvt_pk_bf16_f32 v28, v14, v10
	v_mov_b32_e32 v163, v161
	v_lshlrev_b64 v[0:1], 1, v[162:163]
	v_and_b32_e32 v26, 31, v192
	v_ashrrev_i32_e32 v18, 5, v192
	v_mul_lo_u32 v18, v18, s40
	v_lshl_add_u32 v18, v26, 4, v18
	v_add_u32_e32 v24, 0x2080, v18
	v_add_u32_e32 v25, 0x4100, v18
	v_add_u32_e32 v26, 0x6180, v18
	v_add_u32_e32 v31, 0x8200, v18
	v_add_u32_e32 v37, 0xa280, v18
	v_add_u32_e32 v50, 0xc300, v18
	v_add_u32_e32 v51, 0xe380, v18
	s_waitcnt vmcnt(15)
	ds_write2_b64 v18, v[180:181], v[182:183] offset1:1
	s_waitcnt vmcnt(14)
	ds_write2_b64 v24, v[184:185], v[186:187] offset1:1
	s_waitcnt vmcnt(13)
	ds_write2_b64 v25, v[194:195], v[196:197] offset1:1
	s_waitcnt vmcnt(12)
	ds_write2_b64 v26, v[198:199], v[200:201] offset1:1
	s_waitcnt vmcnt(11)
	ds_write2_b64 v31, v[202:203], v[204:205] offset1:1
	s_waitcnt vmcnt(10)
	ds_write2_b64 v37, v[206:207], v[208:209] offset1:1
	s_waitcnt vmcnt(9)
	ds_write2_b64 v50, v[210:211], v[212:213] offset1:1
	s_waitcnt vmcnt(8)
	ds_write2_b64 v51, v[214:215], v[216:217] offset1:1
	v_add_u32_e32 v14, 0x10400, v18
	v_add_u32_e32 v15, 0x12480, v18
	v_add_u32_e32 v24, 0x14500, v18
	v_add_u32_e32 v25, 0x16580, v18
	v_add_u32_e32 v26, 0x18600, v18
	v_add_u32_e32 v31, 0x1a680, v18
	v_add_u32_e32 v37, 0x1c700, v18
	v_add_u32_e32 v18, 0x1e780, v18
	s_waitcnt vmcnt(7)
	ds_write2_b64 v14, v[218:219], v[220:221] offset1:1
	s_waitcnt vmcnt(6)
	ds_write2_b64 v15, v[222:223], v[224:225] offset1:1
	s_waitcnt vmcnt(5)
	ds_write2_b64 v24, v[226:227], v[228:229] offset1:1
	s_waitcnt vmcnt(4)
	ds_write2_b64 v25, v[230:231], v[232:233] offset1:1
	s_waitcnt vmcnt(3)
	ds_write2_b64 v26, v[234:235], v[236:237] offset1:1
	s_waitcnt vmcnt(2)
	ds_write2_b64 v31, v[238:239], v[240:241] offset1:1
	s_waitcnt vmcnt(1)
	ds_write2_b64 v37, v[242:243], v[244:245] offset1:1
	s_waitcnt vmcnt(0)
	ds_write2_b64 v18, v[248:249], v[250:251] offset1:1
	v_mov_b32_e32 v10, v192
	s_waitcnt lgkmcnt(0)
	s_barrier
; DI unsigned pack2(float a, float b) { f32x2_t v = {a, b}; bf16x2_t r = __builtin_convertvector(v, bf16x2_t); return __builtin_bit_cast(unsigned, r); }
; DI float bflo(unsigned u) { return __uint_as_float(u << 16); }
; DI float bfhi(unsigned u) { return __uint_as_float(u & 0xffff0000u); }
; DI int otid() { int t = threadIdx.x; asm volatile("" : "+v"(t)); return t; }
; template <bool LAST>
; DI void phase_gate(const Params& P, int layer, unsigned char* smem, int L, int G) {
;     ...
;     {
;       const int tid1 = otid();
;       const int lane1 = tid1 & 63, w1 = tid1 >> 6, r1 = lane1 & 31, h1 = lane1 >> 5, wm1 = w1 >> 2, wn1 = w1 & 3;
; #pragma unroll
;       for (int i = 0; i < 4; ++i)
; #pragma unroll
;         for (int q4 = 0; q4 < 4; ++q4) {
; #pragma unroll
;           for (int j = 0; j < 2; ++j) {
;             const uint2 pv = *(const uint2*)(stg + (wn1 * 64 + j * 32 + r1) * STG + wm1 * 128 + i * 32 + 8 * q4 + 4 * h1);
;             const unsigned g0 = gq[i][j][2 * q4], g1 = gq[i][j][2 * q4 + 1];
;             gq[i][j][2 * q4] = pack2(bflo(g0) * bflo(pv.x), bfhi(g0) * bfhi(pv.x));
;             gq[i][j][2 * q4 + 1] = pack2(bflo(g1) * bflo(pv.y), bfhi(g1) * bfhi(pv.y));
;           }
;           __builtin_amdgcn_sched_barrier(0);
;         }
;     }
;     __syncthreads();
	v_and_b32_e32 v13, 0xffff0000, v99
	v_lshrrev_b32_e32 v12, 2, v10
	v_and_b32_e32 v12, 8, v12
	v_and_b32_e32 v11, 0xdf, v10
	v_and_or_b32 v10, v10, s38, v12
	v_mad_u32_u24 v113, v11, s40, v10
	ds_read_b64 v[10:11], v113
	ds_read_b64 v[14:15], v113 offset:16640
	v_lshlrev_b32_e32 v12, 16, v99
	s_waitcnt lgkmcnt(1)
	v_lshlrev_b32_e32 v20, 16, v10
	v_and_b32_e32 v21, 0xffff0000, v10
	v_pk_mul_f32 v[12:13], v[12:13], v[20:21]
	v_lshlrev_b32_e32 v10, 16, v11
	v_cvt_pk_bf16_f32 v31, v12, v13
	v_lshlrev_b32_e32 v12, 16, v98
	v_and_b32_e32 v13, 0xffff0000, v98
	v_and_b32_e32 v11, 0xffff0000, v11
	v_pk_mul_f32 v[10:11], v[12:13], v[10:11]
	s_waitcnt lgkmcnt(0)
	v_lshlrev_b32_e32 v12, 16, v14
	v_cvt_pk_bf16_f32 v98, v10, v11
	v_lshlrev_b32_e32 v10, 16, v97
	v_and_b32_e32 v11, 0xffff0000, v97
	v_and_b32_e32 v13, 0xffff0000, v14
	v_pk_mul_f32 v[10:11], v[10:11], v[12:13]
	v_lshlrev_b32_e32 v12, 16, v15
	v_cvt_pk_bf16_f32 v97, v10, v11
	v_lshlrev_b32_e32 v10, 16, v96
	v_and_b32_e32 v11, 0xffff0000, v96
	v_and_b32_e32 v13, 0xffff0000, v15
	v_pk_mul_f32 v[10:11], v[10:11], v[12:13]
	s_nop 0
	v_cvt_pk_bf16_f32 v96, v10, v11
	ds_read_b64 v[10:11], v113 offset:16
	ds_read_b64 v[14:15], v113 offset:16656
	v_lshlrev_b32_e32 v12, 16, v103
	v_and_b32_e32 v13, 0xffff0000, v103
	s_waitcnt lgkmcnt(1)
	v_lshlrev_b32_e32 v20, 16, v10
	v_and_b32_e32 v21, 0xffff0000, v10
	v_pk_mul_f32 v[12:13], v[12:13], v[20:21]
	v_lshlrev_b32_e32 v10, 16, v11
	v_cvt_pk_bf16_f32 v93, v12, v13
	v_lshlrev_b32_e32 v12, 16, v102
	v_and_b32_e32 v13, 0xffff0000, v102
	v_and_b32_e32 v11, 0xffff0000, v11
	v_pk_mul_f32 v[10:11], v[12:13], v[10:11]
	s_waitcnt lgkmcnt(0)
	v_lshlrev_b32_e32 v12, 16, v14
	v_cvt_pk_bf16_f32 v95, v10, v11
	v_lshlrev_b32_e32 v10, 16, v101
	v_and_b32_e32 v11, 0xffff0000, v101
	v_and_b32_e32 v13, 0xffff0000, v14
	v_pk_mul_f32 v[10:11], v[10:11], v[12:13]
	v_lshlrev_b32_e32 v12, 16, v15
	v_cvt_pk_bf16_f32 v92, v10, v11
	v_lshlrev_b32_e32 v10, 16, v100
	v_and_b32_e32 v11, 0xffff0000, v100
	v_and_b32_e32 v13, 0xffff0000, v15
	v_pk_mul_f32 v[10:11], v[10:11], v[12:13]
	s_nop 0
	v_cvt_pk_bf16_f32 v94, v10, v11
	ds_read_b64 v[10:11], v113 offset:32
	ds_read_b64 v[14:15], v113 offset:16672
	v_lshlrev_b32_e32 v12, 16, v107
	v_and_b32_e32 v13, 0xffff0000, v107
	s_waitcnt lgkmcnt(1)
	v_lshlrev_b32_e32 v20, 16, v10
	v_and_b32_e32 v21, 0xffff0000, v10
	v_pk_mul_f32 v[12:13], v[12:13], v[20:21]
	v_lshlrev_b32_e32 v10, 16, v11
	v_cvt_pk_bf16_f32 v88, v12, v13
	v_lshlrev_b32_e32 v12, 16, v106
	v_and_b32_e32 v13, 0xffff0000, v106
	v_and_b32_e32 v11, 0xffff0000, v11
	v_pk_mul_f32 v[10:11], v[12:13], v[10:11]
	s_waitcnt lgkmcnt(0)
	v_lshlrev_b32_e32 v12, 16, v14
	v_cvt_pk_bf16_f32 v90, v10, v11
	v_lshlrev_b32_e32 v10, 16, v105
	v_and_b32_e32 v11, 0xffff0000, v105
	v_and_b32_e32 v13, 0xffff0000, v14
	v_pk_mul_f32 v[10:11], v[10:11], v[12:13]
	v_lshlrev_b32_e32 v12, 16, v15
	v_cvt_pk_bf16_f32 v87, v10, v11
	v_lshlrev_b32_e32 v10, 16, v104
	v_and_b32_e32 v11, 0xffff0000, v104
	v_and_b32_e32 v13, 0xffff0000, v15
	v_pk_mul_f32 v[10:11], v[10:11], v[12:13]
	s_nop 0
	v_cvt_pk_bf16_f32 v89, v10, v11
	ds_read_b64 v[10:11], v113 offset:48
	ds_read_b64 v[14:15], v113 offset:16688
	v_lshlrev_b32_e32 v12, 16, v111
	v_and_b32_e32 v13, 0xffff0000, v111
	s_waitcnt lgkmcnt(1)
	v_lshlrev_b32_e32 v20, 16, v10
	v_and_b32_e32 v21, 0xffff0000, v10
	v_pk_mul_f32 v[12:13], v[12:13], v[20:21]
	v_lshlrev_b32_e32 v10, 16, v11
	v_cvt_pk_bf16_f32 v61, v12, v13
	v_lshlrev_b32_e32 v12, 16, v110
	v_and_b32_e32 v13, 0xffff0000, v110
	v_and_b32_e32 v11, 0xffff0000, v11
	v_pk_mul_f32 v[10:11], v[12:13], v[10:11]
	s_waitcnt lgkmcnt(0)
	v_lshlrev_b32_e32 v12, 16, v14
	v_cvt_pk_bf16_f32 v63, v10, v11
	v_lshlrev_b32_e32 v10, 16, v109
	v_and_b32_e32 v11, 0xffff0000, v109
	v_and_b32_e32 v13, 0xffff0000, v14
	v_pk_mul_f32 v[10:11], v[10:11], v[12:13]
	v_lshlrev_b32_e32 v12, 16, v15
	v_cvt_pk_bf16_f32 v60, v10, v11
	v_lshlrev_b32_e32 v10, 16, v108
	v_and_b32_e32 v11, 0xffff0000, v108
	v_and_b32_e32 v13, 0xffff0000, v15
	v_pk_mul_f32 v[10:11], v[10:11], v[12:13]
	s_nop 0
	v_cvt_pk_bf16_f32 v62, v10, v11
	ds_read_b64 v[10:11], v113 offset:64
	ds_read_b64 v[14:15], v113 offset:16704
	v_lshlrev_b32_e32 v12, 16, v67
	v_and_b32_e32 v13, 0xffff0000, v67
	s_waitcnt lgkmcnt(1)
	v_lshlrev_b32_e32 v20, 16, v10
	v_and_b32_e32 v21, 0xffff0000, v10
	v_pk_mul_f32 v[12:13], v[12:13], v[20:21]
	v_lshlrev_b32_e32 v10, 16, v11
	v_cvt_pk_bf16_f32 v56, v12, v13
	v_lshlrev_b32_e32 v12, 16, v66
	v_and_b32_e32 v13, 0xffff0000, v66
	v_and_b32_e32 v11, 0xffff0000, v11
	v_pk_mul_f32 v[10:11], v[12:13], v[10:11]
	s_waitcnt lgkmcnt(0)
	v_lshlrev_b32_e32 v12, 16, v14
	v_cvt_pk_bf16_f32 v58, v10, v11
	v_lshlrev_b32_e32 v10, 16, v65
	v_and_b32_e32 v11, 0xffff0000, v65
	v_and_b32_e32 v13, 0xffff0000, v14
	v_pk_mul_f32 v[10:11], v[10:11], v[12:13]
	v_lshlrev_b32_e32 v12, 16, v15
	v_cvt_pk_bf16_f32 v54, v10, v11
	v_lshlrev_b32_e32 v10, 16, v64
	v_and_b32_e32 v11, 0xffff0000, v64
	v_and_b32_e32 v13, 0xffff0000, v15
	v_pk_mul_f32 v[10:11], v[10:11], v[12:13]
	s_nop 0
	v_cvt_pk_bf16_f32 v57, v10, v11
	ds_read_b64 v[10:11], v113 offset:80
	ds_read_b64 v[14:15], v113 offset:16720
	v_lshlrev_b32_e32 v12, 16, v71
	v_and_b32_e32 v13, 0xffff0000, v71
	s_waitcnt lgkmcnt(1)
	v_lshlrev_b32_e32 v20, 16, v10
	v_and_b32_e32 v21, 0xffff0000, v10
	v_pk_mul_f32 v[12:13], v[12:13], v[20:21]
	v_lshlrev_b32_e32 v10, 16, v11
	v_cvt_pk_bf16_f32 v50, v12, v13
	v_lshlrev_b32_e32 v12, 16, v70
	v_and_b32_e32 v13, 0xffff0000, v70
	v_and_b32_e32 v11, 0xffff0000, v11
	v_pk_mul_f32 v[10:11], v[12:13], v[10:11]
	s_waitcnt lgkmcnt(0)
; DI unsigned pack2(float a, float b) { f32x2_t v = {a, b}; bf16x2_t r = __builtin_convertvector(v, bf16x2_t); return __builtin_bit_cast(unsigned, r); }
; DI float bflo(unsigned u) { return __uint_as_float(u << 16); }
; DI float bfhi(unsigned u) { return __uint_as_float(u & 0xffff0000u); }
; DI int otid() { int t = threadIdx.x; asm volatile("" : "+v"(t)); return t; }
; template <bool LAST>
; DI void phase_gate(const Params& P, int layer, unsigned char* smem, int L, int G) {
;     ...
;     {
;       const int tid1 = otid();
;       const int lane1 = tid1 & 63, w1 = tid1 >> 6, r1 = lane1 & 31, h1 = lane1 >> 5, wm1 = w1 >> 2, wn1 = w1 & 3;
; #pragma unroll
;       for (int i = 0; i < 4; ++i)
; #pragma unroll
;         for (int q4 = 0; q4 < 4; ++q4) {
; #pragma unroll
;           for (int j = 0; j < 2; ++j) {
;             const uint2 pv = *(const uint2*)(stg + (wn1 * 64 + j * 32 + r1) * STG + wm1 * 128 + i * 32 + 8 * q4 + 4 * h1);
;             const unsigned g0 = gq[i][j][2 * q4], g1 = gq[i][j][2 * q4 + 1];
;             gq[i][j][2 * q4] = pack2(bflo(g0) * bflo(pv.x), bfhi(g0) * bfhi(pv.x));
;             gq[i][j][2 * q4 + 1] = pack2(bflo(g1) * bflo(pv.y), bfhi(g1) * bfhi(pv.y));
;           }
;           __builtin_amdgcn_sched_barrier(0);
;         }
;     }
;     __syncthreads();
	v_lshlrev_b32_e32 v12, 16, v14
	v_cvt_pk_bf16_f32 v52, v10, v11
	v_lshlrev_b32_e32 v10, 16, v69
	v_and_b32_e32 v11, 0xffff0000, v69
	v_and_b32_e32 v13, 0xffff0000, v14
	v_pk_mul_f32 v[10:11], v[10:11], v[12:13]
	v_lshlrev_b32_e32 v12, 16, v15
	v_cvt_pk_bf16_f32 v49, v10, v11
	v_lshlrev_b32_e32 v10, 16, v68
	v_and_b32_e32 v11, 0xffff0000, v68
	v_and_b32_e32 v13, 0xffff0000, v15
	v_pk_mul_f32 v[10:11], v[10:11], v[12:13]
	s_nop 0
	v_cvt_pk_bf16_f32 v51, v10, v11
	ds_read_b64 v[10:11], v113 offset:96
	ds_read_b64 v[14:15], v113 offset:16736
	v_lshlrev_b32_e32 v12, 16, v75
	v_and_b32_e32 v13, 0xffff0000, v75
	s_waitcnt lgkmcnt(1)
	v_lshlrev_b32_e32 v20, 16, v10
	v_and_b32_e32 v21, 0xffff0000, v10
	v_pk_mul_f32 v[12:13], v[12:13], v[20:21]
	v_lshlrev_b32_e32 v10, 16, v11
	v_cvt_pk_bf16_f32 v46, v12, v13
	v_lshlrev_b32_e32 v12, 16, v74
	v_and_b32_e32 v13, 0xffff0000, v74
	v_and_b32_e32 v11, 0xffff0000, v11
	v_pk_mul_f32 v[10:11], v[12:13], v[10:11]
	s_waitcnt lgkmcnt(0)
	v_lshlrev_b32_e32 v12, 16, v14
	v_cvt_pk_bf16_f32 v48, v10, v11
	v_lshlrev_b32_e32 v10, 16, v73
	v_and_b32_e32 v11, 0xffff0000, v73
	v_and_b32_e32 v13, 0xffff0000, v14
	v_pk_mul_f32 v[10:11], v[10:11], v[12:13]
	v_lshlrev_b32_e32 v12, 16, v15
	v_cvt_pk_bf16_f32 v45, v10, v11
	v_lshlrev_b32_e32 v10, 16, v72
	v_and_b32_e32 v11, 0xffff0000, v72
	v_and_b32_e32 v13, 0xffff0000, v15
	v_pk_mul_f32 v[10:11], v[10:11], v[12:13]
	s_nop 0
	v_cvt_pk_bf16_f32 v47, v10, v11
	ds_read_b64 v[10:11], v113 offset:112
	ds_read_b64 v[14:15], v113 offset:16752
	v_lshlrev_b32_e32 v12, 16, v79
	v_and_b32_e32 v13, 0xffff0000, v79
	s_waitcnt lgkmcnt(1)
	v_lshlrev_b32_e32 v20, 16, v10
	v_and_b32_e32 v21, 0xffff0000, v10
	v_pk_mul_f32 v[12:13], v[12:13], v[20:21]
	v_lshlrev_b32_e32 v10, 16, v11
	v_cvt_pk_bf16_f32 v42, v12, v13
	v_lshlrev_b32_e32 v12, 16, v78
	v_and_b32_e32 v13, 0xffff0000, v78
	v_and_b32_e32 v11, 0xffff0000, v11
	v_pk_mul_f32 v[10:11], v[12:13], v[10:11]
	s_waitcnt lgkmcnt(0)
	v_lshlrev_b32_e32 v12, 16, v14
	v_cvt_pk_bf16_f32 v44, v10, v11
	v_lshlrev_b32_e32 v10, 16, v77
	v_and_b32_e32 v11, 0xffff0000, v77
	v_and_b32_e32 v13, 0xffff0000, v14
	v_pk_mul_f32 v[10:11], v[10:11], v[12:13]
	v_lshlrev_b32_e32 v12, 16, v15
	v_cvt_pk_bf16_f32 v41, v10, v11
	v_lshlrev_b32_e32 v10, 16, v76
	v_and_b32_e32 v11, 0xffff0000, v76
	v_and_b32_e32 v13, 0xffff0000, v15
	v_pk_mul_f32 v[10:11], v[10:11], v[12:13]
	s_nop 0
	v_cvt_pk_bf16_f32 v43, v10, v11
	ds_read_b64 v[10:11], v113 offset:128
	ds_read_b64 v[14:15], v113 offset:16768
	v_lshlrev_b32_e32 v12, 16, v35
	v_and_b32_e32 v13, 0xffff0000, v35
	s_waitcnt lgkmcnt(1)
	v_lshlrev_b32_e32 v20, 16, v10
	v_and_b32_e32 v21, 0xffff0000, v10
	v_pk_mul_f32 v[12:13], v[12:13], v[20:21]
	v_lshlrev_b32_e32 v10, 16, v11
	v_cvt_pk_bf16_f32 v38, v12, v13
	v_lshlrev_b32_e32 v12, 16, v34
	v_and_b32_e32 v13, 0xffff0000, v34
	v_and_b32_e32 v11, 0xffff0000, v11
	v_pk_mul_f32 v[10:11], v[12:13], v[10:11]
	s_waitcnt lgkmcnt(0)
	v_lshlrev_b32_e32 v12, 16, v14
	v_cvt_pk_bf16_f32 v40, v10, v11
	v_lshlrev_b32_e32 v10, 16, v33
	v_and_b32_e32 v11, 0xffff0000, v33
	v_and_b32_e32 v13, 0xffff0000, v14
	v_pk_mul_f32 v[10:11], v[10:11], v[12:13]
	v_lshlrev_b32_e32 v12, 16, v15
	v_cvt_pk_bf16_f32 v37, v10, v11
	v_lshlrev_b32_e32 v10, 16, v32
	v_and_b32_e32 v11, 0xffff0000, v32
	v_and_b32_e32 v13, 0xffff0000, v15
	v_pk_mul_f32 v[10:11], v[10:11], v[12:13]
	s_nop 0
	v_cvt_pk_bf16_f32 v39, v10, v11
	ds_read_b64 v[10:11], v113 offset:144
	ds_read_b64 v[14:15], v113 offset:16784
	v_lshlrev_b32_e32 v12, 16, v80
	v_and_b32_e32 v13, 0xffff0000, v80
	s_waitcnt lgkmcnt(1)
	v_lshlrev_b32_e32 v20, 16, v10
	v_and_b32_e32 v21, 0xffff0000, v10
	v_pk_mul_f32 v[12:13], v[12:13], v[20:21]
	v_lshlrev_b32_e32 v10, 16, v11
	v_cvt_pk_bf16_f32 v34, v12, v13
	v_lshlrev_b32_e32 v12, 16, v36
	v_and_b32_e32 v13, 0xffff0000, v36
	v_and_b32_e32 v11, 0xffff0000, v11
	v_pk_mul_f32 v[10:11], v[12:13], v[10:11]
	s_waitcnt lgkmcnt(0)
	v_lshlrev_b32_e32 v12, 16, v14
	v_cvt_pk_bf16_f32 v36, v10, v11
	v_lshlrev_b32_e32 v10, 16, v55
	v_and_b32_e32 v11, 0xffff0000, v55
	v_and_b32_e32 v13, 0xffff0000, v14
	v_pk_mul_f32 v[10:11], v[10:11], v[12:13]
	v_lshlrev_b32_e32 v12, 16, v15
	v_cvt_pk_bf16_f32 v32, v10, v11
	v_lshlrev_b32_e32 v10, 16, v53
	v_and_b32_e32 v11, 0xffff0000, v53
	v_and_b32_e32 v13, 0xffff0000, v15
	v_pk_mul_f32 v[10:11], v[10:11], v[12:13]
	s_nop 0
	v_cvt_pk_bf16_f32 v35, v10, v11
	ds_read_b64 v[10:11], v113 offset:160
	ds_read_b64 v[14:15], v113 offset:16800
	v_lshlrev_b32_e32 v12, 16, v83
	v_and_b32_e32 v13, 0xffff0000, v83
	s_waitcnt lgkmcnt(1)
	v_lshlrev_b32_e32 v20, 16, v10
	v_and_b32_e32 v21, 0xffff0000, v10
	v_pk_mul_f32 v[12:13], v[12:13], v[20:21]
	v_lshlrev_b32_e32 v10, 16, v11
	v_cvt_pk_bf16_f32 v24, v12, v13
	v_lshlrev_b32_e32 v12, 16, v82
	v_and_b32_e32 v13, 0xffff0000, v82
	v_and_b32_e32 v11, 0xffff0000, v11
	v_pk_mul_f32 v[10:11], v[12:13], v[10:11]
	s_waitcnt lgkmcnt(0)
	v_lshlrev_b32_e32 v12, 16, v14
	v_cvt_pk_bf16_f32 v26, v10, v11
	v_lshlrev_b32_e32 v10, 16, v81
	v_and_b32_e32 v11, 0xffff0000, v81
	v_and_b32_e32 v13, 0xffff0000, v14
	v_pk_mul_f32 v[10:11], v[10:11], v[12:13]
	v_lshlrev_b32_e32 v12, 16, v15
	v_cvt_pk_bf16_f32 v23, v10, v11
	v_lshlrev_b32_e32 v10, 16, v59
	v_and_b32_e32 v11, 0xffff0000, v59
	v_and_b32_e32 v13, 0xffff0000, v15
	v_pk_mul_f32 v[10:11], v[10:11], v[12:13]
	s_nop 0
	v_cvt_pk_bf16_f32 v25, v10, v11
	ds_read_b64 v[10:11], v113 offset:176
	ds_read_b64 v[14:15], v113 offset:16816
	v_lshlrev_b32_e32 v12, 16, v91
	v_and_b32_e32 v13, 0xffff0000, v91
	s_waitcnt lgkmcnt(1)
; DI unsigned pack2(float a, float b) { f32x2_t v = {a, b}; bf16x2_t r = __builtin_convertvector(v, bf16x2_t); return __builtin_bit_cast(unsigned, r); }
; DI float bflo(unsigned u) { return __uint_as_float(u << 16); }
; DI float bfhi(unsigned u) { return __uint_as_float(u & 0xffff0000u); }
; DI int otid() { int t = threadIdx.x; asm volatile("" : "+v"(t)); return t; }
; template <bool LAST>
; DI void phase_gate(const Params& P, int layer, unsigned char* smem, int L, int G) {
;     ...
;     {
;       const int tid1 = otid();
;       const int lane1 = tid1 & 63, w1 = tid1 >> 6, r1 = lane1 & 31, h1 = lane1 >> 5, wm1 = w1 >> 2, wn1 = w1 & 3;
; #pragma unroll
;       for (int i = 0; i < 4; ++i)
; #pragma unroll
;         for (int q4 = 0; q4 < 4; ++q4) {
; #pragma unroll
;           for (int j = 0; j < 2; ++j) {
;             const uint2 pv = *(const uint2*)(stg + (wn1 * 64 + j * 32 + r1) * STG + wm1 * 128 + i * 32 + 8 * q4 + 4 * h1);
;             const unsigned g0 = gq[i][j][2 * q4], g1 = gq[i][j][2 * q4 + 1];
;             gq[i][j][2 * q4] = pack2(bflo(g0) * bflo(pv.x), bfhi(g0) * bfhi(pv.x));
;             gq[i][j][2 * q4 + 1] = pack2(bflo(g1) * bflo(pv.y), bfhi(g1) * bfhi(pv.y));
;           }
;           __builtin_amdgcn_sched_barrier(0);
;         }
;     }
;     __syncthreads();
	v_lshlrev_b32_e32 v20, 16, v10
	v_and_b32_e32 v21, 0xffff0000, v10
	v_pk_mul_f32 v[12:13], v[12:13], v[20:21]
	v_lshlrev_b32_e32 v10, 16, v11
	v_cvt_pk_bf16_f32 v20, v12, v13
	v_lshlrev_b32_e32 v12, 16, v86
	v_and_b32_e32 v13, 0xffff0000, v86
	v_and_b32_e32 v11, 0xffff0000, v11
	v_pk_mul_f32 v[10:11], v[12:13], v[10:11]
	s_waitcnt lgkmcnt(0)
	v_lshlrev_b32_e32 v12, 16, v14
	v_cvt_pk_bf16_f32 v22, v10, v11
	v_lshlrev_b32_e32 v10, 16, v85
	v_and_b32_e32 v11, 0xffff0000, v85
	v_and_b32_e32 v13, 0xffff0000, v14
	v_pk_mul_f32 v[10:11], v[10:11], v[12:13]
	v_lshlrev_b32_e32 v12, 16, v15
	v_cvt_pk_bf16_f32 v18, v10, v11
	v_lshlrev_b32_e32 v10, 16, v84
	v_and_b32_e32 v11, 0xffff0000, v84
	v_and_b32_e32 v13, 0xffff0000, v15
	v_pk_mul_f32 v[10:11], v[10:11], v[12:13]
	s_nop 0
	v_cvt_pk_bf16_f32 v21, v10, v11
	ds_read_b64 v[10:11], v113 offset:192
	ds_read_b64 v[64:65], v113 offset:16832
	v_lshlrev_b32_e32 v12, 16, v17
	v_and_b32_e32 v13, 0xffff0000, v17
	s_waitcnt lgkmcnt(1)
	v_lshlrev_b32_e32 v14, 16, v10
	v_and_b32_e32 v15, 0xffff0000, v10
	v_pk_mul_f32 v[12:13], v[12:13], v[14:15]
	v_lshlrev_b32_e32 v10, 16, v11
	v_cvt_pk_bf16_f32 v15, v12, v13
	v_lshlrev_b32_e32 v12, 16, v16
	v_and_b32_e32 v13, 0xffff0000, v16
	v_and_b32_e32 v11, 0xffff0000, v11
	v_pk_mul_f32 v[10:11], v[12:13], v[10:11]
	s_waitcnt lgkmcnt(0)
	v_lshlrev_b32_e32 v12, 16, v64
	v_cvt_pk_bf16_f32 v17, v10, v11
	v_lshlrev_b32_e32 v10, 16, v3
	v_and_b32_e32 v11, 0xffff0000, v3
	v_and_b32_e32 v13, 0xffff0000, v64
	v_pk_mul_f32 v[10:11], v[10:11], v[12:13]
	v_lshlrev_b32_e32 v12, 16, v65
	v_cvt_pk_bf16_f32 v14, v10, v11
	v_lshlrev_b32_e32 v10, 16, v2
	v_and_b32_e32 v11, 0xffff0000, v2
	v_and_b32_e32 v13, 0xffff0000, v65
	v_pk_mul_f32 v[2:3], v[10:11], v[12:13]
	s_nop 0
	v_cvt_pk_bf16_f32 v16, v2, v3
	ds_read_b64 v[2:3], v113 offset:208
	ds_read_b64 v[64:65], v113 offset:16848
	v_lshlrev_b32_e32 v10, 16, v7
	v_and_b32_e32 v11, 0xffff0000, v7
	s_waitcnt lgkmcnt(1)
	v_lshlrev_b32_e32 v12, 16, v2
	v_and_b32_e32 v13, 0xffff0000, v2
	v_pk_mul_f32 v[10:11], v[10:11], v[12:13]
	v_lshlrev_b32_e32 v12, 16, v6
	v_lshlrev_b32_e32 v2, 16, v3
	v_and_b32_e32 v13, 0xffff0000, v6
	v_and_b32_e32 v3, 0xffff0000, v3
	v_pk_mul_f32 v[2:3], v[12:13], v[2:3]
	s_waitcnt lgkmcnt(0)
	v_lshlrev_b32_e32 v6, 16, v64
	v_cvt_pk_bf16_f32 v13, v2, v3
	v_lshlrev_b32_e32 v2, 16, v5
	v_and_b32_e32 v3, 0xffff0000, v5
	v_and_b32_e32 v7, 0xffff0000, v64
	v_pk_mul_f32 v[2:3], v[2:3], v[6:7]
	v_cvt_pk_bf16_f32 v11, v10, v11
	v_cvt_pk_bf16_f32 v10, v2, v3
	v_lshlrev_b32_e32 v2, 16, v4
	v_lshlrev_b32_e32 v6, 16, v65
	v_and_b32_e32 v3, 0xffff0000, v4
	v_and_b32_e32 v7, 0xffff0000, v65
	v_pk_mul_f32 v[2:3], v[2:3], v[6:7]
	s_nop 0
	v_cvt_pk_bf16_f32 v12, v2, v3
	ds_read_b64 v[2:3], v113 offset:224
	ds_read_b64 v[64:65], v113 offset:16864
	v_lshlrev_b32_e32 v4, 16, v27
	v_and_b32_e32 v5, 0xffff0000, v27
	s_waitcnt lgkmcnt(1)
	v_lshlrev_b32_e32 v6, 16, v2
	v_and_b32_e32 v7, 0xffff0000, v2
	v_pk_mul_f32 v[4:5], v[4:5], v[6:7]
	v_lshlrev_b32_e32 v2, 16, v3
	v_cvt_pk_bf16_f32 v7, v4, v5
	v_lshlrev_b32_e32 v4, 16, v9
	v_and_b32_e32 v5, 0xffff0000, v9
	v_and_b32_e32 v3, 0xffff0000, v3
	v_pk_mul_f32 v[2:3], v[4:5], v[2:3]
	s_waitcnt lgkmcnt(0)
	v_lshlrev_b32_e32 v4, 16, v64
	v_cvt_pk_bf16_f32 v9, v2, v3
	v_lshlrev_b32_e32 v2, 16, v19
	v_and_b32_e32 v3, 0xffff0000, v19
	v_and_b32_e32 v5, 0xffff0000, v64
	v_pk_mul_f32 v[2:3], v[2:3], v[4:5]
	v_lshlrev_b32_e32 v4, 16, v65
	v_cvt_pk_bf16_f32 v6, v2, v3
	v_lshlrev_b32_e32 v2, 16, v8
	v_and_b32_e32 v3, 0xffff0000, v8
	v_and_b32_e32 v5, 0xffff0000, v65
	v_pk_mul_f32 v[2:3], v[2:3], v[4:5]
	s_nop 0
	v_cvt_pk_bf16_f32 v8, v2, v3
	ds_read_b64 v[2:3], v113 offset:240
	ds_read_b64 v[64:65], v113 offset:16880
	v_lshlrev_b32_e32 v4, 16, v112
	v_and_b32_e32 v5, 0xffff0000, v112
	s_waitcnt lgkmcnt(1)
	v_lshlrev_b32_e32 v66, 16, v2
	v_and_b32_e32 v67, 0xffff0000, v2
	v_pk_mul_f32 v[4:5], v[4:5], v[66:67]
	v_lshlrev_b32_e32 v66, 16, v30
	v_lshlrev_b32_e32 v2, 16, v3
	v_and_b32_e32 v67, 0xffff0000, v30
	v_and_b32_e32 v3, 0xffff0000, v3
	v_pk_mul_f32 v[2:3], v[66:67], v[2:3]
	v_cvt_pk_bf16_f32 v4, v4, v5
	v_cvt_pk_bf16_f32 v5, v2, v3
	v_lshlrev_b32_e32 v2, 16, v29
	s_waitcnt lgkmcnt(0)
	v_lshlrev_b32_e32 v66, 16, v64
	v_and_b32_e32 v3, 0xffff0000, v29
	v_and_b32_e32 v67, 0xffff0000, v64
	v_pk_mul_f32 v[2:3], v[2:3], v[66:67]
	v_lshlrev_b32_e32 v66, 16, v28
	v_lshlrev_b32_e32 v64, 16, v65
	v_and_b32_e32 v67, 0xffff0000, v28
	v_and_b32_e32 v65, 0xffff0000, v65
	v_pk_mul_f32 v[28:29], v[66:67], v[64:65]
	v_cvt_pk_bf16_f32 v2, v2, v3
	v_cvt_pk_bf16_f32 v3, v28, v29
	v_mov_b32_e32 v19, v192
	s_barrier
; DI int otid() { int t = threadIdx.x; asm volatile("" : "+v"(t)); return t; }
; template <bool NT>
; DI void stage_load_tile(bf16_t* stg, const bf16_t* tilebase) {
;   const int tid = otid();
;   const int r0 = tid >> 5, c = tid & 31;
;   const unsigned o0 = (unsigned)(r0 * 1024 + c * 8);
;   __builtin_amdgcn_sched_barrier(0);
; #pragma unroll
;   for (int hf = 0; hf < 2; ++hf) {
; #pragma unroll
;     for (int it = 8 * hf; it < 8 * hf + 8; ++it) {
;       const u32x4* gp = (const u32x4*)(tilebase + (o0 + (unsigned)(it * 16 * 1024)));
;       stage_write16(stg, r0 + 16 * it, c, NT ? __builtin_nontemporal_load(gp) : *gp);
;     }
;     __builtin_amdgcn_sched_barrier(0);
;   }
; }
; template <bool LAST>
; DI void phase_gate(const Params& P, int layer, unsigned char* smem, int L, int G) {
;     ...
;     stage_load_tile<false>(stg, Sb + (size_t)mt * 256 * 1024 + nt * 256);
;     __syncthreads();
	s_add_u32 s26, s76, s24
	v_ashrrev_i32_e32 v27, 5, v19
	v_and_b32_e32 v19, 31, v19
	s_addc_u32 s27, s77, s25
	v_lshlrev_b32_e32 v30, 3, v19
	v_lshl_add_u64 v[28:29], s[26:27], 0, v[0:1]
	v_lshl_or_b32 v160, v27, 10, v30
	v_add_u32_e32 v66, 0x4000, v160
	v_mov_b32_e32 v67, v161
	v_add_u32_e32 v72, 0x8000, v160
	v_mov_b32_e32 v73, v161
	v_add_u32_e32 v74, 0xc000, v160
	v_mov_b32_e32 v75, v161
	v_add_u32_e32 v80, 0x10000, v160
	v_mov_b32_e32 v81, v161
	v_add_u32_e32 v82, 0x14000, v160
	v_mov_b32_e32 v83, v161
	v_lshl_add_u64 v[64:65], v[160:161], 1, v[28:29]
	v_lshl_add_u64 v[68:69], v[66:67], 1, v[28:29]
	v_lshl_add_u64 v[72:73], v[72:73], 1, v[28:29]
	v_lshl_add_u64 v[76:77], v[74:75], 1, v[28:29]
	v_lshl_add_u64 v[80:81], v[80:81], 1, v[28:29]
	v_lshl_add_u64 v[84:85], v[82:83], 1, v[28:29]
	global_load_dwordx4 v[64:67], v[64:65], off
	s_nop 0
	global_load_dwordx4 v[68:71], v[68:69], off
	s_nop 0
	global_load_dwordx4 v[72:75], v[72:73], off
	s_nop 0
	global_load_dwordx4 v[76:79], v[76:77], off
	s_nop 0
	global_load_dwordx4 v[80:83], v[80:81], off
	s_nop 0
	global_load_dwordx4 v[100:103], v[84:85], off
	v_add_u32_e32 v84, 0x18000, v160
	v_mov_b32_e32 v85, v161
	v_add_u32_e32 v104, 0x1c000, v160
	v_mov_b32_e32 v105, v161
	v_lshl_add_u64 v[84:85], v[84:85], 1, v[28:29]
	v_lshl_add_u64 v[108:109], v[104:105], 1, v[28:29]
	global_load_dwordx4 v[104:107], v[84:85], off
	s_nop 0
	global_load_dwordx4 v[108:111], v[108:109], off
	v_add_u32_e32 v218, 0x20000, v160
	v_mov_b32_e32 v219, v161
	v_add_u32_e32 v220, 0x24000, v160
	v_mov_b32_e32 v221, v161
	v_add_u32_e32 v226, 0x28000, v160
	v_mov_b32_e32 v227, v161
	v_add_u32_e32 v228, 0x2c000, v160
	v_mov_b32_e32 v229, v161
	v_add_u32_e32 v234, 0x30000, v160
	v_mov_b32_e32 v235, v161
	v_add_u32_e32 v236, 0x34000, v160
	v_mov_b32_e32 v237, v161
	v_lshl_add_u64 v[218:219], v[218:219], 1, v[28:29]
	v_lshl_add_u64 v[222:223], v[220:221], 1, v[28:29]
	v_lshl_add_u64 v[226:227], v[226:227], 1, v[28:29]
	v_lshl_add_u64 v[230:231], v[228:229], 1, v[28:29]
	v_lshl_add_u64 v[234:235], v[234:235], 1, v[28:29]
	v_lshl_add_u64 v[252:253], v[236:237], 1, v[28:29]
	global_load_dwordx4 v[218:221], v[218:219], off
	s_nop 0
	global_load_dwordx4 v[222:225], v[222:223], off
	s_nop 0
	global_load_dwordx4 v[226:229], v[226:227], off
	s_nop 0
	global_load_dwordx4 v[230:233], v[230:231], off
	s_nop 0
	global_load_dwordx4 v[234:237], v[234:235], off
	s_nop 0
	global_load_dwordx4 v[238:241], v[252:253], off
	v_add_u32_e32 v252, 0x38000, v160
	v_mov_b32_e32 v253, v161
	v_lshl_add_u64 v[252:253], v[252:253], 1, v[28:29]
	v_add_u32_e32 v160, 0x3c000, v160
	v_lshl_add_u64 v[190:191], v[160:161], 1, v[28:29]
	global_load_dwordx4 v[242:245], v[252:253], off
	global_load_dwordx4 v[248:251], v[190:191], off
	v_mul_lo_u32 v27, v27, s40
	v_lshl_add_u32 v19, v19, 4, v27
	v_add_u32_e32 v27, 0x2080, v19
	v_add_u32_e32 v30, 0x4100, v19
	v_add_u32_e32 v33, 0x6180, v19
	v_add_u32_e32 v53, 0x8200, v19
	v_add_u32_e32 v55, 0xa280, v19
	v_add_u32_e32 v59, 0xc300, v19
	v_add_u32_e32 v84, 0xe380, v19
	s_waitcnt vmcnt(15)
	ds_write2_b64 v19, v[64:65], v[66:67] offset1:1
	s_waitcnt vmcnt(14)
	ds_write2_b64 v27, v[68:69], v[70:71] offset1:1
	s_waitcnt vmcnt(13)
	ds_write2_b64 v30, v[72:73], v[74:75] offset1:1
	s_waitcnt vmcnt(12)
	ds_write2_b64 v33, v[76:77], v[78:79] offset1:1
	s_waitcnt vmcnt(11)
	ds_write2_b64 v53, v[80:81], v[82:83] offset1:1
	s_waitcnt vmcnt(10)
	ds_write2_b64 v55, v[100:101], v[102:103] offset1:1
	s_waitcnt vmcnt(9)
	ds_write2_b64 v59, v[104:105], v[106:107] offset1:1
	s_waitcnt vmcnt(8)
	ds_write2_b64 v84, v[108:109], v[110:111] offset1:1
	v_add_u32_e32 v27, 0x10400, v19
	v_add_u32_e32 v28, 0x12480, v19
	v_add_u32_e32 v29, 0x14500, v19
	v_add_u32_e32 v30, 0x16580, v19
	v_add_u32_e32 v33, 0x18600, v19
	v_add_u32_e32 v53, 0x1a680, v19
	v_add_u32_e32 v55, 0x1c700, v19
	v_add_u32_e32 v19, 0x1e780, v19
	s_waitcnt vmcnt(7)
	ds_write2_b64 v27, v[218:219], v[220:221] offset1:1
	s_waitcnt vmcnt(6)
	ds_write2_b64 v28, v[222:223], v[224:225] offset1:1
	s_waitcnt vmcnt(5)
	ds_write2_b64 v29, v[226:227], v[228:229] offset1:1
	s_waitcnt vmcnt(4)
	ds_write2_b64 v30, v[230:231], v[232:233] offset1:1
	s_waitcnt vmcnt(3)
	ds_write2_b64 v33, v[234:235], v[236:237] offset1:1
	s_waitcnt vmcnt(2)
	ds_write2_b64 v53, v[238:239], v[240:241] offset1:1
	s_waitcnt vmcnt(1)
	ds_write2_b64 v55, v[242:243], v[244:245] offset1:1
	s_waitcnt vmcnt(0)
	ds_write2_b64 v19, v[248:249], v[250:251] offset1:1
	v_mov_b32_e32 v19, v192
	s_waitcnt lgkmcnt(0)
	s_barrier
; DI unsigned pack2(float a, float b) { f32x2_t v = {a, b}; bf16x2_t r = __builtin_convertvector(v, bf16x2_t); return __builtin_bit_cast(unsigned, r); }
; DI float bflo(unsigned u) { return __uint_as_float(u << 16); }
; DI float bfhi(unsigned u) { return __uint_as_float(u & 0xffff0000u); }
; DI int otid() { int t = threadIdx.x; asm volatile("" : "+v"(t)); return t; }
; template <bool LAST>
; DI void phase_gate(const Params& P, int layer, unsigned char* smem, int L, int G) {
;     ...
;     const int tid2 = otid();
;     const int lane2 = tid2 & 63, w2 = tid2 >> 6, r2 = lane2 & 31, h2 = lane2 >> 5, wm2 = w2 >> 2, wn2 = w2 & 3;
; #pragma unroll
;     for (int i = 0; i < 4; ++i)
; #pragma unroll
;       for (int q4 = 0; q4 < 4; ++q4) {
;         const int fl = wm2 * 128 + i * 32 + 8 * q4 + 4 * h2;
;         const int f0 = nt * 256 + fl;
;         const f32x4 gv = *(const f32x4*)(vecL + 512 + fl), bv = *(const f32x4*)(vecL + 768 + fl);
;         const float ga[4] = {gv.x, gv.y, gv.z, gv.w}, ba[4] = {bv.x, bv.y, bv.z, bv.w};
; #pragma unroll
;         for (int j = 0; j < 2; ++j) {
;           const int lrow = wn2 * 64 + j * 32 + r2;
;           const float mu = rowA[lrow], rstd = rowB[lrow];
;           uint2* sp = (uint2*)(stg + lrow * STG + fl);
;           const uint2 sv = *sp;
;           const float sa[4] = {bflo(sv.x), bfhi(sv.x), bflo(sv.y), bfhi(sv.y)};
;           float y[4];
;           const float gg[4] = {bflo(gq[i][j][2 * q4]), bfhi(gq[i][j][2 * q4]), bflo(gq[i][j][2 * q4 + 1]), bfhi(gq[i][j][2 * q4 + 1])};
; #pragma unroll
;           for (int e = 0; e < 4; ++e) y[e] = (sa[e] - mu) * rstd * ga[e] + ba[e] + gg[e];
;           if (LAST) { f32x4 o = {y[0], y[1], y[2], y[3]}; *(f32x4*)(P.out + (size_t)(mt * 256 + lrow) * 1024 + f0) = o; }
;           else { uint2 pk; pk.x = pack2(y[0], y[1]); pk.y = pack2(y[2], y[3]); *sp = pk; }
;         }
;         __builtin_amdgcn_sched_barrier(0);
;       }
	v_lshlrev_b32_e32 v82, 16, v31
	v_lshrrev_b32_e32 v28, 3, v19
	v_ashrrev_i32_e32 v27, 1, v19
	v_and_b32_e32 v28, 4, v28
	v_and_or_b32 v30, v27, s41, v28
	v_and_b32_e32 v19, 0xdf, v19
	v_lshlrev_b32_e32 v27, 2, v30
	v_lshlrev_b32_e32 v33, 2, v19
	v_mul_u32_u24_e32 v19, 0x208, v19
	v_add_u32_e32 v28, 0x25000, v27
	v_lshl_add_u32 v19, v30, 1, v19
	v_add_u32_e32 v29, 0x25400, v27
	ds_read_b128 v[64:67], v28
	ds_read_b128 v[68:71], v29
	ds_read_b64 v[72:73], v19
	v_or_b32_e32 v29, 0x24000, v33
	v_or_b32_e32 v30, 0x24400, v33
	ds_read_b32 v74, v29
	ds_read_b32 v76, v30
	ds_read_b64 v[78:79], v19 offset:16640
	v_and_b32_e32 v83, 0xffff0000, v31
	s_waitcnt lgkmcnt(3)
	v_lshlrev_b32_e32 v80, 16, v72
	v_and_b32_e32 v81, 0xffff0000, v72
	v_lshlrev_b32_e32 v72, 16, v73
	v_and_b32_e32 v73, 0xffff0000, v73
	s_waitcnt lgkmcnt(2)
	v_pk_add_f32 v[80:81], v[80:81], v[74:75] op_sel_hi:[1,0] neg_lo:[0,1] neg_hi:[0,1]
	v_pk_add_f32 v[72:73], v[72:73], v[74:75] op_sel_hi:[1,0] neg_lo:[0,1] neg_hi:[0,1]
	s_waitcnt lgkmcnt(1)
	v_pk_mul_f32 v[80:81], v[76:77], v[80:81] op_sel_hi:[0,1]
	v_pk_mul_f32 v[72:73], v[76:77], v[72:73] op_sel_hi:[0,1]
	v_lshlrev_b32_e32 v84, 16, v98
	v_and_b32_e32 v85, 0xffff0000, v98
	v_pk_fma_f32 v[80:81], v[64:65], v[80:81], v[68:69]
	v_pk_fma_f32 v[72:73], v[66:67], v[72:73], v[70:71]
	v_pk_add_f32 v[80:81], v[80:81], v[82:83]
	v_pk_add_f32 v[72:73], v[72:73], v[84:85]
	v_cvt_pk_bf16_f32 v74, v80, v81
	v_cvt_pk_bf16_f32 v75, v72, v73
	ds_write_b64 v19, v[74:75]
	v_or_b32_e32 v31, 0x24080, v33
	v_or_b32_e32 v33, 0x24480, v33
	ds_read_b32 v72, v31
	ds_read_b32 v74, v33
	s_waitcnt lgkmcnt(3)
	v_lshlrev_b32_e32 v76, 16, v78
	v_and_b32_e32 v77, 0xffff0000, v78
	v_lshlrev_b32_e32 v78, 16, v79
	s_waitcnt lgkmcnt(1)
	v_pk_add_f32 v[76:77], v[76:77], v[72:73] op_sel_hi:[1,0] neg_lo:[0,1] neg_hi:[0,1]
	v_and_b32_e32 v79, 0xffff0000, v79
	s_waitcnt lgkmcnt(0)
	v_pk_mul_f32 v[76:77], v[74:75], v[76:77] op_sel_hi:[0,1]
	v_pk_fma_f32 v[64:65], v[64:65], v[76:77], v[68:69]
	v_pk_add_f32 v[68:69], v[78:79], v[72:73] op_sel_hi:[1,0] neg_lo:[0,1] neg_hi:[0,1]
	v_lshlrev_b32_e32 v80, 16, v97
	v_pk_mul_f32 v[68:69], v[74:75], v[68:69] op_sel_hi:[0,1]
	v_and_b32_e32 v81, 0xffff0000, v97
	v_lshlrev_b32_e32 v82, 16, v96
	v_and_b32_e32 v83, 0xffff0000, v96
	v_pk_fma_f32 v[66:67], v[66:67], v[68:69], v[70:71]
	v_pk_add_f32 v[64:65], v[64:65], v[80:81]
	v_pk_add_f32 v[66:67], v[66:67], v[82:83]
	v_cvt_pk_bf16_f32 v64, v64, v65
	v_cvt_pk_bf16_f32 v65, v66, v67
	ds_write_b64 v19, v[64:65] offset:16640
	v_add_u32_e32 v53, 0x25020, v27
	v_add_u32_e32 v55, 0x25420, v27
	ds_read_b64 v[72:73], v19 offset:16
	ds_read_b128 v[64:67], v53
	ds_read_b128 v[68:71], v55
	ds_read_b32 v74, v29
	ds_read_b32 v76, v30
	ds_read_b64 v[78:79], v19 offset:16656
	s_waitcnt lgkmcnt(5)
	v_lshlrev_b32_e32 v80, 16, v72
	v_and_b32_e32 v81, 0xffff0000, v72
	v_lshlrev_b32_e32 v72, 16, v73
	v_and_b32_e32 v73, 0xffff0000, v73
	s_waitcnt lgkmcnt(2)
	v_pk_add_f32 v[80:81], v[80:81], v[74:75] op_sel_hi:[1,0] neg_lo:[0,1] neg_hi:[0,1]
	v_pk_add_f32 v[72:73], v[72:73], v[74:75] op_sel_hi:[1,0] neg_lo:[0,1] neg_hi:[0,1]
	s_waitcnt lgkmcnt(1)
	v_pk_mul_f32 v[80:81], v[76:77], v[80:81] op_sel_hi:[0,1]
	v_pk_mul_f32 v[72:73], v[76:77], v[72:73] op_sel_hi:[0,1]
	v_lshlrev_b32_e32 v82, 16, v93
	v_and_b32_e32 v83, 0xffff0000, v93
	v_lshlrev_b32_e32 v84, 16, v95
	v_and_b32_e32 v85, 0xffff0000, v95
	v_pk_fma_f32 v[80:81], v[64:65], v[80:81], v[68:69]
	v_pk_fma_f32 v[72:73], v[66:67], v[72:73], v[70:71]
	v_pk_add_f32 v[80:81], v[80:81], v[82:83]
	v_pk_add_f32 v[72:73], v[72:73], v[84:85]
	v_cvt_pk_bf16_f32 v74, v80, v81
	v_cvt_pk_bf16_f32 v75, v72, v73
	ds_write_b64 v19, v[74:75] offset:16
	ds_read_b32 v72, v31
	ds_read_b32 v74, v33
	s_waitcnt lgkmcnt(3)
	v_lshlrev_b32_e32 v76, 16, v78
	v_and_b32_e32 v77, 0xffff0000, v78
	v_lshlrev_b32_e32 v78, 16, v79
	s_waitcnt lgkmcnt(1)
	v_pk_add_f32 v[76:77], v[76:77], v[72:73] op_sel_hi:[1,0] neg_lo:[0,1] neg_hi:[0,1]
	v_and_b32_e32 v79, 0xffff0000, v79
	s_waitcnt lgkmcnt(0)
	v_pk_mul_f32 v[76:77], v[74:75], v[76:77] op_sel_hi:[0,1]
	v_pk_fma_f32 v[64:65], v[64:65], v[76:77], v[68:69]
	v_pk_add_f32 v[68:69], v[78:79], v[72:73] op_sel_hi:[1,0] neg_lo:[0,1] neg_hi:[0,1]
	v_lshlrev_b32_e32 v80, 16, v92
	v_pk_mul_f32 v[68:69], v[74:75], v[68:69] op_sel_hi:[0,1]
	v_and_b32_e32 v81, 0xffff0000, v92
	v_lshlrev_b32_e32 v82, 16, v94
	v_and_b32_e32 v83, 0xffff0000, v94
	v_pk_fma_f32 v[66:67], v[66:67], v[68:69], v[70:71]
	v_pk_add_f32 v[64:65], v[64:65], v[80:81]
	v_pk_add_f32 v[66:67], v[66:67], v[82:83]
	v_cvt_pk_bf16_f32 v64, v64, v65
	v_cvt_pk_bf16_f32 v65, v66, v67
	ds_write_b64 v19, v[64:65] offset:16656
	v_add_u32_e32 v53, 0x25040, v27
	v_add_u32_e32 v55, 0x25440, v27
	ds_read_b64 v[72:73], v19 offset:32
	ds_read_b128 v[64:67], v53
	ds_read_b128 v[68:71], v55
	ds_read_b32 v74, v29
	ds_read_b32 v76, v30
	ds_read_b64 v[78:79], v19 offset:16672
	s_waitcnt lgkmcnt(5)
	v_lshlrev_b32_e32 v80, 16, v72
	v_and_b32_e32 v81, 0xffff0000, v72
	v_lshlrev_b32_e32 v72, 16, v73
	v_and_b32_e32 v73, 0xffff0000, v73
	s_waitcnt lgkmcnt(2)
	v_pk_add_f32 v[80:81], v[80:81], v[74:75] op_sel_hi:[1,0] neg_lo:[0,1] neg_hi:[0,1]
	v_pk_add_f32 v[72:73], v[72:73], v[74:75] op_sel_hi:[1,0] neg_lo:[0,1] neg_hi:[0,1]
	s_waitcnt lgkmcnt(1)
	v_pk_mul_f32 v[80:81], v[76:77], v[80:81] op_sel_hi:[0,1]
	v_pk_mul_f32 v[72:73], v[76:77], v[72:73] op_sel_hi:[0,1]
	v_lshlrev_b32_e32 v82, 16, v88
	v_and_b32_e32 v83, 0xffff0000, v88
	v_lshlrev_b32_e32 v84, 16, v90
	v_and_b32_e32 v85, 0xffff0000, v90
	v_pk_fma_f32 v[80:81], v[64:65], v[80:81], v[68:69]
	v_pk_fma_f32 v[72:73], v[66:67], v[72:73], v[70:71]
	v_pk_add_f32 v[80:81], v[80:81], v[82:83]
	v_pk_add_f32 v[72:73], v[72:73], v[84:85]
	v_cvt_pk_bf16_f32 v74, v80, v81
	v_cvt_pk_bf16_f32 v75, v72, v73
	ds_write_b64 v19, v[74:75] offset:32
	ds_read_b32 v72, v31
	ds_read_b32 v74, v33
	s_waitcnt lgkmcnt(3)
; DI unsigned pack2(float a, float b) { f32x2_t v = {a, b}; bf16x2_t r = __builtin_convertvector(v, bf16x2_t); return __builtin_bit_cast(unsigned, r); }
; DI float bflo(unsigned u) { return __uint_as_float(u << 16); }
; DI float bfhi(unsigned u) { return __uint_as_float(u & 0xffff0000u); }
; DI int otid() { int t = threadIdx.x; asm volatile("" : "+v"(t)); return t; }
; template <bool LAST>
; DI void phase_gate(const Params& P, int layer, unsigned char* smem, int L, int G) {
;     ...
;     const int tid2 = otid();
;     const int lane2 = tid2 & 63, w2 = tid2 >> 6, r2 = lane2 & 31, h2 = lane2 >> 5, wm2 = w2 >> 2, wn2 = w2 & 3;
; #pragma unroll
;     for (int i = 0; i < 4; ++i)
; #pragma unroll
;       for (int q4 = 0; q4 < 4; ++q4) {
;         const int fl = wm2 * 128 + i * 32 + 8 * q4 + 4 * h2;
;         const int f0 = nt * 256 + fl;
;         const f32x4 gv = *(const f32x4*)(vecL + 512 + fl), bv = *(const f32x4*)(vecL + 768 + fl);
;         const float ga[4] = {gv.x, gv.y, gv.z, gv.w}, ba[4] = {bv.x, bv.y, bv.z, bv.w};
; #pragma unroll
;         for (int j = 0; j < 2; ++j) {
;           const int lrow = wn2 * 64 + j * 32 + r2;
;           const float mu = rowA[lrow], rstd = rowB[lrow];
;           uint2* sp = (uint2*)(stg + lrow * STG + fl);
;           const uint2 sv = *sp;
;           const float sa[4] = {bflo(sv.x), bfhi(sv.x), bflo(sv.y), bfhi(sv.y)};
;           float y[4];
;           const float gg[4] = {bflo(gq[i][j][2 * q4]), bfhi(gq[i][j][2 * q4]), bflo(gq[i][j][2 * q4 + 1]), bfhi(gq[i][j][2 * q4 + 1])};
; #pragma unroll
;           for (int e = 0; e < 4; ++e) y[e] = (sa[e] - mu) * rstd * ga[e] + ba[e] + gg[e];
;           if (LAST) { f32x4 o = {y[0], y[1], y[2], y[3]}; *(f32x4*)(P.out + (size_t)(mt * 256 + lrow) * 1024 + f0) = o; }
;           else { uint2 pk; pk.x = pack2(y[0], y[1]); pk.y = pack2(y[2], y[3]); *sp = pk; }
;         }
;         __builtin_amdgcn_sched_barrier(0);
;       }
	v_lshlrev_b32_e32 v76, 16, v78
	v_and_b32_e32 v77, 0xffff0000, v78
	v_lshlrev_b32_e32 v78, 16, v79
	s_waitcnt lgkmcnt(1)
	v_pk_add_f32 v[76:77], v[76:77], v[72:73] op_sel_hi:[1,0] neg_lo:[0,1] neg_hi:[0,1]
	v_and_b32_e32 v79, 0xffff0000, v79
	s_waitcnt lgkmcnt(0)
	v_pk_mul_f32 v[76:77], v[74:75], v[76:77] op_sel_hi:[0,1]
	v_pk_fma_f32 v[64:65], v[64:65], v[76:77], v[68:69]
	v_pk_add_f32 v[68:69], v[78:79], v[72:73] op_sel_hi:[1,0] neg_lo:[0,1] neg_hi:[0,1]
	v_lshlrev_b32_e32 v80, 16, v87
	v_pk_mul_f32 v[68:69], v[74:75], v[68:69] op_sel_hi:[0,1]
	v_and_b32_e32 v81, 0xffff0000, v87
	v_lshlrev_b32_e32 v82, 16, v89
	v_and_b32_e32 v83, 0xffff0000, v89
	v_pk_fma_f32 v[66:67], v[66:67], v[68:69], v[70:71]
	v_pk_add_f32 v[64:65], v[64:65], v[80:81]
	v_pk_add_f32 v[66:67], v[66:67], v[82:83]
	v_cvt_pk_bf16_f32 v64, v64, v65
	v_cvt_pk_bf16_f32 v65, v66, v67
	ds_write_b64 v19, v[64:65] offset:16672
	v_add_u32_e32 v53, 0x25060, v27
	v_add_u32_e32 v55, 0x25460, v27
	ds_read_b64 v[72:73], v19 offset:48
	ds_read_b128 v[64:67], v53
	ds_read_b128 v[68:71], v55
	ds_read_b32 v74, v29
	ds_read_b32 v76, v30
	ds_read_b64 v[78:79], v19 offset:16688
	s_waitcnt lgkmcnt(5)
	v_lshlrev_b32_e32 v80, 16, v72
	v_and_b32_e32 v81, 0xffff0000, v72
	v_lshlrev_b32_e32 v72, 16, v73
	v_and_b32_e32 v73, 0xffff0000, v73
	s_waitcnt lgkmcnt(2)
	v_pk_add_f32 v[80:81], v[80:81], v[74:75] op_sel_hi:[1,0] neg_lo:[0,1] neg_hi:[0,1]
	v_pk_add_f32 v[72:73], v[72:73], v[74:75] op_sel_hi:[1,0] neg_lo:[0,1] neg_hi:[0,1]
	s_waitcnt lgkmcnt(1)
	v_pk_mul_f32 v[80:81], v[76:77], v[80:81] op_sel_hi:[0,1]
	v_pk_mul_f32 v[72:73], v[76:77], v[72:73] op_sel_hi:[0,1]
	v_lshlrev_b32_e32 v82, 16, v61
	v_and_b32_e32 v83, 0xffff0000, v61
	v_lshlrev_b32_e32 v84, 16, v63
	v_and_b32_e32 v85, 0xffff0000, v63
	v_pk_fma_f32 v[80:81], v[64:65], v[80:81], v[68:69]
	v_pk_fma_f32 v[72:73], v[66:67], v[72:73], v[70:71]
	v_pk_add_f32 v[80:81], v[80:81], v[82:83]
	v_pk_add_f32 v[72:73], v[72:73], v[84:85]
	v_cvt_pk_bf16_f32 v74, v80, v81
	v_cvt_pk_bf16_f32 v75, v72, v73
	ds_write_b64 v19, v[74:75] offset:48
	ds_read_b32 v72, v31
	ds_read_b32 v74, v33
	s_waitcnt lgkmcnt(3)
	v_lshlrev_b32_e32 v76, 16, v78
	v_and_b32_e32 v77, 0xffff0000, v78
	v_lshlrev_b32_e32 v80, 16, v60
	v_and_b32_e32 v81, 0xffff0000, v60
	v_lshlrev_b32_e32 v60, 16, v62
	v_and_b32_e32 v61, 0xffff0000, v62
	s_waitcnt lgkmcnt(1)
	v_pk_add_f32 v[62:63], v[76:77], v[72:73] op_sel_hi:[1,0] neg_lo:[0,1] neg_hi:[0,1]
	v_lshlrev_b32_e32 v78, 16, v79
	v_and_b32_e32 v79, 0xffff0000, v79
	s_waitcnt lgkmcnt(0)
	v_pk_mul_f32 v[62:63], v[74:75], v[62:63] op_sel_hi:[0,1]
	v_pk_fma_f32 v[62:63], v[64:65], v[62:63], v[68:69]
	v_pk_add_f32 v[64:65], v[78:79], v[72:73] op_sel_hi:[1,0] neg_lo:[0,1] neg_hi:[0,1]
	v_pk_add_f32 v[62:63], v[62:63], v[80:81]
	v_pk_mul_f32 v[64:65], v[74:75], v[64:65] op_sel_hi:[0,1]
	v_pk_fma_f32 v[64:65], v[66:67], v[64:65], v[70:71]
	v_cvt_pk_bf16_f32 v62, v62, v63
	v_pk_add_f32 v[60:61], v[64:65], v[60:61]
	s_nop 0
	v_cvt_pk_bf16_f32 v63, v60, v61
	ds_write_b64 v19, v[62:63] offset:16688
	v_add_u32_e32 v53, 0x25080, v27
	v_add_u32_e32 v55, 0x25480, v27
	ds_read_b64 v[68:69], v19 offset:64
	ds_read_b128 v[60:63], v53
	ds_read_b128 v[64:67], v55
	ds_read_b32 v70, v29
	ds_read_b32 v72, v30
	ds_read_b64 v[74:75], v19 offset:16704
	s_waitcnt lgkmcnt(5)
	v_lshlrev_b32_e32 v76, 16, v68
	v_and_b32_e32 v77, 0xffff0000, v68
	v_lshlrev_b32_e32 v68, 16, v69
	v_and_b32_e32 v69, 0xffff0000, v69
	v_lshlrev_b32_e32 v80, 16, v58
	v_and_b32_e32 v81, 0xffff0000, v58
	s_waitcnt lgkmcnt(2)
	v_pk_add_f32 v[58:59], v[76:77], v[70:71] op_sel_hi:[1,0] neg_lo:[0,1] neg_hi:[0,1]
	v_pk_add_f32 v[68:69], v[68:69], v[70:71] op_sel_hi:[1,0] neg_lo:[0,1] neg_hi:[0,1]
	s_waitcnt lgkmcnt(1)
	v_pk_mul_f32 v[58:59], v[72:73], v[58:59] op_sel_hi:[0,1]
	v_pk_mul_f32 v[68:69], v[72:73], v[68:69] op_sel_hi:[0,1]
	v_lshlrev_b32_e32 v78, 16, v56
	v_and_b32_e32 v79, 0xffff0000, v56
	v_pk_fma_f32 v[58:59], v[60:61], v[58:59], v[64:65]
	v_pk_fma_f32 v[68:69], v[62:63], v[68:69], v[66:67]
	v_pk_add_f32 v[58:59], v[58:59], v[78:79]
	v_pk_add_f32 v[68:69], v[68:69], v[80:81]
	v_cvt_pk_bf16_f32 v58, v58, v59
	v_cvt_pk_bf16_f32 v59, v68, v69
	ds_write_b64 v19, v[58:59] offset:64
	ds_read_b32 v56, v31
	ds_read_b32 v58, v33
	s_waitcnt lgkmcnt(3)
	v_lshlrev_b32_e32 v68, 16, v74
	v_and_b32_e32 v69, 0xffff0000, v74
	v_lshlrev_b32_e32 v70, 16, v75
	v_and_b32_e32 v71, 0xffff0000, v75
	v_lshlrev_b32_e32 v72, 16, v54
	v_and_b32_e32 v73, 0xffff0000, v54
	v_lshlrev_b32_e32 v54, 16, v57
	v_and_b32_e32 v55, 0xffff0000, v57
	s_waitcnt lgkmcnt(1)
	v_pk_add_f32 v[68:69], v[68:69], v[56:57] op_sel_hi:[1,0] neg_lo:[0,1] neg_hi:[0,1]
	v_pk_add_f32 v[56:57], v[70:71], v[56:57] op_sel_hi:[1,0] neg_lo:[0,1] neg_hi:[0,1]
	s_waitcnt lgkmcnt(0)
	v_pk_mul_f32 v[68:69], v[58:59], v[68:69] op_sel_hi:[0,1]
	v_pk_mul_f32 v[56:57], v[58:59], v[56:57] op_sel_hi:[0,1]
	v_pk_fma_f32 v[60:61], v[60:61], v[68:69], v[64:65]
	v_pk_fma_f32 v[56:57], v[62:63], v[56:57], v[66:67]
	v_pk_add_f32 v[60:61], v[60:61], v[72:73]
	v_pk_add_f32 v[54:55], v[56:57], v[54:55]
	v_cvt_pk_bf16_f32 v56, v60, v61
	v_cvt_pk_bf16_f32 v57, v54, v55
	ds_write_b64 v19, v[56:57] offset:16704
	v_add_u32_e32 v58, 0x254a0, v27
	v_add_u32_e32 v53, 0x250a0, v27
	ds_read_b64 v[62:63], v19 offset:80
	ds_read_b128 v[54:57], v53
	ds_read_b128 v[58:61], v58
	ds_read_b32 v64, v29
	ds_read_b32 v66, v30
	ds_read_b64 v[68:69], v19 offset:16720
	s_waitcnt lgkmcnt(5)
	v_lshlrev_b32_e32 v70, 16, v62
	v_and_b32_e32 v71, 0xffff0000, v62
	v_lshlrev_b32_e32 v62, 16, v63
	v_and_b32_e32 v63, 0xffff0000, v63
	v_lshlrev_b32_e32 v74, 16, v52
	v_and_b32_e32 v75, 0xffff0000, v52
	s_waitcnt lgkmcnt(2)
; DI unsigned pack2(float a, float b) { f32x2_t v = {a, b}; bf16x2_t r = __builtin_convertvector(v, bf16x2_t); return __builtin_bit_cast(unsigned, r); }
; DI float bflo(unsigned u) { return __uint_as_float(u << 16); }
; DI float bfhi(unsigned u) { return __uint_as_float(u & 0xffff0000u); }
; DI int otid() { int t = threadIdx.x; asm volatile("" : "+v"(t)); return t; }
; template <bool LAST>
; DI void phase_gate(const Params& P, int layer, unsigned char* smem, int L, int G) {
;     ...
;     const int tid2 = otid();
;     const int lane2 = tid2 & 63, w2 = tid2 >> 6, r2 = lane2 & 31, h2 = lane2 >> 5, wm2 = w2 >> 2, wn2 = w2 & 3;
; #pragma unroll
;     for (int i = 0; i < 4; ++i)
; #pragma unroll
;       for (int q4 = 0; q4 < 4; ++q4) {
;         const int fl = wm2 * 128 + i * 32 + 8 * q4 + 4 * h2;
;         const int f0 = nt * 256 + fl;
;         const f32x4 gv = *(const f32x4*)(vecL + 512 + fl), bv = *(const f32x4*)(vecL + 768 + fl);
;         const float ga[4] = {gv.x, gv.y, gv.z, gv.w}, ba[4] = {bv.x, bv.y, bv.z, bv.w};
; #pragma unroll
;         for (int j = 0; j < 2; ++j) {
;           const int lrow = wn2 * 64 + j * 32 + r2;
;           const float mu = rowA[lrow], rstd = rowB[lrow];
;           uint2* sp = (uint2*)(stg + lrow * STG + fl);
;           const uint2 sv = *sp;
;           const float sa[4] = {bflo(sv.x), bfhi(sv.x), bflo(sv.y), bfhi(sv.y)};
;           float y[4];
;           const float gg[4] = {bflo(gq[i][j][2 * q4]), bfhi(gq[i][j][2 * q4]), bflo(gq[i][j][2 * q4 + 1]), bfhi(gq[i][j][2 * q4 + 1])};
; #pragma unroll
;           for (int e = 0; e < 4; ++e) y[e] = (sa[e] - mu) * rstd * ga[e] + ba[e] + gg[e];
;           if (LAST) { f32x4 o = {y[0], y[1], y[2], y[3]}; *(f32x4*)(P.out + (size_t)(mt * 256 + lrow) * 1024 + f0) = o; }
;           else { uint2 pk; pk.x = pack2(y[0], y[1]); pk.y = pack2(y[2], y[3]); *sp = pk; }
;         }
;         __builtin_amdgcn_sched_barrier(0);
;       }
	v_pk_add_f32 v[52:53], v[70:71], v[64:65] op_sel_hi:[1,0] neg_lo:[0,1] neg_hi:[0,1]
	v_pk_add_f32 v[62:63], v[62:63], v[64:65] op_sel_hi:[1,0] neg_lo:[0,1] neg_hi:[0,1]
	s_waitcnt lgkmcnt(1)
	v_pk_mul_f32 v[52:53], v[66:67], v[52:53] op_sel_hi:[0,1]
	v_pk_mul_f32 v[62:63], v[66:67], v[62:63] op_sel_hi:[0,1]
	v_lshlrev_b32_e32 v72, 16, v50
	v_and_b32_e32 v73, 0xffff0000, v50
	v_pk_fma_f32 v[52:53], v[54:55], v[52:53], v[58:59]
	v_pk_fma_f32 v[62:63], v[56:57], v[62:63], v[60:61]
	v_pk_add_f32 v[52:53], v[52:53], v[72:73]
	v_pk_add_f32 v[62:63], v[62:63], v[74:75]
	v_cvt_pk_bf16_f32 v52, v52, v53
	v_cvt_pk_bf16_f32 v53, v62, v63
	ds_write_b64 v19, v[52:53] offset:80
	ds_read_b32 v50, v31
	ds_read_b32 v52, v33
	s_waitcnt lgkmcnt(3)
	v_lshlrev_b32_e32 v62, 16, v68
	v_and_b32_e32 v63, 0xffff0000, v68
	v_lshlrev_b32_e32 v64, 16, v69
	v_and_b32_e32 v65, 0xffff0000, v69
	v_lshlrev_b32_e32 v68, 16, v51
	v_and_b32_e32 v69, 0xffff0000, v51
	s_waitcnt lgkmcnt(1)
	v_pk_add_f32 v[62:63], v[62:63], v[50:51] op_sel_hi:[1,0] neg_lo:[0,1] neg_hi:[0,1]
	v_pk_add_f32 v[50:51], v[64:65], v[50:51] op_sel_hi:[1,0] neg_lo:[0,1] neg_hi:[0,1]
	s_waitcnt lgkmcnt(0)
	v_pk_mul_f32 v[62:63], v[52:53], v[62:63] op_sel_hi:[0,1]
	v_pk_mul_f32 v[50:51], v[52:53], v[50:51] op_sel_hi:[0,1]
	v_lshlrev_b32_e32 v66, 16, v49
	v_and_b32_e32 v67, 0xffff0000, v49
	v_pk_fma_f32 v[54:55], v[54:55], v[62:63], v[58:59]
	v_pk_fma_f32 v[50:51], v[56:57], v[50:51], v[60:61]
	v_pk_add_f32 v[54:55], v[54:55], v[66:67]
	v_pk_add_f32 v[50:51], v[50:51], v[68:69]
	v_cvt_pk_bf16_f32 v52, v54, v55
	v_cvt_pk_bf16_f32 v53, v50, v51
	ds_write_b64 v19, v[52:53] offset:16720
	v_add_u32_e32 v54, 0x254c0, v27
	v_add_u32_e32 v49, 0x250c0, v27
	ds_read_b64 v[58:59], v19 offset:96
	ds_read_b128 v[50:53], v49
	ds_read_b128 v[54:57], v54
	ds_read_b32 v60, v29
	ds_read_b32 v62, v30
	ds_read_b64 v[64:65], v19 offset:16736
	s_waitcnt lgkmcnt(5)
	v_lshlrev_b32_e32 v66, 16, v58
	v_and_b32_e32 v67, 0xffff0000, v58
	v_lshlrev_b32_e32 v58, 16, v59
	v_and_b32_e32 v59, 0xffff0000, v59
	v_lshlrev_b32_e32 v70, 16, v48
	v_and_b32_e32 v71, 0xffff0000, v48
	s_waitcnt lgkmcnt(2)
	v_pk_add_f32 v[48:49], v[66:67], v[60:61] op_sel_hi:[1,0] neg_lo:[0,1] neg_hi:[0,1]
	v_pk_add_f32 v[58:59], v[58:59], v[60:61] op_sel_hi:[1,0] neg_lo:[0,1] neg_hi:[0,1]
	s_waitcnt lgkmcnt(1)
	v_pk_mul_f32 v[48:49], v[62:63], v[48:49] op_sel_hi:[0,1]
	v_pk_mul_f32 v[58:59], v[62:63], v[58:59] op_sel_hi:[0,1]
	v_lshlrev_b32_e32 v68, 16, v46
	v_and_b32_e32 v69, 0xffff0000, v46
	v_pk_fma_f32 v[48:49], v[50:51], v[48:49], v[54:55]
	v_pk_fma_f32 v[58:59], v[52:53], v[58:59], v[56:57]
	v_pk_add_f32 v[48:49], v[48:49], v[68:69]
	v_pk_add_f32 v[58:59], v[58:59], v[70:71]
	v_cvt_pk_bf16_f32 v48, v48, v49
	v_cvt_pk_bf16_f32 v49, v58, v59
	ds_write_b64 v19, v[48:49] offset:96
	ds_read_b32 v46, v31
	ds_read_b32 v48, v33
	s_waitcnt lgkmcnt(3)
	v_lshlrev_b32_e32 v58, 16, v64
	v_and_b32_e32 v59, 0xffff0000, v64
	v_lshlrev_b32_e32 v60, 16, v65
	v_and_b32_e32 v61, 0xffff0000, v65
	v_lshlrev_b32_e32 v64, 16, v47
	v_and_b32_e32 v65, 0xffff0000, v47
	s_waitcnt lgkmcnt(1)
	v_pk_add_f32 v[58:59], v[58:59], v[46:47] op_sel_hi:[1,0] neg_lo:[0,1] neg_hi:[0,1]
	v_pk_add_f32 v[46:47], v[60:61], v[46:47] op_sel_hi:[1,0] neg_lo:[0,1] neg_hi:[0,1]
	s_waitcnt lgkmcnt(0)
	v_pk_mul_f32 v[58:59], v[48:49], v[58:59] op_sel_hi:[0,1]
	v_pk_mul_f32 v[46:47], v[48:49], v[46:47] op_sel_hi:[0,1]
	v_lshlrev_b32_e32 v62, 16, v45
	v_and_b32_e32 v63, 0xffff0000, v45
	v_pk_fma_f32 v[50:51], v[50:51], v[58:59], v[54:55]
	v_pk_fma_f32 v[46:47], v[52:53], v[46:47], v[56:57]
	v_pk_add_f32 v[50:51], v[50:51], v[62:63]
	v_pk_add_f32 v[46:47], v[46:47], v[64:65]
	v_cvt_pk_bf16_f32 v48, v50, v51
	v_cvt_pk_bf16_f32 v49, v46, v47
	ds_write_b64 v19, v[48:49] offset:16736
	v_add_u32_e32 v50, 0x254e0, v27
	v_add_u32_e32 v45, 0x250e0, v27
	ds_read_b64 v[54:55], v19 offset:112
	ds_read_b128 v[46:49], v45
	ds_read_b128 v[50:53], v50
	ds_read_b32 v56, v29
	ds_read_b32 v58, v30
	ds_read_b64 v[60:61], v19 offset:16752
	s_waitcnt lgkmcnt(5)
	v_lshlrev_b32_e32 v62, 16, v54
	v_and_b32_e32 v63, 0xffff0000, v54
	v_lshlrev_b32_e32 v54, 16, v55
	v_and_b32_e32 v55, 0xffff0000, v55
	v_lshlrev_b32_e32 v66, 16, v44
	v_and_b32_e32 v67, 0xffff0000, v44
	s_waitcnt lgkmcnt(2)
	v_pk_add_f32 v[44:45], v[62:63], v[56:57] op_sel_hi:[1,0] neg_lo:[0,1] neg_hi:[0,1]
	v_pk_add_f32 v[54:55], v[54:55], v[56:57] op_sel_hi:[1,0] neg_lo:[0,1] neg_hi:[0,1]
	s_waitcnt lgkmcnt(1)
	v_pk_mul_f32 v[44:45], v[58:59], v[44:45] op_sel_hi:[0,1]
	v_pk_mul_f32 v[54:55], v[58:59], v[54:55] op_sel_hi:[0,1]
	v_lshlrev_b32_e32 v64, 16, v42
	v_and_b32_e32 v65, 0xffff0000, v42
	v_pk_fma_f32 v[44:45], v[46:47], v[44:45], v[50:51]
	v_pk_fma_f32 v[54:55], v[48:49], v[54:55], v[52:53]
	v_pk_add_f32 v[44:45], v[44:45], v[64:65]
	v_pk_add_f32 v[54:55], v[54:55], v[66:67]
	v_cvt_pk_bf16_f32 v44, v44, v45
	v_cvt_pk_bf16_f32 v45, v54, v55
	ds_write_b64 v19, v[44:45] offset:112
	ds_read_b32 v42, v31
	ds_read_b32 v44, v33
	s_waitcnt lgkmcnt(3)
	v_lshlrev_b32_e32 v54, 16, v60
	v_and_b32_e32 v55, 0xffff0000, v60
	v_lshlrev_b32_e32 v56, 16, v61
	v_and_b32_e32 v57, 0xffff0000, v61
	v_lshlrev_b32_e32 v60, 16, v43
	v_and_b32_e32 v61, 0xffff0000, v43
	s_waitcnt lgkmcnt(1)
	v_pk_add_f32 v[54:55], v[54:55], v[42:43] op_sel_hi:[1,0] neg_lo:[0,1] neg_hi:[0,1]
	v_pk_add_f32 v[42:43], v[56:57], v[42:43] op_sel_hi:[1,0] neg_lo:[0,1] neg_hi:[0,1]
	s_waitcnt lgkmcnt(0)
; DI unsigned pack2(float a, float b) { f32x2_t v = {a, b}; bf16x2_t r = __builtin_convertvector(v, bf16x2_t); return __builtin_bit_cast(unsigned, r); }
; DI float bflo(unsigned u) { return __uint_as_float(u << 16); }
; DI float bfhi(unsigned u) { return __uint_as_float(u & 0xffff0000u); }
; DI int otid() { int t = threadIdx.x; asm volatile("" : "+v"(t)); return t; }
; template <bool LAST>
; DI void phase_gate(const Params& P, int layer, unsigned char* smem, int L, int G) {
;     ...
;     const int tid2 = otid();
;     const int lane2 = tid2 & 63, w2 = tid2 >> 6, r2 = lane2 & 31, h2 = lane2 >> 5, wm2 = w2 >> 2, wn2 = w2 & 3;
; #pragma unroll
;     for (int i = 0; i < 4; ++i)
; #pragma unroll
;       for (int q4 = 0; q4 < 4; ++q4) {
;         const int fl = wm2 * 128 + i * 32 + 8 * q4 + 4 * h2;
;         const int f0 = nt * 256 + fl;
;         const f32x4 gv = *(const f32x4*)(vecL + 512 + fl), bv = *(const f32x4*)(vecL + 768 + fl);
;         const float ga[4] = {gv.x, gv.y, gv.z, gv.w}, ba[4] = {bv.x, bv.y, bv.z, bv.w};
; #pragma unroll
;         for (int j = 0; j < 2; ++j) {
;           const int lrow = wn2 * 64 + j * 32 + r2;
;           const float mu = rowA[lrow], rstd = rowB[lrow];
;           uint2* sp = (uint2*)(stg + lrow * STG + fl);
;           const uint2 sv = *sp;
;           const float sa[4] = {bflo(sv.x), bfhi(sv.x), bflo(sv.y), bfhi(sv.y)};
;           float y[4];
;           const float gg[4] = {bflo(gq[i][j][2 * q4]), bfhi(gq[i][j][2 * q4]), bflo(gq[i][j][2 * q4 + 1]), bfhi(gq[i][j][2 * q4 + 1])};
; #pragma unroll
;           for (int e = 0; e < 4; ++e) y[e] = (sa[e] - mu) * rstd * ga[e] + ba[e] + gg[e];
;           if (LAST) { f32x4 o = {y[0], y[1], y[2], y[3]}; *(f32x4*)(P.out + (size_t)(mt * 256 + lrow) * 1024 + f0) = o; }
;           else { uint2 pk; pk.x = pack2(y[0], y[1]); pk.y = pack2(y[2], y[3]); *sp = pk; }
;         }
;         __builtin_amdgcn_sched_barrier(0);
;       }
	v_pk_mul_f32 v[54:55], v[44:45], v[54:55] op_sel_hi:[0,1]
	v_pk_mul_f32 v[42:43], v[44:45], v[42:43] op_sel_hi:[0,1]
	v_lshlrev_b32_e32 v58, 16, v41
	v_and_b32_e32 v59, 0xffff0000, v41
	v_pk_fma_f32 v[46:47], v[46:47], v[54:55], v[50:51]
	v_pk_fma_f32 v[42:43], v[48:49], v[42:43], v[52:53]
	v_pk_add_f32 v[46:47], v[46:47], v[58:59]
	v_pk_add_f32 v[42:43], v[42:43], v[60:61]
	v_cvt_pk_bf16_f32 v44, v46, v47
	v_cvt_pk_bf16_f32 v45, v42, v43
	ds_write_b64 v19, v[44:45] offset:16752
	v_add_u32_e32 v46, 0x25500, v27
	v_add_u32_e32 v41, 0x25100, v27
	ds_read_b64 v[50:51], v19 offset:128
	ds_read_b128 v[42:45], v41
	ds_read_b128 v[46:49], v46
	ds_read_b32 v52, v29
	ds_read_b32 v54, v30
	ds_read_b64 v[56:57], v19 offset:16768
	s_waitcnt lgkmcnt(5)
	v_lshlrev_b32_e32 v58, 16, v50
	v_and_b32_e32 v59, 0xffff0000, v50
	v_lshlrev_b32_e32 v50, 16, v51
	v_and_b32_e32 v51, 0xffff0000, v51
	v_lshlrev_b32_e32 v62, 16, v40
	v_and_b32_e32 v63, 0xffff0000, v40
	s_waitcnt lgkmcnt(2)
	v_pk_add_f32 v[40:41], v[58:59], v[52:53] op_sel_hi:[1,0] neg_lo:[0,1] neg_hi:[0,1]
	v_pk_add_f32 v[50:51], v[50:51], v[52:53] op_sel_hi:[1,0] neg_lo:[0,1] neg_hi:[0,1]
	s_waitcnt lgkmcnt(1)
	v_pk_mul_f32 v[40:41], v[54:55], v[40:41] op_sel_hi:[0,1]
	v_pk_mul_f32 v[50:51], v[54:55], v[50:51] op_sel_hi:[0,1]
	v_lshlrev_b32_e32 v60, 16, v38
	v_and_b32_e32 v61, 0xffff0000, v38
	v_pk_fma_f32 v[40:41], v[42:43], v[40:41], v[46:47]
	v_pk_fma_f32 v[50:51], v[44:45], v[50:51], v[48:49]
	v_pk_add_f32 v[40:41], v[40:41], v[60:61]
	v_pk_add_f32 v[50:51], v[50:51], v[62:63]
	v_cvt_pk_bf16_f32 v40, v40, v41
	v_cvt_pk_bf16_f32 v41, v50, v51
	ds_write_b64 v19, v[40:41] offset:128
	ds_read_b32 v38, v31
	ds_read_b32 v40, v33
	s_waitcnt lgkmcnt(3)
	v_lshlrev_b32_e32 v50, 16, v56
	v_and_b32_e32 v51, 0xffff0000, v56
	v_lshlrev_b32_e32 v52, 16, v57
	v_and_b32_e32 v53, 0xffff0000, v57
	v_lshlrev_b32_e32 v56, 16, v39
	v_and_b32_e32 v57, 0xffff0000, v39
	s_waitcnt lgkmcnt(1)
	v_pk_add_f32 v[50:51], v[50:51], v[38:39] op_sel_hi:[1,0] neg_lo:[0,1] neg_hi:[0,1]
	v_pk_add_f32 v[38:39], v[52:53], v[38:39] op_sel_hi:[1,0] neg_lo:[0,1] neg_hi:[0,1]
	s_waitcnt lgkmcnt(0)
	v_pk_mul_f32 v[50:51], v[40:41], v[50:51] op_sel_hi:[0,1]
	v_pk_mul_f32 v[38:39], v[40:41], v[38:39] op_sel_hi:[0,1]
	v_lshlrev_b32_e32 v54, 16, v37
	v_and_b32_e32 v55, 0xffff0000, v37
	v_pk_fma_f32 v[42:43], v[42:43], v[50:51], v[46:47]
	v_pk_fma_f32 v[38:39], v[44:45], v[38:39], v[48:49]
	v_pk_add_f32 v[42:43], v[42:43], v[54:55]
	v_pk_add_f32 v[38:39], v[38:39], v[56:57]
	v_cvt_pk_bf16_f32 v40, v42, v43
	v_cvt_pk_bf16_f32 v41, v38, v39
	ds_write_b64 v19, v[40:41] offset:16768
	v_add_u32_e32 v42, 0x25520, v27
	v_add_u32_e32 v37, 0x25120, v27
	ds_read_b64 v[46:47], v19 offset:144
	ds_read_b128 v[38:41], v37
	ds_read_b128 v[42:45], v42
	ds_read_b32 v48, v29
	ds_read_b32 v50, v30
	ds_read_b64 v[52:53], v19 offset:16784
	s_waitcnt lgkmcnt(5)
	v_lshlrev_b32_e32 v54, 16, v46
	v_and_b32_e32 v55, 0xffff0000, v46
	v_lshlrev_b32_e32 v46, 16, v47
	v_and_b32_e32 v47, 0xffff0000, v47
	v_lshlrev_b32_e32 v58, 16, v36
	v_and_b32_e32 v59, 0xffff0000, v36
	s_waitcnt lgkmcnt(2)
	v_pk_add_f32 v[36:37], v[54:55], v[48:49] op_sel_hi:[1,0] neg_lo:[0,1] neg_hi:[0,1]
	v_pk_add_f32 v[46:47], v[46:47], v[48:49] op_sel_hi:[1,0] neg_lo:[0,1] neg_hi:[0,1]
	s_waitcnt lgkmcnt(1)
	v_pk_mul_f32 v[36:37], v[50:51], v[36:37] op_sel_hi:[0,1]
	v_pk_mul_f32 v[46:47], v[50:51], v[46:47] op_sel_hi:[0,1]
	v_lshlrev_b32_e32 v56, 16, v34
	v_and_b32_e32 v57, 0xffff0000, v34
	v_pk_fma_f32 v[36:37], v[38:39], v[36:37], v[42:43]
	v_pk_fma_f32 v[46:47], v[40:41], v[46:47], v[44:45]
	v_pk_add_f32 v[36:37], v[36:37], v[56:57]
	v_pk_add_f32 v[46:47], v[46:47], v[58:59]
	v_cvt_pk_bf16_f32 v36, v36, v37
	v_cvt_pk_bf16_f32 v37, v46, v47
	ds_write_b64 v19, v[36:37] offset:144
	ds_read_b32 v34, v31
	ds_read_b32 v36, v33
	s_waitcnt lgkmcnt(3)
	v_lshlrev_b32_e32 v46, 16, v52
	v_and_b32_e32 v47, 0xffff0000, v52
	v_lshlrev_b32_e32 v48, 16, v53
	v_and_b32_e32 v49, 0xffff0000, v53
	v_lshlrev_b32_e32 v52, 16, v35
	v_and_b32_e32 v53, 0xffff0000, v35
	s_waitcnt lgkmcnt(1)
	v_pk_add_f32 v[46:47], v[46:47], v[34:35] op_sel_hi:[1,0] neg_lo:[0,1] neg_hi:[0,1]
	v_pk_add_f32 v[34:35], v[48:49], v[34:35] op_sel_hi:[1,0] neg_lo:[0,1] neg_hi:[0,1]
	s_waitcnt lgkmcnt(0)
	v_pk_mul_f32 v[46:47], v[36:37], v[46:47] op_sel_hi:[0,1]
	v_pk_mul_f32 v[34:35], v[36:37], v[34:35] op_sel_hi:[0,1]
	v_lshlrev_b32_e32 v50, 16, v32
	v_and_b32_e32 v51, 0xffff0000, v32
	v_pk_fma_f32 v[38:39], v[38:39], v[46:47], v[42:43]
	v_pk_fma_f32 v[34:35], v[40:41], v[34:35], v[44:45]
	v_pk_add_f32 v[38:39], v[38:39], v[50:51]
	v_pk_add_f32 v[34:35], v[34:35], v[52:53]
	v_cvt_pk_bf16_f32 v36, v38, v39
	v_cvt_pk_bf16_f32 v37, v34, v35
	ds_write_b64 v19, v[36:37] offset:16784
	v_add_u32_e32 v32, 0x25140, v27
	v_add_u32_e32 v38, 0x25540, v27
	ds_read_b64 v[42:43], v19 offset:160
	ds_read_b128 v[34:37], v32
	ds_read_b128 v[38:41], v38
	ds_read_b32 v32, v29
	ds_read_b32 v44, v30
	ds_read_b64 v[46:47], v19 offset:16800
	s_waitcnt lgkmcnt(5)
	v_lshlrev_b32_e32 v48, 16, v42
	v_and_b32_e32 v49, 0xffff0000, v42
	v_lshlrev_b32_e32 v42, 16, v43
	v_and_b32_e32 v43, 0xffff0000, v43
	s_waitcnt lgkmcnt(2)
	v_pk_add_f32 v[48:49], v[48:49], v[32:33] op_sel_hi:[1,0] neg_lo:[0,1] neg_hi:[0,1]
	v_pk_add_f32 v[42:43], v[42:43], v[32:33] op_sel_hi:[1,0] neg_lo:[0,1] neg_hi:[0,1]
	s_waitcnt lgkmcnt(1)
; DI unsigned pack2(float a, float b) { f32x2_t v = {a, b}; bf16x2_t r = __builtin_convertvector(v, bf16x2_t); return __builtin_bit_cast(unsigned, r); }
; DI float bflo(unsigned u) { return __uint_as_float(u << 16); }
; DI float bfhi(unsigned u) { return __uint_as_float(u & 0xffff0000u); }
; DI int otid() { int t = threadIdx.x; asm volatile("" : "+v"(t)); return t; }
; template <bool LAST>
; DI void phase_gate(const Params& P, int layer, unsigned char* smem, int L, int G) {
;     ...
;     const int tid2 = otid();
;     const int lane2 = tid2 & 63, w2 = tid2 >> 6, r2 = lane2 & 31, h2 = lane2 >> 5, wm2 = w2 >> 2, wn2 = w2 & 3;
; #pragma unroll
;     for (int i = 0; i < 4; ++i)
; #pragma unroll
;       for (int q4 = 0; q4 < 4; ++q4) {
;         const int fl = wm2 * 128 + i * 32 + 8 * q4 + 4 * h2;
;         const int f0 = nt * 256 + fl;
;         const f32x4 gv = *(const f32x4*)(vecL + 512 + fl), bv = *(const f32x4*)(vecL + 768 + fl);
;         const float ga[4] = {gv.x, gv.y, gv.z, gv.w}, ba[4] = {bv.x, bv.y, bv.z, bv.w};
; #pragma unroll
;         for (int j = 0; j < 2; ++j) {
;           const int lrow = wn2 * 64 + j * 32 + r2;
;           const float mu = rowA[lrow], rstd = rowB[lrow];
;           uint2* sp = (uint2*)(stg + lrow * STG + fl);
;           const uint2 sv = *sp;
;           const float sa[4] = {bflo(sv.x), bfhi(sv.x), bflo(sv.y), bfhi(sv.y)};
;           float y[4];
;           const float gg[4] = {bflo(gq[i][j][2 * q4]), bfhi(gq[i][j][2 * q4]), bflo(gq[i][j][2 * q4 + 1]), bfhi(gq[i][j][2 * q4 + 1])};
; #pragma unroll
;           for (int e = 0; e < 4; ++e) y[e] = (sa[e] - mu) * rstd * ga[e] + ba[e] + gg[e];
;           if (LAST) { f32x4 o = {y[0], y[1], y[2], y[3]}; *(f32x4*)(P.out + (size_t)(mt * 256 + lrow) * 1024 + f0) = o; }
;           else { uint2 pk; pk.x = pack2(y[0], y[1]); pk.y = pack2(y[2], y[3]); *sp = pk; }
;         }
;         __builtin_amdgcn_sched_barrier(0);
;       }
	v_pk_mul_f32 v[48:49], v[44:45], v[48:49] op_sel_hi:[0,1]
	v_pk_mul_f32 v[42:43], v[44:45], v[42:43] op_sel_hi:[0,1]
	v_lshlrev_b32_e32 v50, 16, v24
	v_and_b32_e32 v51, 0xffff0000, v24
	v_lshlrev_b32_e32 v52, 16, v26
	v_and_b32_e32 v53, 0xffff0000, v26
	v_pk_fma_f32 v[48:49], v[34:35], v[48:49], v[38:39]
	v_pk_fma_f32 v[42:43], v[36:37], v[42:43], v[40:41]
	v_pk_add_f32 v[48:49], v[48:49], v[50:51]
	v_pk_add_f32 v[42:43], v[42:43], v[52:53]
	v_cvt_pk_bf16_f32 v44, v48, v49
	v_cvt_pk_bf16_f32 v45, v42, v43
	ds_write_b64 v19, v[44:45] offset:160
	ds_read_b32 v24, v31
	ds_read_b32 v26, v33
	s_waitcnt lgkmcnt(3)
	v_lshlrev_b32_e32 v42, 16, v46
	v_and_b32_e32 v43, 0xffff0000, v46
	v_lshlrev_b32_e32 v44, 16, v47
	v_and_b32_e32 v45, 0xffff0000, v47
	v_lshlrev_b32_e32 v48, 16, v25
	v_and_b32_e32 v49, 0xffff0000, v25
	s_waitcnt lgkmcnt(1)
	v_pk_add_f32 v[42:43], v[42:43], v[24:25] op_sel_hi:[1,0] neg_lo:[0,1] neg_hi:[0,1]
	v_pk_add_f32 v[24:25], v[44:45], v[24:25] op_sel_hi:[1,0] neg_lo:[0,1] neg_hi:[0,1]
	s_waitcnt lgkmcnt(0)
	v_pk_mul_f32 v[42:43], v[26:27], v[42:43] op_sel_hi:[0,1]
	v_pk_mul_f32 v[24:25], v[26:27], v[24:25] op_sel_hi:[0,1]
	v_lshlrev_b32_e32 v46, 16, v23
	v_and_b32_e32 v47, 0xffff0000, v23
	v_pk_fma_f32 v[34:35], v[34:35], v[42:43], v[38:39]
	v_pk_fma_f32 v[24:25], v[36:37], v[24:25], v[40:41]
	v_pk_add_f32 v[34:35], v[34:35], v[46:47]
	v_pk_add_f32 v[24:25], v[24:25], v[48:49]
	v_cvt_pk_bf16_f32 v34, v34, v35
	v_cvt_pk_bf16_f32 v35, v24, v25
	ds_write_b64 v19, v[34:35] offset:16800
	v_add_u32_e32 v26, 0x25560, v27
	v_add_u32_e32 v23, 0x25160, v27
	ds_read_b64 v[24:25], v19 offset:176
	ds_read_b128 v[34:37], v23
	ds_read_b128 v[38:41], v26
	ds_read_b32 v26, v29
	ds_read_b32 v32, v30
	ds_read_b64 v[42:43], v19 offset:16816
	s_waitcnt lgkmcnt(5)
	v_lshlrev_b32_e32 v44, 16, v24
	v_and_b32_e32 v45, 0xffff0000, v24
	v_lshlrev_b32_e32 v24, 16, v25
	v_and_b32_e32 v25, 0xffff0000, v25
	v_lshlrev_b32_e32 v48, 16, v22
	v_and_b32_e32 v49, 0xffff0000, v22
	s_waitcnt lgkmcnt(2)
	v_pk_add_f32 v[22:23], v[44:45], v[26:27] op_sel_hi:[1,0] neg_lo:[0,1] neg_hi:[0,1]
	v_pk_add_f32 v[24:25], v[24:25], v[26:27] op_sel_hi:[1,0] neg_lo:[0,1] neg_hi:[0,1]
	s_waitcnt lgkmcnt(1)
	v_pk_mul_f32 v[22:23], v[32:33], v[22:23] op_sel_hi:[0,1]
	v_pk_mul_f32 v[24:25], v[32:33], v[24:25] op_sel_hi:[0,1]
	v_lshlrev_b32_e32 v46, 16, v20
	v_and_b32_e32 v47, 0xffff0000, v20
	v_pk_fma_f32 v[22:23], v[34:35], v[22:23], v[38:39]
	v_pk_fma_f32 v[24:25], v[36:37], v[24:25], v[40:41]
	v_pk_add_f32 v[22:23], v[22:23], v[46:47]
	v_pk_add_f32 v[24:25], v[24:25], v[48:49]
	v_cvt_pk_bf16_f32 v22, v22, v23
	v_cvt_pk_bf16_f32 v23, v24, v25
	ds_write_b64 v19, v[22:23] offset:176
	ds_read_b32 v20, v31
	ds_read_b32 v22, v33
	s_waitcnt lgkmcnt(3)
	v_lshlrev_b32_e32 v24, 16, v42
	v_and_b32_e32 v25, 0xffff0000, v42
	v_lshlrev_b32_e32 v42, 16, v43
	v_and_b32_e32 v43, 0xffff0000, v43
	v_lshlrev_b32_e32 v46, 16, v21
	v_and_b32_e32 v47, 0xffff0000, v21
	s_waitcnt lgkmcnt(1)
	v_pk_add_f32 v[24:25], v[24:25], v[20:21] op_sel_hi:[1,0] neg_lo:[0,1] neg_hi:[0,1]
	v_pk_add_f32 v[20:21], v[42:43], v[20:21] op_sel_hi:[1,0] neg_lo:[0,1] neg_hi:[0,1]
	s_waitcnt lgkmcnt(0)
	v_pk_mul_f32 v[24:25], v[22:23], v[24:25] op_sel_hi:[0,1]
	v_pk_mul_f32 v[20:21], v[22:23], v[20:21] op_sel_hi:[0,1]
	v_lshlrev_b32_e32 v44, 16, v18
	v_and_b32_e32 v45, 0xffff0000, v18
	v_pk_fma_f32 v[24:25], v[34:35], v[24:25], v[38:39]
	v_pk_fma_f32 v[20:21], v[36:37], v[20:21], v[40:41]
	v_pk_add_f32 v[24:25], v[24:25], v[44:45]
	v_pk_add_f32 v[20:21], v[20:21], v[46:47]
	v_cvt_pk_bf16_f32 v22, v24, v25
	v_cvt_pk_bf16_f32 v23, v20, v21
	ds_write_b64 v19, v[22:23] offset:16816
	v_add_u32_e32 v18, 0x25180, v27
	v_add_u32_e32 v26, 0x25580, v27
	ds_read_b64 v[24:25], v19 offset:192
	ds_read_b128 v[20:23], v18
	ds_read_b128 v[34:37], v26
	ds_read_b32 v18, v29
	ds_read_b32 v26, v30
	ds_read_b64 v[38:39], v19 offset:16832
	s_waitcnt lgkmcnt(5)
	v_lshlrev_b32_e32 v40, 16, v24
	v_and_b32_e32 v41, 0xffff0000, v24
	v_lshlrev_b32_e32 v24, 16, v25
	v_and_b32_e32 v25, 0xffff0000, v25
	s_waitcnt lgkmcnt(2)
	v_pk_add_f32 v[40:41], v[40:41], v[18:19] op_sel_hi:[1,0] neg_lo:[0,1] neg_hi:[0,1]
	v_pk_add_f32 v[24:25], v[24:25], v[18:19] op_sel_hi:[1,0] neg_lo:[0,1] neg_hi:[0,1]
	s_waitcnt lgkmcnt(1)
	v_pk_mul_f32 v[40:41], v[26:27], v[40:41] op_sel_hi:[0,1]
	v_pk_mul_f32 v[24:25], v[26:27], v[24:25] op_sel_hi:[0,1]
	v_lshlrev_b32_e32 v42, 16, v15
	v_and_b32_e32 v43, 0xffff0000, v15
	v_lshlrev_b32_e32 v44, 16, v17
	v_and_b32_e32 v45, 0xffff0000, v17
	v_pk_fma_f32 v[40:41], v[20:21], v[40:41], v[34:35]
	v_pk_fma_f32 v[24:25], v[22:23], v[24:25], v[36:37]
	v_pk_add_f32 v[40:41], v[40:41], v[42:43]
	v_pk_add_f32 v[24:25], v[24:25], v[44:45]
	v_cvt_pk_bf16_f32 v40, v40, v41
	v_cvt_pk_bf16_f32 v41, v24, v25
	ds_write_b64 v19, v[40:41] offset:192
	ds_read_b32 v18, v31
	ds_read_b32 v24, v33
	s_waitcnt lgkmcnt(3)
	v_lshlrev_b32_e32 v40, 16, v38
	v_and_b32_e32 v41, 0xffff0000, v38
	v_lshlrev_b32_e32 v42, 16, v14
	v_and_b32_e32 v43, 0xffff0000, v14
	v_lshlrev_b32_e32 v14, 16, v16
	v_and_b32_e32 v15, 0xffff0000, v16
	s_waitcnt lgkmcnt(1)
	v_pk_add_f32 v[16:17], v[40:41], v[18:19] op_sel_hi:[1,0] neg_lo:[0,1] neg_hi:[0,1]
	v_lshlrev_b32_e32 v38, 16, v39
	v_and_b32_e32 v39, 0xffff0000, v39
	s_waitcnt lgkmcnt(0)
; DI unsigned pack2(float a, float b) { f32x2_t v = {a, b}; bf16x2_t r = __builtin_convertvector(v, bf16x2_t); return __builtin_bit_cast(unsigned, r); }
; DI float bflo(unsigned u) { return __uint_as_float(u << 16); }
; DI float bfhi(unsigned u) { return __uint_as_float(u & 0xffff0000u); }
; DI int otid() { int t = threadIdx.x; asm volatile("" : "+v"(t)); return t; }
; template <bool LAST>
; DI void phase_gate(const Params& P, int layer, unsigned char* smem, int L, int G) {
;     ...
;     const int tid2 = otid();
;     const int lane2 = tid2 & 63, w2 = tid2 >> 6, r2 = lane2 & 31, h2 = lane2 >> 5, wm2 = w2 >> 2, wn2 = w2 & 3;
; #pragma unroll
;     for (int i = 0; i < 4; ++i)
; #pragma unroll
;       for (int q4 = 0; q4 < 4; ++q4) {
;         const int fl = wm2 * 128 + i * 32 + 8 * q4 + 4 * h2;
;         const int f0 = nt * 256 + fl;
;         const f32x4 gv = *(const f32x4*)(vecL + 512 + fl), bv = *(const f32x4*)(vecL + 768 + fl);
;         const float ga[4] = {gv.x, gv.y, gv.z, gv.w}, ba[4] = {bv.x, bv.y, bv.z, bv.w};
; #pragma unroll
;         for (int j = 0; j < 2; ++j) {
;           const int lrow = wn2 * 64 + j * 32 + r2;
;           const float mu = rowA[lrow], rstd = rowB[lrow];
;           uint2* sp = (uint2*)(stg + lrow * STG + fl);
;           const uint2 sv = *sp;
;           const float sa[4] = {bflo(sv.x), bfhi(sv.x), bflo(sv.y), bfhi(sv.y)};
;           float y[4];
;           const float gg[4] = {bflo(gq[i][j][2 * q4]), bfhi(gq[i][j][2 * q4]), bflo(gq[i][j][2 * q4 + 1]), bfhi(gq[i][j][2 * q4 + 1])};
; #pragma unroll
;           for (int e = 0; e < 4; ++e) y[e] = (sa[e] - mu) * rstd * ga[e] + ba[e] + gg[e];
;           if (LAST) { f32x4 o = {y[0], y[1], y[2], y[3]}; *(f32x4*)(P.out + (size_t)(mt * 256 + lrow) * 1024 + f0) = o; }
;           else { uint2 pk; pk.x = pack2(y[0], y[1]); pk.y = pack2(y[2], y[3]); *sp = pk; }
;         }
;         __builtin_amdgcn_sched_barrier(0);
;       }
;     __syncthreads();
	v_pk_mul_f32 v[16:17], v[24:25], v[16:17] op_sel_hi:[0,1]
	v_pk_fma_f32 v[16:17], v[20:21], v[16:17], v[34:35]
	v_pk_add_f32 v[20:21], v[38:39], v[18:19] op_sel_hi:[1,0] neg_lo:[0,1] neg_hi:[0,1]
	v_pk_add_f32 v[16:17], v[16:17], v[42:43]
	v_pk_mul_f32 v[20:21], v[24:25], v[20:21] op_sel_hi:[0,1]
	v_pk_fma_f32 v[20:21], v[22:23], v[20:21], v[36:37]
	v_cvt_pk_bf16_f32 v16, v16, v17
	v_pk_add_f32 v[14:15], v[20:21], v[14:15]
	s_nop 0
	v_cvt_pk_bf16_f32 v17, v14, v15
	ds_write_b64 v19, v[16:17] offset:16832
	v_add_u32_e32 v14, 0x251a0, v27
	v_add_u32_e32 v18, 0x255a0, v27
	ds_read_b64 v[24:25], v19 offset:208
	ds_read_b128 v[14:17], v14
	ds_read_b128 v[20:23], v18
	ds_read_b32 v18, v29
	ds_read_b32 v26, v30
	ds_read_b64 v[34:35], v19 offset:16848
	s_waitcnt lgkmcnt(5)
	v_lshlrev_b32_e32 v36, 16, v24
	v_and_b32_e32 v37, 0xffff0000, v24
	v_lshlrev_b32_e32 v24, 16, v25
	v_and_b32_e32 v25, 0xffff0000, v25
	s_waitcnt lgkmcnt(2)
	v_pk_add_f32 v[36:37], v[36:37], v[18:19] op_sel_hi:[1,0] neg_lo:[0,1] neg_hi:[0,1]
	v_pk_add_f32 v[24:25], v[24:25], v[18:19] op_sel_hi:[1,0] neg_lo:[0,1] neg_hi:[0,1]
	s_waitcnt lgkmcnt(1)
	v_pk_mul_f32 v[36:37], v[26:27], v[36:37] op_sel_hi:[0,1]
	v_pk_mul_f32 v[24:25], v[26:27], v[24:25] op_sel_hi:[0,1]
	v_lshlrev_b32_e32 v38, 16, v11
	v_and_b32_e32 v39, 0xffff0000, v11
	v_lshlrev_b32_e32 v40, 16, v13
	v_and_b32_e32 v41, 0xffff0000, v13
	v_pk_fma_f32 v[36:37], v[14:15], v[36:37], v[20:21]
	v_pk_fma_f32 v[24:25], v[16:17], v[24:25], v[22:23]
	v_pk_add_f32 v[36:37], v[36:37], v[38:39]
	v_pk_add_f32 v[24:25], v[24:25], v[40:41]
	v_cvt_pk_bf16_f32 v36, v36, v37
	v_cvt_pk_bf16_f32 v37, v24, v25
	ds_write_b64 v19, v[36:37] offset:208
	ds_read_b32 v18, v31
	ds_read_b32 v24, v33
	s_waitcnt lgkmcnt(3)
	v_lshlrev_b32_e32 v36, 16, v34
	v_and_b32_e32 v37, 0xffff0000, v34
	v_lshlrev_b32_e32 v38, 16, v10
	v_and_b32_e32 v39, 0xffff0000, v10
	v_lshlrev_b32_e32 v10, 16, v12
	v_and_b32_e32 v11, 0xffff0000, v12
	s_waitcnt lgkmcnt(1)
	v_pk_add_f32 v[12:13], v[36:37], v[18:19] op_sel_hi:[1,0] neg_lo:[0,1] neg_hi:[0,1]
	v_lshlrev_b32_e32 v34, 16, v35
	v_and_b32_e32 v35, 0xffff0000, v35
	s_waitcnt lgkmcnt(0)
	v_pk_mul_f32 v[12:13], v[24:25], v[12:13] op_sel_hi:[0,1]
	v_pk_fma_f32 v[12:13], v[14:15], v[12:13], v[20:21]
	v_pk_add_f32 v[14:15], v[34:35], v[18:19] op_sel_hi:[1,0] neg_lo:[0,1] neg_hi:[0,1]
	v_pk_add_f32 v[12:13], v[12:13], v[38:39]
	v_pk_mul_f32 v[14:15], v[24:25], v[14:15] op_sel_hi:[0,1]
	v_pk_fma_f32 v[14:15], v[16:17], v[14:15], v[22:23]
	v_cvt_pk_bf16_f32 v12, v12, v13
	v_pk_add_f32 v[10:11], v[14:15], v[10:11]
	s_nop 0
	v_cvt_pk_bf16_f32 v13, v10, v11
	ds_write_b64 v19, v[12:13] offset:16848
	v_add_u32_e32 v10, 0x251c0, v27
	v_add_u32_e32 v14, 0x255c0, v27
	ds_read_b64 v[20:21], v19 offset:224
	ds_read_b128 v[10:13], v10
	ds_read_b128 v[14:17], v14
	ds_read_b32 v18, v29
	ds_read_b32 v22, v30
	ds_read_b64 v[24:25], v19 offset:16864
	s_waitcnt lgkmcnt(5)
	v_lshlrev_b32_e32 v34, 16, v20
	v_and_b32_e32 v35, 0xffff0000, v20
	v_lshlrev_b32_e32 v20, 16, v21
	v_and_b32_e32 v21, 0xffff0000, v21
	s_waitcnt lgkmcnt(2)
	v_pk_add_f32 v[34:35], v[34:35], v[18:19] op_sel_hi:[1,0] neg_lo:[0,1] neg_hi:[0,1]
	v_pk_add_f32 v[20:21], v[20:21], v[18:19] op_sel_hi:[1,0] neg_lo:[0,1] neg_hi:[0,1]
	s_waitcnt lgkmcnt(1)
	v_pk_mul_f32 v[34:35], v[22:23], v[34:35] op_sel_hi:[0,1]
	v_pk_mul_f32 v[20:21], v[22:23], v[20:21] op_sel_hi:[0,1]
	v_lshlrev_b32_e32 v36, 16, v7
	v_and_b32_e32 v37, 0xffff0000, v7
	v_lshlrev_b32_e32 v38, 16, v9
	v_and_b32_e32 v39, 0xffff0000, v9
	v_pk_fma_f32 v[34:35], v[10:11], v[34:35], v[14:15]
	v_pk_fma_f32 v[20:21], v[12:13], v[20:21], v[16:17]
	v_pk_add_f32 v[34:35], v[34:35], v[36:37]
	v_pk_add_f32 v[20:21], v[20:21], v[38:39]
	v_cvt_pk_bf16_f32 v22, v34, v35
	v_cvt_pk_bf16_f32 v23, v20, v21
	ds_write_b64 v19, v[22:23] offset:224
	ds_read_b32 v18, v31
	ds_read_b32 v20, v33
	s_waitcnt lgkmcnt(3)
	v_lshlrev_b32_e32 v22, 16, v24
	v_and_b32_e32 v23, 0xffff0000, v24
	v_lshlrev_b32_e32 v34, 16, v6
	v_and_b32_e32 v35, 0xffff0000, v6
	v_lshlrev_b32_e32 v6, 16, v8
	v_and_b32_e32 v7, 0xffff0000, v8
	s_waitcnt lgkmcnt(1)
	v_pk_add_f32 v[8:9], v[22:23], v[18:19] op_sel_hi:[1,0] neg_lo:[0,1] neg_hi:[0,1]
	v_lshlrev_b32_e32 v24, 16, v25
	v_and_b32_e32 v25, 0xffff0000, v25
	s_waitcnt lgkmcnt(0)
	v_pk_mul_f32 v[8:9], v[20:21], v[8:9] op_sel_hi:[0,1]
	v_pk_fma_f32 v[8:9], v[10:11], v[8:9], v[14:15]
	v_pk_add_f32 v[10:11], v[24:25], v[18:19] op_sel_hi:[1,0] neg_lo:[0,1] neg_hi:[0,1]
	v_pk_add_f32 v[8:9], v[8:9], v[34:35]
	v_pk_mul_f32 v[10:11], v[20:21], v[10:11] op_sel_hi:[0,1]
	v_pk_fma_f32 v[10:11], v[12:13], v[10:11], v[16:17]
	v_cvt_pk_bf16_f32 v8, v8, v9
	v_pk_add_f32 v[6:7], v[10:11], v[6:7]
	s_nop 0
	v_cvt_pk_bf16_f32 v9, v6, v7
	ds_write_b64 v19, v[8:9] offset:16864
	ds_read_b128 v[6:9], v28 offset:480
	ds_read_b64 v[14:15], v19 offset:240
	ds_read_b32 v16, v29
	ds_read_b32 v18, v30
	v_add_u32_e32 v10, 0x255e0, v27
	ds_read_b128 v[10:13], v10
	s_waitcnt lgkmcnt(3)
	v_lshlrev_b32_e32 v20, 16, v14
	v_and_b32_e32 v21, 0xffff0000, v14
	v_lshlrev_b32_e32 v14, 16, v15
	v_and_b32_e32 v15, 0xffff0000, v15
	s_waitcnt lgkmcnt(2)
	v_pk_add_f32 v[20:21], v[20:21], v[16:17] op_sel_hi:[1,0] neg_lo:[0,1] neg_hi:[0,1]
	v_pk_add_f32 v[14:15], v[14:15], v[16:17] op_sel_hi:[1,0] neg_lo:[0,1] neg_hi:[0,1]
	s_waitcnt lgkmcnt(1)
	v_pk_mul_f32 v[20:21], v[18:19], v[20:21] op_sel_hi:[0,1]
	v_pk_mul_f32 v[14:15], v[18:19], v[14:15] op_sel_hi:[0,1]
	v_lshlrev_b32_e32 v22, 16, v4
	v_and_b32_e32 v23, 0xffff0000, v4
	v_lshlrev_b32_e32 v4, 16, v5
	v_and_b32_e32 v5, 0xffff0000, v5
	s_waitcnt lgkmcnt(0)
	v_pk_fma_f32 v[20:21], v[6:7], v[20:21], v[10:11]
	v_pk_fma_f32 v[14:15], v[8:9], v[14:15], v[12:13]
	v_pk_add_f32 v[20:21], v[20:21], v[22:23]
	v_pk_add_f32 v[4:5], v[14:15], v[4:5]
	v_cvt_pk_bf16_f32 v14, v20, v21
	v_cvt_pk_bf16_f32 v15, v4, v5
	ds_write_b64 v19, v[14:15] offset:240
	ds_read_b32 v4, v33
	ds_read_b64 v[14:15], v19 offset:16880
	ds_read_b32 v16, v31
	v_lshlrev_b32_e32 v22, 16, v2
	v_and_b32_e32 v23, 0xffff0000, v2
	v_lshlrev_b32_e32 v2, 16, v3
	s_waitcnt lgkmcnt(1)
	v_lshlrev_b32_e32 v20, 16, v14
	v_and_b32_e32 v21, 0xffff0000, v14
	s_waitcnt lgkmcnt(0)
	v_pk_add_f32 v[20:21], v[20:21], v[16:17] op_sel_hi:[1,0] neg_lo:[0,1] neg_hi:[0,1]
	v_lshlrev_b32_e32 v14, 16, v15
	v_and_b32_e32 v15, 0xffff0000, v15
	v_pk_mul_f32 v[20:21], v[4:5], v[20:21] op_sel_hi:[0,1]
	v_pk_fma_f32 v[6:7], v[6:7], v[20:21], v[10:11]
	v_pk_add_f32 v[10:11], v[14:15], v[16:17] op_sel_hi:[1,0] neg_lo:[0,1] neg_hi:[0,1]
	v_and_b32_e32 v3, 0xffff0000, v3
	v_pk_mul_f32 v[4:5], v[4:5], v[10:11] op_sel_hi:[0,1]
	v_pk_fma_f32 v[4:5], v[8:9], v[4:5], v[12:13]
	v_pk_add_f32 v[6:7], v[6:7], v[22:23]
	v_pk_add_f32 v[2:3], v[4:5], v[2:3]
	v_cvt_pk_bf16_f32 v4, v6, v7
	v_cvt_pk_bf16_f32 v5, v2, v3
	ds_write_b64 v19, v[4:5] offset:16880
	s_add_u32 s24, s80, s24
	s_addc_u32 s25, s81, s25
	v_lshl_add_u64 v[8:9], s[24:25], 0, v[0:1]
	v_mov_b32_e32 v0, v192
	s_waitcnt lgkmcnt(0)
	s_barrier
; DI int otid() { int t = threadIdx.x; asm volatile("" : "+v"(t)); return t; }
; DI void stg16_nt(void* p, u32x4 v) { __builtin_nontemporal_store(v, (u32x4*)p); }
; DI void stage_store_tile(const bf16_t* stg, bf16_t* tilebase) {
;   const int tid = otid();
;   const int r0 = tid >> 5, c = tid & 31;
;   const unsigned o0 = (unsigned)(r0 * 1024 + c * 8);
; #pragma unroll
;   for (int it = 0; it < 16; ++it) stg16_nt(tilebase + (o0 + (unsigned)(it * 16 * 1024)), stage_read16(stg, r0 + 16 * it, c));
; }
	s_mov_b64 s[100:101], 0x8000
	s_add_i32 s31, s31, s74
	s_add_i32 s28, s28, s69
	s_add_i32 s29, s29, s30
	s_add_i32 s24, s70, s31
	s_cmpk_lt_i32 s24, 0x400
	v_ashrrev_i32_e32 v190, 5, v192
	v_and_b32_e32 v191, 31, v192
	v_mul_lo_u32 v252, v190, s40
	v_lshl_add_u32 v252, v191, 4, v252
	v_lshlrev_b32_e32 v191, 3, v191
	v_lshl_or_b32 v254, v190, 10, v191
	v_mov_b32_e32 v255, v161
	ds_read2_b64 v[218:221], v252 offset1:1
	v_add_u32_e32 v253, 0x2080, v252
	ds_read2_b64 v[222:225], v253 offset1:1
	v_add_u32_e32 v253, 0x4100, v252
	ds_read2_b64 v[226:229], v253 offset1:1
	v_add_u32_e32 v253, 0x6180, v252
	ds_read2_b64 v[230:233], v253 offset1:1
	v_add_u32_e32 v253, 0x8200, v252
	ds_read2_b64 v[234:237], v253 offset1:1
	v_add_u32_e32 v253, 0xa280, v252
	ds_read2_b64 v[238:241], v253 offset1:1
	v_add_u32_e32 v253, 0xc300, v252
	ds_read2_b64 v[242:245], v253 offset1:1
	v_add_u32_e32 v253, 0xe380, v252
	ds_read2_b64 v[248:251], v253 offset1:1
	v_lshl_add_u64 v[254:255], v[254:255], 1, v[8:9]
	s_waitcnt lgkmcnt(7)
	global_store_dwordx4 v[254:255], v[218:221], off nt
	v_add_u32_e32 v253, 0x10400, v252
	ds_read2_b64 v[218:221], v253 offset1:1
	v_lshl_add_u64 v[254:255], v[254:255], 0, s[100:101]
	s_waitcnt lgkmcnt(7)
	global_store_dwordx4 v[254:255], v[222:225], off nt
	v_add_u32_e32 v253, 0x12480, v252
	ds_read2_b64 v[222:225], v253 offset1:1
	v_lshl_add_u64 v[254:255], v[254:255], 0, s[100:101]
	s_waitcnt lgkmcnt(7)
	global_store_dwordx4 v[254:255], v[226:229], off nt
	v_add_u32_e32 v253, 0x14500, v252
	ds_read2_b64 v[226:229], v253 offset1:1
	v_lshl_add_u64 v[254:255], v[254:255], 0, s[100:101]
	s_waitcnt lgkmcnt(7)
	global_store_dwordx4 v[254:255], v[230:233], off nt
	v_add_u32_e32 v253, 0x16580, v252
	ds_read2_b64 v[230:233], v253 offset1:1
	v_lshl_add_u64 v[254:255], v[254:255], 0, s[100:101]
	s_waitcnt lgkmcnt(7)
	global_store_dwordx4 v[254:255], v[234:237], off nt
	v_add_u32_e32 v253, 0x18600, v252
	ds_read2_b64 v[234:237], v253 offset1:1
	v_lshl_add_u64 v[254:255], v[254:255], 0, s[100:101]
	s_waitcnt lgkmcnt(7)
	global_store_dwordx4 v[254:255], v[238:241], off nt
	v_add_u32_e32 v253, 0x1a680, v252
	ds_read2_b64 v[238:241], v253 offset1:1
	v_lshl_add_u64 v[254:255], v[254:255], 0, s[100:101]
	s_waitcnt lgkmcnt(7)
	global_store_dwordx4 v[254:255], v[242:245], off nt
	v_add_u32_e32 v253, 0x1c700, v252
	ds_read2_b64 v[242:245], v253 offset1:1
	v_lshl_add_u64 v[254:255], v[254:255], 0, s[100:101]
	s_waitcnt lgkmcnt(7)
	global_store_dwordx4 v[254:255], v[248:251], off nt
	v_add_u32_e32 v253, 0x1e780, v252
	ds_read2_b64 v[248:251], v253 offset1:1
	v_lshl_add_u64 v[254:255], v[254:255], 0, s[100:101]
	s_waitcnt lgkmcnt(7)
	global_store_dwordx4 v[254:255], v[218:221], off nt
	v_lshl_add_u64 v[254:255], v[254:255], 0, s[100:101]
	s_waitcnt lgkmcnt(6)
	global_store_dwordx4 v[254:255], v[222:225], off nt
	v_lshl_add_u64 v[254:255], v[254:255], 0, s[100:101]
	s_waitcnt lgkmcnt(5)
	global_store_dwordx4 v[254:255], v[226:229], off nt
	v_lshl_add_u64 v[254:255], v[254:255], 0, s[100:101]
	s_waitcnt lgkmcnt(4)
	global_store_dwordx4 v[254:255], v[230:233], off nt
	v_lshl_add_u64 v[254:255], v[254:255], 0, s[100:101]
	s_waitcnt lgkmcnt(3)
	global_store_dwordx4 v[254:255], v[234:237], off nt
	v_lshl_add_u64 v[254:255], v[254:255], 0, s[100:101]
	s_waitcnt lgkmcnt(2)
	global_store_dwordx4 v[254:255], v[238:241], off nt
	v_lshl_add_u64 v[254:255], v[254:255], 0, s[100:101]
	s_waitcnt lgkmcnt(1)
	global_store_dwordx4 v[254:255], v[242:245], off nt
	v_lshl_add_u64 v[254:255], v[254:255], 0, s[100:101]
	s_waitcnt lgkmcnt(0)
	global_store_dwordx4 v[254:255], v[248:251], off nt
	s_barrier
	s_cbranch_scc0 .LBB0_929

; DI int otid() { int t = threadIdx.x; asm volatile("" : "+v"(t)); return t; }
; DI void stg16_nt(void* p, u32x4 v) { __builtin_nontemporal_store(v, (u32x4*)p); }
; DI void stage_store_tile(const bf16_t* stg, bf16_t* tilebase) {
;   const int tid = otid();
;   const int r0 = tid >> 5, c = tid & 31;
;   const unsigned o0 = (unsigned)(r0 * 1024 + c * 8);
; #pragma unroll
;   for (int it = 0; it < 16; ++it) stg16_nt(tilebase + (o0 + (unsigned)(it * 16 * 1024)), stage_read16(stg, r0 + 16 * it, c));
; }
.LBB0_1425:
	s_or_b64 exec, exec, s[14:15]
	v_mov_b32_e32 v0, v192
	s_waitcnt lgkmcnt(0)
	s_barrier
	s_mov_b64 s[100:101], 0x8000
	s_lshl_b64 s[10:11], s[10:11], 18
	s_lshl_b64 s[10:11], s[10:11], 1
	s_add_u32 s10, s76, s10
	s_addc_u32 s11, s77, s11
	s_add_u32 s10, s10, s27
	s_addc_u32 s11, s11, 0
	s_add_i32 s19, s19, s69
	s_andn2_b64 vcc, exec, s[12:13]
	s_add_i32 s20, s20, s17
	v_ashrrev_i32_e32 v190, 5, v192
	v_and_b32_e32 v191, 31, v192
	v_mul_lo_u32 v252, v190, s23
	v_lshl_add_u32 v252, v191, 4, v252
	v_lshlrev_b32_e32 v191, 3, v191
	v_lshl_or_b32 v254, v190, 10, v191
	v_mov_b32_e32 v255, v161
	ds_read2_b64 v[218:221], v252 offset1:1
	v_add_u32_e32 v253, 0x2080, v252
	ds_read2_b64 v[222:225], v253 offset1:1
	v_add_u32_e32 v253, 0x4100, v252
	ds_read2_b64 v[226:229], v253 offset1:1
	v_add_u32_e32 v253, 0x6180, v252
	ds_read2_b64 v[230:233], v253 offset1:1
	v_add_u32_e32 v253, 0x8200, v252
	ds_read2_b64 v[234:237], v253 offset1:1
	v_add_u32_e32 v253, 0xa280, v252
	ds_read2_b64 v[238:241], v253 offset1:1
	v_add_u32_e32 v253, 0xc300, v252
	ds_read2_b64 v[242:245], v253 offset1:1
	v_add_u32_e32 v253, 0xe380, v252
	ds_read2_b64 v[248:251], v253 offset1:1
	v_lshl_add_u64 v[254:255], v[254:255], 1, s[10:11]
	s_waitcnt lgkmcnt(7)
	global_store_dwordx4 v[254:255], v[218:221], off nt
	v_add_u32_e32 v253, 0x10400, v252
	ds_read2_b64 v[218:221], v253 offset1:1
	v_lshl_add_u64 v[254:255], v[254:255], 0, s[100:101]
	s_waitcnt lgkmcnt(7)
	global_store_dwordx4 v[254:255], v[222:225], off nt
	v_add_u32_e32 v253, 0x12480, v252
	ds_read2_b64 v[222:225], v253 offset1:1
	v_lshl_add_u64 v[254:255], v[254:255], 0, s[100:101]
	s_waitcnt lgkmcnt(7)
	global_store_dwordx4 v[254:255], v[226:229], off nt
	v_add_u32_e32 v253, 0x14500, v252
	ds_read2_b64 v[226:229], v253 offset1:1
	v_lshl_add_u64 v[254:255], v[254:255], 0, s[100:101]
	s_waitcnt lgkmcnt(7)
	global_store_dwordx4 v[254:255], v[230:233], off nt
	v_add_u32_e32 v253, 0x16580, v252
	ds_read2_b64 v[230:233], v253 offset1:1
	v_lshl_add_u64 v[254:255], v[254:255], 0, s[100:101]
	s_waitcnt lgkmcnt(7)
	global_store_dwordx4 v[254:255], v[234:237], off nt
	v_add_u32_e32 v253, 0x18600, v252
	ds_read2_b64 v[234:237], v253 offset1:1
	v_lshl_add_u64 v[254:255], v[254:255], 0, s[100:101]
	s_waitcnt lgkmcnt(7)
	global_store_dwordx4 v[254:255], v[238:241], off nt
	v_add_u32_e32 v253, 0x1a680, v252
	ds_read2_b64 v[238:241], v253 offset1:1
	v_lshl_add_u64 v[254:255], v[254:255], 0, s[100:101]
	s_waitcnt lgkmcnt(7)
	global_store_dwordx4 v[254:255], v[242:245], off nt
	v_add_u32_e32 v253, 0x1c700, v252
	ds_read2_b64 v[242:245], v253 offset1:1
	v_lshl_add_u64 v[254:255], v[254:255], 0, s[100:101]
	s_waitcnt lgkmcnt(7)
	global_store_dwordx4 v[254:255], v[248:251], off nt
	v_add_u32_e32 v253, 0x1e780, v252
	ds_read2_b64 v[248:251], v253 offset1:1
	v_lshl_add_u64 v[254:255], v[254:255], 0, s[100:101]
	s_waitcnt lgkmcnt(7)
	global_store_dwordx4 v[254:255], v[218:221], off nt
	v_lshl_add_u64 v[254:255], v[254:255], 0, s[100:101]
	s_waitcnt lgkmcnt(6)
	global_store_dwordx4 v[254:255], v[222:225], off nt
	v_lshl_add_u64 v[254:255], v[254:255], 0, s[100:101]
	s_waitcnt lgkmcnt(5)
	global_store_dwordx4 v[254:255], v[226:229], off nt
	v_lshl_add_u64 v[254:255], v[254:255], 0, s[100:101]
	s_waitcnt lgkmcnt(4)
	global_store_dwordx4 v[254:255], v[230:233], off nt
	v_lshl_add_u64 v[254:255], v[254:255], 0, s[100:101]
	s_waitcnt lgkmcnt(3)
	global_store_dwordx4 v[254:255], v[234:237], off nt
	v_lshl_add_u64 v[254:255], v[254:255], 0, s[100:101]
	s_waitcnt lgkmcnt(2)
	global_store_dwordx4 v[254:255], v[238:241], off nt
	v_lshl_add_u64 v[254:255], v[254:255], 0, s[100:101]
	s_waitcnt lgkmcnt(1)
	global_store_dwordx4 v[254:255], v[242:245], off nt
	v_lshl_add_u64 v[254:255], v[254:255], 0, s[100:101]
	s_waitcnt lgkmcnt(0)
	global_store_dwordx4 v[254:255], v[248:251], off nt
	s_barrier
	s_cbranch_vccz .LBB0_1436

; DI unsigned pack2(float a, float b) { f32x2_t v = {a, b}; bf16x2_t r = __builtin_convertvector(v, bf16x2_t); return __builtin_bit_cast(unsigned, r); }
; DI float sigmoidf_(float x) { return __builtin_amdgcn_rcpf(1.f + __expf(-x)); }
; template <bool LAST>
; DI void phase_gate(const Params& P, int layer, unsigned char* smem, int L, int G) {
;     ...
;     unsigned gq[4][2][8];
; #pragma unroll
;     for (int i = 0; i < 4; ++i)
; #pragma unroll
;       for (int q4 = 0; q4 < 4; ++q4) {
;         const int fl = wm * 128 + i * 32 + 8 * q4 + 4 * h;
;         const f32x4 c1v = *(const f32x4*)(vecL + fl), c2v = *(const f32x4*)(vecL + 256 + fl);
;         const float c1a[4] = {c1v.x, c1v.y, c1v.z, c1v.w}, c2a[4] = {c2v.x, c2v.y, c2v.z, c2v.w};
; #pragma unroll
;         for (int j = 0; j < 2; ++j) {
;           const int lrow = wn * 64 + j * 32 + r;
;           const float mu = rowA[lrow], rstd = rowB[lrow];
;           float sg4[4];
; #pragma unroll
;           for (int e = 0; e < 4; ++e) sg4[e] = sigmoidf_(rstd * (accu[i][j][4 * q4 + e] - mu * c1a[e]) + c2a[e]);
;           gq[i][j][2 * q4] = pack2(sg4[0], sg4[1]); gq[i][j][2 * q4 + 1] = pack2(sg4[2], sg4[3]);
;         }
;         __builtin_amdgcn_sched_barrier(0);
;       }
;     stage_load_tile<true>(stg, PPb + (size_t)mt * 256 * 1024 + nt * 256);
.LBB0_1498:
	s_ashr_i32 s19, s18, 31
	s_lshl_b64 s[18:19], s[18:19], 19
	s_add_u32 s20, s66, s18
	s_addc_u32 s21, s67, s19
	v_and_b32_e32 v188, 31, v192
	v_ashrrev_i32_e32 v189, 5, v192
	v_lshlrev_b32_e32 v188, 3, v188
	v_lshl_or_b32 v188, v189, 10, v188
	v_add_u32_e32 v188, v188, v162
	v_lshlrev_b32_e32 v188, 1, v188
	global_load_dwordx4 v[180:183], v188, s[20:21] nt
	s_add_u32 s100, s20, 0x8000
	s_addc_u32 s101, s21, 0
	global_load_dwordx4 v[184:187], v188, s[100:101] nt
	s_add_u32 s100, s20, 0x10000
	s_addc_u32 s101, s21, 0
	global_load_dwordx4 v[194:197], v188, s[100:101] nt
	s_add_u32 s100, s20, 0x18000
	s_addc_u32 s101, s21, 0
	global_load_dwordx4 v[198:201], v188, s[100:101] nt
	s_add_u32 s100, s20, 0x20000
	s_addc_u32 s101, s21, 0
	global_load_dwordx4 v[202:205], v188, s[100:101] nt
	s_add_u32 s100, s20, 0x28000
	s_addc_u32 s101, s21, 0
	global_load_dwordx4 v[206:209], v188, s[100:101] nt
	s_add_u32 s100, s20, 0x30000
	s_addc_u32 s101, s21, 0
	global_load_dwordx4 v[210:213], v188, s[100:101] nt
	s_add_u32 s100, s20, 0x38000
	s_addc_u32 s101, s21, 0
	global_load_dwordx4 v[214:217], v188, s[100:101] nt
	s_add_u32 s100, s20, 0x40000
	s_addc_u32 s101, s21, 0
	global_load_dwordx4 v[218:221], v188, s[100:101] nt
	s_add_u32 s100, s20, 0x48000
	s_addc_u32 s101, s21, 0
	global_load_dwordx4 v[222:225], v188, s[100:101] nt
	s_add_u32 s100, s20, 0x50000
	s_addc_u32 s101, s21, 0
	global_load_dwordx4 v[226:229], v188, s[100:101] nt
	s_add_u32 s100, s20, 0x58000
	s_addc_u32 s101, s21, 0
	global_load_dwordx4 v[230:233], v188, s[100:101] nt
	s_add_u32 s100, s20, 0x60000
	s_addc_u32 s101, s21, 0
	global_load_dwordx4 v[234:237], v188, s[100:101] nt
	s_add_u32 s100, s20, 0x68000
	s_addc_u32 s101, s21, 0
	global_load_dwordx4 v[238:241], v188, s[100:101] nt
	s_add_u32 s100, s20, 0x70000
	s_addc_u32 s101, s21, 0
	global_load_dwordx4 v[242:245], v188, s[100:101] nt
	s_add_u32 s100, s20, 0x78000
	s_addc_u32 s101, s21, 0
	global_load_dwordx4 v[248:251], v188, s[100:101] nt
	v_lshrrev_b32_e32 v160, 1, v163
	v_lshrrev_b32_e32 v163, 3, v163
	v_and_b32_e32 v163, 4, v163
	v_and_or_b32 v160, v160, s33, v163
	v_lshlrev_b32_e32 v160, 2, v160
	v_add_u32_e32 v163, 0x24800, v160
	v_add_u32_e32 v164, 0x24c00, v160
	v_and_b32_e32 v167, 0x37c, v168
	ds_read_b128 v[170:173], v163
	ds_read_b128 v[174:177], v164
	v_or_b32_e32 v164, 0x24000, v167
	v_or_b32_e32 v166, 0x24080, v167
	v_or_b32_e32 v165, 0x24400, v167
	ds_read_b32 v168, v164
	ds_read_b32 v169, v165
	v_or_b32_e32 v167, 0x24480, v167
	ds_read_b32 v178, v166
	ds_read_b32 v179, v167
	s_waitcnt lgkmcnt(3)
	v_fma_f32 v112, -v170, v168, v112
	v_fma_f32 v113, -v171, v168, v113
	s_waitcnt lgkmcnt(1)
	v_fma_f32 v98, -v172, v178, v98
	v_fma_f32 v114, -v172, v168, v114
	v_fma_f32 v115, -v173, v168, v115
	v_fma_f32 v96, -v170, v178, v96
	v_fma_f32 v97, -v171, v178, v97
	s_waitcnt lgkmcnt(0)
	v_fma_f32 v98, v179, v98, v176
	v_fma_f32 v99, -v173, v178, v99
	v_fma_f32 v112, v169, v112, v174
	v_fma_f32 v113, v169, v113, v175
	v_fma_f32 v114, v169, v114, v176
	v_fma_f32 v115, v169, v115, v177
	v_fma_f32 v96, v179, v96, v174
	v_fma_f32 v97, v179, v97, v175
	v_mul_f32_e32 v98, 0xbfb8aa3b, v98
	v_fmac_f32_e32 v177, v179, v99
	v_mul_f32_e32 v112, 0xbfb8aa3b, v112
	v_mul_f32_e32 v113, 0xbfb8aa3b, v113
	v_mul_f32_e32 v114, 0xbfb8aa3b, v114
	v_mul_f32_e32 v115, 0xbfb8aa3b, v115
	v_mul_f32_e32 v96, 0xbfb8aa3b, v96
	v_mul_f32_e32 v97, 0xbfb8aa3b, v97
	v_exp_f32_e32 v98, v98
	v_mul_f32_e32 v99, 0xbfb8aa3b, v177
	v_exp_f32_e32 v112, v112
	v_exp_f32_e32 v113, v113
	v_exp_f32_e32 v114, v114
	v_exp_f32_e32 v115, v115
	v_exp_f32_e32 v96, v96
	v_exp_f32_e32 v97, v97
	v_exp_f32_e32 v99, v99
	v_add_f32_e32 v98, 1.0, v98
	v_add_f32_e32 v112, 1.0, v112
	v_add_f32_e32 v113, 1.0, v113
	v_add_f32_e32 v114, 1.0, v114
	v_add_f32_e32 v115, 1.0, v115
	v_add_f32_e32 v96, 1.0, v96
	v_add_f32_e32 v97, 1.0, v97
	v_rcp_f32_e32 v168, v98
	v_add_f32_e32 v98, 1.0, v99
	v_rcp_f32_e32 v112, v112
	v_rcp_f32_e32 v113, v113
	v_rcp_f32_e32 v114, v114
	v_rcp_f32_e32 v115, v115
	v_rcp_f32_e32 v96, v96
	v_rcp_f32_e32 v97, v97
	v_rcp_f32_e32 v169, v98
	v_cvt_pk_bf16_f32 v99, v112, v113
	v_cvt_pk_bf16_f32 v98, v114, v115
	v_cvt_pk_bf16_f32 v97, v96, v97
	v_cvt_pk_bf16_f32 v96, v168, v169
	v_add_u32_e32 v112, 0x24820, v160
	v_add_u32_e32 v168, 0x24c20, v160
	ds_read_b128 v[112:115], v112
	ds_read_b128 v[168:171], v168
	ds_read_b32 v172, v164
	ds_read_b32 v173, v165
	ds_read_b32 v174, v166
	ds_read_b32 v175, v167
	s_waitcnt lgkmcnt(3)
	v_fma_f32 v116, -v112, v172, v116
	v_fma_f32 v117, -v113, v172, v117
	s_waitcnt lgkmcnt(1)
	v_fma_f32 v102, -v114, v174, v102
	v_fma_f32 v118, -v114, v172, v118
	v_fma_f32 v119, -v115, v172, v119
	v_fma_f32 v100, -v112, v174, v100
	v_fma_f32 v101, -v113, v174, v101
	s_waitcnt lgkmcnt(0)
	v_fma_f32 v102, v175, v102, v170
	v_fma_f32 v103, -v115, v174, v103
	v_fma_f32 v116, v173, v116, v168
	v_fma_f32 v117, v173, v117, v169
	v_fma_f32 v118, v173, v118, v170
	v_fma_f32 v119, v173, v119, v171
	v_fma_f32 v100, v175, v100, v168
	v_fma_f32 v101, v175, v101, v169
	v_mul_f32_e32 v102, 0xbfb8aa3b, v102
	v_fmac_f32_e32 v171, v175, v103
	v_mul_f32_e32 v116, 0xbfb8aa3b, v116
	v_mul_f32_e32 v117, 0xbfb8aa3b, v117
	v_mul_f32_e32 v118, 0xbfb8aa3b, v118
	v_mul_f32_e32 v119, 0xbfb8aa3b, v119
	v_mul_f32_e32 v100, 0xbfb8aa3b, v100
	v_mul_f32_e32 v101, 0xbfb8aa3b, v101
	v_exp_f32_e32 v102, v102
	v_mul_f32_e32 v103, 0xbfb8aa3b, v171
	v_exp_f32_e32 v116, v116
	v_exp_f32_e32 v117, v117
	v_exp_f32_e32 v118, v118
	v_exp_f32_e32 v119, v119
	v_exp_f32_e32 v100, v100
	v_exp_f32_e32 v101, v101
	v_exp_f32_e32 v103, v103
	v_add_f32_e32 v102, 1.0, v102
	v_add_f32_e32 v116, 1.0, v116
	v_add_f32_e32 v117, 1.0, v117
	v_add_f32_e32 v118, 1.0, v118
	v_add_f32_e32 v119, 1.0, v119
	v_add_f32_e32 v100, 1.0, v100
	v_add_f32_e32 v101, 1.0, v101
	v_rcp_f32_e32 v113, v102
	v_add_f32_e32 v102, 1.0, v103
	v_rcp_f32_e32 v116, v116
	v_rcp_f32_e32 v117, v117
	v_rcp_f32_e32 v118, v118
	v_rcp_f32_e32 v112, v119
	v_rcp_f32_e32 v100, v100
	v_rcp_f32_e32 v101, v101
	v_rcp_f32_e32 v114, v102
	v_cvt_pk_bf16_f32 v103, v116, v117
	v_cvt_pk_bf16_f32 v102, v118, v112
	v_cvt_pk_bf16_f32 v101, v100, v101
	v_cvt_pk_bf16_f32 v100, v113, v114
	v_add_u32_e32 v112, 0x24840, v160
	v_add_u32_e32 v116, 0x24c40, v160
	ds_read_b128 v[112:115], v112
	ds_read_b128 v[116:119], v116
	ds_read_b32 v168, v164
	ds_read_b32 v169, v165
	ds_read_b32 v170, v166
	ds_read_b32 v171, v167
	s_waitcnt lgkmcnt(3)
; DI unsigned pack2(float a, float b) { f32x2_t v = {a, b}; bf16x2_t r = __builtin_convertvector(v, bf16x2_t); return __builtin_bit_cast(unsigned, r); }
; DI float sigmoidf_(float x) { return __builtin_amdgcn_rcpf(1.f + __expf(-x)); }
; template <bool LAST>
; DI void phase_gate(const Params& P, int layer, unsigned char* smem, int L, int G) {
;     ...
;     for (int i = 0; i < 4; ++i)
; #pragma unroll
;       for (int q4 = 0; q4 < 4; ++q4) {
;         const int fl = wm * 128 + i * 32 + 8 * q4 + 4 * h;
;         const f32x4 c1v = *(const f32x4*)(vecL + fl), c2v = *(const f32x4*)(vecL + 256 + fl);
;         const float c1a[4] = {c1v.x, c1v.y, c1v.z, c1v.w}, c2a[4] = {c2v.x, c2v.y, c2v.z, c2v.w};
; #pragma unroll
;         for (int j = 0; j < 2; ++j) {
;           const int lrow = wn * 64 + j * 32 + r;
;           const float mu = rowA[lrow], rstd = rowB[lrow];
;           float sg4[4];
; #pragma unroll
;           for (int e = 0; e < 4; ++e) sg4[e] = sigmoidf_(rstd * (accu[i][j][4 * q4 + e] - mu * c1a[e]) + c2a[e]);
;           gq[i][j][2 * q4] = pack2(sg4[0], sg4[1]); gq[i][j][2 * q4 + 1] = pack2(sg4[2], sg4[3]);
;         }
;         __builtin_amdgcn_sched_barrier(0);
	v_fma_f32 v120, -v112, v168, v120
	v_fma_f32 v121, -v113, v168, v121
	s_waitcnt lgkmcnt(1)
	v_fma_f32 v106, -v114, v170, v106
	v_fma_f32 v122, -v114, v168, v122
	v_fma_f32 v123, -v115, v168, v123
	v_fma_f32 v104, -v112, v170, v104
	v_fma_f32 v105, -v113, v170, v105
	s_waitcnt lgkmcnt(0)
	v_fma_f32 v106, v171, v106, v118
	v_fma_f32 v107, -v115, v170, v107
	v_fma_f32 v120, v169, v120, v116
	v_fma_f32 v121, v169, v121, v117
	v_fma_f32 v122, v169, v122, v118
	v_fma_f32 v123, v169, v123, v119
	v_fma_f32 v104, v171, v104, v116
	v_fma_f32 v105, v171, v105, v117
	v_mul_f32_e32 v106, 0xbfb8aa3b, v106
	v_fmac_f32_e32 v119, v171, v107
	v_mul_f32_e32 v120, 0xbfb8aa3b, v120
	v_mul_f32_e32 v121, 0xbfb8aa3b, v121
	v_mul_f32_e32 v122, 0xbfb8aa3b, v122
	v_mul_f32_e32 v123, 0xbfb8aa3b, v123
	v_mul_f32_e32 v104, 0xbfb8aa3b, v104
	v_mul_f32_e32 v105, 0xbfb8aa3b, v105
	v_exp_f32_e32 v106, v106
	v_mul_f32_e32 v107, 0xbfb8aa3b, v119
	v_exp_f32_e32 v120, v120
	v_exp_f32_e32 v121, v121
	v_exp_f32_e32 v122, v122
	v_exp_f32_e32 v123, v123
	v_exp_f32_e32 v104, v104
	v_exp_f32_e32 v105, v105
	v_exp_f32_e32 v107, v107
	v_add_f32_e32 v106, 1.0, v106
	v_add_f32_e32 v120, 1.0, v120
	v_add_f32_e32 v121, 1.0, v121
	v_add_f32_e32 v122, 1.0, v122
	v_add_f32_e32 v123, 1.0, v123
	v_add_f32_e32 v104, 1.0, v104
	v_add_f32_e32 v105, 1.0, v105
	v_rcp_f32_e32 v113, v106
	v_add_f32_e32 v106, 1.0, v107
	v_rcp_f32_e32 v120, v120
	v_rcp_f32_e32 v121, v121
	v_rcp_f32_e32 v122, v122
	v_rcp_f32_e32 v112, v123
	v_rcp_f32_e32 v104, v104
	v_rcp_f32_e32 v105, v105
	v_rcp_f32_e32 v114, v106
	v_cvt_pk_bf16_f32 v107, v120, v121
	v_cvt_pk_bf16_f32 v106, v122, v112
	v_cvt_pk_bf16_f32 v105, v104, v105
	v_cvt_pk_bf16_f32 v104, v113, v114
	v_add_u32_e32 v112, 0x24860, v160
	v_add_u32_e32 v116, 0x24c60, v160
	ds_read_b128 v[112:115], v112
	ds_read_b128 v[116:119], v116
	ds_read_b32 v120, v164
	ds_read_b32 v121, v165
	ds_read_b32 v122, v166
	ds_read_b32 v123, v167
	s_waitcnt lgkmcnt(3)
	v_fma_f32 v125, -v113, v120, v125
	v_fma_f32 v124, -v112, v120, v124
	s_waitcnt lgkmcnt(1)
	v_fma_f32 v110, -v114, v122, v110
	v_fma_f32 v125, v121, v125, v117
	v_fma_f32 v126, -v114, v120, v126
	v_fma_f32 v120, -v115, v120, v127
	v_fma_f32 v108, -v112, v122, v108
	v_fma_f32 v109, -v113, v122, v109
	s_waitcnt lgkmcnt(0)
	v_fma_f32 v110, v123, v110, v118
	v_fma_f32 v111, -v115, v122, v111
	v_fma_f32 v124, v121, v124, v116
	v_mul_f32_e32 v125, 0xbfb8aa3b, v125
	v_fma_f32 v126, v121, v126, v118
	v_fma_f32 v120, v121, v120, v119
	v_fma_f32 v108, v123, v108, v116
	v_fma_f32 v109, v123, v109, v117
	v_mul_f32_e32 v110, 0xbfb8aa3b, v110
	v_fmac_f32_e32 v119, v123, v111
	v_mul_f32_e32 v124, 0xbfb8aa3b, v124
	v_exp_f32_e32 v125, v125
	v_mul_f32_e32 v126, 0xbfb8aa3b, v126
	v_mul_f32_e32 v120, 0xbfb8aa3b, v120
	v_mul_f32_e32 v108, 0xbfb8aa3b, v108
	v_mul_f32_e32 v109, 0xbfb8aa3b, v109
	v_exp_f32_e32 v110, v110
	v_mul_f32_e32 v111, 0xbfb8aa3b, v119
	v_exp_f32_e32 v124, v124
	v_exp_f32_e32 v126, v126
	v_exp_f32_e32 v120, v120
	v_exp_f32_e32 v108, v108
	v_exp_f32_e32 v109, v109
	v_exp_f32_e32 v111, v111
	v_add_f32_e32 v125, 1.0, v125
	v_add_f32_e32 v110, 1.0, v110
	v_add_f32_e32 v124, 1.0, v124
	v_rcp_f32_e32 v121, v125
	v_add_f32_e32 v125, 1.0, v126
	v_add_f32_e32 v120, 1.0, v120
	v_add_f32_e32 v108, 1.0, v108
	v_add_f32_e32 v109, 1.0, v109
	v_rcp_f32_e32 v113, v110
	v_add_f32_e32 v110, 1.0, v111
	v_rcp_f32_e32 v124, v124
	v_rcp_f32_e32 v125, v125
	v_rcp_f32_e32 v112, v120
	v_rcp_f32_e32 v108, v108
	v_rcp_f32_e32 v109, v109
	v_rcp_f32_e32 v114, v110
	v_cvt_pk_bf16_f32 v111, v124, v121
	v_cvt_pk_bf16_f32 v110, v125, v112
	v_cvt_pk_bf16_f32 v109, v108, v109
	v_cvt_pk_bf16_f32 v108, v113, v114
	v_add_u32_e32 v112, 0x24880, v160
	v_add_u32_e32 v116, 0x24c80, v160
	ds_read_b128 v[112:115], v112
	ds_read_b128 v[116:119], v116
	ds_read_b32 v120, v164
	ds_read_b32 v121, v165
	ds_read_b32 v122, v166
	ds_read_b32 v123, v167
	s_waitcnt lgkmcnt(3)
	v_fma_f32 v80, -v112, v120, v80
	v_fma_f32 v81, -v113, v120, v81
	s_waitcnt lgkmcnt(1)
	v_fma_f32 v66, -v114, v122, v66
	v_fma_f32 v82, -v114, v120, v82
	v_fma_f32 v83, -v115, v120, v83
	v_fma_f32 v64, -v112, v122, v64
	v_fma_f32 v65, -v113, v122, v65
	s_waitcnt lgkmcnt(0)
	v_fma_f32 v66, v123, v66, v118
	v_fma_f32 v67, -v115, v122, v67
	v_fma_f32 v80, v121, v80, v116
	v_fma_f32 v81, v121, v81, v117
	v_fma_f32 v82, v121, v82, v118
	v_fma_f32 v83, v121, v83, v119
	v_fma_f32 v64, v123, v64, v116
	v_fma_f32 v65, v123, v65, v117
	v_mul_f32_e32 v66, 0xbfb8aa3b, v66
	v_fmac_f32_e32 v119, v123, v67
	v_mul_f32_e32 v80, 0xbfb8aa3b, v80
	v_mul_f32_e32 v81, 0xbfb8aa3b, v81
	v_mul_f32_e32 v82, 0xbfb8aa3b, v82
	v_mul_f32_e32 v83, 0xbfb8aa3b, v83
	v_mul_f32_e32 v64, 0xbfb8aa3b, v64
	v_mul_f32_e32 v65, 0xbfb8aa3b, v65
	v_exp_f32_e32 v66, v66
	v_mul_f32_e32 v67, 0xbfb8aa3b, v119
	v_exp_f32_e32 v80, v80
	v_exp_f32_e32 v81, v81
	v_exp_f32_e32 v82, v82
	v_exp_f32_e32 v83, v83
	v_exp_f32_e32 v64, v64
	v_exp_f32_e32 v65, v65
	v_exp_f32_e32 v67, v67
	v_add_f32_e32 v66, 1.0, v66
	v_add_f32_e32 v80, 1.0, v80
	v_add_f32_e32 v81, 1.0, v81
	v_add_f32_e32 v82, 1.0, v82
	v_add_f32_e32 v83, 1.0, v83
	v_add_f32_e32 v64, 1.0, v64
	v_add_f32_e32 v65, 1.0, v65
	v_rcp_f32_e32 v112, v66
	v_add_f32_e32 v66, 1.0, v67
	v_rcp_f32_e32 v80, v80
	v_rcp_f32_e32 v81, v81
	v_rcp_f32_e32 v82, v82
	v_rcp_f32_e32 v83, v83
	v_rcp_f32_e32 v64, v64
	v_rcp_f32_e32 v65, v65
	v_rcp_f32_e32 v113, v66
	v_cvt_pk_bf16_f32 v67, v80, v81
	v_cvt_pk_bf16_f32 v66, v82, v83
	v_cvt_pk_bf16_f32 v65, v64, v65
	v_cvt_pk_bf16_f32 v64, v112, v113
	v_add_u32_e32 v80, 0x248a0, v160
	v_add_u32_e32 v112, 0x24ca0, v160
	ds_read_b128 v[80:83], v80
	ds_read_b128 v[112:115], v112
	ds_read_b32 v116, v164
	ds_read_b32 v117, v165
	ds_read_b32 v118, v166
	ds_read_b32 v119, v167
	s_waitcnt lgkmcnt(3)
; DI unsigned pack2(float a, float b) { f32x2_t v = {a, b}; bf16x2_t r = __builtin_convertvector(v, bf16x2_t); return __builtin_bit_cast(unsigned, r); }
; DI float sigmoidf_(float x) { return __builtin_amdgcn_rcpf(1.f + __expf(-x)); }
; template <bool LAST>
; DI void phase_gate(const Params& P, int layer, unsigned char* smem, int L, int G) {
;     ...
;     for (int i = 0; i < 4; ++i)
; #pragma unroll
;       for (int q4 = 0; q4 < 4; ++q4) {
;         const int fl = wm * 128 + i * 32 + 8 * q4 + 4 * h;
;         const f32x4 c1v = *(const f32x4*)(vecL + fl), c2v = *(const f32x4*)(vecL + 256 + fl);
;         const float c1a[4] = {c1v.x, c1v.y, c1v.z, c1v.w}, c2a[4] = {c2v.x, c2v.y, c2v.z, c2v.w};
; #pragma unroll
;         for (int j = 0; j < 2; ++j) {
;           const int lrow = wn * 64 + j * 32 + r;
;           const float mu = rowA[lrow], rstd = rowB[lrow];
;           float sg4[4];
; #pragma unroll
;           for (int e = 0; e < 4; ++e) sg4[e] = sigmoidf_(rstd * (accu[i][j][4 * q4 + e] - mu * c1a[e]) + c2a[e]);
;           gq[i][j][2 * q4] = pack2(sg4[0], sg4[1]); gq[i][j][2 * q4 + 1] = pack2(sg4[2], sg4[3]);
;         }
;         __builtin_amdgcn_sched_barrier(0);
	v_fma_f32 v84, -v80, v116, v84
	v_fma_f32 v85, -v81, v116, v85
	s_waitcnt lgkmcnt(1)
	v_fma_f32 v70, -v82, v118, v70
	v_fma_f32 v86, -v82, v116, v86
	v_fma_f32 v87, -v83, v116, v87
	v_fma_f32 v68, -v80, v118, v68
	v_fma_f32 v69, -v81, v118, v69
	s_waitcnt lgkmcnt(0)
	v_fma_f32 v70, v119, v70, v114
	v_fma_f32 v71, -v83, v118, v71
	v_fma_f32 v84, v117, v84, v112
	v_fma_f32 v85, v117, v85, v113
	v_fma_f32 v86, v117, v86, v114
	v_fma_f32 v87, v117, v87, v115
	v_fma_f32 v68, v119, v68, v112
	v_fma_f32 v69, v119, v69, v113
	v_mul_f32_e32 v70, 0xbfb8aa3b, v70
	v_fmac_f32_e32 v115, v119, v71
	v_mul_f32_e32 v84, 0xbfb8aa3b, v84
	v_mul_f32_e32 v85, 0xbfb8aa3b, v85
	v_mul_f32_e32 v86, 0xbfb8aa3b, v86
	v_mul_f32_e32 v87, 0xbfb8aa3b, v87
	v_mul_f32_e32 v68, 0xbfb8aa3b, v68
	v_mul_f32_e32 v69, 0xbfb8aa3b, v69
	v_exp_f32_e32 v70, v70
	v_mul_f32_e32 v71, 0xbfb8aa3b, v115
	v_exp_f32_e32 v84, v84
	v_exp_f32_e32 v85, v85
	v_exp_f32_e32 v86, v86
	v_exp_f32_e32 v87, v87
	v_exp_f32_e32 v68, v68
	v_exp_f32_e32 v69, v69
	v_exp_f32_e32 v71, v71
	v_add_f32_e32 v70, 1.0, v70
	v_add_f32_e32 v84, 1.0, v84
	v_add_f32_e32 v85, 1.0, v85
	v_add_f32_e32 v86, 1.0, v86
	v_add_f32_e32 v87, 1.0, v87
	v_add_f32_e32 v68, 1.0, v68
	v_add_f32_e32 v69, 1.0, v69
	v_rcp_f32_e32 v81, v70
	v_add_f32_e32 v70, 1.0, v71
	v_rcp_f32_e32 v84, v84
	v_rcp_f32_e32 v85, v85
	v_rcp_f32_e32 v86, v86
	v_rcp_f32_e32 v80, v87
	v_rcp_f32_e32 v68, v68
	v_rcp_f32_e32 v69, v69
	v_rcp_f32_e32 v82, v70
	v_cvt_pk_bf16_f32 v71, v84, v85
	v_cvt_pk_bf16_f32 v70, v86, v80
	v_cvt_pk_bf16_f32 v69, v68, v69
	v_cvt_pk_bf16_f32 v68, v81, v82
	v_add_u32_e32 v80, 0x248c0, v160
	v_add_u32_e32 v84, 0x24cc0, v160
	ds_read_b128 v[80:83], v80
	ds_read_b128 v[84:87], v84
	ds_read_b32 v112, v164
	ds_read_b32 v113, v165
	ds_read_b32 v114, v166
	ds_read_b32 v115, v167
	s_waitcnt lgkmcnt(3)
	v_fma_f32 v88, -v80, v112, v88
	v_fma_f32 v89, -v81, v112, v89
	s_waitcnt lgkmcnt(1)
	v_fma_f32 v74, -v82, v114, v74
	v_fma_f32 v90, -v82, v112, v90
	v_fma_f32 v91, -v83, v112, v91
	v_fma_f32 v72, -v80, v114, v72
	v_fma_f32 v73, -v81, v114, v73
	s_waitcnt lgkmcnt(0)
	v_fma_f32 v74, v115, v74, v86
	v_fma_f32 v75, -v83, v114, v75
	v_fma_f32 v88, v113, v88, v84
	v_fma_f32 v89, v113, v89, v85
	v_fma_f32 v90, v113, v90, v86
	v_fma_f32 v91, v113, v91, v87
	v_fma_f32 v72, v115, v72, v84
	v_fma_f32 v73, v115, v73, v85
	v_mul_f32_e32 v74, 0xbfb8aa3b, v74
	v_fmac_f32_e32 v87, v115, v75
	v_mul_f32_e32 v88, 0xbfb8aa3b, v88
	v_mul_f32_e32 v89, 0xbfb8aa3b, v89
	v_mul_f32_e32 v90, 0xbfb8aa3b, v90
	v_mul_f32_e32 v91, 0xbfb8aa3b, v91
	v_mul_f32_e32 v72, 0xbfb8aa3b, v72
	v_mul_f32_e32 v73, 0xbfb8aa3b, v73
	v_exp_f32_e32 v74, v74
	v_mul_f32_e32 v75, 0xbfb8aa3b, v87
	v_exp_f32_e32 v88, v88
	v_exp_f32_e32 v89, v89
	v_exp_f32_e32 v90, v90
	v_exp_f32_e32 v91, v91
	v_exp_f32_e32 v72, v72
	v_exp_f32_e32 v73, v73
	v_exp_f32_e32 v75, v75
	v_add_f32_e32 v74, 1.0, v74
	v_add_f32_e32 v88, 1.0, v88
	v_add_f32_e32 v89, 1.0, v89
	v_add_f32_e32 v90, 1.0, v90
	v_add_f32_e32 v91, 1.0, v91
	v_add_f32_e32 v72, 1.0, v72
	v_add_f32_e32 v73, 1.0, v73
	v_rcp_f32_e32 v81, v74
	v_add_f32_e32 v74, 1.0, v75
	v_rcp_f32_e32 v88, v88
	v_rcp_f32_e32 v89, v89
	v_rcp_f32_e32 v90, v90
	v_rcp_f32_e32 v80, v91
	v_rcp_f32_e32 v72, v72
	v_rcp_f32_e32 v73, v73
	v_rcp_f32_e32 v82, v74
	v_cvt_pk_bf16_f32 v75, v88, v89
	v_cvt_pk_bf16_f32 v74, v90, v80
	v_cvt_pk_bf16_f32 v73, v72, v73
	v_cvt_pk_bf16_f32 v72, v81, v82
	v_add_u32_e32 v80, 0x248e0, v160
	v_add_u32_e32 v84, 0x24ce0, v160
	ds_read_b128 v[80:83], v80
	ds_read_b128 v[84:87], v84
	ds_read_b32 v88, v164
	ds_read_b32 v89, v165
	ds_read_b32 v90, v166
	ds_read_b32 v91, v167
	s_waitcnt lgkmcnt(3)
	v_fma_f32 v93, -v81, v88, v93
	v_fma_f32 v92, -v80, v88, v92
	s_waitcnt lgkmcnt(1)
	v_fma_f32 v78, -v82, v90, v78
	v_fma_f32 v93, v89, v93, v85
	v_fma_f32 v94, -v82, v88, v94
	v_fma_f32 v88, -v83, v88, v95
	v_fma_f32 v76, -v80, v90, v76
	v_fma_f32 v77, -v81, v90, v77
	s_waitcnt lgkmcnt(0)
	v_fma_f32 v78, v91, v78, v86
	v_fma_f32 v79, -v83, v90, v79
	v_fma_f32 v92, v89, v92, v84
	v_mul_f32_e32 v93, 0xbfb8aa3b, v93
	v_fma_f32 v94, v89, v94, v86
	v_fma_f32 v88, v89, v88, v87
	v_fma_f32 v76, v91, v76, v84
	v_fma_f32 v77, v91, v77, v85
	v_mul_f32_e32 v78, 0xbfb8aa3b, v78
	v_fmac_f32_e32 v87, v91, v79
	v_mul_f32_e32 v92, 0xbfb8aa3b, v92
	v_exp_f32_e32 v93, v93
	v_mul_f32_e32 v94, 0xbfb8aa3b, v94
	v_mul_f32_e32 v88, 0xbfb8aa3b, v88
	v_mul_f32_e32 v76, 0xbfb8aa3b, v76
	v_mul_f32_e32 v77, 0xbfb8aa3b, v77
	v_exp_f32_e32 v78, v78
	v_mul_f32_e32 v79, 0xbfb8aa3b, v87
	v_exp_f32_e32 v92, v92
	v_exp_f32_e32 v94, v94
	v_exp_f32_e32 v88, v88
	v_exp_f32_e32 v76, v76
	v_exp_f32_e32 v77, v77
	v_exp_f32_e32 v79, v79
	v_add_f32_e32 v93, 1.0, v93
	v_add_f32_e32 v78, 1.0, v78
	v_add_f32_e32 v92, 1.0, v92
	v_rcp_f32_e32 v89, v93
	v_add_f32_e32 v93, 1.0, v94
	v_add_f32_e32 v88, 1.0, v88
	v_add_f32_e32 v76, 1.0, v76
	v_add_f32_e32 v77, 1.0, v77
	v_rcp_f32_e32 v81, v78
	v_add_f32_e32 v78, 1.0, v79
	v_rcp_f32_e32 v92, v92
	v_rcp_f32_e32 v93, v93
	v_rcp_f32_e32 v80, v88
	v_rcp_f32_e32 v76, v76
	v_rcp_f32_e32 v77, v77
	v_rcp_f32_e32 v82, v78
	v_cvt_pk_bf16_f32 v79, v92, v89
	v_cvt_pk_bf16_f32 v78, v93, v80
	v_cvt_pk_bf16_f32 v77, v76, v77
	v_cvt_pk_bf16_f32 v76, v81, v82
	v_add_u32_e32 v80, 0x24900, v160
	v_add_u32_e32 v84, 0x24d00, v160
	ds_read_b128 v[80:83], v80
	ds_read_b128 v[84:87], v84
	ds_read_b32 v88, v164
	ds_read_b32 v89, v165
	ds_read_b32 v90, v166
	ds_read_b32 v91, v167
	s_waitcnt lgkmcnt(3)
	v_fma_f32 v48, -v80, v88, v48
	v_fma_f32 v49, -v81, v88, v49
	s_waitcnt lgkmcnt(1)
	v_fma_f32 v34, -v82, v90, v34
	v_fma_f32 v50, -v82, v88, v50
	v_fma_f32 v51, -v83, v88, v51
	v_fma_f32 v32, -v80, v90, v32
	v_fma_f32 v33, -v81, v90, v33
	s_waitcnt lgkmcnt(0)
; DI unsigned pack2(float a, float b) { f32x2_t v = {a, b}; bf16x2_t r = __builtin_convertvector(v, bf16x2_t); return __builtin_bit_cast(unsigned, r); }
; DI float sigmoidf_(float x) { return __builtin_amdgcn_rcpf(1.f + __expf(-x)); }
; template <bool LAST>
; DI void phase_gate(const Params& P, int layer, unsigned char* smem, int L, int G) {
;     ...
;     for (int i = 0; i < 4; ++i)
; #pragma unroll
;       for (int q4 = 0; q4 < 4; ++q4) {
;         const int fl = wm * 128 + i * 32 + 8 * q4 + 4 * h;
;         const f32x4 c1v = *(const f32x4*)(vecL + fl), c2v = *(const f32x4*)(vecL + 256 + fl);
;         const float c1a[4] = {c1v.x, c1v.y, c1v.z, c1v.w}, c2a[4] = {c2v.x, c2v.y, c2v.z, c2v.w};
; #pragma unroll
;         for (int j = 0; j < 2; ++j) {
;           const int lrow = wn * 64 + j * 32 + r;
;           const float mu = rowA[lrow], rstd = rowB[lrow];
;           float sg4[4];
; #pragma unroll
;           for (int e = 0; e < 4; ++e) sg4[e] = sigmoidf_(rstd * (accu[i][j][4 * q4 + e] - mu * c1a[e]) + c2a[e]);
;           gq[i][j][2 * q4] = pack2(sg4[0], sg4[1]); gq[i][j][2 * q4 + 1] = pack2(sg4[2], sg4[3]);
;         }
;         __builtin_amdgcn_sched_barrier(0);
	v_fma_f32 v34, v91, v34, v86
	v_fma_f32 v35, -v83, v90, v35
	v_fma_f32 v48, v89, v48, v84
	v_fma_f32 v49, v89, v49, v85
	v_fma_f32 v50, v89, v50, v86
	v_fma_f32 v51, v89, v51, v87
	v_fma_f32 v32, v91, v32, v84
	v_fma_f32 v33, v91, v33, v85
	v_mul_f32_e32 v34, 0xbfb8aa3b, v34
	v_fmac_f32_e32 v87, v91, v35
	v_mul_f32_e32 v48, 0xbfb8aa3b, v48
	v_mul_f32_e32 v49, 0xbfb8aa3b, v49
	v_mul_f32_e32 v50, 0xbfb8aa3b, v50
	v_mul_f32_e32 v51, 0xbfb8aa3b, v51
	v_mul_f32_e32 v32, 0xbfb8aa3b, v32
	v_mul_f32_e32 v33, 0xbfb8aa3b, v33
	v_exp_f32_e32 v34, v34
	v_mul_f32_e32 v35, 0xbfb8aa3b, v87
	v_exp_f32_e32 v48, v48
	v_exp_f32_e32 v49, v49
	v_exp_f32_e32 v50, v50
	v_exp_f32_e32 v51, v51
	v_exp_f32_e32 v32, v32
	v_exp_f32_e32 v33, v33
	v_exp_f32_e32 v35, v35
	v_add_f32_e32 v34, 1.0, v34
	v_add_f32_e32 v48, 1.0, v48
	v_add_f32_e32 v49, 1.0, v49
	v_add_f32_e32 v50, 1.0, v50
	v_add_f32_e32 v51, 1.0, v51
	v_add_f32_e32 v32, 1.0, v32
	v_add_f32_e32 v33, 1.0, v33
	v_rcp_f32_e32 v80, v34
	v_add_f32_e32 v34, 1.0, v35
	v_rcp_f32_e32 v48, v48
	v_rcp_f32_e32 v49, v49
	v_rcp_f32_e32 v50, v50
	v_rcp_f32_e32 v51, v51
	v_rcp_f32_e32 v32, v32
	v_rcp_f32_e32 v33, v33
	v_rcp_f32_e32 v81, v34
	v_cvt_pk_bf16_f32 v35, v48, v49
	v_cvt_pk_bf16_f32 v34, v50, v51
	v_cvt_pk_bf16_f32 v33, v32, v33
	v_cvt_pk_bf16_f32 v32, v80, v81
	v_add_u32_e32 v48, 0x24920, v160
	v_add_u32_e32 v80, 0x24d20, v160
	ds_read_b128 v[48:51], v48
	ds_read_b128 v[80:83], v80
	ds_read_b32 v84, v164
	ds_read_b32 v85, v165
	ds_read_b32 v86, v166
	ds_read_b32 v87, v167
	s_waitcnt lgkmcnt(3)
	v_fma_f32 v53, -v49, v84, v53
	v_fma_f32 v52, -v48, v84, v52
	s_waitcnt lgkmcnt(1)
	v_fma_f32 v36, -v48, v86, v36
	s_waitcnt lgkmcnt(0)
	v_fma_f32 v36, v87, v36, v80
	v_fma_f32 v37, -v49, v86, v37
	v_mul_f32_e32 v36, 0xbfb8aa3b, v36
	v_fma_f32 v37, v87, v37, v81
	v_exp_f32_e32 v36, v36
	v_mul_f32_e32 v37, 0xbfb8aa3b, v37
	v_exp_f32_e32 v37, v37
	v_fma_f32 v54, -v50, v84, v54
	v_add_f32_e32 v36, 1.0, v36
	v_rcp_f32_e32 v49, v36
	v_add_f32_e32 v36, 1.0, v37
	v_fma_f32 v37, -v50, v86, v38
	v_fma_f32 v55, -v51, v84, v55
	v_fma_f32 v37, v87, v37, v82
	v_fma_f32 v38, -v51, v86, v39
	v_fma_f32 v52, v85, v52, v80
	v_fma_f32 v53, v85, v53, v81
	v_fma_f32 v54, v85, v54, v82
	v_fma_f32 v55, v85, v55, v83
	v_mul_f32_e32 v37, 0xbfb8aa3b, v37
	v_fmac_f32_e32 v83, v87, v38
	v_mul_f32_e32 v52, 0xbfb8aa3b, v52
	v_mul_f32_e32 v53, 0xbfb8aa3b, v53
	v_mul_f32_e32 v54, 0xbfb8aa3b, v54
	v_mul_f32_e32 v55, 0xbfb8aa3b, v55
	v_exp_f32_e32 v37, v37
	v_mul_f32_e32 v38, 0xbfb8aa3b, v83
	v_exp_f32_e32 v52, v52
	v_exp_f32_e32 v53, v53
	v_exp_f32_e32 v54, v54
	v_exp_f32_e32 v55, v55
	v_exp_f32_e32 v38, v38
	v_rcp_f32_e32 v39, v36
	v_add_f32_e32 v36, 1.0, v37
	v_add_f32_e32 v52, 1.0, v52
	v_add_f32_e32 v53, 1.0, v53
	v_add_f32_e32 v54, 1.0, v54
	v_add_f32_e32 v55, 1.0, v55
	v_rcp_f32_e32 v37, v36
	v_add_f32_e32 v36, 1.0, v38
	v_rcp_f32_e32 v52, v52
	v_rcp_f32_e32 v53, v53
	v_rcp_f32_e32 v54, v54
	v_rcp_f32_e32 v48, v55
	v_rcp_f32_e32 v38, v36
	v_cvt_pk_bf16_f32 v80, v52, v53
	v_cvt_pk_bf16_f32 v55, v49, v39
	v_cvt_pk_bf16_f32 v36, v54, v48
	v_cvt_pk_bf16_f32 v53, v37, v38
	v_add_u32_e32 v37, 0x24940, v160
	v_add_u32_e32 v38, 0x24d40, v160
	ds_read_b128 v[48:51], v37
	ds_read_b128 v[82:85], v38
	ds_read_b32 v37, v164
	ds_read_b32 v38, v165
	ds_read_b32 v39, v166
	ds_read_b32 v52, v167
	s_waitcnt lgkmcnt(3)
	v_fma_f32 v54, -v48, v37, v56
	v_fma_f32 v56, -v49, v37, v57
	s_waitcnt lgkmcnt(2)
	v_fma_f32 v56, v38, v56, v83
	v_fma_f32 v57, -v50, v37, v58
	v_fma_f32 v37, -v51, v37, v59
	s_waitcnt lgkmcnt(1)
	v_fma_f32 v40, -v48, v39, v40
	v_fma_f32 v41, -v49, v39, v41
	v_fma_f32 v42, -v50, v39, v42
	v_fma_f32 v39, -v51, v39, v43
	v_fma_f32 v54, v38, v54, v82
	v_mul_f32_e32 v56, 0xbfb8aa3b, v56
	v_fma_f32 v57, v38, v57, v84
	v_fma_f32 v37, v38, v37, v85
	s_waitcnt lgkmcnt(0)
	v_fma_f32 v40, v52, v40, v82
	v_fma_f32 v41, v52, v41, v83
	v_fma_f32 v42, v52, v42, v84
	v_fmac_f32_e32 v85, v52, v39
	v_mul_f32_e32 v54, 0xbfb8aa3b, v54
	v_exp_f32_e32 v56, v56
	v_mul_f32_e32 v57, 0xbfb8aa3b, v57
	v_mul_f32_e32 v37, 0xbfb8aa3b, v37
	v_mul_f32_e32 v40, 0xbfb8aa3b, v40
	v_mul_f32_e32 v41, 0xbfb8aa3b, v41
	v_mul_f32_e32 v42, 0xbfb8aa3b, v42
	v_mul_f32_e32 v39, 0xbfb8aa3b, v85
	v_exp_f32_e32 v54, v54
	v_exp_f32_e32 v57, v57
	v_exp_f32_e32 v37, v37
	v_exp_f32_e32 v40, v40
	v_exp_f32_e32 v41, v41
	v_exp_f32_e32 v42, v42
	v_exp_f32_e32 v39, v39
	v_add_f32_e32 v56, 1.0, v56
	v_add_f32_e32 v54, 1.0, v54
	v_rcp_f32_e32 v38, v56
	v_add_f32_e32 v56, 1.0, v57
	v_add_f32_e32 v37, 1.0, v37
	v_add_f32_e32 v40, 1.0, v40
	v_add_f32_e32 v41, 1.0, v41
	v_add_f32_e32 v42, 1.0, v42
	v_add_f32_e32 v39, 1.0, v39
	v_rcp_f32_e32 v54, v54
	v_rcp_f32_e32 v56, v56
	v_rcp_f32_e32 v37, v37
	v_rcp_f32_e32 v40, v40
	v_rcp_f32_e32 v41, v41
	v_rcp_f32_e32 v42, v42
	v_rcp_f32_e32 v39, v39
	v_cvt_pk_bf16_f32 v83, v54, v38
	v_cvt_pk_bf16_f32 v82, v56, v37
	v_cvt_pk_bf16_f32 v81, v40, v41
	v_cvt_pk_bf16_f32 v59, v42, v39
	v_add_u32_e32 v37, 0x24960, v160
	v_add_u32_e32 v42, 0x24d60, v160
	ds_read_b128 v[38:41], v37
	ds_read_b128 v[48:51], v42
	ds_read_b32 v37, v164
	ds_read_b32 v42, v165
	ds_read_b32 v43, v166
	ds_read_b32 v52, v167
	s_waitcnt lgkmcnt(3)
	v_fma_f32 v56, -v39, v37, v61
	v_fma_f32 v54, -v38, v37, v60
	s_waitcnt lgkmcnt(2)
	v_fma_f32 v56, v42, v56, v49
	v_fma_f32 v57, -v40, v37, v62
	v_fma_f32 v37, -v41, v37, v63
	s_waitcnt lgkmcnt(1)
	v_fma_f32 v38, -v38, v43, v44
	v_fma_f32 v39, -v39, v43, v45
	v_fma_f32 v40, -v40, v43, v46
	v_fma_f32 v41, -v41, v43, v47
	v_fma_f32 v54, v42, v54, v48
	v_mul_f32_e32 v56, 0xbfb8aa3b, v56
	v_fma_f32 v57, v42, v57, v50
	v_fma_f32 v37, v42, v37, v51
	s_waitcnt lgkmcnt(0)
; DI unsigned pack2(float a, float b) { f32x2_t v = {a, b}; bf16x2_t r = __builtin_convertvector(v, bf16x2_t); return __builtin_bit_cast(unsigned, r); }
; DI float sigmoidf_(float x) { return __builtin_amdgcn_rcpf(1.f + __expf(-x)); }
; template <bool LAST>
; DI void phase_gate(const Params& P, int layer, unsigned char* smem, int L, int G) {
;     ...
;     for (int i = 0; i < 4; ++i)
; #pragma unroll
;       for (int q4 = 0; q4 < 4; ++q4) {
;         const int fl = wm * 128 + i * 32 + 8 * q4 + 4 * h;
;         const f32x4 c1v = *(const f32x4*)(vecL + fl), c2v = *(const f32x4*)(vecL + 256 + fl);
;         const float c1a[4] = {c1v.x, c1v.y, c1v.z, c1v.w}, c2a[4] = {c2v.x, c2v.y, c2v.z, c2v.w};
; #pragma unroll
;         for (int j = 0; j < 2; ++j) {
;           const int lrow = wn * 64 + j * 32 + r;
;           const float mu = rowA[lrow], rstd = rowB[lrow];
;           float sg4[4];
; #pragma unroll
;           for (int e = 0; e < 4; ++e) sg4[e] = sigmoidf_(rstd * (accu[i][j][4 * q4 + e] - mu * c1a[e]) + c2a[e]);
;           gq[i][j][2 * q4] = pack2(sg4[0], sg4[1]); gq[i][j][2 * q4 + 1] = pack2(sg4[2], sg4[3]);
;         }
;         __builtin_amdgcn_sched_barrier(0);
	v_fma_f32 v38, v52, v38, v48
	v_fma_f32 v39, v52, v39, v49
	v_fma_f32 v40, v52, v40, v50
	v_fmac_f32_e32 v51, v52, v41
	v_mul_f32_e32 v54, 0xbfb8aa3b, v54
	v_exp_f32_e32 v56, v56
	v_mul_f32_e32 v57, 0xbfb8aa3b, v57
	v_mul_f32_e32 v37, 0xbfb8aa3b, v37
	v_mul_f32_e32 v38, 0xbfb8aa3b, v38
	v_mul_f32_e32 v39, 0xbfb8aa3b, v39
	v_mul_f32_e32 v40, 0xbfb8aa3b, v40
	v_mul_f32_e32 v41, 0xbfb8aa3b, v51
	v_exp_f32_e32 v54, v54
	v_exp_f32_e32 v57, v57
	v_exp_f32_e32 v37, v37
	v_exp_f32_e32 v38, v38
	v_exp_f32_e32 v39, v39
	v_exp_f32_e32 v40, v40
	v_exp_f32_e32 v41, v41
	v_add_f32_e32 v56, 1.0, v56
	v_add_f32_e32 v54, 1.0, v54
	v_rcp_f32_e32 v42, v56
	v_add_f32_e32 v56, 1.0, v57
	v_add_f32_e32 v37, 1.0, v37
	v_add_f32_e32 v38, 1.0, v38
	v_add_f32_e32 v39, 1.0, v39
	v_add_f32_e32 v40, 1.0, v40
	v_add_f32_e32 v41, 1.0, v41
	v_rcp_f32_e32 v54, v54
	v_rcp_f32_e32 v56, v56
	v_rcp_f32_e32 v37, v37
	v_rcp_f32_e32 v38, v38
	v_rcp_f32_e32 v39, v39
	v_rcp_f32_e32 v40, v40
	v_rcp_f32_e32 v41, v41
	v_cvt_pk_bf16_f32 v91, v54, v42
	v_cvt_pk_bf16_f32 v86, v56, v37
	v_cvt_pk_bf16_f32 v85, v38, v39
	v_cvt_pk_bf16_f32 v84, v40, v41
	v_add_u32_e32 v37, 0x24980, v160
	v_add_u32_e32 v42, 0x24d80, v160
	ds_read_b128 v[38:41], v37
	ds_read_b128 v[42:45], v42
	ds_read_b32 v37, v164
	ds_read_b32 v46, v165
	ds_read_b32 v47, v166
	ds_read_b32 v48, v167
	s_waitcnt lgkmcnt(3)
	v_fma_f32 v16, -v38, v37, v16
	v_fma_f32 v17, -v39, v37, v17
	v_fma_f32 v18, -v40, v37, v18
	v_fma_f32 v19, -v41, v37, v19
	s_waitcnt lgkmcnt(1)
	v_fma_f32 v0, -v38, v47, v0
	v_fma_f32 v1, -v39, v47, v1
	v_fma_f32 v2, -v40, v47, v2
	v_fma_f32 v3, -v41, v47, v3
	v_fma_f32 v16, v46, v16, v42
	v_fma_f32 v17, v46, v17, v43
	v_fma_f32 v18, v46, v18, v44
	v_fma_f32 v19, v46, v19, v45
	s_waitcnt lgkmcnt(0)
	v_fma_f32 v0, v48, v0, v42
	v_fma_f32 v1, v48, v1, v43
	v_fma_f32 v2, v48, v2, v44
	v_fmac_f32_e32 v45, v48, v3
	v_mul_f32_e32 v16, 0xbfb8aa3b, v16
	v_mul_f32_e32 v17, 0xbfb8aa3b, v17
	v_mul_f32_e32 v18, 0xbfb8aa3b, v18
	v_mul_f32_e32 v19, 0xbfb8aa3b, v19
	v_mul_f32_e32 v0, 0xbfb8aa3b, v0
	v_mul_f32_e32 v1, 0xbfb8aa3b, v1
	v_mul_f32_e32 v2, 0xbfb8aa3b, v2
	v_mul_f32_e32 v3, 0xbfb8aa3b, v45
	v_exp_f32_e32 v16, v16
	v_exp_f32_e32 v17, v17
	v_exp_f32_e32 v18, v18
	v_exp_f32_e32 v19, v19
	v_exp_f32_e32 v0, v0
	v_exp_f32_e32 v1, v1
	v_exp_f32_e32 v2, v2
	v_exp_f32_e32 v3, v3
	v_add_f32_e32 v16, 1.0, v16
	v_add_f32_e32 v17, 1.0, v17
	v_add_f32_e32 v18, 1.0, v18
	v_add_f32_e32 v19, 1.0, v19
	v_add_f32_e32 v0, 1.0, v0
	v_add_f32_e32 v1, 1.0, v1
	v_add_f32_e32 v2, 1.0, v2
	v_add_f32_e32 v3, 1.0, v3
	v_rcp_f32_e32 v16, v16
	v_rcp_f32_e32 v17, v17
	v_rcp_f32_e32 v18, v18
	v_rcp_f32_e32 v19, v19
	v_rcp_f32_e32 v0, v0
	v_rcp_f32_e32 v1, v1
	v_rcp_f32_e32 v2, v2
	v_rcp_f32_e32 v37, v3
	v_cvt_pk_bf16_f32 v17, v16, v17
	v_cvt_pk_bf16_f32 v16, v18, v19
	v_cvt_pk_bf16_f32 v3, v0, v1
	v_cvt_pk_bf16_f32 v2, v2, v37
	v_add_u32_e32 v0, 0x249a0, v160
	v_add_u32_e32 v1, 0x24da0, v160
	ds_read_b128 v[38:41], v0
	ds_read_b128 v[42:45], v1
	ds_read_b32 v0, v164
	ds_read_b32 v1, v165
	ds_read_b32 v18, v166
	ds_read_b32 v19, v167
	s_waitcnt lgkmcnt(3)
	v_fma_f32 v21, -v39, v0, v21
	v_fma_f32 v20, -v38, v0, v20
	s_waitcnt lgkmcnt(1)
	v_fma_f32 v6, -v40, v18, v6
	v_fma_f32 v21, v1, v21, v43
	v_fma_f32 v22, -v40, v0, v22
	v_fma_f32 v0, -v41, v0, v23
	v_fma_f32 v4, -v38, v18, v4
	v_fma_f32 v5, -v39, v18, v5
	s_waitcnt lgkmcnt(0)
	v_fma_f32 v6, v19, v6, v44
	v_fma_f32 v7, -v41, v18, v7
	v_fma_f32 v20, v1, v20, v42
	v_mul_f32_e32 v21, 0xbfb8aa3b, v21
	v_fma_f32 v22, v1, v22, v44
	v_fma_f32 v0, v1, v0, v45
	v_fma_f32 v4, v19, v4, v42
	v_fma_f32 v5, v19, v5, v43
	v_mul_f32_e32 v6, 0xbfb8aa3b, v6
	v_fmac_f32_e32 v45, v19, v7
	v_mul_f32_e32 v20, 0xbfb8aa3b, v20
	v_exp_f32_e32 v21, v21
	v_mul_f32_e32 v22, 0xbfb8aa3b, v22
	v_mul_f32_e32 v0, 0xbfb8aa3b, v0
	v_mul_f32_e32 v4, 0xbfb8aa3b, v4
	v_mul_f32_e32 v5, 0xbfb8aa3b, v5
	v_exp_f32_e32 v6, v6
	v_mul_f32_e32 v7, 0xbfb8aa3b, v45
	v_exp_f32_e32 v20, v20
	v_exp_f32_e32 v22, v22
	v_exp_f32_e32 v0, v0
	v_exp_f32_e32 v4, v4
	v_exp_f32_e32 v5, v5
	v_exp_f32_e32 v7, v7
	v_add_f32_e32 v21, 1.0, v21
	v_add_f32_e32 v6, 1.0, v6
	v_add_f32_e32 v20, 1.0, v20
	v_rcp_f32_e32 v1, v21
	v_add_f32_e32 v21, 1.0, v22
	v_add_f32_e32 v0, 1.0, v0
	v_add_f32_e32 v4, 1.0, v4
	v_add_f32_e32 v5, 1.0, v5
	v_rcp_f32_e32 v18, v6
	v_add_f32_e32 v6, 1.0, v7
	v_rcp_f32_e32 v20, v20
	v_rcp_f32_e32 v21, v21
	v_rcp_f32_e32 v0, v0
	v_rcp_f32_e32 v4, v4
	v_rcp_f32_e32 v5, v5
	v_rcp_f32_e32 v19, v6
	v_cvt_pk_bf16_f32 v7, v20, v1
	v_cvt_pk_bf16_f32 v6, v21, v0
	v_cvt_pk_bf16_f32 v5, v4, v5
	v_cvt_pk_bf16_f32 v4, v18, v19
	v_add_u32_e32 v0, 0x249c0, v160
	v_add_u32_e32 v1, 0x24dc0, v160
	ds_read_b128 v[18:21], v0
	ds_read_b128 v[38:41], v1
	ds_read_b32 v0, v164
	ds_read_b32 v1, v165
	ds_read_b32 v22, v166
	ds_read_b32 v23, v167
	s_waitcnt lgkmcnt(3)
	v_fma_f32 v25, -v19, v0, v25
	v_fma_f32 v24, -v18, v0, v24
	s_waitcnt lgkmcnt(1)
	v_fma_f32 v9, -v19, v22, v9
	s_waitcnt lgkmcnt(0)
; DI unsigned pack2(float a, float b) { f32x2_t v = {a, b}; bf16x2_t r = __builtin_convertvector(v, bf16x2_t); return __builtin_bit_cast(unsigned, r); }
; DI float sigmoidf_(float x) { return __builtin_amdgcn_rcpf(1.f + __expf(-x)); }
; template <bool LAST>
; DI void phase_gate(const Params& P, int layer, unsigned char* smem, int L, int G) {
;     ...
;     for (int i = 0; i < 4; ++i)
; #pragma unroll
;       for (int q4 = 0; q4 < 4; ++q4) {
;         const int fl = wm * 128 + i * 32 + 8 * q4 + 4 * h;
;         const f32x4 c1v = *(const f32x4*)(vecL + fl), c2v = *(const f32x4*)(vecL + 256 + fl);
;         const float c1a[4] = {c1v.x, c1v.y, c1v.z, c1v.w}, c2a[4] = {c2v.x, c2v.y, c2v.z, c2v.w};
; #pragma unroll
;         for (int j = 0; j < 2; ++j) {
;           const int lrow = wn * 64 + j * 32 + r;
;           const float mu = rowA[lrow], rstd = rowB[lrow];
;           float sg4[4];
; #pragma unroll
;           for (int e = 0; e < 4; ++e) sg4[e] = sigmoidf_(rstd * (accu[i][j][4 * q4 + e] - mu * c1a[e]) + c2a[e]);
;           gq[i][j][2 * q4] = pack2(sg4[0], sg4[1]); gq[i][j][2 * q4 + 1] = pack2(sg4[2], sg4[3]);
;         }
;         __builtin_amdgcn_sched_barrier(0);
;       }
;     stage_load_tile<true>(stg, PPb + (size_t)mt * 256 * 1024 + nt * 256);
;     __syncthreads();
	v_fma_f32 v9, v23, v9, v39
	v_fma_f32 v10, -v20, v22, v10
	v_fma_f32 v25, v1, v25, v39
	v_fma_f32 v26, -v20, v0, v26
	v_fma_f32 v0, -v21, v0, v27
	v_fma_f32 v8, -v18, v22, v8
	v_mul_f32_e32 v9, 0xbfb8aa3b, v9
	v_fma_f32 v10, v23, v10, v40
	v_fma_f32 v11, -v21, v22, v11
	v_fma_f32 v24, v1, v24, v38
	v_mul_f32_e32 v25, 0xbfb8aa3b, v25
	v_fma_f32 v26, v1, v26, v40
	v_fma_f32 v0, v1, v0, v41
	v_fma_f32 v8, v23, v8, v38
	v_exp_f32_e32 v9, v9
	v_mul_f32_e32 v10, 0xbfb8aa3b, v10
	v_fmac_f32_e32 v41, v23, v11
	v_mul_f32_e32 v24, 0xbfb8aa3b, v24
	v_exp_f32_e32 v25, v25
	v_mul_f32_e32 v26, 0xbfb8aa3b, v26
	v_mul_f32_e32 v0, 0xbfb8aa3b, v0
	v_mul_f32_e32 v8, 0xbfb8aa3b, v8
	v_exp_f32_e32 v10, v10
	v_mul_f32_e32 v11, 0xbfb8aa3b, v41
	v_exp_f32_e32 v24, v24
	v_exp_f32_e32 v26, v26
	v_exp_f32_e32 v0, v0
	v_exp_f32_e32 v8, v8
	v_exp_f32_e32 v11, v11
	v_add_f32_e32 v9, 1.0, v9
	v_add_f32_e32 v25, 1.0, v25
	v_rcp_f32_e32 v18, v9
	v_add_f32_e32 v9, 1.0, v10
	v_add_f32_e32 v24, 1.0, v24
	v_rcp_f32_e32 v1, v25
	v_add_f32_e32 v25, 1.0, v26
	v_add_f32_e32 v0, 1.0, v0
	v_add_f32_e32 v8, 1.0, v8
	v_rcp_f32_e32 v10, v9
	v_add_f32_e32 v9, 1.0, v11
	v_rcp_f32_e32 v24, v24
	v_rcp_f32_e32 v25, v25
	v_rcp_f32_e32 v0, v0
	v_rcp_f32_e32 v8, v8
	v_rcp_f32_e32 v11, v9
	v_cvt_pk_bf16_f32 v27, v24, v1
	v_cvt_pk_bf16_f32 v9, v25, v0
	v_cvt_pk_bf16_f32 v19, v8, v18
	v_cvt_pk_bf16_f32 v8, v10, v11
	v_add_u32_e32 v0, 0x24de0, v160
	ds_read_b128 v[20:23], v163 offset:480
	ds_read_b32 v1, v164
	ds_read_b128 v[38:41], v0
	ds_read_b32 v0, v165
	ds_read_b32 v10, v166
	ds_read_b32 v18, v167
	s_waitcnt lgkmcnt(4)
	v_fma_f32 v24, -v21, v1, v29
	v_fma_f32 v11, -v20, v1, v28
	s_waitcnt lgkmcnt(2)
	v_fma_f32 v24, v0, v24, v39
	v_fma_f32 v25, -v22, v1, v30
	v_fma_f32 v1, -v23, v1, v31
	s_waitcnt lgkmcnt(1)
	v_fma_f32 v12, -v20, v10, v12
	v_fma_f32 v13, -v21, v10, v13
	v_fma_f32 v14, -v22, v10, v14
	v_fma_f32 v10, -v23, v10, v15
	v_fma_f32 v11, v0, v11, v38
	v_mul_f32_e32 v24, 0xbfb8aa3b, v24
	v_fma_f32 v25, v0, v25, v40
	v_fma_f32 v0, v0, v1, v41
	s_waitcnt lgkmcnt(0)
	v_fma_f32 v12, v18, v12, v38
	v_fma_f32 v13, v18, v13, v39
	v_fma_f32 v14, v18, v14, v40
	v_fmac_f32_e32 v41, v18, v10
	v_mul_f32_e32 v11, 0xbfb8aa3b, v11
	v_exp_f32_e32 v24, v24
	v_mul_f32_e32 v25, 0xbfb8aa3b, v25
	v_mul_f32_e32 v0, 0xbfb8aa3b, v0
	v_mul_f32_e32 v12, 0xbfb8aa3b, v12
	v_mul_f32_e32 v13, 0xbfb8aa3b, v13
	v_mul_f32_e32 v14, 0xbfb8aa3b, v14
	v_mul_f32_e32 v10, 0xbfb8aa3b, v41
	v_exp_f32_e32 v11, v11
	v_exp_f32_e32 v25, v25
	v_exp_f32_e32 v0, v0
	v_exp_f32_e32 v12, v12
	v_exp_f32_e32 v13, v13
	v_exp_f32_e32 v14, v14
	v_exp_f32_e32 v10, v10
	v_add_f32_e32 v24, 1.0, v24
	v_add_f32_e32 v11, 1.0, v11
	v_rcp_f32_e32 v1, v24
	v_add_f32_e32 v24, 1.0, v25
	v_add_f32_e32 v0, 1.0, v0
	v_add_f32_e32 v12, 1.0, v12
	v_add_f32_e32 v13, 1.0, v13
	v_add_f32_e32 v14, 1.0, v14
	v_add_f32_e32 v10, 1.0, v10
	v_rcp_f32_e32 v11, v11
	v_rcp_f32_e32 v24, v24
	v_rcp_f32_e32 v0, v0
	v_rcp_f32_e32 v12, v12
	v_rcp_f32_e32 v13, v13
	v_rcp_f32_e32 v14, v14
	v_rcp_f32_e32 v10, v10
	v_cvt_pk_bf16_f32 v112, v11, v1
	v_cvt_pk_bf16_f32 v30, v24, v0
	v_cvt_pk_bf16_f32 v29, v12, v13
	v_cvt_pk_bf16_f32 v28, v14, v10
	v_mov_b32_e32 v163, v161
	v_lshlrev_b64 v[0:1], 1, v[162:163]
	v_and_b32_e32 v26, 31, v192
	v_ashrrev_i32_e32 v18, 5, v192
	v_mul_lo_u32 v18, v18, s34
	v_lshl_add_u32 v18, v26, 4, v18
	v_add_u32_e32 v24, 0x2080, v18
	v_add_u32_e32 v25, 0x4100, v18
	v_add_u32_e32 v26, 0x6180, v18
	v_add_u32_e32 v31, 0x8200, v18
	v_add_u32_e32 v37, 0xa280, v18
	v_add_u32_e32 v50, 0xc300, v18
	v_add_u32_e32 v51, 0xe380, v18
	s_waitcnt vmcnt(15)
	ds_write2_b64 v18, v[180:181], v[182:183] offset1:1
	s_waitcnt vmcnt(14)
	ds_write2_b64 v24, v[184:185], v[186:187] offset1:1
	s_waitcnt vmcnt(13)
	ds_write2_b64 v25, v[194:195], v[196:197] offset1:1
	s_waitcnt vmcnt(12)
	ds_write2_b64 v26, v[198:199], v[200:201] offset1:1
	s_waitcnt vmcnt(11)
	ds_write2_b64 v31, v[202:203], v[204:205] offset1:1
	s_waitcnt vmcnt(10)
	ds_write2_b64 v37, v[206:207], v[208:209] offset1:1
	s_waitcnt vmcnt(9)
	ds_write2_b64 v50, v[210:211], v[212:213] offset1:1
	s_waitcnt vmcnt(8)
	ds_write2_b64 v51, v[214:215], v[216:217] offset1:1
	v_add_u32_e32 v14, 0x10400, v18
	v_add_u32_e32 v15, 0x12480, v18
	v_add_u32_e32 v24, 0x14500, v18
	v_add_u32_e32 v25, 0x16580, v18
	v_add_u32_e32 v26, 0x18600, v18
	v_add_u32_e32 v31, 0x1a680, v18
	v_add_u32_e32 v37, 0x1c700, v18
	v_add_u32_e32 v18, 0x1e780, v18
	s_waitcnt vmcnt(7)
	ds_write2_b64 v14, v[218:219], v[220:221] offset1:1
	s_waitcnt vmcnt(6)
	ds_write2_b64 v15, v[222:223], v[224:225] offset1:1
	s_waitcnt vmcnt(5)
	ds_write2_b64 v24, v[226:227], v[228:229] offset1:1
	s_waitcnt vmcnt(4)
	ds_write2_b64 v25, v[230:231], v[232:233] offset1:1
	s_waitcnt vmcnt(3)
	ds_write2_b64 v26, v[234:235], v[236:237] offset1:1
	s_waitcnt vmcnt(2)
	ds_write2_b64 v31, v[238:239], v[240:241] offset1:1
	s_waitcnt vmcnt(1)
	ds_write2_b64 v37, v[242:243], v[244:245] offset1:1
	s_waitcnt vmcnt(0)
	ds_write2_b64 v18, v[248:249], v[250:251] offset1:1
	v_mov_b32_e32 v10, v192
	s_waitcnt lgkmcnt(0)
	s_barrier
; DI unsigned pack2(float a, float b) { f32x2_t v = {a, b}; bf16x2_t r = __builtin_convertvector(v, bf16x2_t); return __builtin_bit_cast(unsigned, r); }
; DI float bflo(unsigned u) { return __uint_as_float(u << 16); }
; DI float bfhi(unsigned u) { return __uint_as_float(u & 0xffff0000u); }
; DI int otid() { int t = threadIdx.x; asm volatile("" : "+v"(t)); return t; }
; template <bool LAST>
; DI void phase_gate(const Params& P, int layer, unsigned char* smem, int L, int G) {
;     ...
;     {
;       const int tid1 = otid();
;       const int lane1 = tid1 & 63, w1 = tid1 >> 6, r1 = lane1 & 31, h1 = lane1 >> 5, wm1 = w1 >> 2, wn1 = w1 & 3;
; #pragma unroll
;       for (int i = 0; i < 4; ++i)
; #pragma unroll
;         for (int q4 = 0; q4 < 4; ++q4) {
; #pragma unroll
;           for (int j = 0; j < 2; ++j) {
;             const uint2 pv = *(const uint2*)(stg + (wn1 * 64 + j * 32 + r1) * STG + wm1 * 128 + i * 32 + 8 * q4 + 4 * h1);
;             const unsigned g0 = gq[i][j][2 * q4], g1 = gq[i][j][2 * q4 + 1];
;             gq[i][j][2 * q4] = pack2(bflo(g0) * bflo(pv.x), bfhi(g0) * bfhi(pv.x));
;             gq[i][j][2 * q4 + 1] = pack2(bflo(g1) * bflo(pv.y), bfhi(g1) * bfhi(pv.y));
;           }
;           __builtin_amdgcn_sched_barrier(0);
;         }
;     }
	v_and_b32_e32 v13, 0xffff0000, v99
	v_lshrrev_b32_e32 v12, 2, v10
	v_and_b32_e32 v12, 8, v12
	v_and_b32_e32 v11, 0xdf, v10
	v_and_or_b32 v10, v10, s31, v12
	v_mad_u32_u24 v113, v11, s34, v10
	ds_read_b64 v[10:11], v113
	ds_read_b64 v[14:15], v113 offset:16640
	v_lshlrev_b32_e32 v12, 16, v99
	s_waitcnt lgkmcnt(1)
	v_lshlrev_b32_e32 v20, 16, v10
	v_and_b32_e32 v21, 0xffff0000, v10
	v_pk_mul_f32 v[12:13], v[12:13], v[20:21]
	v_lshlrev_b32_e32 v10, 16, v11
	v_cvt_pk_bf16_f32 v31, v12, v13
	v_lshlrev_b32_e32 v12, 16, v98
	v_and_b32_e32 v13, 0xffff0000, v98
	v_and_b32_e32 v11, 0xffff0000, v11
	v_pk_mul_f32 v[10:11], v[12:13], v[10:11]
	s_waitcnt lgkmcnt(0)
	v_lshlrev_b32_e32 v12, 16, v14
	v_cvt_pk_bf16_f32 v98, v10, v11
	v_lshlrev_b32_e32 v10, 16, v97
	v_and_b32_e32 v11, 0xffff0000, v97
	v_and_b32_e32 v13, 0xffff0000, v14
	v_pk_mul_f32 v[10:11], v[10:11], v[12:13]
	v_lshlrev_b32_e32 v12, 16, v15
	v_cvt_pk_bf16_f32 v97, v10, v11
	v_lshlrev_b32_e32 v10, 16, v96
	v_and_b32_e32 v11, 0xffff0000, v96
	v_and_b32_e32 v13, 0xffff0000, v15
	v_pk_mul_f32 v[10:11], v[10:11], v[12:13]
	s_nop 0
	v_cvt_pk_bf16_f32 v96, v10, v11
	ds_read_b64 v[10:11], v113 offset:16
	ds_read_b64 v[14:15], v113 offset:16656
	v_lshlrev_b32_e32 v12, 16, v103
	v_and_b32_e32 v13, 0xffff0000, v103
	s_waitcnt lgkmcnt(1)
	v_lshlrev_b32_e32 v20, 16, v10
	v_and_b32_e32 v21, 0xffff0000, v10
	v_pk_mul_f32 v[12:13], v[12:13], v[20:21]
	v_lshlrev_b32_e32 v10, 16, v11
	v_cvt_pk_bf16_f32 v93, v12, v13
	v_lshlrev_b32_e32 v12, 16, v102
	v_and_b32_e32 v13, 0xffff0000, v102
	v_and_b32_e32 v11, 0xffff0000, v11
	v_pk_mul_f32 v[10:11], v[12:13], v[10:11]
	s_waitcnt lgkmcnt(0)
	v_lshlrev_b32_e32 v12, 16, v14
	v_cvt_pk_bf16_f32 v95, v10, v11
	v_lshlrev_b32_e32 v10, 16, v101
	v_and_b32_e32 v11, 0xffff0000, v101
	v_and_b32_e32 v13, 0xffff0000, v14
	v_pk_mul_f32 v[10:11], v[10:11], v[12:13]
	v_lshlrev_b32_e32 v12, 16, v15
	v_cvt_pk_bf16_f32 v92, v10, v11
	v_lshlrev_b32_e32 v10, 16, v100
	v_and_b32_e32 v11, 0xffff0000, v100
	v_and_b32_e32 v13, 0xffff0000, v15
	v_pk_mul_f32 v[10:11], v[10:11], v[12:13]
	s_nop 0
	v_cvt_pk_bf16_f32 v94, v10, v11
	ds_read_b64 v[10:11], v113 offset:32
	ds_read_b64 v[14:15], v113 offset:16672
	v_lshlrev_b32_e32 v12, 16, v107
	v_and_b32_e32 v13, 0xffff0000, v107
	s_waitcnt lgkmcnt(1)
	v_lshlrev_b32_e32 v20, 16, v10
	v_and_b32_e32 v21, 0xffff0000, v10
	v_pk_mul_f32 v[12:13], v[12:13], v[20:21]
	v_lshlrev_b32_e32 v10, 16, v11
	v_cvt_pk_bf16_f32 v88, v12, v13
	v_lshlrev_b32_e32 v12, 16, v106
	v_and_b32_e32 v13, 0xffff0000, v106
	v_and_b32_e32 v11, 0xffff0000, v11
	v_pk_mul_f32 v[10:11], v[12:13], v[10:11]
	s_waitcnt lgkmcnt(0)
	v_lshlrev_b32_e32 v12, 16, v14
	v_cvt_pk_bf16_f32 v90, v10, v11
	v_lshlrev_b32_e32 v10, 16, v105
	v_and_b32_e32 v11, 0xffff0000, v105
	v_and_b32_e32 v13, 0xffff0000, v14
	v_pk_mul_f32 v[10:11], v[10:11], v[12:13]
	v_lshlrev_b32_e32 v12, 16, v15
	v_cvt_pk_bf16_f32 v87, v10, v11
	v_lshlrev_b32_e32 v10, 16, v104
	v_and_b32_e32 v11, 0xffff0000, v104
	v_and_b32_e32 v13, 0xffff0000, v15
	v_pk_mul_f32 v[10:11], v[10:11], v[12:13]
	s_nop 0
	v_cvt_pk_bf16_f32 v89, v10, v11
	ds_read_b64 v[10:11], v113 offset:48
	ds_read_b64 v[14:15], v113 offset:16688
	v_lshlrev_b32_e32 v12, 16, v111
	v_and_b32_e32 v13, 0xffff0000, v111
	s_waitcnt lgkmcnt(1)
	v_lshlrev_b32_e32 v20, 16, v10
	v_and_b32_e32 v21, 0xffff0000, v10
	v_pk_mul_f32 v[12:13], v[12:13], v[20:21]
	v_lshlrev_b32_e32 v10, 16, v11
	v_cvt_pk_bf16_f32 v61, v12, v13
	v_lshlrev_b32_e32 v12, 16, v110
	v_and_b32_e32 v13, 0xffff0000, v110
	v_and_b32_e32 v11, 0xffff0000, v11
	v_pk_mul_f32 v[10:11], v[12:13], v[10:11]
	s_waitcnt lgkmcnt(0)
	v_lshlrev_b32_e32 v12, 16, v14
	v_cvt_pk_bf16_f32 v63, v10, v11
	v_lshlrev_b32_e32 v10, 16, v109
	v_and_b32_e32 v11, 0xffff0000, v109
	v_and_b32_e32 v13, 0xffff0000, v14
	v_pk_mul_f32 v[10:11], v[10:11], v[12:13]
	v_lshlrev_b32_e32 v12, 16, v15
	v_cvt_pk_bf16_f32 v60, v10, v11
	v_lshlrev_b32_e32 v10, 16, v108
	v_and_b32_e32 v11, 0xffff0000, v108
	v_and_b32_e32 v13, 0xffff0000, v15
	v_pk_mul_f32 v[10:11], v[10:11], v[12:13]
	s_nop 0
	v_cvt_pk_bf16_f32 v62, v10, v11
	ds_read_b64 v[10:11], v113 offset:64
	ds_read_b64 v[14:15], v113 offset:16704
	v_lshlrev_b32_e32 v12, 16, v67
	v_and_b32_e32 v13, 0xffff0000, v67
	s_waitcnt lgkmcnt(1)
	v_lshlrev_b32_e32 v20, 16, v10
	v_and_b32_e32 v21, 0xffff0000, v10
	v_pk_mul_f32 v[12:13], v[12:13], v[20:21]
	v_lshlrev_b32_e32 v10, 16, v11
	v_cvt_pk_bf16_f32 v56, v12, v13
	v_lshlrev_b32_e32 v12, 16, v66
	v_and_b32_e32 v13, 0xffff0000, v66
	v_and_b32_e32 v11, 0xffff0000, v11
	v_pk_mul_f32 v[10:11], v[12:13], v[10:11]
	s_waitcnt lgkmcnt(0)
	v_lshlrev_b32_e32 v12, 16, v14
	v_cvt_pk_bf16_f32 v58, v10, v11
	v_lshlrev_b32_e32 v10, 16, v65
	v_and_b32_e32 v11, 0xffff0000, v65
	v_and_b32_e32 v13, 0xffff0000, v14
	v_pk_mul_f32 v[10:11], v[10:11], v[12:13]
	v_lshlrev_b32_e32 v12, 16, v15
	v_cvt_pk_bf16_f32 v54, v10, v11
	v_lshlrev_b32_e32 v10, 16, v64
	v_and_b32_e32 v11, 0xffff0000, v64
	v_and_b32_e32 v13, 0xffff0000, v15
	v_pk_mul_f32 v[10:11], v[10:11], v[12:13]
	s_nop 0
	v_cvt_pk_bf16_f32 v57, v10, v11
	ds_read_b64 v[10:11], v113 offset:80
	ds_read_b64 v[14:15], v113 offset:16720
	v_lshlrev_b32_e32 v12, 16, v71
	v_and_b32_e32 v13, 0xffff0000, v71
	s_waitcnt lgkmcnt(1)
	v_lshlrev_b32_e32 v20, 16, v10
	v_and_b32_e32 v21, 0xffff0000, v10
	v_pk_mul_f32 v[12:13], v[12:13], v[20:21]
	v_lshlrev_b32_e32 v10, 16, v11
	v_cvt_pk_bf16_f32 v50, v12, v13
	v_lshlrev_b32_e32 v12, 16, v70
	v_and_b32_e32 v13, 0xffff0000, v70
	v_and_b32_e32 v11, 0xffff0000, v11
	v_pk_mul_f32 v[10:11], v[12:13], v[10:11]
	s_waitcnt lgkmcnt(0)
; DI unsigned pack2(float a, float b) { f32x2_t v = {a, b}; bf16x2_t r = __builtin_convertvector(v, bf16x2_t); return __builtin_bit_cast(unsigned, r); }
; DI float bflo(unsigned u) { return __uint_as_float(u << 16); }
; DI float bfhi(unsigned u) { return __uint_as_float(u & 0xffff0000u); }
; template <bool LAST>
; DI void phase_gate(const Params& P, int layer, unsigned char* smem, int L, int G) {
;     ...
; #pragma unroll
;       for (int i = 0; i < 4; ++i)
; #pragma unroll
;         for (int q4 = 0; q4 < 4; ++q4) {
; #pragma unroll
;           for (int j = 0; j < 2; ++j) {
;             const uint2 pv = *(const uint2*)(stg + (wn1 * 64 + j * 32 + r1) * STG + wm1 * 128 + i * 32 + 8 * q4 + 4 * h1);
;             const unsigned g0 = gq[i][j][2 * q4], g1 = gq[i][j][2 * q4 + 1];
;             gq[i][j][2 * q4] = pack2(bflo(g0) * bflo(pv.x), bfhi(g0) * bfhi(pv.x));
;             gq[i][j][2 * q4 + 1] = pack2(bflo(g1) * bflo(pv.y), bfhi(g1) * bfhi(pv.y));
;           }
;           __builtin_amdgcn_sched_barrier(0);
;         }
;     }
	v_lshlrev_b32_e32 v12, 16, v14
	v_cvt_pk_bf16_f32 v52, v10, v11
	v_lshlrev_b32_e32 v10, 16, v69
	v_and_b32_e32 v11, 0xffff0000, v69
	v_and_b32_e32 v13, 0xffff0000, v14
	v_pk_mul_f32 v[10:11], v[10:11], v[12:13]
	v_lshlrev_b32_e32 v12, 16, v15
	v_cvt_pk_bf16_f32 v49, v10, v11
	v_lshlrev_b32_e32 v10, 16, v68
	v_and_b32_e32 v11, 0xffff0000, v68
	v_and_b32_e32 v13, 0xffff0000, v15
	v_pk_mul_f32 v[10:11], v[10:11], v[12:13]
	s_nop 0
	v_cvt_pk_bf16_f32 v51, v10, v11
	ds_read_b64 v[10:11], v113 offset:96
	ds_read_b64 v[14:15], v113 offset:16736
	v_lshlrev_b32_e32 v12, 16, v75
	v_and_b32_e32 v13, 0xffff0000, v75
	s_waitcnt lgkmcnt(1)
	v_lshlrev_b32_e32 v20, 16, v10
	v_and_b32_e32 v21, 0xffff0000, v10
	v_pk_mul_f32 v[12:13], v[12:13], v[20:21]
	v_lshlrev_b32_e32 v10, 16, v11
	v_cvt_pk_bf16_f32 v46, v12, v13
	v_lshlrev_b32_e32 v12, 16, v74
	v_and_b32_e32 v13, 0xffff0000, v74
	v_and_b32_e32 v11, 0xffff0000, v11
	v_pk_mul_f32 v[10:11], v[12:13], v[10:11]
	s_waitcnt lgkmcnt(0)
	v_lshlrev_b32_e32 v12, 16, v14
	v_cvt_pk_bf16_f32 v48, v10, v11
	v_lshlrev_b32_e32 v10, 16, v73
	v_and_b32_e32 v11, 0xffff0000, v73
	v_and_b32_e32 v13, 0xffff0000, v14
	v_pk_mul_f32 v[10:11], v[10:11], v[12:13]
	v_lshlrev_b32_e32 v12, 16, v15
	v_cvt_pk_bf16_f32 v45, v10, v11
	v_lshlrev_b32_e32 v10, 16, v72
	v_and_b32_e32 v11, 0xffff0000, v72
	v_and_b32_e32 v13, 0xffff0000, v15
	v_pk_mul_f32 v[10:11], v[10:11], v[12:13]
	s_nop 0
	v_cvt_pk_bf16_f32 v47, v10, v11
	ds_read_b64 v[10:11], v113 offset:112
	ds_read_b64 v[14:15], v113 offset:16752
	v_lshlrev_b32_e32 v12, 16, v79
	v_and_b32_e32 v13, 0xffff0000, v79
	s_waitcnt lgkmcnt(1)
	v_lshlrev_b32_e32 v20, 16, v10
	v_and_b32_e32 v21, 0xffff0000, v10
	v_pk_mul_f32 v[12:13], v[12:13], v[20:21]
	v_lshlrev_b32_e32 v10, 16, v11
	v_cvt_pk_bf16_f32 v42, v12, v13
	v_lshlrev_b32_e32 v12, 16, v78
	v_and_b32_e32 v13, 0xffff0000, v78
	v_and_b32_e32 v11, 0xffff0000, v11
	v_pk_mul_f32 v[10:11], v[12:13], v[10:11]
	s_waitcnt lgkmcnt(0)
	v_lshlrev_b32_e32 v12, 16, v14
	v_cvt_pk_bf16_f32 v44, v10, v11
	v_lshlrev_b32_e32 v10, 16, v77
	v_and_b32_e32 v11, 0xffff0000, v77
	v_and_b32_e32 v13, 0xffff0000, v14
	v_pk_mul_f32 v[10:11], v[10:11], v[12:13]
	v_lshlrev_b32_e32 v12, 16, v15
	v_cvt_pk_bf16_f32 v41, v10, v11
	v_lshlrev_b32_e32 v10, 16, v76
	v_and_b32_e32 v11, 0xffff0000, v76
	v_and_b32_e32 v13, 0xffff0000, v15
	v_pk_mul_f32 v[10:11], v[10:11], v[12:13]
	s_nop 0
	v_cvt_pk_bf16_f32 v43, v10, v11
	ds_read_b64 v[10:11], v113 offset:128
	ds_read_b64 v[14:15], v113 offset:16768
	v_lshlrev_b32_e32 v12, 16, v35
	v_and_b32_e32 v13, 0xffff0000, v35
	s_waitcnt lgkmcnt(1)
	v_lshlrev_b32_e32 v20, 16, v10
	v_and_b32_e32 v21, 0xffff0000, v10
	v_pk_mul_f32 v[12:13], v[12:13], v[20:21]
	v_lshlrev_b32_e32 v10, 16, v11
	v_cvt_pk_bf16_f32 v38, v12, v13
	v_lshlrev_b32_e32 v12, 16, v34
	v_and_b32_e32 v13, 0xffff0000, v34
	v_and_b32_e32 v11, 0xffff0000, v11
	v_pk_mul_f32 v[10:11], v[12:13], v[10:11]
	s_waitcnt lgkmcnt(0)
	v_lshlrev_b32_e32 v12, 16, v14
	v_cvt_pk_bf16_f32 v40, v10, v11
	v_lshlrev_b32_e32 v10, 16, v33
	v_and_b32_e32 v11, 0xffff0000, v33
	v_and_b32_e32 v13, 0xffff0000, v14
	v_pk_mul_f32 v[10:11], v[10:11], v[12:13]
	v_lshlrev_b32_e32 v12, 16, v15
	v_cvt_pk_bf16_f32 v37, v10, v11
	v_lshlrev_b32_e32 v10, 16, v32
	v_and_b32_e32 v11, 0xffff0000, v32
	v_and_b32_e32 v13, 0xffff0000, v15
	v_pk_mul_f32 v[10:11], v[10:11], v[12:13]
	s_nop 0
	v_cvt_pk_bf16_f32 v39, v10, v11
	ds_read_b64 v[10:11], v113 offset:144
	ds_read_b64 v[14:15], v113 offset:16784
	v_lshlrev_b32_e32 v12, 16, v80
	v_and_b32_e32 v13, 0xffff0000, v80
	s_waitcnt lgkmcnt(1)
	v_lshlrev_b32_e32 v20, 16, v10
	v_and_b32_e32 v21, 0xffff0000, v10
	v_pk_mul_f32 v[12:13], v[12:13], v[20:21]
	v_lshlrev_b32_e32 v10, 16, v11
	v_cvt_pk_bf16_f32 v34, v12, v13
	v_lshlrev_b32_e32 v12, 16, v36
	v_and_b32_e32 v13, 0xffff0000, v36
	v_and_b32_e32 v11, 0xffff0000, v11
	v_pk_mul_f32 v[10:11], v[12:13], v[10:11]
	s_waitcnt lgkmcnt(0)
	v_lshlrev_b32_e32 v12, 16, v14
	v_cvt_pk_bf16_f32 v36, v10, v11
	v_lshlrev_b32_e32 v10, 16, v55
	v_and_b32_e32 v11, 0xffff0000, v55
	v_and_b32_e32 v13, 0xffff0000, v14
	v_pk_mul_f32 v[10:11], v[10:11], v[12:13]
	v_lshlrev_b32_e32 v12, 16, v15
	v_cvt_pk_bf16_f32 v32, v10, v11
	v_lshlrev_b32_e32 v10, 16, v53
	v_and_b32_e32 v11, 0xffff0000, v53
	v_and_b32_e32 v13, 0xffff0000, v15
	v_pk_mul_f32 v[10:11], v[10:11], v[12:13]
	s_nop 0
	v_cvt_pk_bf16_f32 v35, v10, v11
	ds_read_b64 v[10:11], v113 offset:160
	ds_read_b64 v[14:15], v113 offset:16800
	v_lshlrev_b32_e32 v12, 16, v83
	v_and_b32_e32 v13, 0xffff0000, v83
	s_waitcnt lgkmcnt(1)
	v_lshlrev_b32_e32 v20, 16, v10
	v_and_b32_e32 v21, 0xffff0000, v10
	v_pk_mul_f32 v[12:13], v[12:13], v[20:21]
	v_lshlrev_b32_e32 v10, 16, v11
	v_cvt_pk_bf16_f32 v24, v12, v13
	v_lshlrev_b32_e32 v12, 16, v82
	v_and_b32_e32 v13, 0xffff0000, v82
	v_and_b32_e32 v11, 0xffff0000, v11
	v_pk_mul_f32 v[10:11], v[12:13], v[10:11]
	s_waitcnt lgkmcnt(0)
	v_lshlrev_b32_e32 v12, 16, v14
	v_cvt_pk_bf16_f32 v26, v10, v11
	v_lshlrev_b32_e32 v10, 16, v81
	v_and_b32_e32 v11, 0xffff0000, v81
	v_and_b32_e32 v13, 0xffff0000, v14
	v_pk_mul_f32 v[10:11], v[10:11], v[12:13]
	v_lshlrev_b32_e32 v12, 16, v15
	v_cvt_pk_bf16_f32 v23, v10, v11
	v_lshlrev_b32_e32 v10, 16, v59
	v_and_b32_e32 v11, 0xffff0000, v59
	v_and_b32_e32 v13, 0xffff0000, v15
	v_pk_mul_f32 v[10:11], v[10:11], v[12:13]
	s_nop 0
	v_cvt_pk_bf16_f32 v25, v10, v11
	ds_read_b64 v[10:11], v113 offset:176
	ds_read_b64 v[14:15], v113 offset:16816
	v_lshlrev_b32_e32 v12, 16, v91
	v_and_b32_e32 v13, 0xffff0000, v91
	s_waitcnt lgkmcnt(1)
; DI unsigned pack2(float a, float b) { f32x2_t v = {a, b}; bf16x2_t r = __builtin_convertvector(v, bf16x2_t); return __builtin_bit_cast(unsigned, r); }
; DI float bflo(unsigned u) { return __uint_as_float(u << 16); }
; DI float bfhi(unsigned u) { return __uint_as_float(u & 0xffff0000u); }
; template <bool LAST>
; DI void phase_gate(const Params& P, int layer, unsigned char* smem, int L, int G) {
;     ...
; #pragma unroll
;       for (int i = 0; i < 4; ++i)
; #pragma unroll
;         for (int q4 = 0; q4 < 4; ++q4) {
; #pragma unroll
;           for (int j = 0; j < 2; ++j) {
;             const uint2 pv = *(const uint2*)(stg + (wn1 * 64 + j * 32 + r1) * STG + wm1 * 128 + i * 32 + 8 * q4 + 4 * h1);
;             const unsigned g0 = gq[i][j][2 * q4], g1 = gq[i][j][2 * q4 + 1];
;             gq[i][j][2 * q4] = pack2(bflo(g0) * bflo(pv.x), bfhi(g0) * bfhi(pv.x));
;             gq[i][j][2 * q4 + 1] = pack2(bflo(g1) * bflo(pv.y), bfhi(g1) * bfhi(pv.y));
;           }
;           __builtin_amdgcn_sched_barrier(0);
;         }
;     }
;     __syncthreads();
	v_lshlrev_b32_e32 v20, 16, v10
	v_and_b32_e32 v21, 0xffff0000, v10
	v_pk_mul_f32 v[12:13], v[12:13], v[20:21]
	v_lshlrev_b32_e32 v10, 16, v11
	v_cvt_pk_bf16_f32 v20, v12, v13
	v_lshlrev_b32_e32 v12, 16, v86
	v_and_b32_e32 v13, 0xffff0000, v86
	v_and_b32_e32 v11, 0xffff0000, v11
	v_pk_mul_f32 v[10:11], v[12:13], v[10:11]
	s_waitcnt lgkmcnt(0)
	v_lshlrev_b32_e32 v12, 16, v14
	v_cvt_pk_bf16_f32 v22, v10, v11
	v_lshlrev_b32_e32 v10, 16, v85
	v_and_b32_e32 v11, 0xffff0000, v85
	v_and_b32_e32 v13, 0xffff0000, v14
	v_pk_mul_f32 v[10:11], v[10:11], v[12:13]
	v_lshlrev_b32_e32 v12, 16, v15
	v_cvt_pk_bf16_f32 v18, v10, v11
	v_lshlrev_b32_e32 v10, 16, v84
	v_and_b32_e32 v11, 0xffff0000, v84
	v_and_b32_e32 v13, 0xffff0000, v15
	v_pk_mul_f32 v[10:11], v[10:11], v[12:13]
	s_nop 0
	v_cvt_pk_bf16_f32 v21, v10, v11
	ds_read_b64 v[10:11], v113 offset:192
	ds_read_b64 v[64:65], v113 offset:16832
	v_lshlrev_b32_e32 v12, 16, v17
	v_and_b32_e32 v13, 0xffff0000, v17
	s_waitcnt lgkmcnt(1)
	v_lshlrev_b32_e32 v14, 16, v10
	v_and_b32_e32 v15, 0xffff0000, v10
	v_pk_mul_f32 v[12:13], v[12:13], v[14:15]
	v_lshlrev_b32_e32 v10, 16, v11
	v_cvt_pk_bf16_f32 v15, v12, v13
	v_lshlrev_b32_e32 v12, 16, v16
	v_and_b32_e32 v13, 0xffff0000, v16
	v_and_b32_e32 v11, 0xffff0000, v11
	v_pk_mul_f32 v[10:11], v[12:13], v[10:11]
	s_waitcnt lgkmcnt(0)
	v_lshlrev_b32_e32 v12, 16, v64
	v_cvt_pk_bf16_f32 v17, v10, v11
	v_lshlrev_b32_e32 v10, 16, v3
	v_and_b32_e32 v11, 0xffff0000, v3
	v_and_b32_e32 v13, 0xffff0000, v64
	v_pk_mul_f32 v[10:11], v[10:11], v[12:13]
	v_lshlrev_b32_e32 v12, 16, v65
	v_cvt_pk_bf16_f32 v14, v10, v11
	v_lshlrev_b32_e32 v10, 16, v2
	v_and_b32_e32 v11, 0xffff0000, v2
	v_and_b32_e32 v13, 0xffff0000, v65
	v_pk_mul_f32 v[2:3], v[10:11], v[12:13]
	s_nop 0
	v_cvt_pk_bf16_f32 v16, v2, v3
	ds_read_b64 v[2:3], v113 offset:208
	ds_read_b64 v[64:65], v113 offset:16848
	v_lshlrev_b32_e32 v10, 16, v7
	v_and_b32_e32 v11, 0xffff0000, v7
	s_waitcnt lgkmcnt(1)
	v_lshlrev_b32_e32 v12, 16, v2
	v_and_b32_e32 v13, 0xffff0000, v2
	v_pk_mul_f32 v[10:11], v[10:11], v[12:13]
	v_lshlrev_b32_e32 v12, 16, v6
	v_lshlrev_b32_e32 v2, 16, v3
	v_and_b32_e32 v13, 0xffff0000, v6
	v_and_b32_e32 v3, 0xffff0000, v3
	v_pk_mul_f32 v[2:3], v[12:13], v[2:3]
	s_waitcnt lgkmcnt(0)
	v_lshlrev_b32_e32 v6, 16, v64
	v_cvt_pk_bf16_f32 v13, v2, v3
	v_lshlrev_b32_e32 v2, 16, v5
	v_and_b32_e32 v3, 0xffff0000, v5
	v_and_b32_e32 v7, 0xffff0000, v64
	v_pk_mul_f32 v[2:3], v[2:3], v[6:7]
	v_cvt_pk_bf16_f32 v11, v10, v11
	v_cvt_pk_bf16_f32 v10, v2, v3
	v_lshlrev_b32_e32 v2, 16, v4
	v_lshlrev_b32_e32 v6, 16, v65
	v_and_b32_e32 v3, 0xffff0000, v4
	v_and_b32_e32 v7, 0xffff0000, v65
	v_pk_mul_f32 v[2:3], v[2:3], v[6:7]
	s_nop 0
	v_cvt_pk_bf16_f32 v12, v2, v3
	ds_read_b64 v[2:3], v113 offset:224
	ds_read_b64 v[64:65], v113 offset:16864
	v_lshlrev_b32_e32 v4, 16, v27
	v_and_b32_e32 v5, 0xffff0000, v27
	s_waitcnt lgkmcnt(1)
	v_lshlrev_b32_e32 v6, 16, v2
	v_and_b32_e32 v7, 0xffff0000, v2
	v_pk_mul_f32 v[4:5], v[4:5], v[6:7]
	v_lshlrev_b32_e32 v2, 16, v3
	v_cvt_pk_bf16_f32 v7, v4, v5
	v_lshlrev_b32_e32 v4, 16, v9
	v_and_b32_e32 v5, 0xffff0000, v9
	v_and_b32_e32 v3, 0xffff0000, v3
	v_pk_mul_f32 v[2:3], v[4:5], v[2:3]
	s_waitcnt lgkmcnt(0)
	v_lshlrev_b32_e32 v4, 16, v64
	v_cvt_pk_bf16_f32 v9, v2, v3
	v_lshlrev_b32_e32 v2, 16, v19
	v_and_b32_e32 v3, 0xffff0000, v19
	v_and_b32_e32 v5, 0xffff0000, v64
	v_pk_mul_f32 v[2:3], v[2:3], v[4:5]
	v_lshlrev_b32_e32 v4, 16, v65
	v_cvt_pk_bf16_f32 v6, v2, v3
	v_lshlrev_b32_e32 v2, 16, v8
	v_and_b32_e32 v3, 0xffff0000, v8
	v_and_b32_e32 v5, 0xffff0000, v65
	v_pk_mul_f32 v[2:3], v[2:3], v[4:5]
	s_nop 0
	v_cvt_pk_bf16_f32 v8, v2, v3
	ds_read_b64 v[2:3], v113 offset:240
	ds_read_b64 v[64:65], v113 offset:16880
	v_lshlrev_b32_e32 v4, 16, v112
	v_and_b32_e32 v5, 0xffff0000, v112
	s_waitcnt lgkmcnt(1)
	v_lshlrev_b32_e32 v66, 16, v2
	v_and_b32_e32 v67, 0xffff0000, v2
	v_pk_mul_f32 v[4:5], v[4:5], v[66:67]
	v_lshlrev_b32_e32 v66, 16, v30
	v_lshlrev_b32_e32 v2, 16, v3
	v_and_b32_e32 v67, 0xffff0000, v30
	v_and_b32_e32 v3, 0xffff0000, v3
	v_pk_mul_f32 v[2:3], v[66:67], v[2:3]
	v_cvt_pk_bf16_f32 v4, v4, v5
	v_cvt_pk_bf16_f32 v5, v2, v3
	v_lshlrev_b32_e32 v2, 16, v29
	s_waitcnt lgkmcnt(0)
	v_lshlrev_b32_e32 v66, 16, v64
	v_and_b32_e32 v3, 0xffff0000, v29
	v_and_b32_e32 v67, 0xffff0000, v64
	v_pk_mul_f32 v[2:3], v[2:3], v[66:67]
	v_lshlrev_b32_e32 v66, 16, v28
	v_lshlrev_b32_e32 v64, 16, v65
	v_and_b32_e32 v67, 0xffff0000, v28
	v_and_b32_e32 v65, 0xffff0000, v65
	v_pk_mul_f32 v[28:29], v[66:67], v[64:65]
	v_cvt_pk_bf16_f32 v2, v2, v3
	v_cvt_pk_bf16_f32 v3, v28, v29
	v_mov_b32_e32 v19, v192
	s_barrier
; DI int otid() { int t = threadIdx.x; asm volatile("" : "+v"(t)); return t; }
; template <bool NT>
; DI void stage_load_tile(bf16_t* stg, const bf16_t* tilebase) {
;   const int tid = otid();
;   const int r0 = tid >> 5, c = tid & 31;
;   const unsigned o0 = (unsigned)(r0 * 1024 + c * 8);
;   __builtin_amdgcn_sched_barrier(0);
; #pragma unroll
;   for (int hf = 0; hf < 2; ++hf) {
; #pragma unroll
;     for (int it = 8 * hf; it < 8 * hf + 8; ++it) {
;       const u32x4* gp = (const u32x4*)(tilebase + (o0 + (unsigned)(it * 16 * 1024)));
;       stage_write16(stg, r0 + 16 * it, c, NT ? __builtin_nontemporal_load(gp) : *gp);
;     }
;     __builtin_amdgcn_sched_barrier(0);
;   }
; }
; template <bool LAST>
; DI void phase_gate(const Params& P, int layer, unsigned char* smem, int L, int G) {
;     ...
;     stage_load_tile<false>(stg, Sb + (size_t)mt * 256 * 1024 + nt * 256);
;     __syncthreads();
	s_add_u32 s20, s76, s18
	v_ashrrev_i32_e32 v27, 5, v19
	v_and_b32_e32 v19, 31, v19
	s_addc_u32 s21, s77, s19
	v_lshlrev_b32_e32 v30, 3, v19
	v_lshl_add_u64 v[28:29], s[20:21], 0, v[0:1]
	v_lshl_or_b32 v160, v27, 10, v30
	v_add_u32_e32 v66, 0x4000, v160
	v_mov_b32_e32 v67, v161
	v_add_u32_e32 v72, 0x8000, v160
	v_mov_b32_e32 v73, v161
	v_add_u32_e32 v74, 0xc000, v160
	v_mov_b32_e32 v75, v161
	v_add_u32_e32 v80, 0x10000, v160
	v_mov_b32_e32 v81, v161
	v_add_u32_e32 v82, 0x14000, v160
	v_mov_b32_e32 v83, v161
	v_lshl_add_u64 v[64:65], v[160:161], 1, v[28:29]
	v_lshl_add_u64 v[68:69], v[66:67], 1, v[28:29]
	v_lshl_add_u64 v[72:73], v[72:73], 1, v[28:29]
	v_lshl_add_u64 v[76:77], v[74:75], 1, v[28:29]
	v_lshl_add_u64 v[80:81], v[80:81], 1, v[28:29]
	v_lshl_add_u64 v[84:85], v[82:83], 1, v[28:29]
	global_load_dwordx4 v[64:67], v[64:65], off
	s_nop 0
	global_load_dwordx4 v[68:71], v[68:69], off
	s_nop 0
	global_load_dwordx4 v[72:75], v[72:73], off
	s_nop 0
	global_load_dwordx4 v[76:79], v[76:77], off
	s_nop 0
	global_load_dwordx4 v[80:83], v[80:81], off
	s_nop 0
	global_load_dwordx4 v[100:103], v[84:85], off
	v_add_u32_e32 v84, 0x18000, v160
	v_mov_b32_e32 v85, v161
	v_add_u32_e32 v104, 0x1c000, v160
	v_mov_b32_e32 v105, v161
	v_lshl_add_u64 v[84:85], v[84:85], 1, v[28:29]
	v_lshl_add_u64 v[108:109], v[104:105], 1, v[28:29]
	global_load_dwordx4 v[104:107], v[84:85], off
	s_nop 0
	global_load_dwordx4 v[108:111], v[108:109], off
	v_add_u32_e32 v218, 0x20000, v160
	v_mov_b32_e32 v219, v161
	v_add_u32_e32 v220, 0x24000, v160
	v_mov_b32_e32 v221, v161
	v_add_u32_e32 v226, 0x28000, v160
	v_mov_b32_e32 v227, v161
	v_add_u32_e32 v228, 0x2c000, v160
	v_mov_b32_e32 v229, v161
	v_add_u32_e32 v234, 0x30000, v160
	v_mov_b32_e32 v235, v161
	v_add_u32_e32 v236, 0x34000, v160
	v_mov_b32_e32 v237, v161
	v_lshl_add_u64 v[218:219], v[218:219], 1, v[28:29]
	v_lshl_add_u64 v[222:223], v[220:221], 1, v[28:29]
	v_lshl_add_u64 v[226:227], v[226:227], 1, v[28:29]
	v_lshl_add_u64 v[230:231], v[228:229], 1, v[28:29]
	v_lshl_add_u64 v[234:235], v[234:235], 1, v[28:29]
	v_lshl_add_u64 v[252:253], v[236:237], 1, v[28:29]
	global_load_dwordx4 v[218:221], v[218:219], off
	s_nop 0
	global_load_dwordx4 v[222:225], v[222:223], off
	s_nop 0
	global_load_dwordx4 v[226:229], v[226:227], off
	s_nop 0
	global_load_dwordx4 v[230:233], v[230:231], off
	s_nop 0
	global_load_dwordx4 v[234:237], v[234:235], off
	s_nop 0
	global_load_dwordx4 v[238:241], v[252:253], off
	v_add_u32_e32 v252, 0x38000, v160
	v_mov_b32_e32 v253, v161
	v_lshl_add_u64 v[252:253], v[252:253], 1, v[28:29]
	v_add_u32_e32 v160, 0x3c000, v160
	v_lshl_add_u64 v[190:191], v[160:161], 1, v[28:29]
	global_load_dwordx4 v[242:245], v[252:253], off
	global_load_dwordx4 v[248:251], v[190:191], off
	v_mul_lo_u32 v27, v27, s34
	v_lshl_add_u32 v19, v19, 4, v27
	v_add_u32_e32 v27, 0x2080, v19
	v_add_u32_e32 v30, 0x4100, v19
	v_add_u32_e32 v33, 0x6180, v19
	v_add_u32_e32 v53, 0x8200, v19
	v_add_u32_e32 v55, 0xa280, v19
	v_add_u32_e32 v59, 0xc300, v19
	v_add_u32_e32 v84, 0xe380, v19
	s_waitcnt vmcnt(15)
	ds_write2_b64 v19, v[64:65], v[66:67] offset1:1
	s_waitcnt vmcnt(14)
	ds_write2_b64 v27, v[68:69], v[70:71] offset1:1
	s_waitcnt vmcnt(13)
	ds_write2_b64 v30, v[72:73], v[74:75] offset1:1
	s_waitcnt vmcnt(12)
	ds_write2_b64 v33, v[76:77], v[78:79] offset1:1
	s_waitcnt vmcnt(11)
	ds_write2_b64 v53, v[80:81], v[82:83] offset1:1
	s_waitcnt vmcnt(10)
	ds_write2_b64 v55, v[100:101], v[102:103] offset1:1
	s_waitcnt vmcnt(9)
	ds_write2_b64 v59, v[104:105], v[106:107] offset1:1
	s_waitcnt vmcnt(8)
	ds_write2_b64 v84, v[108:109], v[110:111] offset1:1
	v_add_u32_e32 v27, 0x10400, v19
	v_add_u32_e32 v28, 0x12480, v19
	v_add_u32_e32 v29, 0x14500, v19
	v_add_u32_e32 v30, 0x16580, v19
	v_add_u32_e32 v33, 0x18600, v19
	v_add_u32_e32 v53, 0x1a680, v19
	v_add_u32_e32 v55, 0x1c700, v19
	v_add_u32_e32 v19, 0x1e780, v19
	s_waitcnt vmcnt(7)
	ds_write2_b64 v27, v[218:219], v[220:221] offset1:1
	s_waitcnt vmcnt(6)
	ds_write2_b64 v28, v[222:223], v[224:225] offset1:1
	s_waitcnt vmcnt(5)
	ds_write2_b64 v29, v[226:227], v[228:229] offset1:1
	s_waitcnt vmcnt(4)
	ds_write2_b64 v30, v[230:231], v[232:233] offset1:1
	s_waitcnt vmcnt(3)
	ds_write2_b64 v33, v[234:235], v[236:237] offset1:1
	s_waitcnt vmcnt(2)
	ds_write2_b64 v53, v[238:239], v[240:241] offset1:1
	s_waitcnt vmcnt(1)
	ds_write2_b64 v55, v[242:243], v[244:245] offset1:1
	s_waitcnt vmcnt(0)
	ds_write2_b64 v19, v[248:249], v[250:251] offset1:1
	v_mov_b32_e32 v19, v192
	s_waitcnt lgkmcnt(0)
	s_barrier
; DI unsigned pack2(float a, float b) { f32x2_t v = {a, b}; bf16x2_t r = __builtin_convertvector(v, bf16x2_t); return __builtin_bit_cast(unsigned, r); }
; DI float bflo(unsigned u) { return __uint_as_float(u << 16); }
; DI float bfhi(unsigned u) { return __uint_as_float(u & 0xffff0000u); }
; DI int otid() { int t = threadIdx.x; asm volatile("" : "+v"(t)); return t; }
; template <bool LAST>
; DI void phase_gate(const Params& P, int layer, unsigned char* smem, int L, int G) {
;     ...
;     const int tid2 = otid();
;     const int lane2 = tid2 & 63, w2 = tid2 >> 6, r2 = lane2 & 31, h2 = lane2 >> 5, wm2 = w2 >> 2, wn2 = w2 & 3;
; #pragma unroll
;     for (int i = 0; i < 4; ++i)
; #pragma unroll
;       for (int q4 = 0; q4 < 4; ++q4) {
;         const int fl = wm2 * 128 + i * 32 + 8 * q4 + 4 * h2;
;         const int f0 = nt * 256 + fl;
;         const f32x4 gv = *(const f32x4*)(vecL + 512 + fl), bv = *(const f32x4*)(vecL + 768 + fl);
;         const float ga[4] = {gv.x, gv.y, gv.z, gv.w}, ba[4] = {bv.x, bv.y, bv.z, bv.w};
; #pragma unroll
;         for (int j = 0; j < 2; ++j) {
;           const int lrow = wn2 * 64 + j * 32 + r2;
;           const float mu = rowA[lrow], rstd = rowB[lrow];
;           uint2* sp = (uint2*)(stg + lrow * STG + fl);
;           const uint2 sv = *sp;
;           const float sa[4] = {bflo(sv.x), bfhi(sv.x), bflo(sv.y), bfhi(sv.y)};
;           float y[4];
;           const float gg[4] = {bflo(gq[i][j][2 * q4]), bfhi(gq[i][j][2 * q4]), bflo(gq[i][j][2 * q4 + 1]), bfhi(gq[i][j][2 * q4 + 1])};
; #pragma unroll
;           for (int e = 0; e < 4; ++e) y[e] = (sa[e] - mu) * rstd * ga[e] + ba[e] + gg[e];
;           if (LAST) { f32x4 o = {y[0], y[1], y[2], y[3]}; *(f32x4*)(P.out + (size_t)(mt * 256 + lrow) * 1024 + f0) = o; }
;           else { uint2 pk; pk.x = pack2(y[0], y[1]); pk.y = pack2(y[2], y[3]); *sp = pk; }
;         }
;         __builtin_amdgcn_sched_barrier(0);
;       }
	v_lshlrev_b32_e32 v82, 16, v31
	v_lshrrev_b32_e32 v28, 3, v19
	v_ashrrev_i32_e32 v27, 1, v19
	v_and_b32_e32 v28, 4, v28
	v_and_or_b32 v30, v27, s35, v28
	v_and_b32_e32 v19, 0xdf, v19
	v_lshlrev_b32_e32 v27, 2, v30
	v_lshlrev_b32_e32 v33, 2, v19
	v_mul_u32_u24_e32 v19, 0x208, v19
	v_add_u32_e32 v28, 0x25000, v27
	v_lshl_add_u32 v19, v30, 1, v19
	v_add_u32_e32 v29, 0x25400, v27
	ds_read_b128 v[64:67], v28
	ds_read_b128 v[68:71], v29
	ds_read_b64 v[72:73], v19
	v_or_b32_e32 v29, 0x24000, v33
	v_or_b32_e32 v30, 0x24400, v33
	ds_read_b32 v74, v29
	ds_read_b32 v76, v30
	ds_read_b64 v[78:79], v19 offset:16640
	v_and_b32_e32 v83, 0xffff0000, v31
	s_waitcnt lgkmcnt(3)
	v_lshlrev_b32_e32 v80, 16, v72
	v_and_b32_e32 v81, 0xffff0000, v72
	v_lshlrev_b32_e32 v72, 16, v73
	v_and_b32_e32 v73, 0xffff0000, v73
	s_waitcnt lgkmcnt(2)
	v_pk_add_f32 v[80:81], v[80:81], v[74:75] op_sel_hi:[1,0] neg_lo:[0,1] neg_hi:[0,1]
	v_pk_add_f32 v[72:73], v[72:73], v[74:75] op_sel_hi:[1,0] neg_lo:[0,1] neg_hi:[0,1]
	s_waitcnt lgkmcnt(1)
	v_pk_mul_f32 v[80:81], v[76:77], v[80:81] op_sel_hi:[0,1]
	v_pk_mul_f32 v[72:73], v[76:77], v[72:73] op_sel_hi:[0,1]
	v_lshlrev_b32_e32 v84, 16, v98
	v_and_b32_e32 v85, 0xffff0000, v98
	v_pk_fma_f32 v[80:81], v[64:65], v[80:81], v[68:69]
	v_pk_fma_f32 v[72:73], v[66:67], v[72:73], v[70:71]
	v_pk_add_f32 v[80:81], v[80:81], v[82:83]
	v_pk_add_f32 v[72:73], v[72:73], v[84:85]
	v_cvt_pk_bf16_f32 v74, v80, v81
	v_cvt_pk_bf16_f32 v75, v72, v73
	ds_write_b64 v19, v[74:75]
	v_or_b32_e32 v31, 0x24080, v33
	v_or_b32_e32 v33, 0x24480, v33
	ds_read_b32 v72, v31
	ds_read_b32 v74, v33
	s_waitcnt lgkmcnt(3)
	v_lshlrev_b32_e32 v76, 16, v78
	v_and_b32_e32 v77, 0xffff0000, v78
	v_lshlrev_b32_e32 v78, 16, v79
	s_waitcnt lgkmcnt(1)
	v_pk_add_f32 v[76:77], v[76:77], v[72:73] op_sel_hi:[1,0] neg_lo:[0,1] neg_hi:[0,1]
	v_and_b32_e32 v79, 0xffff0000, v79
	s_waitcnt lgkmcnt(0)
	v_pk_mul_f32 v[76:77], v[74:75], v[76:77] op_sel_hi:[0,1]
	v_pk_fma_f32 v[64:65], v[64:65], v[76:77], v[68:69]
	v_pk_add_f32 v[68:69], v[78:79], v[72:73] op_sel_hi:[1,0] neg_lo:[0,1] neg_hi:[0,1]
	v_lshlrev_b32_e32 v80, 16, v97
	v_pk_mul_f32 v[68:69], v[74:75], v[68:69] op_sel_hi:[0,1]
	v_and_b32_e32 v81, 0xffff0000, v97
	v_lshlrev_b32_e32 v82, 16, v96
	v_and_b32_e32 v83, 0xffff0000, v96
	v_pk_fma_f32 v[66:67], v[66:67], v[68:69], v[70:71]
	v_pk_add_f32 v[64:65], v[64:65], v[80:81]
	v_pk_add_f32 v[66:67], v[66:67], v[82:83]
	v_cvt_pk_bf16_f32 v64, v64, v65
	v_cvt_pk_bf16_f32 v65, v66, v67
	ds_write_b64 v19, v[64:65] offset:16640
	v_add_u32_e32 v53, 0x25020, v27
	v_add_u32_e32 v55, 0x25420, v27
	ds_read_b64 v[72:73], v19 offset:16
	ds_read_b128 v[64:67], v53
	ds_read_b128 v[68:71], v55
	ds_read_b32 v74, v29
	ds_read_b32 v76, v30
	ds_read_b64 v[78:79], v19 offset:16656
	s_waitcnt lgkmcnt(5)
	v_lshlrev_b32_e32 v80, 16, v72
	v_and_b32_e32 v81, 0xffff0000, v72
	v_lshlrev_b32_e32 v72, 16, v73
	v_and_b32_e32 v73, 0xffff0000, v73
	s_waitcnt lgkmcnt(2)
	v_pk_add_f32 v[80:81], v[80:81], v[74:75] op_sel_hi:[1,0] neg_lo:[0,1] neg_hi:[0,1]
	v_pk_add_f32 v[72:73], v[72:73], v[74:75] op_sel_hi:[1,0] neg_lo:[0,1] neg_hi:[0,1]
	s_waitcnt lgkmcnt(1)
	v_pk_mul_f32 v[80:81], v[76:77], v[80:81] op_sel_hi:[0,1]
	v_pk_mul_f32 v[72:73], v[76:77], v[72:73] op_sel_hi:[0,1]
	v_lshlrev_b32_e32 v82, 16, v93
	v_and_b32_e32 v83, 0xffff0000, v93
	v_lshlrev_b32_e32 v84, 16, v95
	v_and_b32_e32 v85, 0xffff0000, v95
	v_pk_fma_f32 v[80:81], v[64:65], v[80:81], v[68:69]
	v_pk_fma_f32 v[72:73], v[66:67], v[72:73], v[70:71]
	v_pk_add_f32 v[80:81], v[80:81], v[82:83]
	v_pk_add_f32 v[72:73], v[72:73], v[84:85]
	v_cvt_pk_bf16_f32 v74, v80, v81
	v_cvt_pk_bf16_f32 v75, v72, v73
	ds_write_b64 v19, v[74:75] offset:16
	ds_read_b32 v72, v31
	ds_read_b32 v74, v33
	s_waitcnt lgkmcnt(3)
	v_lshlrev_b32_e32 v76, 16, v78
	v_and_b32_e32 v77, 0xffff0000, v78
	v_lshlrev_b32_e32 v78, 16, v79
	s_waitcnt lgkmcnt(1)
	v_pk_add_f32 v[76:77], v[76:77], v[72:73] op_sel_hi:[1,0] neg_lo:[0,1] neg_hi:[0,1]
	v_and_b32_e32 v79, 0xffff0000, v79
	s_waitcnt lgkmcnt(0)
	v_pk_mul_f32 v[76:77], v[74:75], v[76:77] op_sel_hi:[0,1]
	v_pk_fma_f32 v[64:65], v[64:65], v[76:77], v[68:69]
	v_pk_add_f32 v[68:69], v[78:79], v[72:73] op_sel_hi:[1,0] neg_lo:[0,1] neg_hi:[0,1]
	v_lshlrev_b32_e32 v80, 16, v92
	v_pk_mul_f32 v[68:69], v[74:75], v[68:69] op_sel_hi:[0,1]
	v_and_b32_e32 v81, 0xffff0000, v92
	v_lshlrev_b32_e32 v82, 16, v94
	v_and_b32_e32 v83, 0xffff0000, v94
	v_pk_fma_f32 v[66:67], v[66:67], v[68:69], v[70:71]
	v_pk_add_f32 v[64:65], v[64:65], v[80:81]
	v_pk_add_f32 v[66:67], v[66:67], v[82:83]
	v_cvt_pk_bf16_f32 v64, v64, v65
	v_cvt_pk_bf16_f32 v65, v66, v67
	ds_write_b64 v19, v[64:65] offset:16656
	v_add_u32_e32 v53, 0x25040, v27
	v_add_u32_e32 v55, 0x25440, v27
	ds_read_b64 v[72:73], v19 offset:32
	ds_read_b128 v[64:67], v53
	ds_read_b128 v[68:71], v55
	ds_read_b32 v74, v29
	ds_read_b32 v76, v30
	ds_read_b64 v[78:79], v19 offset:16672
	s_waitcnt lgkmcnt(5)
	v_lshlrev_b32_e32 v80, 16, v72
	v_and_b32_e32 v81, 0xffff0000, v72
	v_lshlrev_b32_e32 v72, 16, v73
	v_and_b32_e32 v73, 0xffff0000, v73
	s_waitcnt lgkmcnt(2)
	v_pk_add_f32 v[80:81], v[80:81], v[74:75] op_sel_hi:[1,0] neg_lo:[0,1] neg_hi:[0,1]
	v_pk_add_f32 v[72:73], v[72:73], v[74:75] op_sel_hi:[1,0] neg_lo:[0,1] neg_hi:[0,1]
	s_waitcnt lgkmcnt(1)
	v_pk_mul_f32 v[80:81], v[76:77], v[80:81] op_sel_hi:[0,1]
	v_pk_mul_f32 v[72:73], v[76:77], v[72:73] op_sel_hi:[0,1]
	v_lshlrev_b32_e32 v82, 16, v88
	v_and_b32_e32 v83, 0xffff0000, v88
	v_lshlrev_b32_e32 v84, 16, v90
	v_and_b32_e32 v85, 0xffff0000, v90
	v_pk_fma_f32 v[80:81], v[64:65], v[80:81], v[68:69]
	v_pk_fma_f32 v[72:73], v[66:67], v[72:73], v[70:71]
	v_pk_add_f32 v[80:81], v[80:81], v[82:83]
	v_pk_add_f32 v[72:73], v[72:73], v[84:85]
	v_cvt_pk_bf16_f32 v74, v80, v81
	v_cvt_pk_bf16_f32 v75, v72, v73
	ds_write_b64 v19, v[74:75] offset:32
	ds_read_b32 v72, v31
	ds_read_b32 v74, v33
	s_waitcnt lgkmcnt(3)
; DI unsigned pack2(float a, float b) { f32x2_t v = {a, b}; bf16x2_t r = __builtin_convertvector(v, bf16x2_t); return __builtin_bit_cast(unsigned, r); }
; DI float bflo(unsigned u) { return __uint_as_float(u << 16); }
; DI float bfhi(unsigned u) { return __uint_as_float(u & 0xffff0000u); }
; template <bool LAST>
; DI void phase_gate(const Params& P, int layer, unsigned char* smem, int L, int G) {
;     ...
; #pragma unroll
;     for (int i = 0; i < 4; ++i)
; #pragma unroll
;       for (int q4 = 0; q4 < 4; ++q4) {
;         const int fl = wm2 * 128 + i * 32 + 8 * q4 + 4 * h2;
;         const int f0 = nt * 256 + fl;
;         const f32x4 gv = *(const f32x4*)(vecL + 512 + fl), bv = *(const f32x4*)(vecL + 768 + fl);
;         const float ga[4] = {gv.x, gv.y, gv.z, gv.w}, ba[4] = {bv.x, bv.y, bv.z, bv.w};
; #pragma unroll
;         for (int j = 0; j < 2; ++j) {
;           const int lrow = wn2 * 64 + j * 32 + r2;
;           const float mu = rowA[lrow], rstd = rowB[lrow];
;           uint2* sp = (uint2*)(stg + lrow * STG + fl);
;           const uint2 sv = *sp;
;           const float sa[4] = {bflo(sv.x), bfhi(sv.x), bflo(sv.y), bfhi(sv.y)};
;           float y[4];
;           const float gg[4] = {bflo(gq[i][j][2 * q4]), bfhi(gq[i][j][2 * q4]), bflo(gq[i][j][2 * q4 + 1]), bfhi(gq[i][j][2 * q4 + 1])};
; #pragma unroll
;           for (int e = 0; e < 4; ++e) y[e] = (sa[e] - mu) * rstd * ga[e] + ba[e] + gg[e];
;           if (LAST) { f32x4 o = {y[0], y[1], y[2], y[3]}; *(f32x4*)(P.out + (size_t)(mt * 256 + lrow) * 1024 + f0) = o; }
;           else { uint2 pk; pk.x = pack2(y[0], y[1]); pk.y = pack2(y[2], y[3]); *sp = pk; }
;         }
;         __builtin_amdgcn_sched_barrier(0);
	v_lshlrev_b32_e32 v76, 16, v78
	v_and_b32_e32 v77, 0xffff0000, v78
	v_lshlrev_b32_e32 v78, 16, v79
	s_waitcnt lgkmcnt(1)
	v_pk_add_f32 v[76:77], v[76:77], v[72:73] op_sel_hi:[1,0] neg_lo:[0,1] neg_hi:[0,1]
	v_and_b32_e32 v79, 0xffff0000, v79
	s_waitcnt lgkmcnt(0)
	v_pk_mul_f32 v[76:77], v[74:75], v[76:77] op_sel_hi:[0,1]
	v_pk_fma_f32 v[64:65], v[64:65], v[76:77], v[68:69]
	v_pk_add_f32 v[68:69], v[78:79], v[72:73] op_sel_hi:[1,0] neg_lo:[0,1] neg_hi:[0,1]
	v_lshlrev_b32_e32 v80, 16, v87
	v_pk_mul_f32 v[68:69], v[74:75], v[68:69] op_sel_hi:[0,1]
	v_and_b32_e32 v81, 0xffff0000, v87
	v_lshlrev_b32_e32 v82, 16, v89
	v_and_b32_e32 v83, 0xffff0000, v89
	v_pk_fma_f32 v[66:67], v[66:67], v[68:69], v[70:71]
	v_pk_add_f32 v[64:65], v[64:65], v[80:81]
	v_pk_add_f32 v[66:67], v[66:67], v[82:83]
	v_cvt_pk_bf16_f32 v64, v64, v65
	v_cvt_pk_bf16_f32 v65, v66, v67
	ds_write_b64 v19, v[64:65] offset:16672
	v_add_u32_e32 v53, 0x25060, v27
	v_add_u32_e32 v55, 0x25460, v27
	ds_read_b64 v[72:73], v19 offset:48
	ds_read_b128 v[64:67], v53
	ds_read_b128 v[68:71], v55
	ds_read_b32 v74, v29
	ds_read_b32 v76, v30
	ds_read_b64 v[78:79], v19 offset:16688
	s_waitcnt lgkmcnt(5)
	v_lshlrev_b32_e32 v80, 16, v72
	v_and_b32_e32 v81, 0xffff0000, v72
	v_lshlrev_b32_e32 v72, 16, v73
	v_and_b32_e32 v73, 0xffff0000, v73
	s_waitcnt lgkmcnt(2)
	v_pk_add_f32 v[80:81], v[80:81], v[74:75] op_sel_hi:[1,0] neg_lo:[0,1] neg_hi:[0,1]
	v_pk_add_f32 v[72:73], v[72:73], v[74:75] op_sel_hi:[1,0] neg_lo:[0,1] neg_hi:[0,1]
	s_waitcnt lgkmcnt(1)
	v_pk_mul_f32 v[80:81], v[76:77], v[80:81] op_sel_hi:[0,1]
	v_pk_mul_f32 v[72:73], v[76:77], v[72:73] op_sel_hi:[0,1]
	v_lshlrev_b32_e32 v82, 16, v61
	v_and_b32_e32 v83, 0xffff0000, v61
	v_lshlrev_b32_e32 v84, 16, v63
	v_and_b32_e32 v85, 0xffff0000, v63
	v_pk_fma_f32 v[80:81], v[64:65], v[80:81], v[68:69]
	v_pk_fma_f32 v[72:73], v[66:67], v[72:73], v[70:71]
	v_pk_add_f32 v[80:81], v[80:81], v[82:83]
	v_pk_add_f32 v[72:73], v[72:73], v[84:85]
	v_cvt_pk_bf16_f32 v74, v80, v81
	v_cvt_pk_bf16_f32 v75, v72, v73
	ds_write_b64 v19, v[74:75] offset:48
	ds_read_b32 v72, v31
	ds_read_b32 v74, v33
	s_waitcnt lgkmcnt(3)
	v_lshlrev_b32_e32 v76, 16, v78
	v_and_b32_e32 v77, 0xffff0000, v78
	v_lshlrev_b32_e32 v80, 16, v60
	v_and_b32_e32 v81, 0xffff0000, v60
	v_lshlrev_b32_e32 v60, 16, v62
	v_and_b32_e32 v61, 0xffff0000, v62
	s_waitcnt lgkmcnt(1)
	v_pk_add_f32 v[62:63], v[76:77], v[72:73] op_sel_hi:[1,0] neg_lo:[0,1] neg_hi:[0,1]
	v_lshlrev_b32_e32 v78, 16, v79
	v_and_b32_e32 v79, 0xffff0000, v79
	s_waitcnt lgkmcnt(0)
	v_pk_mul_f32 v[62:63], v[74:75], v[62:63] op_sel_hi:[0,1]
	v_pk_fma_f32 v[62:63], v[64:65], v[62:63], v[68:69]
	v_pk_add_f32 v[64:65], v[78:79], v[72:73] op_sel_hi:[1,0] neg_lo:[0,1] neg_hi:[0,1]
	v_pk_add_f32 v[62:63], v[62:63], v[80:81]
	v_pk_mul_f32 v[64:65], v[74:75], v[64:65] op_sel_hi:[0,1]
	v_pk_fma_f32 v[64:65], v[66:67], v[64:65], v[70:71]
	v_cvt_pk_bf16_f32 v62, v62, v63
	v_pk_add_f32 v[60:61], v[64:65], v[60:61]
	s_nop 0
	v_cvt_pk_bf16_f32 v63, v60, v61
	ds_write_b64 v19, v[62:63] offset:16688
	v_add_u32_e32 v53, 0x25080, v27
	v_add_u32_e32 v55, 0x25480, v27
	ds_read_b64 v[68:69], v19 offset:64
	ds_read_b128 v[60:63], v53
	ds_read_b128 v[64:67], v55
	ds_read_b32 v70, v29
	ds_read_b32 v72, v30
	ds_read_b64 v[74:75], v19 offset:16704
	s_waitcnt lgkmcnt(5)
	v_lshlrev_b32_e32 v76, 16, v68
	v_and_b32_e32 v77, 0xffff0000, v68
	v_lshlrev_b32_e32 v68, 16, v69
	v_and_b32_e32 v69, 0xffff0000, v69
	v_lshlrev_b32_e32 v80, 16, v58
	v_and_b32_e32 v81, 0xffff0000, v58
	s_waitcnt lgkmcnt(2)
	v_pk_add_f32 v[58:59], v[76:77], v[70:71] op_sel_hi:[1,0] neg_lo:[0,1] neg_hi:[0,1]
	v_pk_add_f32 v[68:69], v[68:69], v[70:71] op_sel_hi:[1,0] neg_lo:[0,1] neg_hi:[0,1]
	s_waitcnt lgkmcnt(1)
	v_pk_mul_f32 v[58:59], v[72:73], v[58:59] op_sel_hi:[0,1]
	v_pk_mul_f32 v[68:69], v[72:73], v[68:69] op_sel_hi:[0,1]
	v_lshlrev_b32_e32 v78, 16, v56
	v_and_b32_e32 v79, 0xffff0000, v56
	v_pk_fma_f32 v[58:59], v[60:61], v[58:59], v[64:65]
	v_pk_fma_f32 v[68:69], v[62:63], v[68:69], v[66:67]
	v_pk_add_f32 v[58:59], v[58:59], v[78:79]
	v_pk_add_f32 v[68:69], v[68:69], v[80:81]
	v_cvt_pk_bf16_f32 v58, v58, v59
	v_cvt_pk_bf16_f32 v59, v68, v69
	ds_write_b64 v19, v[58:59] offset:64
	ds_read_b32 v56, v31
	ds_read_b32 v58, v33
	s_waitcnt lgkmcnt(3)
	v_lshlrev_b32_e32 v68, 16, v74
	v_and_b32_e32 v69, 0xffff0000, v74
	v_lshlrev_b32_e32 v70, 16, v75
	v_and_b32_e32 v71, 0xffff0000, v75
	v_lshlrev_b32_e32 v72, 16, v54
	v_and_b32_e32 v73, 0xffff0000, v54
	v_lshlrev_b32_e32 v54, 16, v57
	v_and_b32_e32 v55, 0xffff0000, v57
	s_waitcnt lgkmcnt(1)
	v_pk_add_f32 v[68:69], v[68:69], v[56:57] op_sel_hi:[1,0] neg_lo:[0,1] neg_hi:[0,1]
	v_pk_add_f32 v[56:57], v[70:71], v[56:57] op_sel_hi:[1,0] neg_lo:[0,1] neg_hi:[0,1]
	s_waitcnt lgkmcnt(0)
	v_pk_mul_f32 v[68:69], v[58:59], v[68:69] op_sel_hi:[0,1]
	v_pk_mul_f32 v[56:57], v[58:59], v[56:57] op_sel_hi:[0,1]
	v_pk_fma_f32 v[60:61], v[60:61], v[68:69], v[64:65]
	v_pk_fma_f32 v[56:57], v[62:63], v[56:57], v[66:67]
	v_pk_add_f32 v[60:61], v[60:61], v[72:73]
	v_pk_add_f32 v[54:55], v[56:57], v[54:55]
	v_cvt_pk_bf16_f32 v56, v60, v61
	v_cvt_pk_bf16_f32 v57, v54, v55
	ds_write_b64 v19, v[56:57] offset:16704
	v_add_u32_e32 v58, 0x254a0, v27
	v_add_u32_e32 v53, 0x250a0, v27
	ds_read_b64 v[62:63], v19 offset:80
	ds_read_b128 v[54:57], v53
	ds_read_b128 v[58:61], v58
	ds_read_b32 v64, v29
	ds_read_b32 v66, v30
	ds_read_b64 v[68:69], v19 offset:16720
	s_waitcnt lgkmcnt(5)
	v_lshlrev_b32_e32 v70, 16, v62
	v_and_b32_e32 v71, 0xffff0000, v62
	v_lshlrev_b32_e32 v62, 16, v63
	v_and_b32_e32 v63, 0xffff0000, v63
	v_lshlrev_b32_e32 v74, 16, v52
	v_and_b32_e32 v75, 0xffff0000, v52
	s_waitcnt lgkmcnt(2)
; DI unsigned pack2(float a, float b) { f32x2_t v = {a, b}; bf16x2_t r = __builtin_convertvector(v, bf16x2_t); return __builtin_bit_cast(unsigned, r); }
; DI float bflo(unsigned u) { return __uint_as_float(u << 16); }
; DI float bfhi(unsigned u) { return __uint_as_float(u & 0xffff0000u); }
; template <bool LAST>
; DI void phase_gate(const Params& P, int layer, unsigned char* smem, int L, int G) {
;     ...
; #pragma unroll
;     for (int i = 0; i < 4; ++i)
; #pragma unroll
;       for (int q4 = 0; q4 < 4; ++q4) {
;         const int fl = wm2 * 128 + i * 32 + 8 * q4 + 4 * h2;
;         const int f0 = nt * 256 + fl;
;         const f32x4 gv = *(const f32x4*)(vecL + 512 + fl), bv = *(const f32x4*)(vecL + 768 + fl);
;         const float ga[4] = {gv.x, gv.y, gv.z, gv.w}, ba[4] = {bv.x, bv.y, bv.z, bv.w};
; #pragma unroll
;         for (int j = 0; j < 2; ++j) {
;           const int lrow = wn2 * 64 + j * 32 + r2;
;           const float mu = rowA[lrow], rstd = rowB[lrow];
;           uint2* sp = (uint2*)(stg + lrow * STG + fl);
;           const uint2 sv = *sp;
;           const float sa[4] = {bflo(sv.x), bfhi(sv.x), bflo(sv.y), bfhi(sv.y)};
;           float y[4];
;           const float gg[4] = {bflo(gq[i][j][2 * q4]), bfhi(gq[i][j][2 * q4]), bflo(gq[i][j][2 * q4 + 1]), bfhi(gq[i][j][2 * q4 + 1])};
; #pragma unroll
;           for (int e = 0; e < 4; ++e) y[e] = (sa[e] - mu) * rstd * ga[e] + ba[e] + gg[e];
;           if (LAST) { f32x4 o = {y[0], y[1], y[2], y[3]}; *(f32x4*)(P.out + (size_t)(mt * 256 + lrow) * 1024 + f0) = o; }
;           else { uint2 pk; pk.x = pack2(y[0], y[1]); pk.y = pack2(y[2], y[3]); *sp = pk; }
;         }
;         __builtin_amdgcn_sched_barrier(0);
	v_pk_add_f32 v[52:53], v[70:71], v[64:65] op_sel_hi:[1,0] neg_lo:[0,1] neg_hi:[0,1]
	v_pk_add_f32 v[62:63], v[62:63], v[64:65] op_sel_hi:[1,0] neg_lo:[0,1] neg_hi:[0,1]
	s_waitcnt lgkmcnt(1)
	v_pk_mul_f32 v[52:53], v[66:67], v[52:53] op_sel_hi:[0,1]
	v_pk_mul_f32 v[62:63], v[66:67], v[62:63] op_sel_hi:[0,1]
	v_lshlrev_b32_e32 v72, 16, v50
	v_and_b32_e32 v73, 0xffff0000, v50
	v_pk_fma_f32 v[52:53], v[54:55], v[52:53], v[58:59]
	v_pk_fma_f32 v[62:63], v[56:57], v[62:63], v[60:61]
	v_pk_add_f32 v[52:53], v[52:53], v[72:73]
	v_pk_add_f32 v[62:63], v[62:63], v[74:75]
	v_cvt_pk_bf16_f32 v52, v52, v53
	v_cvt_pk_bf16_f32 v53, v62, v63
	ds_write_b64 v19, v[52:53] offset:80
	ds_read_b32 v50, v31
	ds_read_b32 v52, v33
	s_waitcnt lgkmcnt(3)
	v_lshlrev_b32_e32 v62, 16, v68
	v_and_b32_e32 v63, 0xffff0000, v68
	v_lshlrev_b32_e32 v64, 16, v69
	v_and_b32_e32 v65, 0xffff0000, v69
	v_lshlrev_b32_e32 v68, 16, v51
	v_and_b32_e32 v69, 0xffff0000, v51
	s_waitcnt lgkmcnt(1)
	v_pk_add_f32 v[62:63], v[62:63], v[50:51] op_sel_hi:[1,0] neg_lo:[0,1] neg_hi:[0,1]
	v_pk_add_f32 v[50:51], v[64:65], v[50:51] op_sel_hi:[1,0] neg_lo:[0,1] neg_hi:[0,1]
	s_waitcnt lgkmcnt(0)
	v_pk_mul_f32 v[62:63], v[52:53], v[62:63] op_sel_hi:[0,1]
	v_pk_mul_f32 v[50:51], v[52:53], v[50:51] op_sel_hi:[0,1]
	v_lshlrev_b32_e32 v66, 16, v49
	v_and_b32_e32 v67, 0xffff0000, v49
	v_pk_fma_f32 v[54:55], v[54:55], v[62:63], v[58:59]
	v_pk_fma_f32 v[50:51], v[56:57], v[50:51], v[60:61]
	v_pk_add_f32 v[54:55], v[54:55], v[66:67]
	v_pk_add_f32 v[50:51], v[50:51], v[68:69]
	v_cvt_pk_bf16_f32 v52, v54, v55
	v_cvt_pk_bf16_f32 v53, v50, v51
	ds_write_b64 v19, v[52:53] offset:16720
	v_add_u32_e32 v54, 0x254c0, v27
	v_add_u32_e32 v49, 0x250c0, v27
	ds_read_b64 v[58:59], v19 offset:96
	ds_read_b128 v[50:53], v49
	ds_read_b128 v[54:57], v54
	ds_read_b32 v60, v29
	ds_read_b32 v62, v30
	ds_read_b64 v[64:65], v19 offset:16736
	s_waitcnt lgkmcnt(5)
	v_lshlrev_b32_e32 v66, 16, v58
	v_and_b32_e32 v67, 0xffff0000, v58
	v_lshlrev_b32_e32 v58, 16, v59
	v_and_b32_e32 v59, 0xffff0000, v59
	v_lshlrev_b32_e32 v70, 16, v48
	v_and_b32_e32 v71, 0xffff0000, v48
	s_waitcnt lgkmcnt(2)
	v_pk_add_f32 v[48:49], v[66:67], v[60:61] op_sel_hi:[1,0] neg_lo:[0,1] neg_hi:[0,1]
	v_pk_add_f32 v[58:59], v[58:59], v[60:61] op_sel_hi:[1,0] neg_lo:[0,1] neg_hi:[0,1]
	s_waitcnt lgkmcnt(1)
	v_pk_mul_f32 v[48:49], v[62:63], v[48:49] op_sel_hi:[0,1]
	v_pk_mul_f32 v[58:59], v[62:63], v[58:59] op_sel_hi:[0,1]
	v_lshlrev_b32_e32 v68, 16, v46
	v_and_b32_e32 v69, 0xffff0000, v46
	v_pk_fma_f32 v[48:49], v[50:51], v[48:49], v[54:55]
	v_pk_fma_f32 v[58:59], v[52:53], v[58:59], v[56:57]
	v_pk_add_f32 v[48:49], v[48:49], v[68:69]
	v_pk_add_f32 v[58:59], v[58:59], v[70:71]
	v_cvt_pk_bf16_f32 v48, v48, v49
	v_cvt_pk_bf16_f32 v49, v58, v59
	ds_write_b64 v19, v[48:49] offset:96
	ds_read_b32 v46, v31
	ds_read_b32 v48, v33
	s_waitcnt lgkmcnt(3)
	v_lshlrev_b32_e32 v58, 16, v64
	v_and_b32_e32 v59, 0xffff0000, v64
	v_lshlrev_b32_e32 v60, 16, v65
	v_and_b32_e32 v61, 0xffff0000, v65
	v_lshlrev_b32_e32 v64, 16, v47
	v_and_b32_e32 v65, 0xffff0000, v47
	s_waitcnt lgkmcnt(1)
	v_pk_add_f32 v[58:59], v[58:59], v[46:47] op_sel_hi:[1,0] neg_lo:[0,1] neg_hi:[0,1]
	v_pk_add_f32 v[46:47], v[60:61], v[46:47] op_sel_hi:[1,0] neg_lo:[0,1] neg_hi:[0,1]
	s_waitcnt lgkmcnt(0)
	v_pk_mul_f32 v[58:59], v[48:49], v[58:59] op_sel_hi:[0,1]
	v_pk_mul_f32 v[46:47], v[48:49], v[46:47] op_sel_hi:[0,1]
	v_lshlrev_b32_e32 v62, 16, v45
	v_and_b32_e32 v63, 0xffff0000, v45
	v_pk_fma_f32 v[50:51], v[50:51], v[58:59], v[54:55]
	v_pk_fma_f32 v[46:47], v[52:53], v[46:47], v[56:57]
	v_pk_add_f32 v[50:51], v[50:51], v[62:63]
	v_pk_add_f32 v[46:47], v[46:47], v[64:65]
	v_cvt_pk_bf16_f32 v48, v50, v51
	v_cvt_pk_bf16_f32 v49, v46, v47
	ds_write_b64 v19, v[48:49] offset:16736
	v_add_u32_e32 v50, 0x254e0, v27
	v_add_u32_e32 v45, 0x250e0, v27
	ds_read_b64 v[54:55], v19 offset:112
	ds_read_b128 v[46:49], v45
	ds_read_b128 v[50:53], v50
	ds_read_b32 v56, v29
	ds_read_b32 v58, v30
	ds_read_b64 v[60:61], v19 offset:16752
	s_waitcnt lgkmcnt(5)
	v_lshlrev_b32_e32 v62, 16, v54
	v_and_b32_e32 v63, 0xffff0000, v54
	v_lshlrev_b32_e32 v54, 16, v55
	v_and_b32_e32 v55, 0xffff0000, v55
	v_lshlrev_b32_e32 v66, 16, v44
	v_and_b32_e32 v67, 0xffff0000, v44
	s_waitcnt lgkmcnt(2)
	v_pk_add_f32 v[44:45], v[62:63], v[56:57] op_sel_hi:[1,0] neg_lo:[0,1] neg_hi:[0,1]
	v_pk_add_f32 v[54:55], v[54:55], v[56:57] op_sel_hi:[1,0] neg_lo:[0,1] neg_hi:[0,1]
	s_waitcnt lgkmcnt(1)
	v_pk_mul_f32 v[44:45], v[58:59], v[44:45] op_sel_hi:[0,1]
	v_pk_mul_f32 v[54:55], v[58:59], v[54:55] op_sel_hi:[0,1]
	v_lshlrev_b32_e32 v64, 16, v42
	v_and_b32_e32 v65, 0xffff0000, v42
	v_pk_fma_f32 v[44:45], v[46:47], v[44:45], v[50:51]
	v_pk_fma_f32 v[54:55], v[48:49], v[54:55], v[52:53]
	v_pk_add_f32 v[44:45], v[44:45], v[64:65]
	v_pk_add_f32 v[54:55], v[54:55], v[66:67]
	v_cvt_pk_bf16_f32 v44, v44, v45
	v_cvt_pk_bf16_f32 v45, v54, v55
	ds_write_b64 v19, v[44:45] offset:112
	ds_read_b32 v42, v31
	ds_read_b32 v44, v33
	s_waitcnt lgkmcnt(3)
	v_lshlrev_b32_e32 v54, 16, v60
	v_and_b32_e32 v55, 0xffff0000, v60
	v_lshlrev_b32_e32 v56, 16, v61
	v_and_b32_e32 v57, 0xffff0000, v61
	v_lshlrev_b32_e32 v60, 16, v43
	v_and_b32_e32 v61, 0xffff0000, v43
	s_waitcnt lgkmcnt(1)
	v_pk_add_f32 v[54:55], v[54:55], v[42:43] op_sel_hi:[1,0] neg_lo:[0,1] neg_hi:[0,1]
	v_pk_add_f32 v[42:43], v[56:57], v[42:43] op_sel_hi:[1,0] neg_lo:[0,1] neg_hi:[0,1]
	s_waitcnt lgkmcnt(0)
; DI unsigned pack2(float a, float b) { f32x2_t v = {a, b}; bf16x2_t r = __builtin_convertvector(v, bf16x2_t); return __builtin_bit_cast(unsigned, r); }
; DI float bflo(unsigned u) { return __uint_as_float(u << 16); }
; DI float bfhi(unsigned u) { return __uint_as_float(u & 0xffff0000u); }
; template <bool LAST>
; DI void phase_gate(const Params& P, int layer, unsigned char* smem, int L, int G) {
;     ...
; #pragma unroll
;     for (int i = 0; i < 4; ++i)
; #pragma unroll
;       for (int q4 = 0; q4 < 4; ++q4) {
;         const int fl = wm2 * 128 + i * 32 + 8 * q4 + 4 * h2;
;         const int f0 = nt * 256 + fl;
;         const f32x4 gv = *(const f32x4*)(vecL + 512 + fl), bv = *(const f32x4*)(vecL + 768 + fl);
;         const float ga[4] = {gv.x, gv.y, gv.z, gv.w}, ba[4] = {bv.x, bv.y, bv.z, bv.w};
; #pragma unroll
;         for (int j = 0; j < 2; ++j) {
;           const int lrow = wn2 * 64 + j * 32 + r2;
;           const float mu = rowA[lrow], rstd = rowB[lrow];
;           uint2* sp = (uint2*)(stg + lrow * STG + fl);
;           const uint2 sv = *sp;
;           const float sa[4] = {bflo(sv.x), bfhi(sv.x), bflo(sv.y), bfhi(sv.y)};
;           float y[4];
;           const float gg[4] = {bflo(gq[i][j][2 * q4]), bfhi(gq[i][j][2 * q4]), bflo(gq[i][j][2 * q4 + 1]), bfhi(gq[i][j][2 * q4 + 1])};
; #pragma unroll
;           for (int e = 0; e < 4; ++e) y[e] = (sa[e] - mu) * rstd * ga[e] + ba[e] + gg[e];
;           if (LAST) { f32x4 o = {y[0], y[1], y[2], y[3]}; *(f32x4*)(P.out + (size_t)(mt * 256 + lrow) * 1024 + f0) = o; }
;           else { uint2 pk; pk.x = pack2(y[0], y[1]); pk.y = pack2(y[2], y[3]); *sp = pk; }
;         }
;         __builtin_amdgcn_sched_barrier(0);
	v_pk_mul_f32 v[54:55], v[44:45], v[54:55] op_sel_hi:[0,1]
	v_pk_mul_f32 v[42:43], v[44:45], v[42:43] op_sel_hi:[0,1]
	v_lshlrev_b32_e32 v58, 16, v41
	v_and_b32_e32 v59, 0xffff0000, v41
	v_pk_fma_f32 v[46:47], v[46:47], v[54:55], v[50:51]
	v_pk_fma_f32 v[42:43], v[48:49], v[42:43], v[52:53]
	v_pk_add_f32 v[46:47], v[46:47], v[58:59]
	v_pk_add_f32 v[42:43], v[42:43], v[60:61]
	v_cvt_pk_bf16_f32 v44, v46, v47
	v_cvt_pk_bf16_f32 v45, v42, v43
	ds_write_b64 v19, v[44:45] offset:16752
	v_add_u32_e32 v46, 0x25500, v27
	v_add_u32_e32 v41, 0x25100, v27
	ds_read_b64 v[50:51], v19 offset:128
	ds_read_b128 v[42:45], v41
	ds_read_b128 v[46:49], v46
	ds_read_b32 v52, v29
	ds_read_b32 v54, v30
	ds_read_b64 v[56:57], v19 offset:16768
	s_waitcnt lgkmcnt(5)
	v_lshlrev_b32_e32 v58, 16, v50
	v_and_b32_e32 v59, 0xffff0000, v50
	v_lshlrev_b32_e32 v50, 16, v51
	v_and_b32_e32 v51, 0xffff0000, v51
	v_lshlrev_b32_e32 v62, 16, v40
	v_and_b32_e32 v63, 0xffff0000, v40
	s_waitcnt lgkmcnt(2)
	v_pk_add_f32 v[40:41], v[58:59], v[52:53] op_sel_hi:[1,0] neg_lo:[0,1] neg_hi:[0,1]
	v_pk_add_f32 v[50:51], v[50:51], v[52:53] op_sel_hi:[1,0] neg_lo:[0,1] neg_hi:[0,1]
	s_waitcnt lgkmcnt(1)
	v_pk_mul_f32 v[40:41], v[54:55], v[40:41] op_sel_hi:[0,1]
	v_pk_mul_f32 v[50:51], v[54:55], v[50:51] op_sel_hi:[0,1]
	v_lshlrev_b32_e32 v60, 16, v38
	v_and_b32_e32 v61, 0xffff0000, v38
	v_pk_fma_f32 v[40:41], v[42:43], v[40:41], v[46:47]
	v_pk_fma_f32 v[50:51], v[44:45], v[50:51], v[48:49]
	v_pk_add_f32 v[40:41], v[40:41], v[60:61]
	v_pk_add_f32 v[50:51], v[50:51], v[62:63]
	v_cvt_pk_bf16_f32 v40, v40, v41
	v_cvt_pk_bf16_f32 v41, v50, v51
	ds_write_b64 v19, v[40:41] offset:128
	ds_read_b32 v38, v31
	ds_read_b32 v40, v33
	s_waitcnt lgkmcnt(3)
	v_lshlrev_b32_e32 v50, 16, v56
	v_and_b32_e32 v51, 0xffff0000, v56
	v_lshlrev_b32_e32 v52, 16, v57
	v_and_b32_e32 v53, 0xffff0000, v57
	v_lshlrev_b32_e32 v56, 16, v39
	v_and_b32_e32 v57, 0xffff0000, v39
	s_waitcnt lgkmcnt(1)
	v_pk_add_f32 v[50:51], v[50:51], v[38:39] op_sel_hi:[1,0] neg_lo:[0,1] neg_hi:[0,1]
	v_pk_add_f32 v[38:39], v[52:53], v[38:39] op_sel_hi:[1,0] neg_lo:[0,1] neg_hi:[0,1]
	s_waitcnt lgkmcnt(0)
	v_pk_mul_f32 v[50:51], v[40:41], v[50:51] op_sel_hi:[0,1]
	v_pk_mul_f32 v[38:39], v[40:41], v[38:39] op_sel_hi:[0,1]
	v_lshlrev_b32_e32 v54, 16, v37
	v_and_b32_e32 v55, 0xffff0000, v37
	v_pk_fma_f32 v[42:43], v[42:43], v[50:51], v[46:47]
	v_pk_fma_f32 v[38:39], v[44:45], v[38:39], v[48:49]
	v_pk_add_f32 v[42:43], v[42:43], v[54:55]
	v_pk_add_f32 v[38:39], v[38:39], v[56:57]
	v_cvt_pk_bf16_f32 v40, v42, v43
	v_cvt_pk_bf16_f32 v41, v38, v39
	ds_write_b64 v19, v[40:41] offset:16768
	v_add_u32_e32 v42, 0x25520, v27
	v_add_u32_e32 v37, 0x25120, v27
	ds_read_b64 v[46:47], v19 offset:144
	ds_read_b128 v[38:41], v37
	ds_read_b128 v[42:45], v42
	ds_read_b32 v48, v29
	ds_read_b32 v50, v30
	ds_read_b64 v[52:53], v19 offset:16784
	s_waitcnt lgkmcnt(5)
	v_lshlrev_b32_e32 v54, 16, v46
	v_and_b32_e32 v55, 0xffff0000, v46
	v_lshlrev_b32_e32 v46, 16, v47
	v_and_b32_e32 v47, 0xffff0000, v47
	v_lshlrev_b32_e32 v58, 16, v36
	v_and_b32_e32 v59, 0xffff0000, v36
	s_waitcnt lgkmcnt(2)
	v_pk_add_f32 v[36:37], v[54:55], v[48:49] op_sel_hi:[1,0] neg_lo:[0,1] neg_hi:[0,1]
	v_pk_add_f32 v[46:47], v[46:47], v[48:49] op_sel_hi:[1,0] neg_lo:[0,1] neg_hi:[0,1]
	s_waitcnt lgkmcnt(1)
	v_pk_mul_f32 v[36:37], v[50:51], v[36:37] op_sel_hi:[0,1]
	v_pk_mul_f32 v[46:47], v[50:51], v[46:47] op_sel_hi:[0,1]
	v_lshlrev_b32_e32 v56, 16, v34
	v_and_b32_e32 v57, 0xffff0000, v34
	v_pk_fma_f32 v[36:37], v[38:39], v[36:37], v[42:43]
	v_pk_fma_f32 v[46:47], v[40:41], v[46:47], v[44:45]
	v_pk_add_f32 v[36:37], v[36:37], v[56:57]
	v_pk_add_f32 v[46:47], v[46:47], v[58:59]
	v_cvt_pk_bf16_f32 v36, v36, v37
	v_cvt_pk_bf16_f32 v37, v46, v47
	ds_write_b64 v19, v[36:37] offset:144
	ds_read_b32 v34, v31
	ds_read_b32 v36, v33
	s_waitcnt lgkmcnt(3)
	v_lshlrev_b32_e32 v46, 16, v52
	v_and_b32_e32 v47, 0xffff0000, v52
	v_lshlrev_b32_e32 v48, 16, v53
	v_and_b32_e32 v49, 0xffff0000, v53
	v_lshlrev_b32_e32 v52, 16, v35
	v_and_b32_e32 v53, 0xffff0000, v35
	s_waitcnt lgkmcnt(1)
	v_pk_add_f32 v[46:47], v[46:47], v[34:35] op_sel_hi:[1,0] neg_lo:[0,1] neg_hi:[0,1]
	v_pk_add_f32 v[34:35], v[48:49], v[34:35] op_sel_hi:[1,0] neg_lo:[0,1] neg_hi:[0,1]
	s_waitcnt lgkmcnt(0)
	v_pk_mul_f32 v[46:47], v[36:37], v[46:47] op_sel_hi:[0,1]
	v_pk_mul_f32 v[34:35], v[36:37], v[34:35] op_sel_hi:[0,1]
	v_lshlrev_b32_e32 v50, 16, v32
	v_and_b32_e32 v51, 0xffff0000, v32
	v_pk_fma_f32 v[38:39], v[38:39], v[46:47], v[42:43]
	v_pk_fma_f32 v[34:35], v[40:41], v[34:35], v[44:45]
	v_pk_add_f32 v[38:39], v[38:39], v[50:51]
	v_pk_add_f32 v[34:35], v[34:35], v[52:53]
	v_cvt_pk_bf16_f32 v36, v38, v39
	v_cvt_pk_bf16_f32 v37, v34, v35
	ds_write_b64 v19, v[36:37] offset:16784
	v_add_u32_e32 v32, 0x25140, v27
	v_add_u32_e32 v38, 0x25540, v27
	ds_read_b64 v[42:43], v19 offset:160
	ds_read_b128 v[34:37], v32
	ds_read_b128 v[38:41], v38
	ds_read_b32 v32, v29
	ds_read_b32 v44, v30
	ds_read_b64 v[46:47], v19 offset:16800
	s_waitcnt lgkmcnt(5)
	v_lshlrev_b32_e32 v48, 16, v42
	v_and_b32_e32 v49, 0xffff0000, v42
	v_lshlrev_b32_e32 v42, 16, v43
	v_and_b32_e32 v43, 0xffff0000, v43
	s_waitcnt lgkmcnt(2)
	v_pk_add_f32 v[48:49], v[48:49], v[32:33] op_sel_hi:[1,0] neg_lo:[0,1] neg_hi:[0,1]
	v_pk_add_f32 v[42:43], v[42:43], v[32:33] op_sel_hi:[1,0] neg_lo:[0,1] neg_hi:[0,1]
	s_waitcnt lgkmcnt(1)
; DI unsigned pack2(float a, float b) { f32x2_t v = {a, b}; bf16x2_t r = __builtin_convertvector(v, bf16x2_t); return __builtin_bit_cast(unsigned, r); }
; DI float bflo(unsigned u) { return __uint_as_float(u << 16); }
; DI float bfhi(unsigned u) { return __uint_as_float(u & 0xffff0000u); }
; template <bool LAST>
; DI void phase_gate(const Params& P, int layer, unsigned char* smem, int L, int G) {
;     ...
; #pragma unroll
;     for (int i = 0; i < 4; ++i)
; #pragma unroll
;       for (int q4 = 0; q4 < 4; ++q4) {
;         const int fl = wm2 * 128 + i * 32 + 8 * q4 + 4 * h2;
;         const int f0 = nt * 256 + fl;
;         const f32x4 gv = *(const f32x4*)(vecL + 512 + fl), bv = *(const f32x4*)(vecL + 768 + fl);
;         const float ga[4] = {gv.x, gv.y, gv.z, gv.w}, ba[4] = {bv.x, bv.y, bv.z, bv.w};
; #pragma unroll
;         for (int j = 0; j < 2; ++j) {
;           const int lrow = wn2 * 64 + j * 32 + r2;
;           const float mu = rowA[lrow], rstd = rowB[lrow];
;           uint2* sp = (uint2*)(stg + lrow * STG + fl);
;           const uint2 sv = *sp;
;           const float sa[4] = {bflo(sv.x), bfhi(sv.x), bflo(sv.y), bfhi(sv.y)};
;           float y[4];
;           const float gg[4] = {bflo(gq[i][j][2 * q4]), bfhi(gq[i][j][2 * q4]), bflo(gq[i][j][2 * q4 + 1]), bfhi(gq[i][j][2 * q4 + 1])};
; #pragma unroll
;           for (int e = 0; e < 4; ++e) y[e] = (sa[e] - mu) * rstd * ga[e] + ba[e] + gg[e];
;           if (LAST) { f32x4 o = {y[0], y[1], y[2], y[3]}; *(f32x4*)(P.out + (size_t)(mt * 256 + lrow) * 1024 + f0) = o; }
;           else { uint2 pk; pk.x = pack2(y[0], y[1]); pk.y = pack2(y[2], y[3]); *sp = pk; }
;         }
;         __builtin_amdgcn_sched_barrier(0);
	v_pk_mul_f32 v[48:49], v[44:45], v[48:49] op_sel_hi:[0,1]
	v_pk_mul_f32 v[42:43], v[44:45], v[42:43] op_sel_hi:[0,1]
	v_lshlrev_b32_e32 v50, 16, v24
	v_and_b32_e32 v51, 0xffff0000, v24
	v_lshlrev_b32_e32 v52, 16, v26
	v_and_b32_e32 v53, 0xffff0000, v26
	v_pk_fma_f32 v[48:49], v[34:35], v[48:49], v[38:39]
	v_pk_fma_f32 v[42:43], v[36:37], v[42:43], v[40:41]
	v_pk_add_f32 v[48:49], v[48:49], v[50:51]
	v_pk_add_f32 v[42:43], v[42:43], v[52:53]
	v_cvt_pk_bf16_f32 v44, v48, v49
	v_cvt_pk_bf16_f32 v45, v42, v43
	ds_write_b64 v19, v[44:45] offset:160
	ds_read_b32 v24, v31
	ds_read_b32 v26, v33
	s_waitcnt lgkmcnt(3)
	v_lshlrev_b32_e32 v42, 16, v46
	v_and_b32_e32 v43, 0xffff0000, v46
	v_lshlrev_b32_e32 v44, 16, v47
	v_and_b32_e32 v45, 0xffff0000, v47
	v_lshlrev_b32_e32 v48, 16, v25
	v_and_b32_e32 v49, 0xffff0000, v25
	s_waitcnt lgkmcnt(1)
	v_pk_add_f32 v[42:43], v[42:43], v[24:25] op_sel_hi:[1,0] neg_lo:[0,1] neg_hi:[0,1]
	v_pk_add_f32 v[24:25], v[44:45], v[24:25] op_sel_hi:[1,0] neg_lo:[0,1] neg_hi:[0,1]
	s_waitcnt lgkmcnt(0)
	v_pk_mul_f32 v[42:43], v[26:27], v[42:43] op_sel_hi:[0,1]
	v_pk_mul_f32 v[24:25], v[26:27], v[24:25] op_sel_hi:[0,1]
	v_lshlrev_b32_e32 v46, 16, v23
	v_and_b32_e32 v47, 0xffff0000, v23
	v_pk_fma_f32 v[34:35], v[34:35], v[42:43], v[38:39]
	v_pk_fma_f32 v[24:25], v[36:37], v[24:25], v[40:41]
	v_pk_add_f32 v[34:35], v[34:35], v[46:47]
	v_pk_add_f32 v[24:25], v[24:25], v[48:49]
	v_cvt_pk_bf16_f32 v34, v34, v35
	v_cvt_pk_bf16_f32 v35, v24, v25
	ds_write_b64 v19, v[34:35] offset:16800
	v_add_u32_e32 v26, 0x25560, v27
	v_add_u32_e32 v23, 0x25160, v27
	ds_read_b64 v[24:25], v19 offset:176
	ds_read_b128 v[34:37], v23
	ds_read_b128 v[38:41], v26
	ds_read_b32 v26, v29
	ds_read_b32 v32, v30
	ds_read_b64 v[42:43], v19 offset:16816
	s_waitcnt lgkmcnt(5)
	v_lshlrev_b32_e32 v44, 16, v24
	v_and_b32_e32 v45, 0xffff0000, v24
	v_lshlrev_b32_e32 v24, 16, v25
	v_and_b32_e32 v25, 0xffff0000, v25
	v_lshlrev_b32_e32 v48, 16, v22
	v_and_b32_e32 v49, 0xffff0000, v22
	s_waitcnt lgkmcnt(2)
	v_pk_add_f32 v[22:23], v[44:45], v[26:27] op_sel_hi:[1,0] neg_lo:[0,1] neg_hi:[0,1]
	v_pk_add_f32 v[24:25], v[24:25], v[26:27] op_sel_hi:[1,0] neg_lo:[0,1] neg_hi:[0,1]
	s_waitcnt lgkmcnt(1)
	v_pk_mul_f32 v[22:23], v[32:33], v[22:23] op_sel_hi:[0,1]
	v_pk_mul_f32 v[24:25], v[32:33], v[24:25] op_sel_hi:[0,1]
	v_lshlrev_b32_e32 v46, 16, v20
	v_and_b32_e32 v47, 0xffff0000, v20
	v_pk_fma_f32 v[22:23], v[34:35], v[22:23], v[38:39]
	v_pk_fma_f32 v[24:25], v[36:37], v[24:25], v[40:41]
	v_pk_add_f32 v[22:23], v[22:23], v[46:47]
	v_pk_add_f32 v[24:25], v[24:25], v[48:49]
	v_cvt_pk_bf16_f32 v22, v22, v23
	v_cvt_pk_bf16_f32 v23, v24, v25
	ds_write_b64 v19, v[22:23] offset:176
	ds_read_b32 v20, v31
	ds_read_b32 v22, v33
	s_waitcnt lgkmcnt(3)
	v_lshlrev_b32_e32 v24, 16, v42
	v_and_b32_e32 v25, 0xffff0000, v42
	v_lshlrev_b32_e32 v42, 16, v43
	v_and_b32_e32 v43, 0xffff0000, v43
	v_lshlrev_b32_e32 v46, 16, v21
	v_and_b32_e32 v47, 0xffff0000, v21
	s_waitcnt lgkmcnt(1)
	v_pk_add_f32 v[24:25], v[24:25], v[20:21] op_sel_hi:[1,0] neg_lo:[0,1] neg_hi:[0,1]
	v_pk_add_f32 v[20:21], v[42:43], v[20:21] op_sel_hi:[1,0] neg_lo:[0,1] neg_hi:[0,1]
	s_waitcnt lgkmcnt(0)
	v_pk_mul_f32 v[24:25], v[22:23], v[24:25] op_sel_hi:[0,1]
	v_pk_mul_f32 v[20:21], v[22:23], v[20:21] op_sel_hi:[0,1]
	v_lshlrev_b32_e32 v44, 16, v18
	v_and_b32_e32 v45, 0xffff0000, v18
	v_pk_fma_f32 v[24:25], v[34:35], v[24:25], v[38:39]
	v_pk_fma_f32 v[20:21], v[36:37], v[20:21], v[40:41]
	v_pk_add_f32 v[24:25], v[24:25], v[44:45]
	v_pk_add_f32 v[20:21], v[20:21], v[46:47]
	v_cvt_pk_bf16_f32 v22, v24, v25
	v_cvt_pk_bf16_f32 v23, v20, v21
	ds_write_b64 v19, v[22:23] offset:16816
	v_add_u32_e32 v18, 0x25180, v27
	v_add_u32_e32 v26, 0x25580, v27
	ds_read_b64 v[24:25], v19 offset:192
	ds_read_b128 v[20:23], v18
	ds_read_b128 v[34:37], v26
	ds_read_b32 v18, v29
	ds_read_b32 v26, v30
	ds_read_b64 v[38:39], v19 offset:16832
	s_waitcnt lgkmcnt(5)
	v_lshlrev_b32_e32 v40, 16, v24
	v_and_b32_e32 v41, 0xffff0000, v24
	v_lshlrev_b32_e32 v24, 16, v25
	v_and_b32_e32 v25, 0xffff0000, v25
	s_waitcnt lgkmcnt(2)
	v_pk_add_f32 v[40:41], v[40:41], v[18:19] op_sel_hi:[1,0] neg_lo:[0,1] neg_hi:[0,1]
	v_pk_add_f32 v[24:25], v[24:25], v[18:19] op_sel_hi:[1,0] neg_lo:[0,1] neg_hi:[0,1]
	s_waitcnt lgkmcnt(1)
	v_pk_mul_f32 v[40:41], v[26:27], v[40:41] op_sel_hi:[0,1]
	v_pk_mul_f32 v[24:25], v[26:27], v[24:25] op_sel_hi:[0,1]
	v_lshlrev_b32_e32 v42, 16, v15
	v_and_b32_e32 v43, 0xffff0000, v15
	v_lshlrev_b32_e32 v44, 16, v17
	v_and_b32_e32 v45, 0xffff0000, v17
	v_pk_fma_f32 v[40:41], v[20:21], v[40:41], v[34:35]
	v_pk_fma_f32 v[24:25], v[22:23], v[24:25], v[36:37]
	v_pk_add_f32 v[40:41], v[40:41], v[42:43]
	v_pk_add_f32 v[24:25], v[24:25], v[44:45]
	v_cvt_pk_bf16_f32 v40, v40, v41
	v_cvt_pk_bf16_f32 v41, v24, v25
	ds_write_b64 v19, v[40:41] offset:192
	ds_read_b32 v18, v31
	ds_read_b32 v24, v33
	s_waitcnt lgkmcnt(3)
	v_lshlrev_b32_e32 v40, 16, v38
	v_and_b32_e32 v41, 0xffff0000, v38
	v_lshlrev_b32_e32 v42, 16, v14
	v_and_b32_e32 v43, 0xffff0000, v14
	v_lshlrev_b32_e32 v14, 16, v16
	v_and_b32_e32 v15, 0xffff0000, v16
	s_waitcnt lgkmcnt(1)
	v_pk_add_f32 v[16:17], v[40:41], v[18:19] op_sel_hi:[1,0] neg_lo:[0,1] neg_hi:[0,1]
	v_lshlrev_b32_e32 v38, 16, v39
	v_and_b32_e32 v39, 0xffff0000, v39
	s_waitcnt lgkmcnt(0)
; DI unsigned pack2(float a, float b) { f32x2_t v = {a, b}; bf16x2_t r = __builtin_convertvector(v, bf16x2_t); return __builtin_bit_cast(unsigned, r); }
; DI float bflo(unsigned u) { return __uint_as_float(u << 16); }
; DI float bfhi(unsigned u) { return __uint_as_float(u & 0xffff0000u); }
; template <bool LAST>
; DI void phase_gate(const Params& P, int layer, unsigned char* smem, int L, int G) {
;     ...
; #pragma unroll
;     for (int i = 0; i < 4; ++i)
; #pragma unroll
;       for (int q4 = 0; q4 < 4; ++q4) {
;         const int fl = wm2 * 128 + i * 32 + 8 * q4 + 4 * h2;
;         const int f0 = nt * 256 + fl;
;         const f32x4 gv = *(const f32x4*)(vecL + 512 + fl), bv = *(const f32x4*)(vecL + 768 + fl);
;         const float ga[4] = {gv.x, gv.y, gv.z, gv.w}, ba[4] = {bv.x, bv.y, bv.z, bv.w};
; #pragma unroll
;         for (int j = 0; j < 2; ++j) {
;           const int lrow = wn2 * 64 + j * 32 + r2;
;           const float mu = rowA[lrow], rstd = rowB[lrow];
;           uint2* sp = (uint2*)(stg + lrow * STG + fl);
;           const uint2 sv = *sp;
;           const float sa[4] = {bflo(sv.x), bfhi(sv.x), bflo(sv.y), bfhi(sv.y)};
;           float y[4];
;           const float gg[4] = {bflo(gq[i][j][2 * q4]), bfhi(gq[i][j][2 * q4]), bflo(gq[i][j][2 * q4 + 1]), bfhi(gq[i][j][2 * q4 + 1])};
; #pragma unroll
;           for (int e = 0; e < 4; ++e) y[e] = (sa[e] - mu) * rstd * ga[e] + ba[e] + gg[e];
;           if (LAST) { f32x4 o = {y[0], y[1], y[2], y[3]}; *(f32x4*)(P.out + (size_t)(mt * 256 + lrow) * 1024 + f0) = o; }
;           else { uint2 pk; pk.x = pack2(y[0], y[1]); pk.y = pack2(y[2], y[3]); *sp = pk; }
;         }
;         __builtin_amdgcn_sched_barrier(0);
;       }
;     __syncthreads();
	v_pk_mul_f32 v[16:17], v[24:25], v[16:17] op_sel_hi:[0,1]
	v_pk_fma_f32 v[16:17], v[20:21], v[16:17], v[34:35]
	v_pk_add_f32 v[20:21], v[38:39], v[18:19] op_sel_hi:[1,0] neg_lo:[0,1] neg_hi:[0,1]
	v_pk_add_f32 v[16:17], v[16:17], v[42:43]
	v_pk_mul_f32 v[20:21], v[24:25], v[20:21] op_sel_hi:[0,1]
	v_pk_fma_f32 v[20:21], v[22:23], v[20:21], v[36:37]
	v_cvt_pk_bf16_f32 v16, v16, v17
	v_pk_add_f32 v[14:15], v[20:21], v[14:15]
	s_nop 0
	v_cvt_pk_bf16_f32 v17, v14, v15
	ds_write_b64 v19, v[16:17] offset:16832
	v_add_u32_e32 v14, 0x251a0, v27
	v_add_u32_e32 v18, 0x255a0, v27
	ds_read_b64 v[24:25], v19 offset:208
	ds_read_b128 v[14:17], v14
	ds_read_b128 v[20:23], v18
	ds_read_b32 v18, v29
	ds_read_b32 v26, v30
	ds_read_b64 v[34:35], v19 offset:16848
	s_waitcnt lgkmcnt(5)
	v_lshlrev_b32_e32 v36, 16, v24
	v_and_b32_e32 v37, 0xffff0000, v24
	v_lshlrev_b32_e32 v24, 16, v25
	v_and_b32_e32 v25, 0xffff0000, v25
	s_waitcnt lgkmcnt(2)
	v_pk_add_f32 v[36:37], v[36:37], v[18:19] op_sel_hi:[1,0] neg_lo:[0,1] neg_hi:[0,1]
	v_pk_add_f32 v[24:25], v[24:25], v[18:19] op_sel_hi:[1,0] neg_lo:[0,1] neg_hi:[0,1]
	s_waitcnt lgkmcnt(1)
	v_pk_mul_f32 v[36:37], v[26:27], v[36:37] op_sel_hi:[0,1]
	v_pk_mul_f32 v[24:25], v[26:27], v[24:25] op_sel_hi:[0,1]
	v_lshlrev_b32_e32 v38, 16, v11
	v_and_b32_e32 v39, 0xffff0000, v11
	v_lshlrev_b32_e32 v40, 16, v13
	v_and_b32_e32 v41, 0xffff0000, v13
	v_pk_fma_f32 v[36:37], v[14:15], v[36:37], v[20:21]
	v_pk_fma_f32 v[24:25], v[16:17], v[24:25], v[22:23]
	v_pk_add_f32 v[36:37], v[36:37], v[38:39]
	v_pk_add_f32 v[24:25], v[24:25], v[40:41]
	v_cvt_pk_bf16_f32 v36, v36, v37
	v_cvt_pk_bf16_f32 v37, v24, v25
	ds_write_b64 v19, v[36:37] offset:208
	ds_read_b32 v18, v31
	ds_read_b32 v24, v33
	s_waitcnt lgkmcnt(3)
	v_lshlrev_b32_e32 v36, 16, v34
	v_and_b32_e32 v37, 0xffff0000, v34
	v_lshlrev_b32_e32 v38, 16, v10
	v_and_b32_e32 v39, 0xffff0000, v10
	v_lshlrev_b32_e32 v10, 16, v12
	v_and_b32_e32 v11, 0xffff0000, v12
	s_waitcnt lgkmcnt(1)
	v_pk_add_f32 v[12:13], v[36:37], v[18:19] op_sel_hi:[1,0] neg_lo:[0,1] neg_hi:[0,1]
	v_lshlrev_b32_e32 v34, 16, v35
	v_and_b32_e32 v35, 0xffff0000, v35
	s_waitcnt lgkmcnt(0)
	v_pk_mul_f32 v[12:13], v[24:25], v[12:13] op_sel_hi:[0,1]
	v_pk_fma_f32 v[12:13], v[14:15], v[12:13], v[20:21]
	v_pk_add_f32 v[14:15], v[34:35], v[18:19] op_sel_hi:[1,0] neg_lo:[0,1] neg_hi:[0,1]
	v_pk_add_f32 v[12:13], v[12:13], v[38:39]
	v_pk_mul_f32 v[14:15], v[24:25], v[14:15] op_sel_hi:[0,1]
	v_pk_fma_f32 v[14:15], v[16:17], v[14:15], v[22:23]
	v_cvt_pk_bf16_f32 v12, v12, v13
	v_pk_add_f32 v[10:11], v[14:15], v[10:11]
	s_nop 0
	v_cvt_pk_bf16_f32 v13, v10, v11
	ds_write_b64 v19, v[12:13] offset:16848
	v_add_u32_e32 v10, 0x251c0, v27
	v_add_u32_e32 v14, 0x255c0, v27
	ds_read_b64 v[20:21], v19 offset:224
	ds_read_b128 v[10:13], v10
	ds_read_b128 v[14:17], v14
	ds_read_b32 v18, v29
	ds_read_b32 v22, v30
	ds_read_b64 v[24:25], v19 offset:16864
	s_waitcnt lgkmcnt(5)
	v_lshlrev_b32_e32 v34, 16, v20
	v_and_b32_e32 v35, 0xffff0000, v20
	v_lshlrev_b32_e32 v20, 16, v21
	v_and_b32_e32 v21, 0xffff0000, v21
	s_waitcnt lgkmcnt(2)
	v_pk_add_f32 v[34:35], v[34:35], v[18:19] op_sel_hi:[1,0] neg_lo:[0,1] neg_hi:[0,1]
	v_pk_add_f32 v[20:21], v[20:21], v[18:19] op_sel_hi:[1,0] neg_lo:[0,1] neg_hi:[0,1]
	s_waitcnt lgkmcnt(1)
	v_pk_mul_f32 v[34:35], v[22:23], v[34:35] op_sel_hi:[0,1]
	v_pk_mul_f32 v[20:21], v[22:23], v[20:21] op_sel_hi:[0,1]
	v_lshlrev_b32_e32 v36, 16, v7
	v_and_b32_e32 v37, 0xffff0000, v7
	v_lshlrev_b32_e32 v38, 16, v9
	v_and_b32_e32 v39, 0xffff0000, v9
	v_pk_fma_f32 v[34:35], v[10:11], v[34:35], v[14:15]
	v_pk_fma_f32 v[20:21], v[12:13], v[20:21], v[16:17]
	v_pk_add_f32 v[34:35], v[34:35], v[36:37]
	v_pk_add_f32 v[20:21], v[20:21], v[38:39]
	v_cvt_pk_bf16_f32 v22, v34, v35
	v_cvt_pk_bf16_f32 v23, v20, v21
	ds_write_b64 v19, v[22:23] offset:224
	ds_read_b32 v18, v31
	ds_read_b32 v20, v33
	s_waitcnt lgkmcnt(3)
	v_lshlrev_b32_e32 v22, 16, v24
	v_and_b32_e32 v23, 0xffff0000, v24
	v_lshlrev_b32_e32 v34, 16, v6
	v_and_b32_e32 v35, 0xffff0000, v6
	v_lshlrev_b32_e32 v6, 16, v8
	v_and_b32_e32 v7, 0xffff0000, v8
	s_waitcnt lgkmcnt(1)
	v_pk_add_f32 v[8:9], v[22:23], v[18:19] op_sel_hi:[1,0] neg_lo:[0,1] neg_hi:[0,1]
	v_lshlrev_b32_e32 v24, 16, v25
	v_and_b32_e32 v25, 0xffff0000, v25
	s_waitcnt lgkmcnt(0)
	v_pk_mul_f32 v[8:9], v[20:21], v[8:9] op_sel_hi:[0,1]
	v_pk_fma_f32 v[8:9], v[10:11], v[8:9], v[14:15]
	v_pk_add_f32 v[10:11], v[24:25], v[18:19] op_sel_hi:[1,0] neg_lo:[0,1] neg_hi:[0,1]
	v_pk_add_f32 v[8:9], v[8:9], v[34:35]
	v_pk_mul_f32 v[10:11], v[20:21], v[10:11] op_sel_hi:[0,1]
	v_pk_fma_f32 v[10:11], v[12:13], v[10:11], v[16:17]
	v_cvt_pk_bf16_f32 v8, v8, v9
	v_pk_add_f32 v[6:7], v[10:11], v[6:7]
	s_nop 0
	v_cvt_pk_bf16_f32 v9, v6, v7
	ds_write_b64 v19, v[8:9] offset:16864
	ds_read_b128 v[6:9], v28 offset:480
	ds_read_b64 v[14:15], v19 offset:240
	ds_read_b32 v16, v29
	ds_read_b32 v18, v30
	v_add_u32_e32 v10, 0x255e0, v27
	ds_read_b128 v[10:13], v10
	s_waitcnt lgkmcnt(3)
	v_lshlrev_b32_e32 v20, 16, v14
	v_and_b32_e32 v21, 0xffff0000, v14
	v_lshlrev_b32_e32 v14, 16, v15
	v_and_b32_e32 v15, 0xffff0000, v15
	s_waitcnt lgkmcnt(2)
	v_pk_add_f32 v[20:21], v[20:21], v[16:17] op_sel_hi:[1,0] neg_lo:[0,1] neg_hi:[0,1]
	v_pk_add_f32 v[14:15], v[14:15], v[16:17] op_sel_hi:[1,0] neg_lo:[0,1] neg_hi:[0,1]
	s_waitcnt lgkmcnt(1)
	v_pk_mul_f32 v[20:21], v[18:19], v[20:21] op_sel_hi:[0,1]
	v_pk_mul_f32 v[14:15], v[18:19], v[14:15] op_sel_hi:[0,1]
	v_lshlrev_b32_e32 v22, 16, v4
	v_and_b32_e32 v23, 0xffff0000, v4
	v_lshlrev_b32_e32 v4, 16, v5
	v_and_b32_e32 v5, 0xffff0000, v5
	s_waitcnt lgkmcnt(0)
	v_pk_fma_f32 v[20:21], v[6:7], v[20:21], v[10:11]
	v_pk_fma_f32 v[14:15], v[8:9], v[14:15], v[12:13]
	v_pk_add_f32 v[20:21], v[20:21], v[22:23]
	v_pk_add_f32 v[4:5], v[14:15], v[4:5]
	v_cvt_pk_bf16_f32 v14, v20, v21
	v_cvt_pk_bf16_f32 v15, v4, v5
	ds_write_b64 v19, v[14:15] offset:240
	ds_read_b32 v4, v33
	ds_read_b64 v[14:15], v19 offset:16880
	ds_read_b32 v16, v31
	v_lshlrev_b32_e32 v22, 16, v2
	v_and_b32_e32 v23, 0xffff0000, v2
	v_lshlrev_b32_e32 v2, 16, v3
	s_waitcnt lgkmcnt(1)
	v_lshlrev_b32_e32 v20, 16, v14
	v_and_b32_e32 v21, 0xffff0000, v14
	s_waitcnt lgkmcnt(0)
	v_pk_add_f32 v[20:21], v[20:21], v[16:17] op_sel_hi:[1,0] neg_lo:[0,1] neg_hi:[0,1]
	v_lshlrev_b32_e32 v14, 16, v15
	v_and_b32_e32 v15, 0xffff0000, v15
	v_pk_mul_f32 v[20:21], v[4:5], v[20:21] op_sel_hi:[0,1]
	v_pk_fma_f32 v[6:7], v[6:7], v[20:21], v[10:11]
	v_pk_add_f32 v[10:11], v[14:15], v[16:17] op_sel_hi:[1,0] neg_lo:[0,1] neg_hi:[0,1]
	v_and_b32_e32 v3, 0xffff0000, v3
	v_pk_mul_f32 v[4:5], v[4:5], v[10:11] op_sel_hi:[0,1]
	v_pk_fma_f32 v[4:5], v[8:9], v[4:5], v[12:13]
	v_pk_add_f32 v[6:7], v[6:7], v[22:23]
	v_pk_add_f32 v[2:3], v[4:5], v[2:3]
	v_cvt_pk_bf16_f32 v4, v6, v7
	v_cvt_pk_bf16_f32 v5, v2, v3
	ds_write_b64 v19, v[4:5] offset:16880
	s_add_u32 s18, s80, s18
	s_addc_u32 s19, s81, s19
	v_lshl_add_u64 v[8:9], s[18:19], 0, v[0:1]
	v_mov_b32_e32 v0, v192
	s_waitcnt lgkmcnt(0)
	s_barrier
; DI int otid() { int t = threadIdx.x; asm volatile("" : "+v"(t)); return t; }
; DI void stg16_nt(void* p, u32x4 v) { __builtin_nontemporal_store(v, (u32x4*)p); }
; DI void stage_store_tile(const bf16_t* stg, bf16_t* tilebase) {
;   const int tid = otid();
;   const int r0 = tid >> 5, c = tid & 31;
;   const unsigned o0 = (unsigned)(r0 * 1024 + c * 8);
; #pragma unroll
;   for (int it = 0; it < 16; ++it) stg16_nt(tilebase + (o0 + (unsigned)(it * 16 * 1024)), stage_read16(stg, r0 + 16 * it, c));
; }
	s_mov_b64 s[100:101], 0x8000
	s_add_i32 s25, s25, s74
	s_add_i32 s22, s22, s69
	s_add_i32 s23, s23, s24
	s_add_i32 s18, s70, s25
	s_cmpk_lt_i32 s18, 0x400
	v_ashrrev_i32_e32 v190, 5, v192
	v_and_b32_e32 v191, 31, v192
	v_mul_lo_u32 v252, v190, s34
	v_lshl_add_u32 v252, v191, 4, v252
	v_lshlrev_b32_e32 v191, 3, v191
	v_lshl_or_b32 v254, v190, 10, v191
	v_mov_b32_e32 v255, v161
	ds_read2_b64 v[218:221], v252 offset1:1
	v_add_u32_e32 v253, 0x2080, v252
	ds_read2_b64 v[222:225], v253 offset1:1
	v_add_u32_e32 v253, 0x4100, v252
	ds_read2_b64 v[226:229], v253 offset1:1
	v_add_u32_e32 v253, 0x6180, v252
	ds_read2_b64 v[230:233], v253 offset1:1
	v_add_u32_e32 v253, 0x8200, v252
	ds_read2_b64 v[234:237], v253 offset1:1
	v_add_u32_e32 v253, 0xa280, v252
	ds_read2_b64 v[238:241], v253 offset1:1
	v_add_u32_e32 v253, 0xc300, v252
	ds_read2_b64 v[242:245], v253 offset1:1
	v_add_u32_e32 v253, 0xe380, v252
	ds_read2_b64 v[248:251], v253 offset1:1
	v_lshl_add_u64 v[254:255], v[254:255], 1, v[8:9]
	s_waitcnt lgkmcnt(7)
	global_store_dwordx4 v[254:255], v[218:221], off nt
	v_add_u32_e32 v253, 0x10400, v252
	ds_read2_b64 v[218:221], v253 offset1:1
	v_lshl_add_u64 v[254:255], v[254:255], 0, s[100:101]
	s_waitcnt lgkmcnt(7)
	global_store_dwordx4 v[254:255], v[222:225], off nt
	v_add_u32_e32 v253, 0x12480, v252
	ds_read2_b64 v[222:225], v253 offset1:1
	v_lshl_add_u64 v[254:255], v[254:255], 0, s[100:101]
	s_waitcnt lgkmcnt(7)
	global_store_dwordx4 v[254:255], v[226:229], off nt
	v_add_u32_e32 v253, 0x14500, v252
	ds_read2_b64 v[226:229], v253 offset1:1
	v_lshl_add_u64 v[254:255], v[254:255], 0, s[100:101]
	s_waitcnt lgkmcnt(7)
	global_store_dwordx4 v[254:255], v[230:233], off nt
	v_add_u32_e32 v253, 0x16580, v252
	ds_read2_b64 v[230:233], v253 offset1:1
	v_lshl_add_u64 v[254:255], v[254:255], 0, s[100:101]
	s_waitcnt lgkmcnt(7)
	global_store_dwordx4 v[254:255], v[234:237], off nt
	v_add_u32_e32 v253, 0x18600, v252
	ds_read2_b64 v[234:237], v253 offset1:1
	v_lshl_add_u64 v[254:255], v[254:255], 0, s[100:101]
	s_waitcnt lgkmcnt(7)
	global_store_dwordx4 v[254:255], v[238:241], off nt
	v_add_u32_e32 v253, 0x1a680, v252
	ds_read2_b64 v[238:241], v253 offset1:1
	v_lshl_add_u64 v[254:255], v[254:255], 0, s[100:101]
	s_waitcnt lgkmcnt(7)
	global_store_dwordx4 v[254:255], v[242:245], off nt
	v_add_u32_e32 v253, 0x1c700, v252
	ds_read2_b64 v[242:245], v253 offset1:1
	v_lshl_add_u64 v[254:255], v[254:255], 0, s[100:101]
	s_waitcnt lgkmcnt(7)
	global_store_dwordx4 v[254:255], v[248:251], off nt
	v_add_u32_e32 v253, 0x1e780, v252
	ds_read2_b64 v[248:251], v253 offset1:1
	v_lshl_add_u64 v[254:255], v[254:255], 0, s[100:101]
	s_waitcnt lgkmcnt(7)
	global_store_dwordx4 v[254:255], v[218:221], off nt
	v_lshl_add_u64 v[254:255], v[254:255], 0, s[100:101]
	s_waitcnt lgkmcnt(6)
	global_store_dwordx4 v[254:255], v[222:225], off nt
	v_lshl_add_u64 v[254:255], v[254:255], 0, s[100:101]
	s_waitcnt lgkmcnt(5)
	global_store_dwordx4 v[254:255], v[226:229], off nt
	v_lshl_add_u64 v[254:255], v[254:255], 0, s[100:101]
	s_waitcnt lgkmcnt(4)
	global_store_dwordx4 v[254:255], v[230:233], off nt
	v_lshl_add_u64 v[254:255], v[254:255], 0, s[100:101]
	s_waitcnt lgkmcnt(3)
	global_store_dwordx4 v[254:255], v[234:237], off nt
	v_lshl_add_u64 v[254:255], v[254:255], 0, s[100:101]
	s_waitcnt lgkmcnt(2)
	global_store_dwordx4 v[254:255], v[238:241], off nt
	v_lshl_add_u64 v[254:255], v[254:255], 0, s[100:101]
	s_waitcnt lgkmcnt(1)
	global_store_dwordx4 v[254:255], v[242:245], off nt
	v_lshl_add_u64 v[254:255], v[254:255], 0, s[100:101]
	s_waitcnt lgkmcnt(0)
	global_store_dwordx4 v[254:255], v[248:251], off nt
	s_barrier
	s_cbranch_scc0 .LBB0_1507
